# GEMM loops: per-MFMA-block s_setprio toggles removed, one static s_setprio 1 for the trailing wave half (waves 4-7) at kernel entry
# baseline (speedup 1.0000x reference)
; __global__ void __launch_bounds__(512, 2) mega_fwd(Params p_arg) {
;   typedef const __attribute__((address_space(4))) Params* KParamsPtr;
;   KParamsPtr pptr = (KParamsPtr)__builtin_amdgcn_kernarg_segment_ptr(); asm volatile("" : "+s"(pptr));
;   const __attribute__((address_space(4))) Params& p = *pptr;
;   __shared__ __attribute__((aligned(16))) char smem[147456 + 16];
;   cg::grid_group grid = cg::this_grid();
;   if (p.flags) grid.sync();
;   const int wv = __builtin_amdgcn_readfirstlane((int)(threadIdx.x >> 6));
_Z8mega_fwd6Params:
	v_readfirstlane_b32 s98, v0
	s_and_b32 s98, s98, 0x3ff
	s_cmp_lt_u32 s98, 0x100
	s_cbranch_scc1 .Lprio_lead
	s_setprio 1
.Lprio_lead:
	s_mov_b64 s[24:25], s[0:1]
	s_mov_b32 s26, s2
	s_load_dword s2, s[24:25], 0x108
	s_load_dwordx2 s[28:29], s[0:1], 0x110
	s_load_dword s92, s[0:1], 0x118
	s_add_u32 s0, s0, 0x110
	s_addc_u32 s1, s1, 0
	s_waitcnt lgkmcnt(0)
	s_cmp_lg_u32 s2, 0
	v_writelane_b32 v252, s0, 0
	v_and_b32_e32 v1, 0x3ff, v0
	s_nop 0
	v_writelane_b32 v252, s1, 1
	s_cbranch_scc0 .LBB0_12
	v_and_b32_e32 v0, 0x3fffffff, v0
	v_cmp_eq_u32_e32 vcc, 0, v0
	s_barrier
	s_and_saveexec_b64 s[0:1], vcc
	s_cbranch_execz .LBB0_11
	v_readlane_b32 s2, v252, 0
	v_readlane_b32 s3, v252, 1
	buffer_wbl2 sc1
	s_load_dwordx2 s[2:3], s[2:3], 0x58
	v_mov_b32_e32 v3, 0
	s_mov_b64 s[4:5], exec
	v_mbcnt_lo_u32_b32 v2, s4, 0
	v_mbcnt_hi_u32_b32 v2, s5, v2
	s_waitcnt lgkmcnt(0)
	global_load_dword v0, v3, s[2:3] offset:40
	v_cmp_eq_u32_e32 vcc, 0, v2
	s_and_saveexec_b64 s[6:7], vcc
	s_cbranch_execz .LBB0_4
	s_bcnt1_i32_b64 s4, s[4:5]
	v_mov_b32_e32 v4, s4
	global_atomic_add v4, v3, v4, s[2:3] offset:32 sc0

; #define PG8_STAGE(bufoff, gbase, voff) do { _Pragma("unroll") for (int _i = 0; _i < 2; ++_i) \
;         __builtin_amdgcn_global_load_lds((const unsigned*)((const char*)(gbase) + (voff)[_i]), (PG8_LAS unsigned*)(lds + (bufoff) + ldsw + _i * 8192), 16, 0, 0); } while (0)
; #define PG8_LDA(dst, b, h) do { _Pragma("unroll") for (int m = 0; m < 4; ++m) _Pragma("unroll") for (int k = 0; k < 2; ++k) dst[m][k] = *(const PG8_LAS bf16x8*)(lds + PG8_SA(b, h) + aoff + m * 2048 + k * 1024); } while (0)
; #define PG8_LDB(dst, b, h) do { _Pragma("unroll") for (int n = 0; n < 2; ++n) _Pragma("unroll") for (int k = 0; k < 2; ++k) dst[n][k] = *(const PG8_LAS bf16x8*)(lds + PG8_SB(b, h) + boff + n * 2048 + k * 1024); } while (0)
; #define PG8_WAIT_V(n) asm volatile("s_waitcnt vmcnt(" #n ")" ::: "memory")
; #define PG8_WAIT_L(n) asm volatile("s_waitcnt lgkmcnt(" #n ")" ::: "memory")
; #define PG8_BAR __builtin_amdgcn_s_barrier()
; #define PG8_SCHED __builtin_amdgcn_sched_barrier(0)
; template <class Epi, class Sched, bool ALIGN_EPI = false, bool SP2 = false, bool F16 = false, bool TOKPERM = false>
; __device__ __forceinline__ void gemm_phase(PG8_LAS unsigned char* lds, const Gemm g, const Sched& S, const Epi& E, int wv) {
;     ...
;         const bool has_next = S.next(ui + 1, nxt);
;         const char* nA = has_next ? (const char*)g.A + (size_t)nxt.pm * tstep : cA; const char* nB = has_next ? (const char*)g.Bt + (size_t)nxt.pn * tstep : cB;
;         for (int t = 0; t < nt; t += 2) {
;             const bool last = (t == nt - 2);
;             const char* a1 = cA + (size_t)(t + 1) * kstep;
;             const char* a2 = last ? nA : cA + (size_t)(t + 2) * kstep; const char* b2 = last ? nB : cB + (size_t)(t + 2) * kstep;
;             const char* a3 = a2 + kstep; const char* b3 = b2 + kstep;
;             if (last && has_next) S.a_ready(nxt);
;             if constexpr (SP2) {
;             PG8_LDB(B0, 0, 0); PG8_LDB(B1, 0, 1); PG8_SCHED; PG8_LDA(At, 0, 0); PG8_STAGE(PG8_SA(1, 1), a1 + hstep, voffA);
;             PG8_WAIT_V(8); PG8_WAIT_L(0); PG8_BAR; PG8_MMA(0, 0, At, B0); PG8_MMA(0, 1, At, B1); PG8_BAR; PG8_SCHED;
;             PG8_LDA(At, 0, 1); PG8_STAGE(PG8_SB(0, 0), b2, voffB); PG8_STAGE(PG8_SB(0, 1), b2 + hstep, voffB); PG8_STAGE(PG8_SA(0, 0), a2, voffA);
;             PG8_WAIT_V(8); PG8_WAIT_L(0); PG8_BAR; PG8_MMA(1, 0, At, B0); PG8_MMA(1, 1, At, B1); PG8_BAR; PG8_SCHED;
.LBB0_180:
	s_ashr_i32 s51, s50, 31
	s_lshl_b64 s[52:53], s[50:51], 19
	s_add_u32 s52, s40, s52
	s_addc_u32 s53, s41, s53
	s_and_b64 s[54:55], s[2:3], exec
	s_cselect_b32 s51, s53, s7
	s_cselect_b32 s77, s52, s6
	s_ashr_i32 s49, s48, 31
	s_lshl_b64 s[54:55], s[48:49], 19
	s_add_u32 s54, s33, s54
	s_addc_u32 s55, s36, s55
	s_and_b64 s[56:57], s[2:3], exec
	s_cselect_b32 s49, s55, s9
	s_cselect_b32 s78, s54, s8
	s_add_u32 s6, s6, 0x40080
	s_addc_u32 s7, s7, 0
	s_add_u32 s79, s8, 0x100
	s_addc_u32 s80, s9, 0
	s_mov_b32 s81, -2
	ds_read_b128 v[172:175], v155
	ds_read_b128 v[176:179], v156
	ds_read_b128 v[180:183], v157
	ds_read_b128 v[184:187], v158
	ds_read_b128 v[188:191], v159
	ds_read_b128 v[192:195], v160
	ds_read_b128 v[196:199], v161
	ds_read_b128 v[200:203], v162
	s_add_u32 s8, s6, 0xfffc0080
	s_addc_u32 s9, s7, -1
	s_cmp_eq_u32 s81, 12
	s_cselect_b32 s57, s51, s9
	s_cselect_b32 s56, s77, s8
	s_cselect_b32 s9, s49, s80
	s_cselect_b32 s8, s78, s79
	s_mov_b32 m0, s73
	v_lshl_add_u64 v[148:149], s[6:7], 0, v[140:141]
	ds_read_b128 v[204:207], v153
	ds_read_b128 v[208:211], v153 offset:1024
	ds_read_b128 v[212:215], v153 offset:2048
	ds_read_b128 v[216:219], v153 offset:3072
	ds_read_b128 v[220:223], v153 offset:4096
	ds_read_b128 v[228:231], v153 offset:5120
	ds_read_b128 v[232:235], v153 offset:6144
	ds_read_b128 v[236:239], v153 offset:7168
	global_load_lds_dwordx4 v[148:149], off
	v_lshl_add_u64 v[148:149], s[6:7], 0, v[142:143]
	s_mov_b32 m0, s74
	s_nop 0
	global_load_lds_dwordx4 v[148:149], off
	s_waitcnt vmcnt(8)
	s_waitcnt lgkmcnt(0)
	s_barrier
	s_waitcnt lgkmcnt(0)
	v_mfma_f32_16x16x32_f16 v[124:127], v[172:175], v[204:207], 0
	v_mfma_f32_16x16x32_f16 v[116:119], v[180:183], v[204:207], 0
	v_mfma_f32_16x16x32_f16 v[108:111], v[172:175], v[212:215], 0
	v_mfma_f32_16x16x32_f16 v[104:107], v[180:183], v[212:215], 0
	v_mfma_f32_16x16x32_f16 v[92:95], v[172:175], v[220:223], 0
	v_mfma_f32_16x16x32_f16 v[88:91], v[180:183], v[220:223], 0
	v_mfma_f32_16x16x32_f16 v[76:79], v[172:175], v[232:235], 0
	v_mfma_f32_16x16x32_f16 v[72:75], v[180:183], v[232:235], 0
	v_mfma_f32_16x16x32_f16 v[124:127], v[176:179], v[208:211], v[124:127]
	v_mfma_f32_16x16x32_f16 v[116:119], v[184:187], v[208:211], v[116:119]
	v_mfma_f32_16x16x32_f16 v[108:111], v[176:179], v[216:219], v[108:111]
	v_mfma_f32_16x16x32_f16 v[104:107], v[184:187], v[216:219], v[104:107]
	v_mfma_f32_16x16x32_f16 v[92:95], v[176:179], v[228:231], v[92:95]
	v_mfma_f32_16x16x32_f16 v[88:91], v[184:187], v[228:231], v[88:91]
	v_mfma_f32_16x16x32_f16 v[76:79], v[176:179], v[236:239], v[76:79]
	v_mfma_f32_16x16x32_f16 v[72:75], v[184:187], v[236:239], v[72:75]
	v_mfma_f32_16x16x32_f16 v[120:123], v[188:191], v[204:207], 0
	v_mfma_f32_16x16x32_f16 v[112:115], v[196:199], v[204:207], 0
	v_mfma_f32_16x16x32_f16 v[100:103], v[188:191], v[212:215], 0
	v_mfma_f32_16x16x32_f16 v[96:99], v[196:199], v[212:215], 0
	v_mfma_f32_16x16x32_f16 v[84:87], v[188:191], v[220:223], 0
	v_mfma_f32_16x16x32_f16 v[80:83], v[196:199], v[220:223], 0
	v_mfma_f32_16x16x32_f16 v[68:71], v[188:191], v[232:235], 0
	v_mfma_f32_16x16x32_f16 v[64:67], v[196:199], v[232:235], 0
	v_mfma_f32_16x16x32_f16 v[120:123], v[192:195], v[208:211], v[120:123]
	v_mfma_f32_16x16x32_f16 v[112:115], v[200:203], v[208:211], v[112:115]
	v_mfma_f32_16x16x32_f16 v[100:103], v[192:195], v[216:219], v[100:103]
	v_mfma_f32_16x16x32_f16 v[96:99], v[200:203], v[216:219], v[96:99]
	v_mfma_f32_16x16x32_f16 v[84:87], v[192:195], v[228:231], v[84:87]
	v_mfma_f32_16x16x32_f16 v[80:83], v[200:203], v[228:231], v[80:83]
	v_mfma_f32_16x16x32_f16 v[68:71], v[192:195], v[236:239], v[68:71]
	v_mfma_f32_16x16x32_f16 v[64:67], v[200:203], v[236:239], v[64:67]
	s_barrier
	s_mov_b32 m0, s37
	v_lshl_add_u64 v[148:149], s[8:9], 0, v[132:133]
	s_add_u32 s82, s8, 0x40000
	ds_read_b128 v[204:207], v153 offset:16384
	ds_read_b128 v[208:211], v153 offset:17408
	ds_read_b128 v[212:215], v153 offset:18432
	ds_read_b128 v[216:219], v153 offset:19456
	ds_read_b128 v[220:223], v153 offset:20480
	ds_read_b128 v[228:231], v153 offset:21504
	ds_read_b128 v[232:235], v153 offset:22528
	ds_read_b128 v[236:239], v153 offset:23552
	global_load_lds_dwordx4 v[148:149], off
	v_lshl_add_u64 v[224:225], s[8:9], 0, v[128:129]
	s_mov_b32 m0, s45
	s_addc_u32 s83, s9, 0
	global_load_lds_dwordx4 v[224:225], off
	v_lshl_add_u64 v[240:241], s[82:83], 0, v[132:133]
	s_mov_b32 m0, s58
	v_lshl_add_u64 v[242:243], s[56:57], 0, v[130:131]
	global_load_lds_dwordx4 v[240:241], off
	v_lshl_add_u64 v[240:241], s[82:83], 0, v[128:129]
	s_mov_b32 m0, s59
	s_nop 0
	global_load_lds_dwordx4 v[240:241], off
	v_lshl_add_u64 v[240:241], s[56:57], 0, v[134:135]
	s_mov_b32 m0, s20
	s_nop 0
	global_load_lds_dwordx4 v[240:241], off
	s_mov_b32 m0, s60
	s_nop 0
	global_load_lds_dwordx4 v[242:243], off
	s_waitcnt vmcnt(8)
	s_waitcnt lgkmcnt(0)
	s_barrier
; #define PG8_STAGE(bufoff, gbase, voff) do { _Pragma("unroll") for (int _i = 0; _i < 2; ++_i) \
;         __builtin_amdgcn_global_load_lds((const unsigned*)((const char*)(gbase) + (voff)[_i]), (PG8_LAS unsigned*)(lds + (bufoff) + ldsw + _i * 8192), 16, 0, 0); } while (0)
; #define PG8_LDA(dst, b, h) do { _Pragma("unroll") for (int m = 0; m < 4; ++m) _Pragma("unroll") for (int k = 0; k < 2; ++k) dst[m][k] = *(const PG8_LAS bf16x8*)(lds + PG8_SA(b, h) + aoff + m * 2048 + k * 1024); } while (0)
; #define PG8_LDB(dst, b, h) do { _Pragma("unroll") for (int n = 0; n < 2; ++n) _Pragma("unroll") for (int k = 0; k < 2; ++k) dst[n][k] = *(const PG8_LAS bf16x8*)(lds + PG8_SB(b, h) + boff + n * 2048 + k * 1024); } while (0)
; #define PG8_MMA(ai, bj, At, Bt) do { __builtin_amdgcn_s_setprio(1); _Pragma("unroll") for (int m = 0; m < 4; ++m) _Pragma("unroll") for (int n = 0; n < 2; ++n) _Pragma("unroll") for (int k = 0; k < 2; ++k) \
;         acc[ai][bj][m][n] = mma16<F16>(Bt[n][k], At[m][k], acc[ai][bj][m][n]); __builtin_amdgcn_s_setprio(0); } while (0)
; #define PG8_WAIT_V(n) asm volatile("s_waitcnt vmcnt(" #n ")" ::: "memory")
; #define PG8_WAIT_L(n) asm volatile("s_waitcnt lgkmcnt(" #n ")" ::: "memory")
; #define PG8_BAR __builtin_amdgcn_s_barrier()
; #define PG8_SCHED __builtin_amdgcn_sched_barrier(0)
; template <class Epi, class Sched, bool ALIGN_EPI = false, bool SP2 = false, bool F16 = false, bool TOKPERM = false>
; __device__ __forceinline__ void gemm_phase(PG8_LAS unsigned char* lds, const Gemm g, const Sched& S, const Epi& E, int wv) {
;     ...
;             PG8_WAIT_V(8); PG8_WAIT_L(0); PG8_BAR; PG8_MMA(0, 0, At, B0); PG8_MMA(0, 1, At, B1); PG8_BAR; PG8_SCHED;
;             PG8_LDA(At, 0, 1); PG8_STAGE(PG8_SB(0, 0), b2, voffB); PG8_STAGE(PG8_SB(0, 1), b2 + hstep, voffB); PG8_STAGE(PG8_SA(0, 0), a2, voffA);
;             PG8_WAIT_V(8); PG8_WAIT_L(0); PG8_BAR; PG8_MMA(1, 0, At, B0); PG8_MMA(1, 1, At, B1); PG8_BAR; PG8_SCHED;
;             PG8_LDB(B0, 1, 0); PG8_LDB(B1, 1, 1); PG8_SCHED; PG8_LDA(At, 1, 0); PG8_STAGE(PG8_SA(0, 1), a2 + hstep, voffA);
;             PG8_WAIT_V(8); PG8_WAIT_L(0); PG8_BAR; PG8_MMA(0, 0, At, B0); PG8_MMA(0, 1, At, B1); PG8_BAR; PG8_SCHED;
	s_waitcnt lgkmcnt(0)
	v_mfma_f32_16x16x32_f16 v[60:63], v[172:175], v[204:207], 0
	v_mfma_f32_16x16x32_f16 v[56:59], v[180:183], v[204:207], 0
	v_mfma_f32_16x16x32_f16 v[44:47], v[172:175], v[212:215], 0
	v_mfma_f32_16x16x32_f16 v[40:43], v[180:183], v[212:215], 0
	v_mfma_f32_16x16x32_f16 v[28:31], v[172:175], v[220:223], 0
	v_mfma_f32_16x16x32_f16 v[24:27], v[180:183], v[220:223], 0
	v_mfma_f32_16x16x32_f16 v[12:15], v[172:175], v[232:235], 0
	v_mfma_f32_16x16x32_f16 v[8:11], v[180:183], v[232:235], 0
	v_mfma_f32_16x16x32_f16 v[60:63], v[176:179], v[208:211], v[60:63]
	v_mfma_f32_16x16x32_f16 v[56:59], v[184:187], v[208:211], v[56:59]
	v_mfma_f32_16x16x32_f16 v[44:47], v[176:179], v[216:219], v[44:47]
	v_mfma_f32_16x16x32_f16 v[40:43], v[184:187], v[216:219], v[40:43]
	v_mfma_f32_16x16x32_f16 v[28:31], v[176:179], v[228:231], v[28:31]
	v_mfma_f32_16x16x32_f16 v[24:27], v[184:187], v[228:231], v[24:27]
	v_mfma_f32_16x16x32_f16 v[12:15], v[176:179], v[236:239], v[12:15]
	v_mfma_f32_16x16x32_f16 v[8:11], v[184:187], v[236:239], v[8:11]
	v_mfma_f32_16x16x32_f16 v[52:55], v[188:191], v[204:207], 0
	v_mfma_f32_16x16x32_f16 v[48:51], v[196:199], v[204:207], 0
	v_mfma_f32_16x16x32_f16 v[36:39], v[188:191], v[212:215], 0
	v_mfma_f32_16x16x32_f16 v[32:35], v[196:199], v[212:215], 0
	v_mfma_f32_16x16x32_f16 v[20:23], v[188:191], v[220:223], 0
	v_mfma_f32_16x16x32_f16 v[16:19], v[196:199], v[220:223], 0
	v_mfma_f32_16x16x32_f16 v[4:7], v[188:191], v[232:235], 0
	v_mfma_f32_16x16x32_f16 v[0:3], v[196:199], v[232:235], 0
	v_mfma_f32_16x16x32_f16 v[52:55], v[192:195], v[208:211], v[52:55]
	v_mfma_f32_16x16x32_f16 v[48:51], v[200:203], v[208:211], v[48:51]
	v_mfma_f32_16x16x32_f16 v[36:39], v[192:195], v[216:219], v[36:39]
	v_mfma_f32_16x16x32_f16 v[32:35], v[200:203], v[216:219], v[32:35]
	v_mfma_f32_16x16x32_f16 v[20:23], v[192:195], v[228:231], v[20:23]
	v_mfma_f32_16x16x32_f16 v[16:19], v[200:203], v[228:231], v[16:19]
	v_mfma_f32_16x16x32_f16 v[4:7], v[192:195], v[236:239], v[4:7]
	v_mfma_f32_16x16x32_f16 v[0:3], v[200:203], v[236:239], v[0:3]
	s_barrier
	ds_read_b128 v[172:175], v163
	ds_read_b128 v[176:179], v164
	ds_read_b128 v[180:183], v165
	ds_read_b128 v[184:187], v166
	ds_read_b128 v[188:191], v167
	ds_read_b128 v[192:195], v168
	ds_read_b128 v[196:199], v169
	ds_read_b128 v[200:203], v170
	s_add_u32 s56, s56, 0x40000
	s_addc_u32 s57, s57, 0
	s_mov_b32 m0, s61
	v_lshl_add_u64 v[244:245], s[56:57], 0, v[134:135]
	ds_read_b128 v[204:207], v153 offset:32768
	ds_read_b128 v[208:211], v153 offset:33792
	ds_read_b128 v[212:215], v153 offset:34816
	ds_read_b128 v[216:219], v153 offset:35840
	ds_read_b128 v[220:223], v153 offset:36864
	ds_read_b128 v[228:231], v153 offset:37888
	ds_read_b128 v[232:235], v153 offset:38912
	ds_read_b128 v[236:239], v153 offset:39936
	global_load_lds_dwordx4 v[244:245], off
	v_lshl_add_u64 v[244:245], s[56:57], 0, v[130:131]
	s_mov_b32 m0, s62
	s_nop 0
	global_load_lds_dwordx4 v[244:245], off
	s_waitcnt vmcnt(8)
	s_waitcnt lgkmcnt(0)
	s_barrier
	s_waitcnt lgkmcnt(0)
	v_mfma_f32_16x16x32_f16 v[124:127], v[172:175], v[204:207], v[124:127]
	v_mfma_f32_16x16x32_f16 v[116:119], v[180:183], v[204:207], v[116:119]
	v_mfma_f32_16x16x32_f16 v[108:111], v[172:175], v[212:215], v[108:111]
	v_mfma_f32_16x16x32_f16 v[104:107], v[180:183], v[212:215], v[104:107]
	v_mfma_f32_16x16x32_f16 v[92:95], v[172:175], v[220:223], v[92:95]
	v_mfma_f32_16x16x32_f16 v[88:91], v[180:183], v[220:223], v[88:91]
	v_mfma_f32_16x16x32_f16 v[76:79], v[172:175], v[232:235], v[76:79]
	v_mfma_f32_16x16x32_f16 v[72:75], v[180:183], v[232:235], v[72:75]
	v_mfma_f32_16x16x32_f16 v[124:127], v[176:179], v[208:211], v[124:127]
	v_mfma_f32_16x16x32_f16 v[116:119], v[184:187], v[208:211], v[116:119]
	v_mfma_f32_16x16x32_f16 v[108:111], v[176:179], v[216:219], v[108:111]
	v_mfma_f32_16x16x32_f16 v[104:107], v[184:187], v[216:219], v[104:107]
	v_mfma_f32_16x16x32_f16 v[92:95], v[176:179], v[228:231], v[92:95]
	v_mfma_f32_16x16x32_f16 v[88:91], v[184:187], v[228:231], v[88:91]
	v_mfma_f32_16x16x32_f16 v[76:79], v[176:179], v[236:239], v[76:79]
	v_mfma_f32_16x16x32_f16 v[72:75], v[184:187], v[236:239], v[72:75]
	v_mfma_f32_16x16x32_f16 v[120:123], v[188:191], v[204:207], v[120:123]
	v_mfma_f32_16x16x32_f16 v[112:115], v[196:199], v[204:207], v[112:115]
	v_mfma_f32_16x16x32_f16 v[100:103], v[188:191], v[212:215], v[100:103]
	v_mfma_f32_16x16x32_f16 v[96:99], v[196:199], v[212:215], v[96:99]
	v_mfma_f32_16x16x32_f16 v[84:87], v[188:191], v[220:223], v[84:87]
	v_mfma_f32_16x16x32_f16 v[80:83], v[196:199], v[220:223], v[80:83]
	v_mfma_f32_16x16x32_f16 v[68:71], v[188:191], v[232:235], v[68:71]
	v_mfma_f32_16x16x32_f16 v[64:67], v[196:199], v[232:235], v[64:67]
	v_mfma_f32_16x16x32_f16 v[120:123], v[192:195], v[208:211], v[120:123]
	v_mfma_f32_16x16x32_f16 v[112:115], v[200:203], v[208:211], v[112:115]
	v_mfma_f32_16x16x32_f16 v[100:103], v[192:195], v[216:219], v[100:103]
	v_mfma_f32_16x16x32_f16 v[96:99], v[200:203], v[216:219], v[96:99]
	v_mfma_f32_16x16x32_f16 v[84:87], v[192:195], v[228:231], v[84:87]
	v_mfma_f32_16x16x32_f16 v[80:83], v[200:203], v[228:231], v[80:83]
	v_mfma_f32_16x16x32_f16 v[68:71], v[192:195], v[236:239], v[68:71]
	v_mfma_f32_16x16x32_f16 v[64:67], v[200:203], v[236:239], v[64:67]
	s_barrier
; #define PG8_STAGE(bufoff, gbase, voff) do { _Pragma("unroll") for (int _i = 0; _i < 2; ++_i) \
;         __builtin_amdgcn_global_load_lds((const unsigned*)((const char*)(gbase) + (voff)[_i]), (PG8_LAS unsigned*)(lds + (bufoff) + ldsw + _i * 8192), 16, 0, 0); } while (0)
; #define PG8_LDA(dst, b, h) do { _Pragma("unroll") for (int m = 0; m < 4; ++m) _Pragma("unroll") for (int k = 0; k < 2; ++k) dst[m][k] = *(const PG8_LAS bf16x8*)(lds + PG8_SA(b, h) + aoff + m * 2048 + k * 1024); } while (0)
; #define PG8_LDB(dst, b, h) do { _Pragma("unroll") for (int n = 0; n < 2; ++n) _Pragma("unroll") for (int k = 0; k < 2; ++k) dst[n][k] = *(const PG8_LAS bf16x8*)(lds + PG8_SB(b, h) + boff + n * 2048 + k * 1024); } while (0)
; #define PG8_MMA(ai, bj, At, Bt) do { __builtin_amdgcn_s_setprio(1); _Pragma("unroll") for (int m = 0; m < 4; ++m) _Pragma("unroll") for (int n = 0; n < 2; ++n) _Pragma("unroll") for (int k = 0; k < 2; ++k) \
;         acc[ai][bj][m][n] = mma16<F16>(Bt[n][k], At[m][k], acc[ai][bj][m][n]); __builtin_amdgcn_s_setprio(0); } while (0)
; #define PG8_BAR __builtin_amdgcn_s_barrier()
; template <class Epi, class Sched, bool ALIGN_EPI = false, bool SP2 = false, bool F16 = false, bool TOKPERM = false>
; __device__ __forceinline__ void gemm_phase(PG8_LAS unsigned char* lds, const Gemm g, const Sched& S, const Epi& E, int wv) {
;     ...
;             PG8_LDB(B0, 0, 0); PG8_LDB(B1, 0, 1); PG8_SCHED; PG8_LDA(At, 0, 0); PG8_STAGE(PG8_SA(1, 1), a1 + hstep, voffA);
;             PG8_WAIT_V(8); PG8_WAIT_L(0); PG8_BAR; PG8_MMA(0, 0, At, B0); PG8_MMA(0, 1, At, B1); PG8_BAR; PG8_SCHED;
;             PG8_LDA(At, 0, 1); PG8_STAGE(PG8_SB(0, 0), b2, voffB); PG8_STAGE(PG8_SB(0, 1), b2 + hstep, voffB); PG8_STAGE(PG8_SA(0, 0), a2, voffA);
;             PG8_WAIT_V(8); PG8_WAIT_L(0); PG8_BAR; PG8_MMA(1, 0, At, B0); PG8_MMA(1, 1, At, B1); PG8_BAR; PG8_SCHED;
;             PG8_LDB(B0, 1, 0); PG8_LDB(B1, 1, 1); PG8_SCHED; PG8_LDA(At, 1, 0); PG8_STAGE(PG8_SA(0, 1), a2 + hstep, voffA);
;             PG8_WAIT_V(8); PG8_WAIT_L(0); PG8_BAR; PG8_MMA(0, 0, At, B0); PG8_MMA(0, 1, At, B1); PG8_BAR; PG8_SCHED;
;             PG8_LDA(At, 1, 1); PG8_STAGE(PG8_SB(1, 0), b3, voffB); PG8_STAGE(PG8_SB(1, 1), b3 + hstep, voffB); PG8_STAGE(PG8_SA(1, 0), a3, voffA);
;             PG8_WAIT_V(8); PG8_WAIT_L(0); PG8_BAR; PG8_MMA(1, 0, At, B0); PG8_MMA(1, 1, At, B1); PG8_BAR; PG8_SCHED;
	s_mov_b32 m0, s64
	v_lshl_add_u64 v[148:149], v[148:149], 0, s[16:17]
	s_add_u32 s8, s8, 0x40080
	ds_read_b128 v[204:207], v153 offset:49152
	ds_read_b128 v[208:211], v153 offset:50176
	ds_read_b128 v[212:215], v153 offset:51200
	ds_read_b128 v[216:219], v153 offset:52224
	ds_read_b128 v[220:223], v153 offset:53248
	ds_read_b128 v[228:231], v153 offset:54272
	ds_read_b128 v[232:235], v153 offset:55296
	ds_read_b128 v[236:239], v153 offset:56320
	global_load_lds_dwordx4 v[148:149], off
	v_lshl_add_u64 v[148:149], v[224:225], 0, s[16:17]
	s_mov_b32 m0, s65
	s_addc_u32 s9, s9, 0
	global_load_lds_dwordx4 v[148:149], off
	v_lshl_add_u64 v[148:149], s[8:9], 0, v[132:133]
	s_mov_b32 m0, s69
	s_nop 0
	global_load_lds_dwordx4 v[148:149], off
	v_lshl_add_u64 v[148:149], s[8:9], 0, v[128:129]
	s_mov_b32 m0, s70
	s_nop 0
	global_load_lds_dwordx4 v[148:149], off
	v_lshl_add_u64 v[148:149], v[240:241], 0, s[16:17]
	s_mov_b32 m0, s66
	s_nop 0
	global_load_lds_dwordx4 v[148:149], off
	v_lshl_add_u64 v[148:149], v[242:243], 0, s[16:17]
	s_mov_b32 m0, s68
	s_nop 0
	global_load_lds_dwordx4 v[148:149], off
	s_waitcnt vmcnt(8)
	s_waitcnt lgkmcnt(0)
	s_barrier
	s_waitcnt lgkmcnt(0)
	v_mfma_f32_16x16x32_f16 v[60:63], v[172:175], v[204:207], v[60:63]
	v_mfma_f32_16x16x32_f16 v[56:59], v[180:183], v[204:207], v[56:59]
	v_mfma_f32_16x16x32_f16 v[44:47], v[172:175], v[212:215], v[44:47]
	v_mfma_f32_16x16x32_f16 v[40:43], v[180:183], v[212:215], v[40:43]
	v_mfma_f32_16x16x32_f16 v[28:31], v[172:175], v[220:223], v[28:31]
	v_mfma_f32_16x16x32_f16 v[24:27], v[180:183], v[220:223], v[24:27]
	v_mfma_f32_16x16x32_f16 v[12:15], v[172:175], v[232:235], v[12:15]
	v_mfma_f32_16x16x32_f16 v[8:11], v[180:183], v[232:235], v[8:11]
	v_mfma_f32_16x16x32_f16 v[60:63], v[176:179], v[208:211], v[60:63]
	v_mfma_f32_16x16x32_f16 v[56:59], v[184:187], v[208:211], v[56:59]
	v_mfma_f32_16x16x32_f16 v[44:47], v[176:179], v[216:219], v[44:47]
	v_mfma_f32_16x16x32_f16 v[40:43], v[184:187], v[216:219], v[40:43]
	v_mfma_f32_16x16x32_f16 v[28:31], v[176:179], v[228:231], v[28:31]
	v_mfma_f32_16x16x32_f16 v[24:27], v[184:187], v[228:231], v[24:27]
	v_mfma_f32_16x16x32_f16 v[12:15], v[176:179], v[236:239], v[12:15]
	v_mfma_f32_16x16x32_f16 v[8:11], v[184:187], v[236:239], v[8:11]
	v_mfma_f32_16x16x32_f16 v[52:55], v[188:191], v[204:207], v[52:55]
	v_mfma_f32_16x16x32_f16 v[48:51], v[196:199], v[204:207], v[48:51]
	v_mfma_f32_16x16x32_f16 v[36:39], v[188:191], v[212:215], v[36:39]
	v_mfma_f32_16x16x32_f16 v[32:35], v[196:199], v[212:215], v[32:35]
	v_mfma_f32_16x16x32_f16 v[20:23], v[188:191], v[220:223], v[20:23]
	v_mfma_f32_16x16x32_f16 v[16:19], v[196:199], v[220:223], v[16:19]
	v_mfma_f32_16x16x32_f16 v[4:7], v[188:191], v[232:235], v[4:7]
	v_mfma_f32_16x16x32_f16 v[0:3], v[196:199], v[232:235], v[0:3]
	v_mfma_f32_16x16x32_f16 v[52:55], v[192:195], v[208:211], v[52:55]
	v_mfma_f32_16x16x32_f16 v[48:51], v[200:203], v[208:211], v[48:51]
	v_mfma_f32_16x16x32_f16 v[36:39], v[192:195], v[216:219], v[36:39]
	v_mfma_f32_16x16x32_f16 v[32:35], v[200:203], v[216:219], v[32:35]
	v_mfma_f32_16x16x32_f16 v[20:23], v[192:195], v[228:231], v[20:23]
	v_mfma_f32_16x16x32_f16 v[16:19], v[200:203], v[228:231], v[16:19]
	v_mfma_f32_16x16x32_f16 v[4:7], v[192:195], v[236:239], v[4:7]
	v_mfma_f32_16x16x32_f16 v[0:3], v[200:203], v[236:239], v[0:3]
	s_barrier
	s_add_i32 s81, s81, 2
	s_add_u32 s6, s6, 0x100
	s_addc_u32 s7, s7, 0
	s_add_u32 s79, s79, 0x100
	s_addc_u32 s80, s80, 0
	s_cmp_gt_u32 s81, 13
.LBB0_181:
	ds_read_b128 v[172:175], v155
	ds_read_b128 v[176:179], v156
	ds_read_b128 v[180:183], v157
	ds_read_b128 v[184:187], v158
	ds_read_b128 v[188:191], v159
	ds_read_b128 v[192:195], v160
	ds_read_b128 v[196:199], v161
	ds_read_b128 v[200:203], v162
	s_add_u32 s8, s6, 0xfffc0080
	s_addc_u32 s9, s7, -1
	s_cmp_eq_u32 s81, 12
	s_cselect_b32 s57, s51, s9
	s_cselect_b32 s56, s77, s8
	s_cselect_b32 s9, s49, s80
	s_cselect_b32 s8, s78, s79
	s_mov_b32 m0, s73
	v_lshl_add_u64 v[148:149], s[6:7], 0, v[140:141]
	ds_read_b128 v[204:207], v153
	ds_read_b128 v[208:211], v153 offset:1024
	ds_read_b128 v[212:215], v153 offset:2048
	ds_read_b128 v[216:219], v153 offset:3072
	ds_read_b128 v[220:223], v153 offset:4096
	ds_read_b128 v[228:231], v153 offset:5120
	ds_read_b128 v[232:235], v153 offset:6144
	ds_read_b128 v[236:239], v153 offset:7168
	global_load_lds_dwordx4 v[148:149], off
	v_lshl_add_u64 v[148:149], s[6:7], 0, v[142:143]
	s_mov_b32 m0, s74
	s_nop 0
	global_load_lds_dwordx4 v[148:149], off
	s_waitcnt vmcnt(8)
	s_waitcnt lgkmcnt(0)
	s_barrier
; #define PG8_STAGE(bufoff, gbase, voff) do { _Pragma("unroll") for (int _i = 0; _i < 2; ++_i) \
;         __builtin_amdgcn_global_load_lds((const unsigned*)((const char*)(gbase) + (voff)[_i]), (PG8_LAS unsigned*)(lds + (bufoff) + ldsw + _i * 8192), 16, 0, 0); } while (0)
; #define PG8_LDA(dst, b, h) do { _Pragma("unroll") for (int m = 0; m < 4; ++m) _Pragma("unroll") for (int k = 0; k < 2; ++k) dst[m][k] = *(const PG8_LAS bf16x8*)(lds + PG8_SA(b, h) + aoff + m * 2048 + k * 1024); } while (0)
; #define PG8_LDB(dst, b, h) do { _Pragma("unroll") for (int n = 0; n < 2; ++n) _Pragma("unroll") for (int k = 0; k < 2; ++k) dst[n][k] = *(const PG8_LAS bf16x8*)(lds + PG8_SB(b, h) + boff + n * 2048 + k * 1024); } while (0)
; #define PG8_MMA(ai, bj, At, Bt) do { __builtin_amdgcn_s_setprio(1); _Pragma("unroll") for (int m = 0; m < 4; ++m) _Pragma("unroll") for (int n = 0; n < 2; ++n) _Pragma("unroll") for (int k = 0; k < 2; ++k) \
;         acc[ai][bj][m][n] = mma16<F16>(Bt[n][k], At[m][k], acc[ai][bj][m][n]); __builtin_amdgcn_s_setprio(0); } while (0)
; #define PG8_WAIT_V(n) asm volatile("s_waitcnt vmcnt(" #n ")" ::: "memory")
; #define PG8_WAIT_L(n) asm volatile("s_waitcnt lgkmcnt(" #n ")" ::: "memory")
; #define PG8_BAR __builtin_amdgcn_s_barrier()
; #define PG8_SCHED __builtin_amdgcn_sched_barrier(0)
; template <class Epi, class Sched, bool ALIGN_EPI = false, bool SP2 = false, bool F16 = false, bool TOKPERM = false>
; __device__ __forceinline__ void gemm_phase(PG8_LAS unsigned char* lds, const Gemm g, const Sched& S, const Epi& E, int wv) {
;     ...
;             PG8_LDB(B0, 0, 0); PG8_LDB(B1, 0, 1); PG8_SCHED; PG8_LDA(At, 0, 0); PG8_STAGE(PG8_SA(1, 1), a1 + hstep, voffA);
;             PG8_WAIT_V(8); PG8_WAIT_L(0); PG8_BAR; PG8_MMA(0, 0, At, B0); PG8_MMA(0, 1, At, B1); PG8_BAR; PG8_SCHED;
;             PG8_LDA(At, 0, 1); PG8_STAGE(PG8_SB(0, 0), b2, voffB); PG8_STAGE(PG8_SB(0, 1), b2 + hstep, voffB); PG8_STAGE(PG8_SA(0, 0), a2, voffA);
;             PG8_WAIT_V(8); PG8_WAIT_L(0); PG8_BAR; PG8_MMA(1, 0, At, B0); PG8_MMA(1, 1, At, B1); PG8_BAR; PG8_SCHED;
;             PG8_LDB(B0, 1, 0); PG8_LDB(B1, 1, 1); PG8_SCHED; PG8_LDA(At, 1, 0); PG8_STAGE(PG8_SA(0, 1), a2 + hstep, voffA);
;             PG8_WAIT_V(8); PG8_WAIT_L(0); PG8_BAR; PG8_MMA(0, 0, At, B0); PG8_MMA(0, 1, At, B1); PG8_BAR; PG8_SCHED;
	s_waitcnt lgkmcnt(0)
	v_mfma_f32_16x16x32_f16 v[124:127], v[172:175], v[204:207], v[124:127]
	v_mfma_f32_16x16x32_f16 v[116:119], v[180:183], v[204:207], v[116:119]
	v_mfma_f32_16x16x32_f16 v[108:111], v[172:175], v[212:215], v[108:111]
	v_mfma_f32_16x16x32_f16 v[104:107], v[180:183], v[212:215], v[104:107]
	v_mfma_f32_16x16x32_f16 v[92:95], v[172:175], v[220:223], v[92:95]
	v_mfma_f32_16x16x32_f16 v[88:91], v[180:183], v[220:223], v[88:91]
	v_mfma_f32_16x16x32_f16 v[76:79], v[172:175], v[232:235], v[76:79]
	v_mfma_f32_16x16x32_f16 v[72:75], v[180:183], v[232:235], v[72:75]
	v_mfma_f32_16x16x32_f16 v[124:127], v[176:179], v[208:211], v[124:127]
	v_mfma_f32_16x16x32_f16 v[116:119], v[184:187], v[208:211], v[116:119]
	v_mfma_f32_16x16x32_f16 v[108:111], v[176:179], v[216:219], v[108:111]
	v_mfma_f32_16x16x32_f16 v[104:107], v[184:187], v[216:219], v[104:107]
	v_mfma_f32_16x16x32_f16 v[92:95], v[176:179], v[228:231], v[92:95]
	v_mfma_f32_16x16x32_f16 v[88:91], v[184:187], v[228:231], v[88:91]
	v_mfma_f32_16x16x32_f16 v[76:79], v[176:179], v[236:239], v[76:79]
	v_mfma_f32_16x16x32_f16 v[72:75], v[184:187], v[236:239], v[72:75]
	v_mfma_f32_16x16x32_f16 v[120:123], v[188:191], v[204:207], v[120:123]
	v_mfma_f32_16x16x32_f16 v[112:115], v[196:199], v[204:207], v[112:115]
	v_mfma_f32_16x16x32_f16 v[100:103], v[188:191], v[212:215], v[100:103]
	v_mfma_f32_16x16x32_f16 v[96:99], v[196:199], v[212:215], v[96:99]
	v_mfma_f32_16x16x32_f16 v[84:87], v[188:191], v[220:223], v[84:87]
	v_mfma_f32_16x16x32_f16 v[80:83], v[196:199], v[220:223], v[80:83]
	v_mfma_f32_16x16x32_f16 v[68:71], v[188:191], v[232:235], v[68:71]
	v_mfma_f32_16x16x32_f16 v[64:67], v[196:199], v[232:235], v[64:67]
	v_mfma_f32_16x16x32_f16 v[120:123], v[192:195], v[208:211], v[120:123]
	v_mfma_f32_16x16x32_f16 v[112:115], v[200:203], v[208:211], v[112:115]
	v_mfma_f32_16x16x32_f16 v[100:103], v[192:195], v[216:219], v[100:103]
	v_mfma_f32_16x16x32_f16 v[96:99], v[200:203], v[216:219], v[96:99]
	v_mfma_f32_16x16x32_f16 v[84:87], v[192:195], v[228:231], v[84:87]
	v_mfma_f32_16x16x32_f16 v[80:83], v[200:203], v[228:231], v[80:83]
	v_mfma_f32_16x16x32_f16 v[68:71], v[192:195], v[236:239], v[68:71]
	v_mfma_f32_16x16x32_f16 v[64:67], v[200:203], v[236:239], v[64:67]
	s_barrier
	s_mov_b32 m0, s37
	v_lshl_add_u64 v[148:149], s[8:9], 0, v[132:133]
	s_add_u32 s82, s8, 0x40000
	ds_read_b128 v[204:207], v153 offset:16384
	ds_read_b128 v[208:211], v153 offset:17408
	ds_read_b128 v[212:215], v153 offset:18432
	ds_read_b128 v[216:219], v153 offset:19456
	ds_read_b128 v[220:223], v153 offset:20480
	ds_read_b128 v[228:231], v153 offset:21504
	ds_read_b128 v[232:235], v153 offset:22528
	ds_read_b128 v[236:239], v153 offset:23552
	global_load_lds_dwordx4 v[148:149], off
	v_lshl_add_u64 v[224:225], s[8:9], 0, v[128:129]
	s_mov_b32 m0, s45
	s_addc_u32 s83, s9, 0
	global_load_lds_dwordx4 v[224:225], off
	v_lshl_add_u64 v[240:241], s[82:83], 0, v[132:133]
	s_mov_b32 m0, s58
	v_lshl_add_u64 v[242:243], s[56:57], 0, v[130:131]
	global_load_lds_dwordx4 v[240:241], off
	v_lshl_add_u64 v[240:241], s[82:83], 0, v[128:129]
	s_mov_b32 m0, s59
	s_nop 0
	global_load_lds_dwordx4 v[240:241], off
	v_lshl_add_u64 v[240:241], s[56:57], 0, v[134:135]
	s_mov_b32 m0, s20
	s_nop 0
	global_load_lds_dwordx4 v[240:241], off
	s_mov_b32 m0, s60
	s_nop 0
	global_load_lds_dwordx4 v[242:243], off
	s_waitcnt vmcnt(8)
	s_waitcnt lgkmcnt(0)
	s_barrier
	s_waitcnt lgkmcnt(0)
	v_mfma_f32_16x16x32_f16 v[60:63], v[172:175], v[204:207], v[60:63]
	v_mfma_f32_16x16x32_f16 v[56:59], v[180:183], v[204:207], v[56:59]
	v_mfma_f32_16x16x32_f16 v[44:47], v[172:175], v[212:215], v[44:47]
	v_mfma_f32_16x16x32_f16 v[40:43], v[180:183], v[212:215], v[40:43]
	v_mfma_f32_16x16x32_f16 v[28:31], v[172:175], v[220:223], v[28:31]
	v_mfma_f32_16x16x32_f16 v[24:27], v[180:183], v[220:223], v[24:27]
	v_mfma_f32_16x16x32_f16 v[12:15], v[172:175], v[232:235], v[12:15]
	v_mfma_f32_16x16x32_f16 v[8:11], v[180:183], v[232:235], v[8:11]
	v_mfma_f32_16x16x32_f16 v[60:63], v[176:179], v[208:211], v[60:63]
	v_mfma_f32_16x16x32_f16 v[56:59], v[184:187], v[208:211], v[56:59]
	v_mfma_f32_16x16x32_f16 v[44:47], v[176:179], v[216:219], v[44:47]
	v_mfma_f32_16x16x32_f16 v[40:43], v[184:187], v[216:219], v[40:43]
	v_mfma_f32_16x16x32_f16 v[28:31], v[176:179], v[228:231], v[28:31]
	v_mfma_f32_16x16x32_f16 v[24:27], v[184:187], v[228:231], v[24:27]
	v_mfma_f32_16x16x32_f16 v[12:15], v[176:179], v[236:239], v[12:15]
	v_mfma_f32_16x16x32_f16 v[8:11], v[184:187], v[236:239], v[8:11]
	v_mfma_f32_16x16x32_f16 v[52:55], v[188:191], v[204:207], v[52:55]
	v_mfma_f32_16x16x32_f16 v[48:51], v[196:199], v[204:207], v[48:51]
	v_mfma_f32_16x16x32_f16 v[36:39], v[188:191], v[212:215], v[36:39]
	v_mfma_f32_16x16x32_f16 v[32:35], v[196:199], v[212:215], v[32:35]
	v_mfma_f32_16x16x32_f16 v[20:23], v[188:191], v[220:223], v[20:23]
	v_mfma_f32_16x16x32_f16 v[16:19], v[196:199], v[220:223], v[16:19]
	v_mfma_f32_16x16x32_f16 v[4:7], v[188:191], v[232:235], v[4:7]
	v_mfma_f32_16x16x32_f16 v[0:3], v[196:199], v[232:235], v[0:3]
	v_mfma_f32_16x16x32_f16 v[52:55], v[192:195], v[208:211], v[52:55]
	v_mfma_f32_16x16x32_f16 v[48:51], v[200:203], v[208:211], v[48:51]
	v_mfma_f32_16x16x32_f16 v[36:39], v[192:195], v[216:219], v[36:39]
	v_mfma_f32_16x16x32_f16 v[32:35], v[200:203], v[216:219], v[32:35]
	v_mfma_f32_16x16x32_f16 v[20:23], v[192:195], v[228:231], v[20:23]
	v_mfma_f32_16x16x32_f16 v[16:19], v[200:203], v[228:231], v[16:19]
	v_mfma_f32_16x16x32_f16 v[4:7], v[192:195], v[236:239], v[4:7]
	v_mfma_f32_16x16x32_f16 v[0:3], v[200:203], v[236:239], v[0:3]
	s_barrier
; #define PG8_STAGE(bufoff, gbase, voff) do { _Pragma("unroll") for (int _i = 0; _i < 2; ++_i) \
;         __builtin_amdgcn_global_load_lds((const unsigned*)((const char*)(gbase) + (voff)[_i]), (PG8_LAS unsigned*)(lds + (bufoff) + ldsw + _i * 8192), 16, 0, 0); } while (0)
; #define PG8_LDA(dst, b, h) do { _Pragma("unroll") for (int m = 0; m < 4; ++m) _Pragma("unroll") for (int k = 0; k < 2; ++k) dst[m][k] = *(const PG8_LAS bf16x8*)(lds + PG8_SA(b, h) + aoff + m * 2048 + k * 1024); } while (0)
; #define PG8_LDB(dst, b, h) do { _Pragma("unroll") for (int n = 0; n < 2; ++n) _Pragma("unroll") for (int k = 0; k < 2; ++k) dst[n][k] = *(const PG8_LAS bf16x8*)(lds + PG8_SB(b, h) + boff + n * 2048 + k * 1024); } while (0)
; #define PG8_MMA(ai, bj, At, Bt) do { __builtin_amdgcn_s_setprio(1); _Pragma("unroll") for (int m = 0; m < 4; ++m) _Pragma("unroll") for (int n = 0; n < 2; ++n) _Pragma("unroll") for (int k = 0; k < 2; ++k) \
;         acc[ai][bj][m][n] = mma16<F16>(Bt[n][k], At[m][k], acc[ai][bj][m][n]); __builtin_amdgcn_s_setprio(0); } while (0)
; #define PG8_WAIT_V(n) asm volatile("s_waitcnt vmcnt(" #n ")" ::: "memory")
; #define PG8_WAIT_L(n) asm volatile("s_waitcnt lgkmcnt(" #n ")" ::: "memory")
; #define PG8_BAR __builtin_amdgcn_s_barrier()
; #define PG8_SCHED __builtin_amdgcn_sched_barrier(0)
; template <class Epi, class Sched, bool ALIGN_EPI = false, bool SP2 = false, bool F16 = false, bool TOKPERM = false>
; __device__ __forceinline__ void gemm_phase(PG8_LAS unsigned char* lds, const Gemm g, const Sched& S, const Epi& E, int wv) {
;     ...
;             PG8_LDB(B0, 1, 0); PG8_LDB(B1, 1, 1); PG8_SCHED; PG8_LDA(At, 1, 0); PG8_STAGE(PG8_SA(0, 1), a2 + hstep, voffA);
;             PG8_WAIT_V(8); PG8_WAIT_L(0); PG8_BAR; PG8_MMA(0, 0, At, B0); PG8_MMA(0, 1, At, B1); PG8_BAR; PG8_SCHED;
;             PG8_LDA(At, 1, 1); PG8_STAGE(PG8_SB(1, 0), b3, voffB); PG8_STAGE(PG8_SB(1, 1), b3 + hstep, voffB); PG8_STAGE(PG8_SA(1, 0), a3, voffA);
;             PG8_WAIT_V(8); PG8_WAIT_L(0); PG8_BAR; PG8_MMA(1, 0, At, B0); PG8_MMA(1, 1, At, B1); PG8_BAR; PG8_SCHED;
;     ...
;         if constexpr (ALIGN_EPI) { if (wr == 0) PG8_BAR; }
	ds_read_b128 v[172:175], v163
	ds_read_b128 v[176:179], v164
	ds_read_b128 v[180:183], v165
	ds_read_b128 v[184:187], v166
	ds_read_b128 v[188:191], v167
	ds_read_b128 v[192:195], v168
	ds_read_b128 v[196:199], v169
	ds_read_b128 v[200:203], v170
	s_add_u32 s56, s56, 0x40000
	s_addc_u32 s57, s57, 0
	s_mov_b32 m0, s61
	v_lshl_add_u64 v[244:245], s[56:57], 0, v[134:135]
	ds_read_b128 v[204:207], v153 offset:32768
	ds_read_b128 v[208:211], v153 offset:33792
	ds_read_b128 v[212:215], v153 offset:34816
	ds_read_b128 v[216:219], v153 offset:35840
	ds_read_b128 v[220:223], v153 offset:36864
	ds_read_b128 v[228:231], v153 offset:37888
	ds_read_b128 v[232:235], v153 offset:38912
	ds_read_b128 v[236:239], v153 offset:39936
	global_load_lds_dwordx4 v[244:245], off
	v_lshl_add_u64 v[244:245], s[56:57], 0, v[130:131]
	s_mov_b32 m0, s62
	s_nop 0
	global_load_lds_dwordx4 v[244:245], off
	s_waitcnt vmcnt(8)
	s_waitcnt lgkmcnt(0)
	s_barrier
	s_waitcnt lgkmcnt(0)
	v_mfma_f32_16x16x32_f16 v[124:127], v[172:175], v[204:207], v[124:127]
	v_mfma_f32_16x16x32_f16 v[116:119], v[180:183], v[204:207], v[116:119]
	v_mfma_f32_16x16x32_f16 v[108:111], v[172:175], v[212:215], v[108:111]
	v_mfma_f32_16x16x32_f16 v[104:107], v[180:183], v[212:215], v[104:107]
	v_mfma_f32_16x16x32_f16 v[92:95], v[172:175], v[220:223], v[92:95]
	v_mfma_f32_16x16x32_f16 v[88:91], v[180:183], v[220:223], v[88:91]
	v_mfma_f32_16x16x32_f16 v[76:79], v[172:175], v[232:235], v[76:79]
	v_mfma_f32_16x16x32_f16 v[72:75], v[180:183], v[232:235], v[72:75]
	v_mfma_f32_16x16x32_f16 v[124:127], v[176:179], v[208:211], v[124:127]
	v_mfma_f32_16x16x32_f16 v[116:119], v[184:187], v[208:211], v[116:119]
	v_mfma_f32_16x16x32_f16 v[108:111], v[176:179], v[216:219], v[108:111]
	v_mfma_f32_16x16x32_f16 v[104:107], v[184:187], v[216:219], v[104:107]
	v_mfma_f32_16x16x32_f16 v[92:95], v[176:179], v[228:231], v[92:95]
	v_mfma_f32_16x16x32_f16 v[88:91], v[184:187], v[228:231], v[88:91]
	v_mfma_f32_16x16x32_f16 v[76:79], v[176:179], v[236:239], v[76:79]
	v_mfma_f32_16x16x32_f16 v[72:75], v[184:187], v[236:239], v[72:75]
	v_mfma_f32_16x16x32_f16 v[120:123], v[188:191], v[204:207], v[120:123]
	v_mfma_f32_16x16x32_f16 v[112:115], v[196:199], v[204:207], v[112:115]
	v_mfma_f32_16x16x32_f16 v[100:103], v[188:191], v[212:215], v[100:103]
	v_mfma_f32_16x16x32_f16 v[96:99], v[196:199], v[212:215], v[96:99]
	v_mfma_f32_16x16x32_f16 v[84:87], v[188:191], v[220:223], v[84:87]
	v_mfma_f32_16x16x32_f16 v[80:83], v[196:199], v[220:223], v[80:83]
	v_mfma_f32_16x16x32_f16 v[68:71], v[188:191], v[232:235], v[68:71]
	v_mfma_f32_16x16x32_f16 v[64:67], v[196:199], v[232:235], v[64:67]
	v_mfma_f32_16x16x32_f16 v[120:123], v[192:195], v[208:211], v[120:123]
	v_mfma_f32_16x16x32_f16 v[112:115], v[200:203], v[208:211], v[112:115]
	v_mfma_f32_16x16x32_f16 v[100:103], v[192:195], v[216:219], v[100:103]
	v_mfma_f32_16x16x32_f16 v[96:99], v[200:203], v[216:219], v[96:99]
	v_mfma_f32_16x16x32_f16 v[84:87], v[192:195], v[228:231], v[84:87]
	v_mfma_f32_16x16x32_f16 v[80:83], v[200:203], v[228:231], v[80:83]
	v_mfma_f32_16x16x32_f16 v[68:71], v[192:195], v[236:239], v[68:71]
	v_mfma_f32_16x16x32_f16 v[64:67], v[200:203], v[236:239], v[64:67]
	s_barrier
	s_mov_b32 m0, s64
	v_lshl_add_u64 v[148:149], v[148:149], 0, s[16:17]
	s_add_u32 s8, s8, 0x40080
	ds_read_b128 v[204:207], v153 offset:49152
	ds_read_b128 v[208:211], v153 offset:50176
	ds_read_b128 v[212:215], v153 offset:51200
	ds_read_b128 v[216:219], v153 offset:52224
	ds_read_b128 v[220:223], v153 offset:53248
	ds_read_b128 v[228:231], v153 offset:54272
	ds_read_b128 v[232:235], v153 offset:55296
	ds_read_b128 v[236:239], v153 offset:56320
	global_load_lds_dwordx4 v[148:149], off
	v_lshl_add_u64 v[148:149], v[224:225], 0, s[16:17]
	s_mov_b32 m0, s65
	s_addc_u32 s9, s9, 0
	global_load_lds_dwordx4 v[148:149], off
	v_lshl_add_u64 v[148:149], s[8:9], 0, v[132:133]
	s_mov_b32 m0, s69
	s_nop 0
	global_load_lds_dwordx4 v[148:149], off
	v_lshl_add_u64 v[148:149], s[8:9], 0, v[128:129]
	s_mov_b32 m0, s70
	s_nop 0
	global_load_lds_dwordx4 v[148:149], off
	v_lshl_add_u64 v[148:149], v[240:241], 0, s[16:17]
	s_mov_b32 m0, s66
	s_nop 0
	global_load_lds_dwordx4 v[148:149], off
	v_lshl_add_u64 v[148:149], v[242:243], 0, s[16:17]
	s_mov_b32 m0, s68
	s_nop 0
	global_load_lds_dwordx4 v[148:149], off
	s_waitcnt vmcnt(8)
	s_waitcnt lgkmcnt(0)
	s_barrier
	s_waitcnt lgkmcnt(0)
	v_mfma_f32_16x16x32_f16 v[60:63], v[172:175], v[204:207], v[60:63]
	v_mfma_f32_16x16x32_f16 v[56:59], v[180:183], v[204:207], v[56:59]
	v_mfma_f32_16x16x32_f16 v[44:47], v[172:175], v[212:215], v[44:47]
	v_mfma_f32_16x16x32_f16 v[40:43], v[180:183], v[212:215], v[40:43]
	v_mfma_f32_16x16x32_f16 v[28:31], v[172:175], v[220:223], v[28:31]
	v_mfma_f32_16x16x32_f16 v[24:27], v[180:183], v[220:223], v[24:27]
	v_mfma_f32_16x16x32_f16 v[12:15], v[172:175], v[232:235], v[12:15]
	v_mfma_f32_16x16x32_f16 v[8:11], v[180:183], v[232:235], v[8:11]
	v_mfma_f32_16x16x32_f16 v[60:63], v[176:179], v[208:211], v[60:63]
	v_mfma_f32_16x16x32_f16 v[56:59], v[184:187], v[208:211], v[56:59]
	v_mfma_f32_16x16x32_f16 v[44:47], v[176:179], v[216:219], v[44:47]
	v_mfma_f32_16x16x32_f16 v[40:43], v[184:187], v[216:219], v[40:43]
	v_mfma_f32_16x16x32_f16 v[28:31], v[176:179], v[228:231], v[28:31]
	v_mfma_f32_16x16x32_f16 v[24:27], v[184:187], v[228:231], v[24:27]
	v_mfma_f32_16x16x32_f16 v[12:15], v[176:179], v[236:239], v[12:15]
	v_mfma_f32_16x16x32_f16 v[8:11], v[184:187], v[236:239], v[8:11]
	v_mfma_f32_16x16x32_f16 v[52:55], v[188:191], v[204:207], v[52:55]
	v_mfma_f32_16x16x32_f16 v[48:51], v[196:199], v[204:207], v[48:51]
	v_mfma_f32_16x16x32_f16 v[36:39], v[188:191], v[212:215], v[36:39]
	v_mfma_f32_16x16x32_f16 v[32:35], v[196:199], v[212:215], v[32:35]
	v_mfma_f32_16x16x32_f16 v[20:23], v[188:191], v[220:223], v[20:23]
	v_mfma_f32_16x16x32_f16 v[16:19], v[196:199], v[220:223], v[16:19]
	v_mfma_f32_16x16x32_f16 v[4:7], v[188:191], v[232:235], v[4:7]
	v_mfma_f32_16x16x32_f16 v[0:3], v[196:199], v[232:235], v[0:3]
	v_mfma_f32_16x16x32_f16 v[52:55], v[192:195], v[208:211], v[52:55]
	v_mfma_f32_16x16x32_f16 v[48:51], v[200:203], v[208:211], v[48:51]
	v_mfma_f32_16x16x32_f16 v[36:39], v[192:195], v[216:219], v[36:39]
	v_mfma_f32_16x16x32_f16 v[32:35], v[200:203], v[216:219], v[32:35]
	v_mfma_f32_16x16x32_f16 v[20:23], v[192:195], v[228:231], v[20:23]
	v_mfma_f32_16x16x32_f16 v[16:19], v[200:203], v[228:231], v[16:19]
	v_mfma_f32_16x16x32_f16 v[4:7], v[192:195], v[236:239], v[4:7]
	v_mfma_f32_16x16x32_f16 v[0:3], v[200:203], v[236:239], v[0:3]
	s_barrier
	s_add_i32 s81, s81, 2
	s_add_u32 s6, s6, 0x100
	s_addc_u32 s7, s7, 0
	s_add_u32 s79, s79, 0x100
	s_addc_u32 s80, s80, 0
	s_cmp_gt_u32 s81, 13
	s_cbranch_scc0 .LBB0_181
	s_and_b64 vcc, exec, s[18:19]
	s_cbranch_vccz .LBB0_184
	s_barrier

; #define PG8_STAGE(bufoff, gbase, voff) do { _Pragma("unroll") for (int _i = 0; _i < 2; ++_i) \
;         __builtin_amdgcn_global_load_lds((const unsigned*)((const char*)(gbase) + (voff)[_i]), (PG8_LAS unsigned*)(lds + (bufoff) + ldsw + _i * 8192), 16, 0, 0); } while (0)
; #define PG8_LDA(dst, b, h) do { _Pragma("unroll") for (int m = 0; m < 4; ++m) _Pragma("unroll") for (int k = 0; k < 2; ++k) dst[m][k] = *(const PG8_LAS bf16x8*)(lds + PG8_SA(b, h) + aoff + m * 2048 + k * 1024); } while (0)
; #define PG8_LDB(dst, b, h) do { _Pragma("unroll") for (int n = 0; n < 2; ++n) _Pragma("unroll") for (int k = 0; k < 2; ++k) dst[n][k] = *(const PG8_LAS bf16x8*)(lds + PG8_SB(b, h) + boff + n * 2048 + k * 1024); } while (0)
; #define PG8_MMA(ai, bj, At, Bt) do { __builtin_amdgcn_s_setprio(1); _Pragma("unroll") for (int m = 0; m < 4; ++m) _Pragma("unroll") for (int n = 0; n < 2; ++n) _Pragma("unroll") for (int k = 0; k < 2; ++k) \
;         acc[ai][bj][m][n] = mma16<F16>(Bt[n][k], At[m][k], acc[ai][bj][m][n]); __builtin_amdgcn_s_setprio(0); } while (0)
; #define PG8_WAIT_V(n) asm volatile("s_waitcnt vmcnt(" #n ")" ::: "memory")
; #define PG8_WAIT_L(n) asm volatile("s_waitcnt lgkmcnt(" #n ")" ::: "memory")
; #define PG8_BAR __builtin_amdgcn_s_barrier()
; #define PG8_SCHED __builtin_amdgcn_sched_barrier(0)
; template <class Epi, class Sched, bool ALIGN_EPI = false, bool SP2 = false, bool F16 = false, bool TOKPERM = false>
; __device__ __forceinline__ void gemm_phase(PG8_LAS unsigned char* lds, const Gemm g, const Sched& S, const Epi& E, int wv) {
;     ...
;             PG8_LDB(B0, 0, 0); PG8_LDB(B1, 0, 1); PG8_SCHED; PG8_LDA(At, 0, 0); PG8_STAGE(PG8_SA(1, 1), a1 + hstep, voffA);
;             PG8_WAIT_V(8); PG8_WAIT_L(0); PG8_BAR; PG8_MMA(0, 0, At, B0); PG8_MMA(0, 1, At, B1); PG8_BAR; PG8_SCHED;
;             PG8_LDA(At, 0, 1); PG8_STAGE(PG8_SB(0, 0), b2, voffB); PG8_STAGE(PG8_SB(0, 1), b2 + hstep, voffB); PG8_STAGE(PG8_SA(0, 0), a2, voffA);
;             PG8_WAIT_V(8); PG8_WAIT_L(0); PG8_BAR; PG8_MMA(1, 0, At, B0); PG8_MMA(1, 1, At, B1); PG8_BAR; PG8_SCHED;
.LBB0_297:
	ds_read_b128 v[166:169], v149
	ds_read_b128 v[170:173], v150
	ds_read_b128 v[174:177], v151
	ds_read_b128 v[178:181], v152
	ds_read_b128 v[182:185], v153
	ds_read_b128 v[186:189], v154
	ds_read_b128 v[190:193], v155
	ds_read_b128 v[194:197], v156
	s_add_u32 s18, s16, 0x100
	s_addc_u32 s19, s17, 0
	s_cmp_eq_u32 s70, 40
	s_cselect_b32 s51, s9, s19
	s_cselect_b32 s50, s8, s18
	s_cselect_b32 s49, s11, s69
	s_cselect_b32 s48, s10, s68
	s_mov_b32 m0, s61
	v_lshl_add_u64 v[232:233], s[16:17], 0, v[138:139]
	ds_read_b128 v[198:201], v147
	ds_read_b128 v[202:205], v147 offset:1024
	ds_read_b128 v[206:209], v147 offset:2048
	ds_read_b128 v[210:213], v147 offset:3072
	ds_read_b128 v[214:217], v147 offset:4096
	ds_read_b128 v[218:221], v147 offset:5120
	ds_read_b128 v[222:225], v147 offset:6144
	ds_read_b128 v[228:231], v147 offset:7168
	global_load_lds_dwordx4 v[232:233], off
	v_lshl_add_u64 v[232:233], s[16:17], 0, v[140:141]
	s_mov_b32 m0, s62
	s_nop 0
	global_load_lds_dwordx4 v[232:233], off
	s_waitcnt vmcnt(8)
	s_waitcnt lgkmcnt(0)
	s_barrier
	s_waitcnt lgkmcnt(0)
	v_mfma_f32_16x16x32_bf16 v[124:127], v[166:169], v[198:201], v[124:127]
	v_mfma_f32_16x16x32_bf16 v[120:123], v[174:177], v[198:201], v[120:123]
	v_mfma_f32_16x16x32_bf16 v[108:111], v[166:169], v[206:209], v[108:111]
	v_mfma_f32_16x16x32_bf16 v[104:107], v[174:177], v[206:209], v[104:107]
	v_mfma_f32_16x16x32_bf16 v[92:95], v[166:169], v[214:217], v[92:95]
	v_mfma_f32_16x16x32_bf16 v[88:91], v[174:177], v[214:217], v[88:91]
	v_mfma_f32_16x16x32_bf16 v[76:79], v[166:169], v[222:225], v[76:79]
	v_mfma_f32_16x16x32_bf16 v[72:75], v[174:177], v[222:225], v[72:75]
	v_mfma_f32_16x16x32_bf16 v[124:127], v[170:173], v[202:205], v[124:127]
	v_mfma_f32_16x16x32_bf16 v[120:123], v[178:181], v[202:205], v[120:123]
	v_mfma_f32_16x16x32_bf16 v[108:111], v[170:173], v[210:213], v[108:111]
	v_mfma_f32_16x16x32_bf16 v[104:107], v[178:181], v[210:213], v[104:107]
	v_mfma_f32_16x16x32_bf16 v[92:95], v[170:173], v[218:221], v[92:95]
	v_mfma_f32_16x16x32_bf16 v[88:91], v[178:181], v[218:221], v[88:91]
	v_mfma_f32_16x16x32_bf16 v[76:79], v[170:173], v[228:231], v[76:79]
	v_mfma_f32_16x16x32_bf16 v[72:75], v[178:181], v[228:231], v[72:75]
	v_mfma_f32_16x16x32_bf16 v[116:119], v[182:185], v[198:201], v[116:119]
	v_mfma_f32_16x16x32_bf16 v[112:115], v[190:193], v[198:201], v[112:115]
	v_mfma_f32_16x16x32_bf16 v[100:103], v[182:185], v[206:209], v[100:103]
	v_mfma_f32_16x16x32_bf16 v[96:99], v[190:193], v[206:209], v[96:99]
	v_mfma_f32_16x16x32_bf16 v[84:87], v[182:185], v[214:217], v[84:87]
	v_mfma_f32_16x16x32_bf16 v[80:83], v[190:193], v[214:217], v[80:83]
	v_mfma_f32_16x16x32_bf16 v[68:71], v[182:185], v[222:225], v[68:71]
	v_mfma_f32_16x16x32_bf16 v[64:67], v[190:193], v[222:225], v[64:67]
	v_mfma_f32_16x16x32_bf16 v[116:119], v[186:189], v[202:205], v[116:119]
	v_mfma_f32_16x16x32_bf16 v[112:115], v[194:197], v[202:205], v[112:115]
	v_mfma_f32_16x16x32_bf16 v[100:103], v[186:189], v[210:213], v[100:103]
	v_mfma_f32_16x16x32_bf16 v[96:99], v[194:197], v[210:213], v[96:99]
	v_mfma_f32_16x16x32_bf16 v[84:87], v[186:189], v[218:221], v[84:87]
	v_mfma_f32_16x16x32_bf16 v[80:83], v[194:197], v[218:221], v[80:83]
	v_mfma_f32_16x16x32_bf16 v[68:71], v[186:189], v[228:231], v[68:71]
	v_mfma_f32_16x16x32_bf16 v[64:67], v[194:197], v[228:231], v[64:67]
	s_barrier
	s_mov_b32 m0, s3
	v_lshl_add_u64 v[232:233], s[48:49], 0, v[130:131]
	s_add_u32 s16, s48, 0xb0000
	ds_read_b128 v[198:201], v147 offset:16384
	ds_read_b128 v[202:205], v147 offset:17408
	ds_read_b128 v[206:209], v147 offset:18432
	ds_read_b128 v[210:213], v147 offset:19456
	ds_read_b128 v[214:217], v147 offset:20480
	ds_read_b128 v[218:221], v147 offset:21504
	ds_read_b128 v[222:225], v147 offset:22528
	ds_read_b128 v[228:231], v147 offset:23552
	global_load_lds_dwordx4 v[232:233], off
	v_lshl_add_u64 v[234:235], s[48:49], 0, v[134:135]
	s_mov_b32 m0, s21
	s_addc_u32 s17, s49, 0
	global_load_lds_dwordx4 v[234:235], off
	v_lshl_add_u64 v[236:237], s[16:17], 0, v[130:131]
	s_mov_b32 m0, s22
	v_lshl_add_u64 v[238:239], s[50:51], 0, v[132:133]
	global_load_lds_dwordx4 v[236:237], off
	v_lshl_add_u64 v[236:237], s[16:17], 0, v[134:135]
	s_mov_b32 m0, s23
	s_nop 0
	global_load_lds_dwordx4 v[236:237], off
	v_lshl_add_u64 v[236:237], s[50:51], 0, v[128:129]
	s_mov_b32 m0, s2
	s_nop 0
	global_load_lds_dwordx4 v[236:237], off
	s_mov_b32 m0, s33
	s_nop 0
	global_load_lds_dwordx4 v[238:239], off
	s_waitcnt vmcnt(8)
	s_waitcnt lgkmcnt(0)
	s_barrier
	s_waitcnt lgkmcnt(0)
	v_mfma_f32_16x16x32_bf16 v[60:63], v[166:169], v[198:201], v[60:63]
	v_mfma_f32_16x16x32_bf16 v[56:59], v[174:177], v[198:201], v[56:59]
	v_mfma_f32_16x16x32_bf16 v[44:47], v[166:169], v[206:209], v[44:47]
	v_mfma_f32_16x16x32_bf16 v[40:43], v[174:177], v[206:209], v[40:43]
	v_mfma_f32_16x16x32_bf16 v[28:31], v[166:169], v[214:217], v[28:31]
	v_mfma_f32_16x16x32_bf16 v[24:27], v[174:177], v[214:217], v[24:27]
	v_mfma_f32_16x16x32_bf16 v[12:15], v[166:169], v[222:225], v[12:15]
	v_mfma_f32_16x16x32_bf16 v[8:11], v[174:177], v[222:225], v[8:11]
	v_mfma_f32_16x16x32_bf16 v[60:63], v[170:173], v[202:205], v[60:63]
	v_mfma_f32_16x16x32_bf16 v[56:59], v[178:181], v[202:205], v[56:59]
	v_mfma_f32_16x16x32_bf16 v[44:47], v[170:173], v[210:213], v[44:47]
	v_mfma_f32_16x16x32_bf16 v[40:43], v[178:181], v[210:213], v[40:43]
	v_mfma_f32_16x16x32_bf16 v[28:31], v[170:173], v[218:221], v[28:31]
	v_mfma_f32_16x16x32_bf16 v[24:27], v[178:181], v[218:221], v[24:27]
	v_mfma_f32_16x16x32_bf16 v[12:15], v[170:173], v[228:231], v[12:15]
	v_mfma_f32_16x16x32_bf16 v[8:11], v[178:181], v[228:231], v[8:11]
	v_mfma_f32_16x16x32_bf16 v[52:55], v[182:185], v[198:201], v[52:55]
	v_mfma_f32_16x16x32_bf16 v[48:51], v[190:193], v[198:201], v[48:51]
	v_mfma_f32_16x16x32_bf16 v[36:39], v[182:185], v[206:209], v[36:39]
	v_mfma_f32_16x16x32_bf16 v[32:35], v[190:193], v[206:209], v[32:35]
	v_mfma_f32_16x16x32_bf16 v[20:23], v[182:185], v[214:217], v[20:23]
	v_mfma_f32_16x16x32_bf16 v[16:19], v[190:193], v[214:217], v[16:19]
	v_mfma_f32_16x16x32_bf16 v[4:7], v[182:185], v[222:225], v[4:7]
	v_mfma_f32_16x16x32_bf16 v[0:3], v[190:193], v[222:225], v[0:3]
	v_mfma_f32_16x16x32_bf16 v[52:55], v[186:189], v[202:205], v[52:55]
	v_mfma_f32_16x16x32_bf16 v[48:51], v[194:197], v[202:205], v[48:51]
	v_mfma_f32_16x16x32_bf16 v[36:39], v[186:189], v[210:213], v[36:39]
	v_mfma_f32_16x16x32_bf16 v[32:35], v[194:197], v[210:213], v[32:35]
	v_mfma_f32_16x16x32_bf16 v[20:23], v[186:189], v[218:221], v[20:23]
	v_mfma_f32_16x16x32_bf16 v[16:19], v[194:197], v[218:221], v[16:19]
	v_mfma_f32_16x16x32_bf16 v[4:7], v[186:189], v[228:231], v[4:7]
	v_mfma_f32_16x16x32_bf16 v[0:3], v[194:197], v[228:231], v[0:3]
	s_barrier
; #define PG8_STAGE(bufoff, gbase, voff) do { _Pragma("unroll") for (int _i = 0; _i < 2; ++_i) \
;         __builtin_amdgcn_global_load_lds((const unsigned*)((const char*)(gbase) + (voff)[_i]), (PG8_LAS unsigned*)(lds + (bufoff) + ldsw + _i * 8192), 16, 0, 0); } while (0)
; #define PG8_LDA(dst, b, h) do { _Pragma("unroll") for (int m = 0; m < 4; ++m) _Pragma("unroll") for (int k = 0; k < 2; ++k) dst[m][k] = *(const PG8_LAS bf16x8*)(lds + PG8_SA(b, h) + aoff + m * 2048 + k * 1024); } while (0)
; #define PG8_LDB(dst, b, h) do { _Pragma("unroll") for (int n = 0; n < 2; ++n) _Pragma("unroll") for (int k = 0; k < 2; ++k) dst[n][k] = *(const PG8_LAS bf16x8*)(lds + PG8_SB(b, h) + boff + n * 2048 + k * 1024); } while (0)
; #define PG8_MMA(ai, bj, At, Bt) do { __builtin_amdgcn_s_setprio(1); _Pragma("unroll") for (int m = 0; m < 4; ++m) _Pragma("unroll") for (int n = 0; n < 2; ++n) _Pragma("unroll") for (int k = 0; k < 2; ++k) \
;         acc[ai][bj][m][n] = mma16<F16>(Bt[n][k], At[m][k], acc[ai][bj][m][n]); __builtin_amdgcn_s_setprio(0); } while (0)
; #define PG8_WAIT_V(n) asm volatile("s_waitcnt vmcnt(" #n ")" ::: "memory")
; #define PG8_WAIT_L(n) asm volatile("s_waitcnt lgkmcnt(" #n ")" ::: "memory")
; #define PG8_BAR __builtin_amdgcn_s_barrier()
; #define PG8_SCHED __builtin_amdgcn_sched_barrier(0)
; template <class Epi, class Sched, bool ALIGN_EPI = false, bool SP2 = false, bool F16 = false, bool TOKPERM = false>
; __device__ __forceinline__ void gemm_phase(PG8_LAS unsigned char* lds, const Gemm g, const Sched& S, const Epi& E, int wv) {
;     ...
;             PG8_WAIT_V(8); PG8_WAIT_L(0); PG8_BAR; PG8_MMA(1, 0, At, B0); PG8_MMA(1, 1, At, B1); PG8_BAR; PG8_SCHED;
;             PG8_LDB(B0, 1, 0); PG8_LDB(B1, 1, 1); PG8_SCHED; PG8_LDA(At, 1, 0); PG8_STAGE(PG8_SA(0, 1), a2 + hstep, voffA);
;             PG8_WAIT_V(8); PG8_WAIT_L(0); PG8_BAR; PG8_MMA(0, 0, At, B0); PG8_MMA(0, 1, At, B1); PG8_BAR; PG8_SCHED;
;             PG8_LDA(At, 1, 1); PG8_STAGE(PG8_SB(1, 0), b3, voffB); PG8_STAGE(PG8_SB(1, 1), b3 + hstep, voffB); PG8_STAGE(PG8_SA(1, 0), a3, voffA);
;             PG8_WAIT_V(8); PG8_WAIT_L(0); PG8_BAR; PG8_MMA(1, 0, At, B0); PG8_MMA(1, 1, At, B1); PG8_BAR; PG8_SCHED;
	ds_read_b128 v[166:169], v157
	ds_read_b128 v[170:173], v158
	ds_read_b128 v[174:177], v159
	ds_read_b128 v[178:181], v160
	ds_read_b128 v[182:185], v161
	ds_read_b128 v[186:189], v162
	ds_read_b128 v[190:193], v163
	ds_read_b128 v[194:197], v164
	s_add_u32 s16, s50, 0xb0000
	s_addc_u32 s17, s51, 0
	s_mov_b32 m0, s36
	v_lshl_add_u64 v[240:241], s[16:17], 0, v[128:129]
	ds_read_b128 v[198:201], v147 offset:32768
	ds_read_b128 v[202:205], v147 offset:33792
	ds_read_b128 v[206:209], v147 offset:34816
	ds_read_b128 v[210:213], v147 offset:35840
	ds_read_b128 v[214:217], v147 offset:36864
	ds_read_b128 v[218:221], v147 offset:37888
	ds_read_b128 v[222:225], v147 offset:38912
	ds_read_b128 v[228:231], v147 offset:39936
	global_load_lds_dwordx4 v[240:241], off
	v_lshl_add_u64 v[240:241], s[16:17], 0, v[132:133]
	s_mov_b32 m0, s37
	s_nop 0
	global_load_lds_dwordx4 v[240:241], off
	s_waitcnt vmcnt(8)
	s_waitcnt lgkmcnt(0)
	s_barrier
	s_waitcnt lgkmcnt(0)
	v_mfma_f32_16x16x32_bf16 v[124:127], v[166:169], v[198:201], v[124:127]
	v_mfma_f32_16x16x32_bf16 v[120:123], v[174:177], v[198:201], v[120:123]
	v_mfma_f32_16x16x32_bf16 v[108:111], v[166:169], v[206:209], v[108:111]
	v_mfma_f32_16x16x32_bf16 v[104:107], v[174:177], v[206:209], v[104:107]
	v_mfma_f32_16x16x32_bf16 v[92:95], v[166:169], v[214:217], v[92:95]
	v_mfma_f32_16x16x32_bf16 v[88:91], v[174:177], v[214:217], v[88:91]
	v_mfma_f32_16x16x32_bf16 v[76:79], v[166:169], v[222:225], v[76:79]
	v_mfma_f32_16x16x32_bf16 v[72:75], v[174:177], v[222:225], v[72:75]
	v_mfma_f32_16x16x32_bf16 v[124:127], v[170:173], v[202:205], v[124:127]
	v_mfma_f32_16x16x32_bf16 v[120:123], v[178:181], v[202:205], v[120:123]
	v_mfma_f32_16x16x32_bf16 v[108:111], v[170:173], v[210:213], v[108:111]
	v_mfma_f32_16x16x32_bf16 v[104:107], v[178:181], v[210:213], v[104:107]
	v_mfma_f32_16x16x32_bf16 v[92:95], v[170:173], v[218:221], v[92:95]
	v_mfma_f32_16x16x32_bf16 v[88:91], v[178:181], v[218:221], v[88:91]
	v_mfma_f32_16x16x32_bf16 v[76:79], v[170:173], v[228:231], v[76:79]
	v_mfma_f32_16x16x32_bf16 v[72:75], v[178:181], v[228:231], v[72:75]
	v_mfma_f32_16x16x32_bf16 v[116:119], v[182:185], v[198:201], v[116:119]
	v_mfma_f32_16x16x32_bf16 v[112:115], v[190:193], v[198:201], v[112:115]
	v_mfma_f32_16x16x32_bf16 v[100:103], v[182:185], v[206:209], v[100:103]
	v_mfma_f32_16x16x32_bf16 v[96:99], v[190:193], v[206:209], v[96:99]
	v_mfma_f32_16x16x32_bf16 v[84:87], v[182:185], v[214:217], v[84:87]
	v_mfma_f32_16x16x32_bf16 v[80:83], v[190:193], v[214:217], v[80:83]
	v_mfma_f32_16x16x32_bf16 v[68:71], v[182:185], v[222:225], v[68:71]
	v_mfma_f32_16x16x32_bf16 v[64:67], v[190:193], v[222:225], v[64:67]
	v_mfma_f32_16x16x32_bf16 v[116:119], v[186:189], v[202:205], v[116:119]
	v_mfma_f32_16x16x32_bf16 v[112:115], v[194:197], v[202:205], v[112:115]
	v_mfma_f32_16x16x32_bf16 v[100:103], v[186:189], v[210:213], v[100:103]
	v_mfma_f32_16x16x32_bf16 v[96:99], v[194:197], v[210:213], v[96:99]
	v_mfma_f32_16x16x32_bf16 v[84:87], v[186:189], v[218:221], v[84:87]
	v_mfma_f32_16x16x32_bf16 v[80:83], v[194:197], v[218:221], v[80:83]
	v_mfma_f32_16x16x32_bf16 v[68:71], v[186:189], v[228:231], v[68:71]
	v_mfma_f32_16x16x32_bf16 v[64:67], v[194:197], v[228:231], v[64:67]
	s_barrier
	s_mov_b32 m0, s45
	v_lshl_add_u64 v[232:233], v[232:233], 0, s[12:13]
	s_add_u32 s16, s48, 0xb0080
	ds_read_b128 v[198:201], v147 offset:49152
	ds_read_b128 v[202:205], v147 offset:50176
	ds_read_b128 v[206:209], v147 offset:51200
	ds_read_b128 v[210:213], v147 offset:52224
	ds_read_b128 v[214:217], v147 offset:53248
	ds_read_b128 v[218:221], v147 offset:54272
	ds_read_b128 v[222:225], v147 offset:55296
	ds_read_b128 v[228:231], v147 offset:56320
	global_load_lds_dwordx4 v[232:233], off
	v_lshl_add_u64 v[232:233], v[234:235], 0, s[12:13]
	s_mov_b32 m0, s52
	s_addc_u32 s17, s49, 0
	global_load_lds_dwordx4 v[232:233], off
	v_lshl_add_u64 v[232:233], s[16:17], 0, v[130:131]
	s_mov_b32 m0, s55
	s_nop 0
	global_load_lds_dwordx4 v[232:233], off
	v_lshl_add_u64 v[232:233], s[16:17], 0, v[134:135]
	s_mov_b32 m0, s56
	s_nop 0
	global_load_lds_dwordx4 v[232:233], off
	v_lshl_add_u64 v[232:233], v[236:237], 0, s[12:13]
	s_mov_b32 m0, s53
	s_nop 0
	global_load_lds_dwordx4 v[232:233], off
	v_lshl_add_u64 v[232:233], v[238:239], 0, s[12:13]
	s_mov_b32 m0, s54
	s_nop 0
	global_load_lds_dwordx4 v[232:233], off
	s_waitcnt vmcnt(8)
	s_waitcnt lgkmcnt(0)
	s_barrier
	s_waitcnt lgkmcnt(0)
	v_mfma_f32_16x16x32_bf16 v[60:63], v[166:169], v[198:201], v[60:63]
	v_mfma_f32_16x16x32_bf16 v[56:59], v[174:177], v[198:201], v[56:59]
	v_mfma_f32_16x16x32_bf16 v[44:47], v[166:169], v[206:209], v[44:47]
	v_mfma_f32_16x16x32_bf16 v[40:43], v[174:177], v[206:209], v[40:43]
	v_mfma_f32_16x16x32_bf16 v[28:31], v[166:169], v[214:217], v[28:31]
	v_mfma_f32_16x16x32_bf16 v[24:27], v[174:177], v[214:217], v[24:27]
	v_mfma_f32_16x16x32_bf16 v[12:15], v[166:169], v[222:225], v[12:15]
	v_mfma_f32_16x16x32_bf16 v[8:11], v[174:177], v[222:225], v[8:11]
	v_mfma_f32_16x16x32_bf16 v[60:63], v[170:173], v[202:205], v[60:63]
	v_mfma_f32_16x16x32_bf16 v[56:59], v[178:181], v[202:205], v[56:59]
	v_mfma_f32_16x16x32_bf16 v[44:47], v[170:173], v[210:213], v[44:47]
	v_mfma_f32_16x16x32_bf16 v[40:43], v[178:181], v[210:213], v[40:43]
	v_mfma_f32_16x16x32_bf16 v[28:31], v[170:173], v[218:221], v[28:31]
	v_mfma_f32_16x16x32_bf16 v[24:27], v[178:181], v[218:221], v[24:27]
	v_mfma_f32_16x16x32_bf16 v[12:15], v[170:173], v[228:231], v[12:15]
	v_mfma_f32_16x16x32_bf16 v[8:11], v[178:181], v[228:231], v[8:11]
	v_mfma_f32_16x16x32_bf16 v[52:55], v[182:185], v[198:201], v[52:55]
	v_mfma_f32_16x16x32_bf16 v[48:51], v[190:193], v[198:201], v[48:51]
	v_mfma_f32_16x16x32_bf16 v[36:39], v[182:185], v[206:209], v[36:39]
	v_mfma_f32_16x16x32_bf16 v[32:35], v[190:193], v[206:209], v[32:35]
	v_mfma_f32_16x16x32_bf16 v[20:23], v[182:185], v[214:217], v[20:23]
	v_mfma_f32_16x16x32_bf16 v[16:19], v[190:193], v[214:217], v[16:19]
	v_mfma_f32_16x16x32_bf16 v[4:7], v[182:185], v[222:225], v[4:7]
	v_mfma_f32_16x16x32_bf16 v[0:3], v[190:193], v[222:225], v[0:3]
	v_mfma_f32_16x16x32_bf16 v[52:55], v[186:189], v[202:205], v[52:55]
	v_mfma_f32_16x16x32_bf16 v[48:51], v[194:197], v[202:205], v[48:51]
	v_mfma_f32_16x16x32_bf16 v[36:39], v[186:189], v[210:213], v[36:39]
	v_mfma_f32_16x16x32_bf16 v[32:35], v[194:197], v[210:213], v[32:35]
	v_mfma_f32_16x16x32_bf16 v[20:23], v[186:189], v[218:221], v[20:23]
	v_mfma_f32_16x16x32_bf16 v[16:19], v[194:197], v[218:221], v[16:19]
	v_mfma_f32_16x16x32_bf16 v[4:7], v[186:189], v[228:231], v[4:7]
	v_mfma_f32_16x16x32_bf16 v[0:3], v[194:197], v[228:231], v[0:3]
	s_barrier
; template <class Epi, class Sched, bool ALIGN_EPI = false, bool SP2 = false, bool F16 = false, bool TOKPERM = false>
; __device__ __forceinline__ void gemm_phase(PG8_LAS unsigned char* lds, const Gemm g, const Sched& S, const Epi& E, int wv) {
;     ...
;         for (int t = 0; t < nt; t += 2) {
;             const bool last = (t == nt - 2);
;             const char* a1 = cA + (size_t)(t + 1) * kstep;
;             const char* a2 = last ? nA : cA + (size_t)(t + 2) * kstep; const char* b2 = last ? nB : cB + (size_t)(t + 2) * kstep;
;   __device__ __forceinline__ void operator()(const pg8::f32x4 (&acc)[2][2][4][2], const pg8::Unit& u, int wr, int wc, int fr, int fq) const {
;     ...
;     const int row0 = u.pm * 256 + wr * 64 + fr + z, colb = u.pn * 256 + wc * 32 + 8 * fq + z;
; #pragma unroll
;     for (int ai = 0; ai < 2; ++ai)
; #pragma unroll
;       for (int m = 0; m < 4; ++m) {
;         const int tok = row0 + ai * 128 + m * 16; float ss = 0.f;
; #pragma unroll
;         for (int bj = 0; bj < 2; ++bj) {
;           const unsigned off = (unsigned)tok * DM + colb + 128 * bj;
;           f8_t n = __builtin_convertvector(*(const h8_t*)(x16 + off), f8_t);
; #pragma unroll
;           for (int c = 0; c < 4; ++c) { n[c] += sc * acc[ai][bj][m][0][c]; n[4 + c] += sc * acc[ai][bj][m][1][c]; }
;           if (aux) {
;             *(h8_t*)(x16 + off) = __builtin_convertvector(n, h8_t);
;             ss += ((n[0] * n[0] + n[1] * n[1]) + (n[2] * n[2] + n[3] * n[3])) + ((n[4] * n[4] + n[5] * n[5]) + (n[6] * n[6] + n[7] * n[7]));
;           } else {
;             *(f32x4*)(xout + off) = (f32x4){n[0], n[1], n[2], n[3]}; *(f32x4*)(xout + off + 4) = (f32x4){n[4], n[5], n[6], n[7]};
;           }
;         }
;         if (aux) { ss += __shfl_xor(ss, 16); ss += __shfl_xor(ss, 32); if (fq == 0) ssq[(unsigned)tok * 16 + u.pn * 4 + wc] = ss; }
	s_add_i32 s70, s70, 2
	s_add_u32 s68, s68, 0x100
	s_addc_u32 s69, s69, 0
	s_cmp_gt_u32 s70, 41
	s_mov_b64 s[16:17], s[18:19]
	s_cbranch_scc0 .LBB0_297
	s_lshl_b32 s16, s66, 8
	v_lshl_or_b32 v166, s65, 8, v148
	v_mov_b32 v136, 0
	v_xor_b32_e32 v169, 32, v165
	v_add3_u32 v167, s16, v146, v136
	v_add_u32_e32 v168, v166, v136
	v_lshl_add_u32 v136, v167, 10, v168
	v_lshl_add_u64 v[178:179], v[136:137], 1, s[40:41]
	v_add_u32_e32 v136, 0x80, v136
	global_load_dwordx4 v[170:173], v[178:179], off
	v_lshl_add_u64 v[180:181], v[136:137], 1, s[40:41]
	global_load_dwordx4 v[174:177], v[180:181], off
	v_add_u32_e32 v136, 16, v167
	v_lshl_add_u32 v136, v136, 10, v168
	v_lshl_add_u64 v[224:225], v[136:137], 1, s[40:41]
	v_add_u32_e32 v136, 0x80, v136
	global_load_dwordx4 v[192:195], v[224:225], off
	v_lshl_add_u64 v[248:249], v[136:137], 1, s[40:41]
	global_load_dwordx4 v[196:199], v[248:249], off
	v_add_u32_e32 v136, 32, v167
	v_lshl_add_u32 v136, v136, 10, v168
	v_lshl_add_u64 v[224:225], v[136:137], 1, s[40:41]
	v_add_u32_e32 v136, 0x80, v136
	global_load_dwordx4 v[200:203], v[224:225], off
	v_lshl_add_u64 v[248:249], v[136:137], 1, s[40:41]
	global_load_dwordx4 v[204:207], v[248:249], off
	v_add_u32_e32 v136, 48, v167
	v_lshl_add_u32 v136, v136, 10, v168
	v_lshl_add_u64 v[224:225], v[136:137], 1, s[40:41]
	v_add_u32_e32 v136, 0x80, v136
	global_load_dwordx4 v[208:211], v[224:225], off
	v_lshl_add_u64 v[248:249], v[136:137], 1, s[40:41]
	global_load_dwordx4 v[212:215], v[248:249], off
	v_add_u32_e32 v136, 0x80, v167
	v_lshl_add_u32 v136, v136, 10, v168
	v_lshl_add_u64 v[224:225], v[136:137], 1, s[40:41]
	v_add_u32_e32 v136, 0x80, v136
	global_load_dwordx4 v[216:219], v[224:225], off
	v_lshl_add_u64 v[248:249], v[136:137], 1, s[40:41]
	global_load_dwordx4 v[220:223], v[248:249], off
	v_add_u32_e32 v136, 0x90, v167
	v_lshl_add_u32 v136, v136, 10, v168
	v_lshl_add_u64 v[224:225], v[136:137], 1, s[40:41]
	v_add_u32_e32 v136, 0x80, v136
	global_load_dwordx4 v[228:231], v[224:225], off
	v_lshl_add_u64 v[248:249], v[136:137], 1, s[40:41]
	global_load_dwordx4 v[244:247], v[248:249], off
	v_and_b32_e32 v166, 64, v165
	v_xor_b32_e32 v136, 16, v165
	v_add_u32_e32 v166, 64, v166
	v_cmp_lt_i32_e32 vcc, v136, v166
	s_lshl_b32 s16, s65, 2
	s_or_b32 s18, s16, s44
	v_cndmask_b32_e32 v136, v165, v136, vcc
	v_cmp_lt_i32_e32 vcc, v169, v166
	v_lshlrev_b32_e32 v166, 2, v136
	s_waitcnt vmcnt(10)
	v_cvt_f32_f16_e32 v182, v173
	v_cvt_f32_f16_sdwa v183, v173 dst_sel:DWORD dst_unused:UNUSED_PAD src0_sel:WORD_1
	v_cvt_f32_f16_e32 v184, v171
	v_cvt_f32_f16_sdwa v185, v171 dst_sel:DWORD dst_unused:UNUSED_PAD src0_sel:WORD_1
	v_cvt_f32_f16_e32 v186, v172
	v_cvt_f32_f16_sdwa v187, v172 dst_sel:DWORD dst_unused:UNUSED_PAD src0_sel:WORD_1
	v_cvt_f32_f16_e32 v172, v170
	v_cvt_f32_f16_sdwa v173, v170 dst_sel:DWORD dst_unused:UNUSED_PAD src0_sel:WORD_1
	v_cvt_f32_f16_e32 v170, v177
	v_cvt_f32_f16_sdwa v171, v177 dst_sel:DWORD dst_unused:UNUSED_PAD src0_sel:WORD_1
	v_cvt_f32_f16_e32 v188, v175
	v_cvt_f32_f16_sdwa v189, v175 dst_sel:DWORD dst_unused:UNUSED_PAD src0_sel:WORD_1
	v_cvt_f32_f16_e32 v190, v176
	v_cvt_f32_f16_sdwa v191, v176 dst_sel:DWORD dst_unused:UNUSED_PAD src0_sel:WORD_1
	v_cvt_f32_f16_e32 v176, v174
	v_cvt_f32_f16_sdwa v177, v174 dst_sel:DWORD dst_unused:UNUSED_PAD src0_sel:WORD_1
	v_pk_fma_f32 v[124:125], v[124:125], 0.5, v[172:173] op_sel_hi:[1,0,1]
	v_pk_fma_f32 v[172:173], v[120:121], 0.5, v[186:187] op_sel_hi:[1,0,1]
	v_pk_fma_f32 v[126:127], v[126:127], 0.5, v[184:185] op_sel_hi:[1,0,1]
	v_pk_fma_f32 v[122:123], v[122:123], 0.5, v[182:183] op_sel_hi:[1,0,1]
	v_cvt_pk_f16_f32 v120, v172, v173
	v_cvt_pk_f16_f32 v121, v122, v123
	v_pk_mul_f32 v[174:175], v[124:125], v[124:125]
	v_pk_mul_f32 v[182:183], v[126:127], v[126:127]
	v_pk_fma_f32 v[174:175], v[172:173], v[172:173], v[174:175]
	v_pk_fma_f32 v[182:183], v[122:123], v[122:123], v[182:183]
	v_pk_fma_f32 v[176:177], v[116:117], 0.5, v[176:177] op_sel_hi:[1,0,1]
	v_pk_fma_f32 v[116:117], v[112:113], 0.5, v[190:191] op_sel_hi:[1,0,1]
	v_pk_fma_f32 v[184:185], v[118:119], 0.5, v[188:189] op_sel_hi:[1,0,1]
	v_pk_fma_f32 v[112:113], v[114:115], 0.5, v[170:171] op_sel_hi:[1,0,1]
	v_pk_fma_f32 v[174:175], v[176:177], v[176:177], v[174:175]
	v_pk_fma_f32 v[182:183], v[184:185], v[184:185], v[182:183]
	v_pk_fma_f32 v[174:175], v[116:117], v[116:117], v[174:175]
	v_pk_fma_f32 v[182:183], v[112:113], v[112:113], v[182:183]
	v_pk_add_f32 v[174:175], v[174:175], v[182:183]
	v_add_f32_e32 v114, v174, v175
	v_mov_b32_e32 v115, v114
	s_nop 1
	v_permlane16_swap_b32_e32 v114, v115
	v_cndmask_b32_e32 v169, v165, v169, vcc
	v_cvt_pk_f16_f32 v119, v126, v127
	v_cvt_pk_f16_f32 v118, v124, v125
	global_store_dwordx4 v[178:179], v[118:121], off
	s_nop 1
	v_cvt_pk_f16_f32 v119, v112, v113
	s_waitcnt lgkmcnt(0)
	v_add_f32_e32 v113, v114, v115
	v_lshlrev_b32_e32 v112, 2, v169
	v_mov_b32_e32 v114, v113
	s_nop 1
	v_permlane32_swap_b32_e32 v113, v114
	v_cvt_pk_f16_f32 v118, v116, v117
	v_cvt_pk_f16_f32 v117, v184, v185
	v_cvt_pk_f16_f32 v116, v176, v177
	global_store_dwordx4 v[180:181], v[116:119], off
	s_and_saveexec_b64 s[16:17], s[4:5]
	s_cbranch_execz .LBB0_300
	v_lshl_add_u32 v136, v167, 4, s18
	s_waitcnt lgkmcnt(0)
	v_add_f32_e32 v113, v113, v114
	v_lshl_add_u64 v[114:115], v[136:137], 2, s[42:43]
	global_store_dword v[114:115], v113, off

; #define PG8_STAGE(bufoff, gbase, voff) do { _Pragma("unroll") for (int _i = 0; _i < 2; ++_i) \
;         __builtin_amdgcn_global_load_lds((const unsigned*)((const char*)(gbase) + (voff)[_i]), (PG8_LAS unsigned*)(lds + (bufoff) + ldsw + _i * 8192), 16, 0, 0); } while (0)
; #define PG8_LDA(dst, b, h) do { _Pragma("unroll") for (int m = 0; m < 4; ++m) _Pragma("unroll") for (int k = 0; k < 2; ++k) dst[m][k] = *(const PG8_LAS bf16x8*)(lds + PG8_SA(b, h) + aoff + m * 2048 + k * 1024); } while (0)
; #define PG8_LDB(dst, b, h) do { _Pragma("unroll") for (int n = 0; n < 2; ++n) _Pragma("unroll") for (int k = 0; k < 2; ++k) dst[n][k] = *(const PG8_LAS bf16x8*)(lds + PG8_SB(b, h) + boff + n * 2048 + k * 1024); } while (0)
; #define PG8_WAIT_V(n) asm volatile("s_waitcnt vmcnt(" #n ")" ::: "memory")
; #define PG8_WAIT_L(n) asm volatile("s_waitcnt lgkmcnt(" #n ")" ::: "memory")
; #define PG8_BAR __builtin_amdgcn_s_barrier()
; #define PG8_SCHED __builtin_amdgcn_sched_barrier(0)
; template <class Epi, class Sched, bool ALIGN_EPI = false, bool SP2 = false, bool F16 = false, bool TOKPERM = false>
; __device__ __forceinline__ void gemm_phase(PG8_LAS unsigned char* lds, const Gemm g, const Sched& S, const Epi& E, int wv) {
;     ...
;         const bool has_next = S.next(ui + 1, nxt);
;         const char* nA = has_next ? (const char*)g.A + (size_t)nxt.pm * tstep : cA; const char* nB = has_next ? (const char*)g.Bt + (size_t)nxt.pn * tstep : cB;
;         for (int t = 0; t < nt; t += 2) {
;             const bool last = (t == nt - 2);
;             const char* a1 = cA + (size_t)(t + 1) * kstep;
;             const char* a2 = last ? nA : cA + (size_t)(t + 2) * kstep; const char* b2 = last ? nB : cB + (size_t)(t + 2) * kstep;
;             const char* a3 = a2 + kstep; const char* b3 = b2 + kstep;
;             if (last && has_next) S.a_ready(nxt);
;             if constexpr (SP2) {
;             PG8_LDB(B0, 0, 0); PG8_LDB(B1, 0, 1); PG8_SCHED; PG8_LDA(At, 0, 0); PG8_STAGE(PG8_SA(1, 1), a1 + hstep, voffA);
;             PG8_WAIT_V(8); PG8_WAIT_L(0); PG8_BAR; PG8_MMA(0, 0, At, B0); PG8_MMA(0, 1, At, B1); PG8_BAR; PG8_SCHED;
;             PG8_LDA(At, 0, 1); PG8_STAGE(PG8_SB(0, 0), b2, voffB); PG8_STAGE(PG8_SB(0, 1), b2 + hstep, voffB); PG8_STAGE(PG8_SA(0, 0), a2, voffA);
;             PG8_WAIT_V(8); PG8_WAIT_L(0); PG8_BAR; PG8_MMA(1, 0, At, B0); PG8_MMA(1, 1, At, B1); PG8_BAR; PG8_SCHED;
.LBB0_381:
	s_ashr_i32 s71, s70, 31
	s_lshl_b64 s[10:11], s[70:71], 19
	s_add_u32 s72, s40, s10
	s_addc_u32 s73, s41, s11
	s_and_b64 s[10:11], s[4:5], exec
	s_cselect_b32 s12, s73, s7
	s_cselect_b32 s13, s72, s6
	s_ashr_i32 s69, s68, 31
	s_lshl_b64 s[10:11], s[68:69], 19
	s_add_u32 s74, s46, s10
	s_addc_u32 s75, s47, s11
	s_and_b64 s[10:11], s[4:5], exec
	s_cselect_b32 s59, s75, s9
	s_cselect_b32 s64, s74, s8
	s_add_u32 s6, s6, 0x40080
	s_addc_u32 s7, s7, 0
	s_add_u32 s69, s8, 0x100
	s_addc_u32 s71, s9, 0
	s_mov_b32 s76, -2
	s_waitcnt lgkmcnt(0)
	ds_read_b128 v[156:159], v181
	ds_read_b128 v[160:163], v182
	ds_read_b128 v[164:167], v183
	ds_read_b128 v[168:171], v184
	ds_read_b128 v[172:175], v185
	ds_read_b128 v[176:179], v186
	ds_read_b128 v[200:203], v187
	ds_read_b128 v[204:207], v188
	s_add_u32 s8, s6, 0xfffc0080
	s_addc_u32 s9, s7, -1
	s_cmp_eq_u32 s76, 12
	s_cselect_b32 s11, s12, s9
	s_cselect_b32 s10, s13, s8
	s_cselect_b32 s9, s59, s71
	s_cselect_b32 s8, s64, s69
	s_mov_b32 m0, s36
	v_lshl_add_u64 v[224:225], s[6:7], 0, v[146:147]
	ds_read_b128 v[208:211], v155
	ds_read_b128 v[212:215], v155 offset:1024
	ds_read_b128 v[216:219], v155 offset:2048
	ds_read_b128 v[220:223], v155 offset:3072
	ds_read_b128 v[228:231], v155 offset:4096
	ds_read_b128 v[232:235], v155 offset:5120
	ds_read_b128 v[236:239], v155 offset:6144
	ds_read_b128 v[240:243], v155 offset:7168
	global_load_lds_dwordx4 v[224:225], off
	v_lshl_add_u64 v[224:225], s[6:7], 0, v[148:149]
	s_mov_b32 m0, s2
	s_nop 0
	global_load_lds_dwordx4 v[224:225], off
	s_waitcnt vmcnt(8)
	s_waitcnt lgkmcnt(0)
	s_barrier
	s_waitcnt lgkmcnt(0)
	v_mfma_f32_16x16x32_f16 v[124:127], v[156:159], v[208:211], 0
	v_mfma_f32_16x16x32_f16 v[120:123], v[164:167], v[208:211], 0
	v_mfma_f32_16x16x32_f16 v[108:111], v[156:159], v[216:219], 0
	v_mfma_f32_16x16x32_f16 v[104:107], v[164:167], v[216:219], 0
	v_mfma_f32_16x16x32_f16 v[92:95], v[156:159], v[228:231], 0
	v_mfma_f32_16x16x32_f16 v[88:91], v[164:167], v[228:231], 0
	v_mfma_f32_16x16x32_f16 v[76:79], v[156:159], v[236:239], 0
	v_mfma_f32_16x16x32_f16 v[72:75], v[164:167], v[236:239], 0
	v_mfma_f32_16x16x32_f16 v[124:127], v[160:163], v[212:215], v[124:127]
	v_mfma_f32_16x16x32_f16 v[120:123], v[168:171], v[212:215], v[120:123]
	v_mfma_f32_16x16x32_f16 v[108:111], v[160:163], v[220:223], v[108:111]
	v_mfma_f32_16x16x32_f16 v[104:107], v[168:171], v[220:223], v[104:107]
	v_mfma_f32_16x16x32_f16 v[92:95], v[160:163], v[232:235], v[92:95]
	v_mfma_f32_16x16x32_f16 v[88:91], v[168:171], v[232:235], v[88:91]
	v_mfma_f32_16x16x32_f16 v[76:79], v[160:163], v[240:243], v[76:79]
	v_mfma_f32_16x16x32_f16 v[72:75], v[168:171], v[240:243], v[72:75]
	v_mfma_f32_16x16x32_f16 v[116:119], v[172:175], v[208:211], 0
	v_mfma_f32_16x16x32_f16 v[112:115], v[200:203], v[208:211], 0
	v_mfma_f32_16x16x32_f16 v[100:103], v[172:175], v[216:219], 0
	v_mfma_f32_16x16x32_f16 v[96:99], v[200:203], v[216:219], 0
	v_mfma_f32_16x16x32_f16 v[84:87], v[172:175], v[228:231], 0
	v_mfma_f32_16x16x32_f16 v[80:83], v[200:203], v[228:231], 0
	v_mfma_f32_16x16x32_f16 v[68:71], v[172:175], v[236:239], 0
	v_mfma_f32_16x16x32_f16 v[64:67], v[200:203], v[236:239], 0
	v_mfma_f32_16x16x32_f16 v[116:119], v[176:179], v[212:215], v[116:119]
	v_mfma_f32_16x16x32_f16 v[112:115], v[204:207], v[212:215], v[112:115]
	v_mfma_f32_16x16x32_f16 v[100:103], v[176:179], v[220:223], v[100:103]
	v_mfma_f32_16x16x32_f16 v[96:99], v[204:207], v[220:223], v[96:99]
	v_mfma_f32_16x16x32_f16 v[84:87], v[176:179], v[232:235], v[84:87]
	v_mfma_f32_16x16x32_f16 v[80:83], v[204:207], v[232:235], v[80:83]
	v_mfma_f32_16x16x32_f16 v[68:71], v[176:179], v[240:243], v[68:71]
	v_mfma_f32_16x16x32_f16 v[64:67], v[204:207], v[240:243], v[64:67]
	s_barrier
	s_mov_b32 m0, s53
	v_lshl_add_u64 v[224:225], s[8:9], 0, v[130:131]
	s_add_u32 s78, s8, 0x40000
	ds_read_b128 v[208:211], v155 offset:16384
	ds_read_b128 v[212:215], v155 offset:17408
	ds_read_b128 v[216:219], v155 offset:18432
	ds_read_b128 v[220:223], v155 offset:19456
	ds_read_b128 v[228:231], v155 offset:20480
	ds_read_b128 v[232:235], v155 offset:21504
	ds_read_b128 v[236:239], v155 offset:22528
	ds_read_b128 v[240:243], v155 offset:23552
	global_load_lds_dwordx4 v[224:225], off
	v_lshl_add_u64 v[244:245], s[8:9], 0, v[134:135]
	s_mov_b32 m0, s55
	s_addc_u32 s79, s9, 0
	global_load_lds_dwordx4 v[244:245], off
	v_lshl_add_u64 v[246:247], s[78:79], 0, v[130:131]
	s_mov_b32 m0, s91
	v_lshl_add_u64 v[248:249], s[10:11], 0, v[132:133]
	global_load_lds_dwordx4 v[246:247], off
	v_lshl_add_u64 v[246:247], s[78:79], 0, v[134:135]
	s_mov_b32 m0, s92
	s_nop 0
	global_load_lds_dwordx4 v[246:247], off
	v_lshl_add_u64 v[246:247], s[10:11], 0, v[128:129]
	s_mov_b32 m0, s90
	s_nop 0
	global_load_lds_dwordx4 v[246:247], off
	s_mov_b32 m0, s93
	s_nop 0
	global_load_lds_dwordx4 v[248:249], off
	s_waitcnt vmcnt(8)
	s_waitcnt lgkmcnt(0)
	s_barrier
; #define PG8_STAGE(bufoff, gbase, voff) do { _Pragma("unroll") for (int _i = 0; _i < 2; ++_i) \
;         __builtin_amdgcn_global_load_lds((const unsigned*)((const char*)(gbase) + (voff)[_i]), (PG8_LAS unsigned*)(lds + (bufoff) + ldsw + _i * 8192), 16, 0, 0); } while (0)
; #define PG8_LDA(dst, b, h) do { _Pragma("unroll") for (int m = 0; m < 4; ++m) _Pragma("unroll") for (int k = 0; k < 2; ++k) dst[m][k] = *(const PG8_LAS bf16x8*)(lds + PG8_SA(b, h) + aoff + m * 2048 + k * 1024); } while (0)
; #define PG8_LDB(dst, b, h) do { _Pragma("unroll") for (int n = 0; n < 2; ++n) _Pragma("unroll") for (int k = 0; k < 2; ++k) dst[n][k] = *(const PG8_LAS bf16x8*)(lds + PG8_SB(b, h) + boff + n * 2048 + k * 1024); } while (0)
; #define PG8_MMA(ai, bj, At, Bt) do { __builtin_amdgcn_s_setprio(1); _Pragma("unroll") for (int m = 0; m < 4; ++m) _Pragma("unroll") for (int n = 0; n < 2; ++n) _Pragma("unroll") for (int k = 0; k < 2; ++k) \
;         acc[ai][bj][m][n] = mma16<F16>(Bt[n][k], At[m][k], acc[ai][bj][m][n]); __builtin_amdgcn_s_setprio(0); } while (0)
; #define PG8_WAIT_V(n) asm volatile("s_waitcnt vmcnt(" #n ")" ::: "memory")
; #define PG8_WAIT_L(n) asm volatile("s_waitcnt lgkmcnt(" #n ")" ::: "memory")
; #define PG8_BAR __builtin_amdgcn_s_barrier()
; #define PG8_SCHED __builtin_amdgcn_sched_barrier(0)
; template <class Epi, class Sched, bool ALIGN_EPI = false, bool SP2 = false, bool F16 = false, bool TOKPERM = false>
; __device__ __forceinline__ void gemm_phase(PG8_LAS unsigned char* lds, const Gemm g, const Sched& S, const Epi& E, int wv) {
;     ...
;             PG8_WAIT_V(8); PG8_WAIT_L(0); PG8_BAR; PG8_MMA(0, 0, At, B0); PG8_MMA(0, 1, At, B1); PG8_BAR; PG8_SCHED;
;             PG8_LDA(At, 0, 1); PG8_STAGE(PG8_SB(0, 0), b2, voffB); PG8_STAGE(PG8_SB(0, 1), b2 + hstep, voffB); PG8_STAGE(PG8_SA(0, 0), a2, voffA);
;             PG8_WAIT_V(8); PG8_WAIT_L(0); PG8_BAR; PG8_MMA(1, 0, At, B0); PG8_MMA(1, 1, At, B1); PG8_BAR; PG8_SCHED;
;             PG8_LDB(B0, 1, 0); PG8_LDB(B1, 1, 1); PG8_SCHED; PG8_LDA(At, 1, 0); PG8_STAGE(PG8_SA(0, 1), a2 + hstep, voffA);
;             PG8_WAIT_V(8); PG8_WAIT_L(0); PG8_BAR; PG8_MMA(0, 0, At, B0); PG8_MMA(0, 1, At, B1); PG8_BAR; PG8_SCHED;
	s_waitcnt lgkmcnt(0)
	v_mfma_f32_16x16x32_f16 v[60:63], v[156:159], v[208:211], 0
	v_mfma_f32_16x16x32_f16 v[56:59], v[164:167], v[208:211], 0
	v_mfma_f32_16x16x32_f16 v[44:47], v[156:159], v[216:219], 0
	v_mfma_f32_16x16x32_f16 v[40:43], v[164:167], v[216:219], 0
	v_mfma_f32_16x16x32_f16 v[28:31], v[156:159], v[228:231], 0
	v_mfma_f32_16x16x32_f16 v[24:27], v[164:167], v[228:231], 0
	v_mfma_f32_16x16x32_f16 v[12:15], v[156:159], v[236:239], 0
	v_mfma_f32_16x16x32_f16 v[8:11], v[164:167], v[236:239], 0
	v_mfma_f32_16x16x32_f16 v[60:63], v[160:163], v[212:215], v[60:63]
	v_mfma_f32_16x16x32_f16 v[56:59], v[168:171], v[212:215], v[56:59]
	v_mfma_f32_16x16x32_f16 v[44:47], v[160:163], v[220:223], v[44:47]
	v_mfma_f32_16x16x32_f16 v[40:43], v[168:171], v[220:223], v[40:43]
	v_mfma_f32_16x16x32_f16 v[28:31], v[160:163], v[232:235], v[28:31]
	v_mfma_f32_16x16x32_f16 v[24:27], v[168:171], v[232:235], v[24:27]
	v_mfma_f32_16x16x32_f16 v[12:15], v[160:163], v[240:243], v[12:15]
	v_mfma_f32_16x16x32_f16 v[8:11], v[168:171], v[240:243], v[8:11]
	v_mfma_f32_16x16x32_f16 v[52:55], v[172:175], v[208:211], 0
	v_mfma_f32_16x16x32_f16 v[48:51], v[200:203], v[208:211], 0
	v_mfma_f32_16x16x32_f16 v[36:39], v[172:175], v[216:219], 0
	v_mfma_f32_16x16x32_f16 v[32:35], v[200:203], v[216:219], 0
	v_mfma_f32_16x16x32_f16 v[20:23], v[172:175], v[228:231], 0
	v_mfma_f32_16x16x32_f16 v[16:19], v[200:203], v[228:231], 0
	v_mfma_f32_16x16x32_f16 v[4:7], v[172:175], v[236:239], 0
	v_mfma_f32_16x16x32_f16 v[0:3], v[200:203], v[236:239], 0
	v_mfma_f32_16x16x32_f16 v[52:55], v[176:179], v[212:215], v[52:55]
	v_mfma_f32_16x16x32_f16 v[48:51], v[204:207], v[212:215], v[48:51]
	v_mfma_f32_16x16x32_f16 v[36:39], v[176:179], v[220:223], v[36:39]
	v_mfma_f32_16x16x32_f16 v[32:35], v[204:207], v[220:223], v[32:35]
	v_mfma_f32_16x16x32_f16 v[20:23], v[176:179], v[232:235], v[20:23]
	v_mfma_f32_16x16x32_f16 v[16:19], v[204:207], v[232:235], v[16:19]
	v_mfma_f32_16x16x32_f16 v[4:7], v[176:179], v[240:243], v[4:7]
	v_mfma_f32_16x16x32_f16 v[0:3], v[204:207], v[240:243], v[0:3]
	s_barrier
	ds_read_b128 v[156:159], v189
	ds_read_b128 v[160:163], v190
	ds_read_b128 v[164:167], v191
	ds_read_b128 v[168:171], v192
	ds_read_b128 v[172:175], v193
	ds_read_b128 v[176:179], v194
	ds_read_b128 v[200:203], v195
	ds_read_b128 v[204:207], v196
	s_add_u32 s10, s10, 0x40000
	s_addc_u32 s11, s11, 0
	s_mov_b32 m0, s95
	v_lshl_add_u64 v[250:251], s[10:11], 0, v[128:129]
	ds_read_b128 v[208:211], v155 offset:32768
	ds_read_b128 v[212:215], v155 offset:33792
	ds_read_b128 v[216:219], v155 offset:34816
	ds_read_b128 v[220:223], v155 offset:35840
	ds_read_b128 v[228:231], v155 offset:36864
	ds_read_b128 v[232:235], v155 offset:37888
	ds_read_b128 v[236:239], v155 offset:38912
	ds_read_b128 v[240:243], v155 offset:39936
	global_load_lds_dwordx4 v[250:251], off
	v_lshl_add_u64 v[250:251], s[10:11], 0, v[132:133]
	s_mov_b32 m0, s96
	s_nop 0
	global_load_lds_dwordx4 v[250:251], off
	s_waitcnt vmcnt(8)
	s_waitcnt lgkmcnt(0)
	s_barrier
	s_waitcnt lgkmcnt(0)
	v_mfma_f32_16x16x32_f16 v[124:127], v[156:159], v[208:211], v[124:127]
	v_mfma_f32_16x16x32_f16 v[120:123], v[164:167], v[208:211], v[120:123]
	v_mfma_f32_16x16x32_f16 v[108:111], v[156:159], v[216:219], v[108:111]
	v_mfma_f32_16x16x32_f16 v[104:107], v[164:167], v[216:219], v[104:107]
	v_mfma_f32_16x16x32_f16 v[92:95], v[156:159], v[228:231], v[92:95]
	v_mfma_f32_16x16x32_f16 v[88:91], v[164:167], v[228:231], v[88:91]
	v_mfma_f32_16x16x32_f16 v[76:79], v[156:159], v[236:239], v[76:79]
	v_mfma_f32_16x16x32_f16 v[72:75], v[164:167], v[236:239], v[72:75]
	v_mfma_f32_16x16x32_f16 v[124:127], v[160:163], v[212:215], v[124:127]
	v_mfma_f32_16x16x32_f16 v[120:123], v[168:171], v[212:215], v[120:123]
	v_mfma_f32_16x16x32_f16 v[108:111], v[160:163], v[220:223], v[108:111]
	v_mfma_f32_16x16x32_f16 v[104:107], v[168:171], v[220:223], v[104:107]
	v_mfma_f32_16x16x32_f16 v[92:95], v[160:163], v[232:235], v[92:95]
	v_mfma_f32_16x16x32_f16 v[88:91], v[168:171], v[232:235], v[88:91]
	v_mfma_f32_16x16x32_f16 v[76:79], v[160:163], v[240:243], v[76:79]
	v_mfma_f32_16x16x32_f16 v[72:75], v[168:171], v[240:243], v[72:75]
	v_mfma_f32_16x16x32_f16 v[116:119], v[172:175], v[208:211], v[116:119]
	v_mfma_f32_16x16x32_f16 v[112:115], v[200:203], v[208:211], v[112:115]
	v_mfma_f32_16x16x32_f16 v[100:103], v[172:175], v[216:219], v[100:103]
	v_mfma_f32_16x16x32_f16 v[96:99], v[200:203], v[216:219], v[96:99]
	v_mfma_f32_16x16x32_f16 v[84:87], v[172:175], v[228:231], v[84:87]
	v_mfma_f32_16x16x32_f16 v[80:83], v[200:203], v[228:231], v[80:83]
	v_mfma_f32_16x16x32_f16 v[68:71], v[172:175], v[236:239], v[68:71]
	v_mfma_f32_16x16x32_f16 v[64:67], v[200:203], v[236:239], v[64:67]
	v_mfma_f32_16x16x32_f16 v[116:119], v[176:179], v[212:215], v[116:119]
	v_mfma_f32_16x16x32_f16 v[112:115], v[204:207], v[212:215], v[112:115]
	v_mfma_f32_16x16x32_f16 v[100:103], v[176:179], v[220:223], v[100:103]
	v_mfma_f32_16x16x32_f16 v[96:99], v[204:207], v[220:223], v[96:99]
	v_mfma_f32_16x16x32_f16 v[84:87], v[176:179], v[232:235], v[84:87]
	v_mfma_f32_16x16x32_f16 v[80:83], v[204:207], v[232:235], v[80:83]
	v_mfma_f32_16x16x32_f16 v[68:71], v[176:179], v[240:243], v[68:71]
	v_mfma_f32_16x16x32_f16 v[64:67], v[204:207], v[240:243], v[64:67]
	s_barrier
; #define PG8_STAGE(bufoff, gbase, voff) do { _Pragma("unroll") for (int _i = 0; _i < 2; ++_i) \
;         __builtin_amdgcn_global_load_lds((const unsigned*)((const char*)(gbase) + (voff)[_i]), (PG8_LAS unsigned*)(lds + (bufoff) + ldsw + _i * 8192), 16, 0, 0); } while (0)
; #define PG8_LDA(dst, b, h) do { _Pragma("unroll") for (int m = 0; m < 4; ++m) _Pragma("unroll") for (int k = 0; k < 2; ++k) dst[m][k] = *(const PG8_LAS bf16x8*)(lds + PG8_SA(b, h) + aoff + m * 2048 + k * 1024); } while (0)
; #define PG8_LDB(dst, b, h) do { _Pragma("unroll") for (int n = 0; n < 2; ++n) _Pragma("unroll") for (int k = 0; k < 2; ++k) dst[n][k] = *(const PG8_LAS bf16x8*)(lds + PG8_SB(b, h) + boff + n * 2048 + k * 1024); } while (0)
; #define PG8_MMA(ai, bj, At, Bt) do { __builtin_amdgcn_s_setprio(1); _Pragma("unroll") for (int m = 0; m < 4; ++m) _Pragma("unroll") for (int n = 0; n < 2; ++n) _Pragma("unroll") for (int k = 0; k < 2; ++k) \
;         acc[ai][bj][m][n] = mma16<F16>(Bt[n][k], At[m][k], acc[ai][bj][m][n]); __builtin_amdgcn_s_setprio(0); } while (0)
; #define PG8_BAR __builtin_amdgcn_s_barrier()
; template <class Epi, class Sched, bool ALIGN_EPI = false, bool SP2 = false, bool F16 = false, bool TOKPERM = false>
; __device__ __forceinline__ void gemm_phase(PG8_LAS unsigned char* lds, const Gemm g, const Sched& S, const Epi& E, int wv) {
;     ...
;             PG8_LDB(B0, 0, 0); PG8_LDB(B1, 0, 1); PG8_SCHED; PG8_LDA(At, 0, 0); PG8_STAGE(PG8_SA(1, 1), a1 + hstep, voffA);
;             PG8_WAIT_V(8); PG8_WAIT_L(0); PG8_BAR; PG8_MMA(0, 0, At, B0); PG8_MMA(0, 1, At, B1); PG8_BAR; PG8_SCHED;
;             PG8_LDA(At, 0, 1); PG8_STAGE(PG8_SB(0, 0), b2, voffB); PG8_STAGE(PG8_SB(0, 1), b2 + hstep, voffB); PG8_STAGE(PG8_SA(0, 0), a2, voffA);
;             PG8_WAIT_V(8); PG8_WAIT_L(0); PG8_BAR; PG8_MMA(1, 0, At, B0); PG8_MMA(1, 1, At, B1); PG8_BAR; PG8_SCHED;
;             PG8_LDB(B0, 1, 0); PG8_LDB(B1, 1, 1); PG8_SCHED; PG8_LDA(At, 1, 0); PG8_STAGE(PG8_SA(0, 1), a2 + hstep, voffA);
;             PG8_WAIT_V(8); PG8_WAIT_L(0); PG8_BAR; PG8_MMA(0, 0, At, B0); PG8_MMA(0, 1, At, B1); PG8_BAR; PG8_SCHED;
;             PG8_LDA(At, 1, 1); PG8_STAGE(PG8_SB(1, 0), b3, voffB); PG8_STAGE(PG8_SB(1, 1), b3 + hstep, voffB); PG8_STAGE(PG8_SA(1, 0), a3, voffA);
;             PG8_WAIT_V(8); PG8_WAIT_L(0); PG8_BAR; PG8_MMA(1, 0, At, B0); PG8_MMA(1, 1, At, B1); PG8_BAR; PG8_SCHED;
	s_mov_b32 m0, s20
	v_lshl_add_u64 v[224:225], v[224:225], 0, s[60:61]
	s_add_u32 s8, s8, 0x40080
	ds_read_b128 v[208:211], v155 offset:49152
	ds_read_b128 v[212:215], v155 offset:50176
	ds_read_b128 v[216:219], v155 offset:51200
	ds_read_b128 v[220:223], v155 offset:52224
	ds_read_b128 v[228:231], v155 offset:53248
	ds_read_b128 v[232:235], v155 offset:54272
	ds_read_b128 v[236:239], v155 offset:55296
	ds_read_b128 v[240:243], v155 offset:56320
	global_load_lds_dwordx4 v[224:225], off
	v_lshl_add_u64 v[224:225], v[244:245], 0, s[60:61]
	s_mov_b32 m0, s21
	s_addc_u32 s9, s9, 0
	global_load_lds_dwordx4 v[224:225], off
	v_lshl_add_u64 v[224:225], s[8:9], 0, v[130:131]
	s_mov_b32 m0, s44
	s_nop 0
	global_load_lds_dwordx4 v[224:225], off
	v_lshl_add_u64 v[224:225], s[8:9], 0, v[134:135]
	s_mov_b32 m0, s45
	s_nop 0
	global_load_lds_dwordx4 v[224:225], off
	v_lshl_add_u64 v[224:225], v[246:247], 0, s[60:61]
	s_mov_b32 m0, s22
	s_nop 0
	global_load_lds_dwordx4 v[224:225], off
	v_lshl_add_u64 v[224:225], v[248:249], 0, s[60:61]
	s_mov_b32 m0, s23
	s_nop 0
	global_load_lds_dwordx4 v[224:225], off
	s_waitcnt vmcnt(8)
	s_waitcnt lgkmcnt(0)
	s_barrier
	s_waitcnt lgkmcnt(0)
	v_mfma_f32_16x16x32_f16 v[60:63], v[156:159], v[208:211], v[60:63]
	v_mfma_f32_16x16x32_f16 v[56:59], v[164:167], v[208:211], v[56:59]
	v_mfma_f32_16x16x32_f16 v[44:47], v[156:159], v[216:219], v[44:47]
	v_mfma_f32_16x16x32_f16 v[40:43], v[164:167], v[216:219], v[40:43]
	v_mfma_f32_16x16x32_f16 v[28:31], v[156:159], v[228:231], v[28:31]
	v_mfma_f32_16x16x32_f16 v[24:27], v[164:167], v[228:231], v[24:27]
	v_mfma_f32_16x16x32_f16 v[12:15], v[156:159], v[236:239], v[12:15]
	v_mfma_f32_16x16x32_f16 v[8:11], v[164:167], v[236:239], v[8:11]
	v_mfma_f32_16x16x32_f16 v[60:63], v[160:163], v[212:215], v[60:63]
	v_mfma_f32_16x16x32_f16 v[56:59], v[168:171], v[212:215], v[56:59]
	v_mfma_f32_16x16x32_f16 v[44:47], v[160:163], v[220:223], v[44:47]
	v_mfma_f32_16x16x32_f16 v[40:43], v[168:171], v[220:223], v[40:43]
	v_mfma_f32_16x16x32_f16 v[28:31], v[160:163], v[232:235], v[28:31]
	v_mfma_f32_16x16x32_f16 v[24:27], v[168:171], v[232:235], v[24:27]
	v_mfma_f32_16x16x32_f16 v[12:15], v[160:163], v[240:243], v[12:15]
	v_mfma_f32_16x16x32_f16 v[8:11], v[168:171], v[240:243], v[8:11]
	v_mfma_f32_16x16x32_f16 v[52:55], v[172:175], v[208:211], v[52:55]
	v_mfma_f32_16x16x32_f16 v[48:51], v[200:203], v[208:211], v[48:51]
	v_mfma_f32_16x16x32_f16 v[36:39], v[172:175], v[216:219], v[36:39]
	v_mfma_f32_16x16x32_f16 v[32:35], v[200:203], v[216:219], v[32:35]
	v_mfma_f32_16x16x32_f16 v[20:23], v[172:175], v[228:231], v[20:23]
	v_mfma_f32_16x16x32_f16 v[16:19], v[200:203], v[228:231], v[16:19]
	v_mfma_f32_16x16x32_f16 v[4:7], v[172:175], v[236:239], v[4:7]
	v_mfma_f32_16x16x32_f16 v[0:3], v[200:203], v[236:239], v[0:3]
	v_mfma_f32_16x16x32_f16 v[52:55], v[176:179], v[212:215], v[52:55]
	v_mfma_f32_16x16x32_f16 v[48:51], v[204:207], v[212:215], v[48:51]
	v_mfma_f32_16x16x32_f16 v[36:39], v[176:179], v[220:223], v[36:39]
	v_mfma_f32_16x16x32_f16 v[32:35], v[204:207], v[220:223], v[32:35]
	v_mfma_f32_16x16x32_f16 v[20:23], v[176:179], v[232:235], v[20:23]
	v_mfma_f32_16x16x32_f16 v[16:19], v[204:207], v[232:235], v[16:19]
	v_mfma_f32_16x16x32_f16 v[4:7], v[176:179], v[240:243], v[4:7]
	v_mfma_f32_16x16x32_f16 v[0:3], v[204:207], v[240:243], v[0:3]
	s_barrier
	s_add_i32 s76, s76, 2
	s_add_u32 s6, s6, 0x100
	s_addc_u32 s7, s7, 0
	s_add_u32 s69, s69, 0x100
	s_addc_u32 s71, s71, 0
	s_cmp_gt_u32 s76, 13
.LBB0_382:
	ds_read_b128 v[156:159], v181
	ds_read_b128 v[160:163], v182
	ds_read_b128 v[164:167], v183
	ds_read_b128 v[168:171], v184
	ds_read_b128 v[172:175], v185
	ds_read_b128 v[176:179], v186
	ds_read_b128 v[200:203], v187
	ds_read_b128 v[204:207], v188
	s_add_u32 s8, s6, 0xfffc0080
	s_addc_u32 s9, s7, -1
	s_cmp_eq_u32 s76, 12
	s_cselect_b32 s11, s12, s9
	s_cselect_b32 s10, s13, s8
	s_cselect_b32 s9, s59, s71
	s_cselect_b32 s8, s64, s69
	s_mov_b32 m0, s36
	v_lshl_add_u64 v[224:225], s[6:7], 0, v[146:147]
	ds_read_b128 v[208:211], v155
	ds_read_b128 v[212:215], v155 offset:1024
	ds_read_b128 v[216:219], v155 offset:2048
	ds_read_b128 v[220:223], v155 offset:3072
	ds_read_b128 v[228:231], v155 offset:4096
	ds_read_b128 v[232:235], v155 offset:5120
	ds_read_b128 v[236:239], v155 offset:6144
	ds_read_b128 v[240:243], v155 offset:7168
	global_load_lds_dwordx4 v[224:225], off
	v_lshl_add_u64 v[224:225], s[6:7], 0, v[148:149]
	s_mov_b32 m0, s2
	s_nop 0
	global_load_lds_dwordx4 v[224:225], off
	s_waitcnt vmcnt(8)
	s_waitcnt lgkmcnt(0)
	s_barrier
; #define PG8_STAGE(bufoff, gbase, voff) do { _Pragma("unroll") for (int _i = 0; _i < 2; ++_i) \
;         __builtin_amdgcn_global_load_lds((const unsigned*)((const char*)(gbase) + (voff)[_i]), (PG8_LAS unsigned*)(lds + (bufoff) + ldsw + _i * 8192), 16, 0, 0); } while (0)
; #define PG8_LDA(dst, b, h) do { _Pragma("unroll") for (int m = 0; m < 4; ++m) _Pragma("unroll") for (int k = 0; k < 2; ++k) dst[m][k] = *(const PG8_LAS bf16x8*)(lds + PG8_SA(b, h) + aoff + m * 2048 + k * 1024); } while (0)
; #define PG8_LDB(dst, b, h) do { _Pragma("unroll") for (int n = 0; n < 2; ++n) _Pragma("unroll") for (int k = 0; k < 2; ++k) dst[n][k] = *(const PG8_LAS bf16x8*)(lds + PG8_SB(b, h) + boff + n * 2048 + k * 1024); } while (0)
; #define PG8_MMA(ai, bj, At, Bt) do { __builtin_amdgcn_s_setprio(1); _Pragma("unroll") for (int m = 0; m < 4; ++m) _Pragma("unroll") for (int n = 0; n < 2; ++n) _Pragma("unroll") for (int k = 0; k < 2; ++k) \
;         acc[ai][bj][m][n] = mma16<F16>(Bt[n][k], At[m][k], acc[ai][bj][m][n]); __builtin_amdgcn_s_setprio(0); } while (0)
; #define PG8_WAIT_V(n) asm volatile("s_waitcnt vmcnt(" #n ")" ::: "memory")
; #define PG8_WAIT_L(n) asm volatile("s_waitcnt lgkmcnt(" #n ")" ::: "memory")
; #define PG8_BAR __builtin_amdgcn_s_barrier()
; #define PG8_SCHED __builtin_amdgcn_sched_barrier(0)
; template <class Epi, class Sched, bool ALIGN_EPI = false, bool SP2 = false, bool F16 = false, bool TOKPERM = false>
; __device__ __forceinline__ void gemm_phase(PG8_LAS unsigned char* lds, const Gemm g, const Sched& S, const Epi& E, int wv) {
;     ...
;             PG8_LDB(B0, 0, 0); PG8_LDB(B1, 0, 1); PG8_SCHED; PG8_LDA(At, 0, 0); PG8_STAGE(PG8_SA(1, 1), a1 + hstep, voffA);
;             PG8_WAIT_V(8); PG8_WAIT_L(0); PG8_BAR; PG8_MMA(0, 0, At, B0); PG8_MMA(0, 1, At, B1); PG8_BAR; PG8_SCHED;
;             PG8_LDA(At, 0, 1); PG8_STAGE(PG8_SB(0, 0), b2, voffB); PG8_STAGE(PG8_SB(0, 1), b2 + hstep, voffB); PG8_STAGE(PG8_SA(0, 0), a2, voffA);
;             PG8_WAIT_V(8); PG8_WAIT_L(0); PG8_BAR; PG8_MMA(1, 0, At, B0); PG8_MMA(1, 1, At, B1); PG8_BAR; PG8_SCHED;
;             PG8_LDB(B0, 1, 0); PG8_LDB(B1, 1, 1); PG8_SCHED; PG8_LDA(At, 1, 0); PG8_STAGE(PG8_SA(0, 1), a2 + hstep, voffA);
;             PG8_WAIT_V(8); PG8_WAIT_L(0); PG8_BAR; PG8_MMA(0, 0, At, B0); PG8_MMA(0, 1, At, B1); PG8_BAR; PG8_SCHED;
	s_waitcnt lgkmcnt(0)
	v_mfma_f32_16x16x32_f16 v[124:127], v[156:159], v[208:211], v[124:127]
	v_mfma_f32_16x16x32_f16 v[120:123], v[164:167], v[208:211], v[120:123]
	v_mfma_f32_16x16x32_f16 v[108:111], v[156:159], v[216:219], v[108:111]
	v_mfma_f32_16x16x32_f16 v[104:107], v[164:167], v[216:219], v[104:107]
	v_mfma_f32_16x16x32_f16 v[92:95], v[156:159], v[228:231], v[92:95]
	v_mfma_f32_16x16x32_f16 v[88:91], v[164:167], v[228:231], v[88:91]
	v_mfma_f32_16x16x32_f16 v[76:79], v[156:159], v[236:239], v[76:79]
	v_mfma_f32_16x16x32_f16 v[72:75], v[164:167], v[236:239], v[72:75]
	v_mfma_f32_16x16x32_f16 v[124:127], v[160:163], v[212:215], v[124:127]
	v_mfma_f32_16x16x32_f16 v[120:123], v[168:171], v[212:215], v[120:123]
	v_mfma_f32_16x16x32_f16 v[108:111], v[160:163], v[220:223], v[108:111]
	v_mfma_f32_16x16x32_f16 v[104:107], v[168:171], v[220:223], v[104:107]
	v_mfma_f32_16x16x32_f16 v[92:95], v[160:163], v[232:235], v[92:95]
	v_mfma_f32_16x16x32_f16 v[88:91], v[168:171], v[232:235], v[88:91]
	v_mfma_f32_16x16x32_f16 v[76:79], v[160:163], v[240:243], v[76:79]
	v_mfma_f32_16x16x32_f16 v[72:75], v[168:171], v[240:243], v[72:75]
	v_mfma_f32_16x16x32_f16 v[116:119], v[172:175], v[208:211], v[116:119]
	v_mfma_f32_16x16x32_f16 v[112:115], v[200:203], v[208:211], v[112:115]
	v_mfma_f32_16x16x32_f16 v[100:103], v[172:175], v[216:219], v[100:103]
	v_mfma_f32_16x16x32_f16 v[96:99], v[200:203], v[216:219], v[96:99]
	v_mfma_f32_16x16x32_f16 v[84:87], v[172:175], v[228:231], v[84:87]
	v_mfma_f32_16x16x32_f16 v[80:83], v[200:203], v[228:231], v[80:83]
	v_mfma_f32_16x16x32_f16 v[68:71], v[172:175], v[236:239], v[68:71]
	v_mfma_f32_16x16x32_f16 v[64:67], v[200:203], v[236:239], v[64:67]
	v_mfma_f32_16x16x32_f16 v[116:119], v[176:179], v[212:215], v[116:119]
	v_mfma_f32_16x16x32_f16 v[112:115], v[204:207], v[212:215], v[112:115]
	v_mfma_f32_16x16x32_f16 v[100:103], v[176:179], v[220:223], v[100:103]
	v_mfma_f32_16x16x32_f16 v[96:99], v[204:207], v[220:223], v[96:99]
	v_mfma_f32_16x16x32_f16 v[84:87], v[176:179], v[232:235], v[84:87]
	v_mfma_f32_16x16x32_f16 v[80:83], v[204:207], v[232:235], v[80:83]
	v_mfma_f32_16x16x32_f16 v[68:71], v[176:179], v[240:243], v[68:71]
	v_mfma_f32_16x16x32_f16 v[64:67], v[204:207], v[240:243], v[64:67]
	s_barrier
	s_mov_b32 m0, s53
	v_lshl_add_u64 v[224:225], s[8:9], 0, v[130:131]
	s_add_u32 s78, s8, 0x40000
	ds_read_b128 v[208:211], v155 offset:16384
	ds_read_b128 v[212:215], v155 offset:17408
	ds_read_b128 v[216:219], v155 offset:18432
	ds_read_b128 v[220:223], v155 offset:19456
	ds_read_b128 v[228:231], v155 offset:20480
	ds_read_b128 v[232:235], v155 offset:21504
	ds_read_b128 v[236:239], v155 offset:22528
	ds_read_b128 v[240:243], v155 offset:23552
	global_load_lds_dwordx4 v[224:225], off
	v_lshl_add_u64 v[244:245], s[8:9], 0, v[134:135]
	s_mov_b32 m0, s55
	s_addc_u32 s79, s9, 0
	global_load_lds_dwordx4 v[244:245], off
	v_lshl_add_u64 v[246:247], s[78:79], 0, v[130:131]
	s_mov_b32 m0, s91
	v_lshl_add_u64 v[248:249], s[10:11], 0, v[132:133]
	global_load_lds_dwordx4 v[246:247], off
	v_lshl_add_u64 v[246:247], s[78:79], 0, v[134:135]
	s_mov_b32 m0, s92
	s_nop 0
	global_load_lds_dwordx4 v[246:247], off
	v_lshl_add_u64 v[246:247], s[10:11], 0, v[128:129]
	s_mov_b32 m0, s90
	s_nop 0
	global_load_lds_dwordx4 v[246:247], off
	s_mov_b32 m0, s93
	s_nop 0
	global_load_lds_dwordx4 v[248:249], off
	s_waitcnt vmcnt(8)
	s_waitcnt lgkmcnt(0)
	s_barrier
	s_waitcnt lgkmcnt(0)
	v_mfma_f32_16x16x32_f16 v[60:63], v[156:159], v[208:211], v[60:63]
	v_mfma_f32_16x16x32_f16 v[56:59], v[164:167], v[208:211], v[56:59]
	v_mfma_f32_16x16x32_f16 v[44:47], v[156:159], v[216:219], v[44:47]
	v_mfma_f32_16x16x32_f16 v[40:43], v[164:167], v[216:219], v[40:43]
	v_mfma_f32_16x16x32_f16 v[28:31], v[156:159], v[228:231], v[28:31]
	v_mfma_f32_16x16x32_f16 v[24:27], v[164:167], v[228:231], v[24:27]
	v_mfma_f32_16x16x32_f16 v[12:15], v[156:159], v[236:239], v[12:15]
	v_mfma_f32_16x16x32_f16 v[8:11], v[164:167], v[236:239], v[8:11]
	v_mfma_f32_16x16x32_f16 v[60:63], v[160:163], v[212:215], v[60:63]
	v_mfma_f32_16x16x32_f16 v[56:59], v[168:171], v[212:215], v[56:59]
	v_mfma_f32_16x16x32_f16 v[44:47], v[160:163], v[220:223], v[44:47]
	v_mfma_f32_16x16x32_f16 v[40:43], v[168:171], v[220:223], v[40:43]
	v_mfma_f32_16x16x32_f16 v[28:31], v[160:163], v[232:235], v[28:31]
	v_mfma_f32_16x16x32_f16 v[24:27], v[168:171], v[232:235], v[24:27]
	v_mfma_f32_16x16x32_f16 v[12:15], v[160:163], v[240:243], v[12:15]
	v_mfma_f32_16x16x32_f16 v[8:11], v[168:171], v[240:243], v[8:11]
	v_mfma_f32_16x16x32_f16 v[52:55], v[172:175], v[208:211], v[52:55]
	v_mfma_f32_16x16x32_f16 v[48:51], v[200:203], v[208:211], v[48:51]
	v_mfma_f32_16x16x32_f16 v[36:39], v[172:175], v[216:219], v[36:39]
	v_mfma_f32_16x16x32_f16 v[32:35], v[200:203], v[216:219], v[32:35]
	v_mfma_f32_16x16x32_f16 v[20:23], v[172:175], v[228:231], v[20:23]
	v_mfma_f32_16x16x32_f16 v[16:19], v[200:203], v[228:231], v[16:19]
	v_mfma_f32_16x16x32_f16 v[4:7], v[172:175], v[236:239], v[4:7]
	v_mfma_f32_16x16x32_f16 v[0:3], v[200:203], v[236:239], v[0:3]
	v_mfma_f32_16x16x32_f16 v[52:55], v[176:179], v[212:215], v[52:55]
	v_mfma_f32_16x16x32_f16 v[48:51], v[204:207], v[212:215], v[48:51]
	v_mfma_f32_16x16x32_f16 v[36:39], v[176:179], v[220:223], v[36:39]
	v_mfma_f32_16x16x32_f16 v[32:35], v[204:207], v[220:223], v[32:35]
	v_mfma_f32_16x16x32_f16 v[20:23], v[176:179], v[232:235], v[20:23]
	v_mfma_f32_16x16x32_f16 v[16:19], v[204:207], v[232:235], v[16:19]
	v_mfma_f32_16x16x32_f16 v[4:7], v[176:179], v[240:243], v[4:7]
	v_mfma_f32_16x16x32_f16 v[0:3], v[204:207], v[240:243], v[0:3]
	s_barrier
; #define PG8_STAGE(bufoff, gbase, voff) do { _Pragma("unroll") for (int _i = 0; _i < 2; ++_i) \
;         __builtin_amdgcn_global_load_lds((const unsigned*)((const char*)(gbase) + (voff)[_i]), (PG8_LAS unsigned*)(lds + (bufoff) + ldsw + _i * 8192), 16, 0, 0); } while (0)
; #define PG8_LDA(dst, b, h) do { _Pragma("unroll") for (int m = 0; m < 4; ++m) _Pragma("unroll") for (int k = 0; k < 2; ++k) dst[m][k] = *(const PG8_LAS bf16x8*)(lds + PG8_SA(b, h) + aoff + m * 2048 + k * 1024); } while (0)
; #define PG8_LDB(dst, b, h) do { _Pragma("unroll") for (int n = 0; n < 2; ++n) _Pragma("unroll") for (int k = 0; k < 2; ++k) dst[n][k] = *(const PG8_LAS bf16x8*)(lds + PG8_SB(b, h) + boff + n * 2048 + k * 1024); } while (0)
; #define PG8_MMA(ai, bj, At, Bt) do { __builtin_amdgcn_s_setprio(1); _Pragma("unroll") for (int m = 0; m < 4; ++m) _Pragma("unroll") for (int n = 0; n < 2; ++n) _Pragma("unroll") for (int k = 0; k < 2; ++k) \
;         acc[ai][bj][m][n] = mma16<F16>(Bt[n][k], At[m][k], acc[ai][bj][m][n]); __builtin_amdgcn_s_setprio(0); } while (0)
; #define PG8_WAIT_V(n) asm volatile("s_waitcnt vmcnt(" #n ")" ::: "memory")
; #define PG8_WAIT_L(n) asm volatile("s_waitcnt lgkmcnt(" #n ")" ::: "memory")
; #define PG8_BAR __builtin_amdgcn_s_barrier()
; #define PG8_SCHED __builtin_amdgcn_sched_barrier(0)
; template <class Epi, class Sched, bool ALIGN_EPI = false, bool SP2 = false, bool F16 = false, bool TOKPERM = false>
; __device__ __forceinline__ void gemm_phase(PG8_LAS unsigned char* lds, const Gemm g, const Sched& S, const Epi& E, int wv) {
;     ...
;             PG8_LDB(B0, 1, 0); PG8_LDB(B1, 1, 1); PG8_SCHED; PG8_LDA(At, 1, 0); PG8_STAGE(PG8_SA(0, 1), a2 + hstep, voffA);
;             PG8_WAIT_V(8); PG8_WAIT_L(0); PG8_BAR; PG8_MMA(0, 0, At, B0); PG8_MMA(0, 1, At, B1); PG8_BAR; PG8_SCHED;
;             PG8_LDA(At, 1, 1); PG8_STAGE(PG8_SB(1, 0), b3, voffB); PG8_STAGE(PG8_SB(1, 1), b3 + hstep, voffB); PG8_STAGE(PG8_SA(1, 0), a3, voffA);
;             PG8_WAIT_V(8); PG8_WAIT_L(0); PG8_BAR; PG8_MMA(1, 0, At, B0); PG8_MMA(1, 1, At, B1); PG8_BAR; PG8_SCHED;
	ds_read_b128 v[156:159], v189
	ds_read_b128 v[160:163], v190
	ds_read_b128 v[164:167], v191
	ds_read_b128 v[168:171], v192
	ds_read_b128 v[172:175], v193
	ds_read_b128 v[176:179], v194
	ds_read_b128 v[200:203], v195
	ds_read_b128 v[204:207], v196
	s_add_u32 s10, s10, 0x40000
	s_addc_u32 s11, s11, 0
	s_mov_b32 m0, s95
	v_lshl_add_u64 v[250:251], s[10:11], 0, v[128:129]
	ds_read_b128 v[208:211], v155 offset:32768
	ds_read_b128 v[212:215], v155 offset:33792
	ds_read_b128 v[216:219], v155 offset:34816
	ds_read_b128 v[220:223], v155 offset:35840
	ds_read_b128 v[228:231], v155 offset:36864
	ds_read_b128 v[232:235], v155 offset:37888
	ds_read_b128 v[236:239], v155 offset:38912
	ds_read_b128 v[240:243], v155 offset:39936
	global_load_lds_dwordx4 v[250:251], off
	v_lshl_add_u64 v[250:251], s[10:11], 0, v[132:133]
	s_mov_b32 m0, s96
	s_nop 0
	global_load_lds_dwordx4 v[250:251], off
	s_waitcnt vmcnt(8)
	s_waitcnt lgkmcnt(0)
	s_barrier
	s_waitcnt lgkmcnt(0)
	v_mfma_f32_16x16x32_f16 v[124:127], v[156:159], v[208:211], v[124:127]
	v_mfma_f32_16x16x32_f16 v[120:123], v[164:167], v[208:211], v[120:123]
	v_mfma_f32_16x16x32_f16 v[108:111], v[156:159], v[216:219], v[108:111]
	v_mfma_f32_16x16x32_f16 v[104:107], v[164:167], v[216:219], v[104:107]
	v_mfma_f32_16x16x32_f16 v[92:95], v[156:159], v[228:231], v[92:95]
	v_mfma_f32_16x16x32_f16 v[88:91], v[164:167], v[228:231], v[88:91]
	v_mfma_f32_16x16x32_f16 v[76:79], v[156:159], v[236:239], v[76:79]
	v_mfma_f32_16x16x32_f16 v[72:75], v[164:167], v[236:239], v[72:75]
	v_mfma_f32_16x16x32_f16 v[124:127], v[160:163], v[212:215], v[124:127]
	v_mfma_f32_16x16x32_f16 v[120:123], v[168:171], v[212:215], v[120:123]
	v_mfma_f32_16x16x32_f16 v[108:111], v[160:163], v[220:223], v[108:111]
	v_mfma_f32_16x16x32_f16 v[104:107], v[168:171], v[220:223], v[104:107]
	v_mfma_f32_16x16x32_f16 v[92:95], v[160:163], v[232:235], v[92:95]
	v_mfma_f32_16x16x32_f16 v[88:91], v[168:171], v[232:235], v[88:91]
	v_mfma_f32_16x16x32_f16 v[76:79], v[160:163], v[240:243], v[76:79]
	v_mfma_f32_16x16x32_f16 v[72:75], v[168:171], v[240:243], v[72:75]
	v_mfma_f32_16x16x32_f16 v[116:119], v[172:175], v[208:211], v[116:119]
	v_mfma_f32_16x16x32_f16 v[112:115], v[200:203], v[208:211], v[112:115]
	v_mfma_f32_16x16x32_f16 v[100:103], v[172:175], v[216:219], v[100:103]
	v_mfma_f32_16x16x32_f16 v[96:99], v[200:203], v[216:219], v[96:99]
	v_mfma_f32_16x16x32_f16 v[84:87], v[172:175], v[228:231], v[84:87]
	v_mfma_f32_16x16x32_f16 v[80:83], v[200:203], v[228:231], v[80:83]
	v_mfma_f32_16x16x32_f16 v[68:71], v[172:175], v[236:239], v[68:71]
	v_mfma_f32_16x16x32_f16 v[64:67], v[200:203], v[236:239], v[64:67]
	v_mfma_f32_16x16x32_f16 v[116:119], v[176:179], v[212:215], v[116:119]
	v_mfma_f32_16x16x32_f16 v[112:115], v[204:207], v[212:215], v[112:115]
	v_mfma_f32_16x16x32_f16 v[100:103], v[176:179], v[220:223], v[100:103]
	v_mfma_f32_16x16x32_f16 v[96:99], v[204:207], v[220:223], v[96:99]
	v_mfma_f32_16x16x32_f16 v[84:87], v[176:179], v[232:235], v[84:87]
	v_mfma_f32_16x16x32_f16 v[80:83], v[204:207], v[232:235], v[80:83]
	v_mfma_f32_16x16x32_f16 v[68:71], v[176:179], v[240:243], v[68:71]
	v_mfma_f32_16x16x32_f16 v[64:67], v[204:207], v[240:243], v[64:67]
	s_barrier
	s_mov_b32 m0, s20
	v_lshl_add_u64 v[224:225], v[224:225], 0, s[60:61]
	s_add_u32 s8, s8, 0x40080
	ds_read_b128 v[208:211], v155 offset:49152
	ds_read_b128 v[212:215], v155 offset:50176
	ds_read_b128 v[216:219], v155 offset:51200
	ds_read_b128 v[220:223], v155 offset:52224
	ds_read_b128 v[228:231], v155 offset:53248
	ds_read_b128 v[232:235], v155 offset:54272
	ds_read_b128 v[236:239], v155 offset:55296
	ds_read_b128 v[240:243], v155 offset:56320
	global_load_lds_dwordx4 v[224:225], off
	v_lshl_add_u64 v[224:225], v[244:245], 0, s[60:61]
	s_mov_b32 m0, s21
	s_addc_u32 s9, s9, 0
	global_load_lds_dwordx4 v[224:225], off
	v_lshl_add_u64 v[224:225], s[8:9], 0, v[130:131]
	s_mov_b32 m0, s44
	s_nop 0
	global_load_lds_dwordx4 v[224:225], off
	v_lshl_add_u64 v[224:225], s[8:9], 0, v[134:135]
	s_mov_b32 m0, s45
	s_nop 0
	global_load_lds_dwordx4 v[224:225], off
	v_lshl_add_u64 v[224:225], v[246:247], 0, s[60:61]
	s_mov_b32 m0, s22
	s_nop 0
	global_load_lds_dwordx4 v[224:225], off
	v_lshl_add_u64 v[224:225], v[248:249], 0, s[60:61]
	s_mov_b32 m0, s23
	s_nop 0
	global_load_lds_dwordx4 v[224:225], off
	s_waitcnt vmcnt(8)
	s_waitcnt lgkmcnt(0)
	s_barrier
	s_waitcnt lgkmcnt(0)
	v_mfma_f32_16x16x32_f16 v[60:63], v[156:159], v[208:211], v[60:63]
	v_mfma_f32_16x16x32_f16 v[56:59], v[164:167], v[208:211], v[56:59]
	v_mfma_f32_16x16x32_f16 v[44:47], v[156:159], v[216:219], v[44:47]
	v_mfma_f32_16x16x32_f16 v[40:43], v[164:167], v[216:219], v[40:43]
	v_mfma_f32_16x16x32_f16 v[28:31], v[156:159], v[228:231], v[28:31]
	v_mfma_f32_16x16x32_f16 v[24:27], v[164:167], v[228:231], v[24:27]
	v_mfma_f32_16x16x32_f16 v[12:15], v[156:159], v[236:239], v[12:15]
	v_mfma_f32_16x16x32_f16 v[8:11], v[164:167], v[236:239], v[8:11]
	v_mfma_f32_16x16x32_f16 v[60:63], v[160:163], v[212:215], v[60:63]
	v_mfma_f32_16x16x32_f16 v[56:59], v[168:171], v[212:215], v[56:59]
	v_mfma_f32_16x16x32_f16 v[44:47], v[160:163], v[220:223], v[44:47]
	v_mfma_f32_16x16x32_f16 v[40:43], v[168:171], v[220:223], v[40:43]
	v_mfma_f32_16x16x32_f16 v[28:31], v[160:163], v[232:235], v[28:31]
	v_mfma_f32_16x16x32_f16 v[24:27], v[168:171], v[232:235], v[24:27]
	v_mfma_f32_16x16x32_f16 v[12:15], v[160:163], v[240:243], v[12:15]
	v_mfma_f32_16x16x32_f16 v[8:11], v[168:171], v[240:243], v[8:11]
	v_mfma_f32_16x16x32_f16 v[52:55], v[172:175], v[208:211], v[52:55]
	v_mfma_f32_16x16x32_f16 v[48:51], v[200:203], v[208:211], v[48:51]
	v_mfma_f32_16x16x32_f16 v[36:39], v[172:175], v[216:219], v[36:39]
	v_mfma_f32_16x16x32_f16 v[32:35], v[200:203], v[216:219], v[32:35]
	v_mfma_f32_16x16x32_f16 v[20:23], v[172:175], v[228:231], v[20:23]
	v_mfma_f32_16x16x32_f16 v[16:19], v[200:203], v[228:231], v[16:19]
	v_mfma_f32_16x16x32_f16 v[4:7], v[172:175], v[236:239], v[4:7]
	v_mfma_f32_16x16x32_f16 v[0:3], v[200:203], v[236:239], v[0:3]
	v_mfma_f32_16x16x32_f16 v[52:55], v[176:179], v[212:215], v[52:55]
	v_mfma_f32_16x16x32_f16 v[48:51], v[204:207], v[212:215], v[48:51]
	v_mfma_f32_16x16x32_f16 v[36:39], v[176:179], v[220:223], v[36:39]
	v_mfma_f32_16x16x32_f16 v[32:35], v[204:207], v[220:223], v[32:35]
	v_mfma_f32_16x16x32_f16 v[20:23], v[176:179], v[232:235], v[20:23]
	v_mfma_f32_16x16x32_f16 v[16:19], v[204:207], v[232:235], v[16:19]
	v_mfma_f32_16x16x32_f16 v[4:7], v[176:179], v[240:243], v[4:7]
	v_mfma_f32_16x16x32_f16 v[0:3], v[204:207], v[240:243], v[0:3]
	s_barrier
	s_add_i32 s76, s76, 2
	s_add_u32 s6, s6, 0x100
	s_addc_u32 s7, s7, 0
	s_add_u32 s69, s69, 0x100
	s_addc_u32 s71, s71, 0
	s_cmp_gt_u32 s76, 13
	s_cbranch_scc0 .LBB0_382
	s_and_b64 vcc, exec, s[62:63]
	s_cbranch_vccz .LBB0_385
	s_barrier

; #define PG8_STAGE(bufoff, gbase, voff) do { _Pragma("unroll") for (int _i = 0; _i < 2; ++_i) \
;         __builtin_amdgcn_global_load_lds((const unsigned*)((const char*)(gbase) + (voff)[_i]), (PG8_LAS unsigned*)(lds + (bufoff) + ldsw + _i * 8192), 16, 0, 0); } while (0)
; #define PG8_LDA(dst, b, h) do { _Pragma("unroll") for (int m = 0; m < 4; ++m) _Pragma("unroll") for (int k = 0; k < 2; ++k) dst[m][k] = *(const PG8_LAS bf16x8*)(lds + PG8_SA(b, h) + aoff + m * 2048 + k * 1024); } while (0)
; #define PG8_LDB(dst, b, h) do { _Pragma("unroll") for (int n = 0; n < 2; ++n) _Pragma("unroll") for (int k = 0; k < 2; ++k) dst[n][k] = *(const PG8_LAS bf16x8*)(lds + PG8_SB(b, h) + boff + n * 2048 + k * 1024); } while (0)
; #define PG8_MMA(ai, bj, At, Bt) do { __builtin_amdgcn_s_setprio(1); _Pragma("unroll") for (int m = 0; m < 4; ++m) _Pragma("unroll") for (int n = 0; n < 2; ++n) _Pragma("unroll") for (int k = 0; k < 2; ++k) \
;         acc[ai][bj][m][n] = mma16<F16>(Bt[n][k], At[m][k], acc[ai][bj][m][n]); __builtin_amdgcn_s_setprio(0); } while (0)
; #define PG8_WAIT_V(n) asm volatile("s_waitcnt vmcnt(" #n ")" ::: "memory")
; #define PG8_BAR __builtin_amdgcn_s_barrier()
; template <class Epi, class Sched, bool ALIGN_EPI = false, bool SP2 = false, bool F16 = false, bool TOKPERM = false>
; __device__ __forceinline__ void gemm_phase(PG8_LAS unsigned char* lds, const Gemm g, const Sched& S, const Epi& E, int wv) {
;     ...
;         for (int t = 0; t < nt; t += 2) {
;             const bool last = (t == nt - 2);
;             const char* a1 = cA + (size_t)(t + 1) * kstep;
;             const char* a2 = last ? nA : cA + (size_t)(t + 2) * kstep; const char* b2 = last ? nB : cB + (size_t)(t + 2) * kstep;
;             const char* a3 = a2 + kstep; const char* b3 = b2 + kstep;
;             if (last && has_next) S.a_ready(nxt);
;             if constexpr (SP2) {
;             PG8_LDB(B0, 0, 0); PG8_LDB(B1, 0, 1); PG8_SCHED; PG8_LDA(At, 0, 0); PG8_STAGE(PG8_SA(1, 1), a1 + hstep, voffA);
;             PG8_WAIT_V(8); PG8_WAIT_L(0); PG8_BAR; PG8_MMA(0, 0, At, B0); PG8_MMA(0, 1, At, B1); PG8_BAR; PG8_SCHED;
;             PG8_LDA(At, 0, 1); PG8_STAGE(PG8_SB(0, 0), b2, voffB); PG8_STAGE(PG8_SB(0, 1), b2 + hstep, voffB); PG8_STAGE(PG8_SA(0, 0), a2, voffA);
;             PG8_WAIT_V(8); PG8_WAIT_L(0); PG8_BAR; PG8_MMA(1, 0, At, B0); PG8_MMA(1, 1, At, B1); PG8_BAR; PG8_SCHED;
.LBB0_685:
	ds_read_b128 v[166:169], v149
	ds_read_b128 v[170:173], v150
	ds_read_b128 v[174:177], v151
	ds_read_b128 v[178:181], v152
	ds_read_b128 v[182:185], v153
	ds_read_b128 v[186:189], v154
	ds_read_b128 v[190:193], v155
	ds_read_b128 v[194:197], v156
	s_add_u32 s54, s52, 0xfffc0080
	s_addc_u32 s55, s53, -1
	s_cmp_eq_u32 s69, 12
	s_cselect_b32 s57, s13, s55
	s_cselect_b32 s56, s49, s54
	s_cselect_b32 s55, s11, s68
	s_cselect_b32 s54, s66, s67
	s_mov_b32 m0, s64
	v_lshl_add_u64 v[232:233], s[52:53], 0, v[138:139]
	ds_read_b128 v[198:201], v147
	ds_read_b128 v[202:205], v147 offset:1024
	ds_read_b128 v[206:209], v147 offset:2048
	ds_read_b128 v[210:213], v147 offset:3072
	ds_read_b128 v[214:217], v147 offset:4096
	ds_read_b128 v[218:221], v147 offset:5120
	ds_read_b128 v[222:225], v147 offset:6144
	ds_read_b128 v[228:231], v147 offset:7168
	global_load_lds_dwordx4 v[232:233], off
	v_lshl_add_u64 v[232:233], s[52:53], 0, v[140:141]
	s_mov_b32 m0, s65
	s_nop 0
	global_load_lds_dwordx4 v[232:233], off
	s_waitcnt vmcnt(8)
	s_waitcnt lgkmcnt(0)
	s_barrier
	s_waitcnt lgkmcnt(0)
	v_mfma_f32_16x16x32_bf16 v[124:127], v[166:169], v[198:201], v[124:127]
	v_mfma_f32_16x16x32_bf16 v[120:123], v[174:177], v[198:201], v[120:123]
	v_mfma_f32_16x16x32_bf16 v[108:111], v[166:169], v[206:209], v[108:111]
	v_mfma_f32_16x16x32_bf16 v[104:107], v[174:177], v[206:209], v[104:107]
	v_mfma_f32_16x16x32_bf16 v[92:95], v[166:169], v[214:217], v[92:95]
	v_mfma_f32_16x16x32_bf16 v[88:91], v[174:177], v[214:217], v[88:91]
	v_mfma_f32_16x16x32_bf16 v[76:79], v[166:169], v[222:225], v[76:79]
	v_mfma_f32_16x16x32_bf16 v[72:75], v[174:177], v[222:225], v[72:75]
	v_mfma_f32_16x16x32_bf16 v[124:127], v[170:173], v[202:205], v[124:127]
	v_mfma_f32_16x16x32_bf16 v[120:123], v[178:181], v[202:205], v[120:123]
	v_mfma_f32_16x16x32_bf16 v[108:111], v[170:173], v[210:213], v[108:111]
	v_mfma_f32_16x16x32_bf16 v[104:107], v[178:181], v[210:213], v[104:107]
	v_mfma_f32_16x16x32_bf16 v[92:95], v[170:173], v[218:221], v[92:95]
	v_mfma_f32_16x16x32_bf16 v[88:91], v[178:181], v[218:221], v[88:91]
	v_mfma_f32_16x16x32_bf16 v[76:79], v[170:173], v[228:231], v[76:79]
	v_mfma_f32_16x16x32_bf16 v[72:75], v[178:181], v[228:231], v[72:75]
	v_mfma_f32_16x16x32_bf16 v[116:119], v[182:185], v[198:201], v[116:119]
	v_mfma_f32_16x16x32_bf16 v[112:115], v[190:193], v[198:201], v[112:115]
	v_mfma_f32_16x16x32_bf16 v[100:103], v[182:185], v[206:209], v[100:103]
	v_mfma_f32_16x16x32_bf16 v[96:99], v[190:193], v[206:209], v[96:99]
	v_mfma_f32_16x16x32_bf16 v[84:87], v[182:185], v[214:217], v[84:87]
	v_mfma_f32_16x16x32_bf16 v[80:83], v[190:193], v[214:217], v[80:83]
	v_mfma_f32_16x16x32_bf16 v[68:71], v[182:185], v[222:225], v[68:71]
	v_mfma_f32_16x16x32_bf16 v[64:67], v[190:193], v[222:225], v[64:67]
	v_mfma_f32_16x16x32_bf16 v[116:119], v[186:189], v[202:205], v[116:119]
	v_mfma_f32_16x16x32_bf16 v[112:115], v[194:197], v[202:205], v[112:115]
	v_mfma_f32_16x16x32_bf16 v[100:103], v[186:189], v[210:213], v[100:103]
	v_mfma_f32_16x16x32_bf16 v[96:99], v[194:197], v[210:213], v[96:99]
	v_mfma_f32_16x16x32_bf16 v[84:87], v[186:189], v[218:221], v[84:87]
	v_mfma_f32_16x16x32_bf16 v[80:83], v[194:197], v[218:221], v[80:83]
	v_mfma_f32_16x16x32_bf16 v[68:71], v[186:189], v[228:231], v[68:71]
	v_mfma_f32_16x16x32_bf16 v[64:67], v[194:197], v[228:231], v[64:67]
	s_barrier
	s_mov_b32 m0, s2
	v_lshl_add_u64 v[232:233], s[54:55], 0, v[130:131]
	s_add_u32 s70, s54, 0x40000
	ds_read_b128 v[198:201], v147 offset:16384
	ds_read_b128 v[202:205], v147 offset:17408
	ds_read_b128 v[206:209], v147 offset:18432
	ds_read_b128 v[210:213], v147 offset:19456
	ds_read_b128 v[214:217], v147 offset:20480
	ds_read_b128 v[218:221], v147 offset:21504
	ds_read_b128 v[222:225], v147 offset:22528
	ds_read_b128 v[228:231], v147 offset:23552
	global_load_lds_dwordx4 v[232:233], off
	v_lshl_add_u64 v[234:235], s[54:55], 0, v[134:135]
	s_mov_b32 m0, s3
	s_addc_u32 s71, s55, 0
	global_load_lds_dwordx4 v[234:235], off
	v_lshl_add_u64 v[236:237], s[70:71], 0, v[130:131]
	s_mov_b32 m0, s20
	v_lshl_add_u64 v[238:239], s[56:57], 0, v[132:133]
	global_load_lds_dwordx4 v[236:237], off
	v_lshl_add_u64 v[236:237], s[70:71], 0, v[134:135]
	s_mov_b32 m0, s21
	s_nop 0
	global_load_lds_dwordx4 v[236:237], off
	v_lshl_add_u64 v[236:237], s[56:57], 0, v[128:129]
	s_mov_b32 m0, s1
	s_nop 0
	global_load_lds_dwordx4 v[236:237], off
	s_mov_b32 m0, s22
	s_nop 0
	global_load_lds_dwordx4 v[238:239], off
	s_waitcnt vmcnt(8)
	s_waitcnt lgkmcnt(0)
	s_barrier
	s_waitcnt lgkmcnt(0)
	v_mfma_f32_16x16x32_bf16 v[60:63], v[166:169], v[198:201], v[60:63]
	v_mfma_f32_16x16x32_bf16 v[56:59], v[174:177], v[198:201], v[56:59]
	v_mfma_f32_16x16x32_bf16 v[44:47], v[166:169], v[206:209], v[44:47]
	v_mfma_f32_16x16x32_bf16 v[40:43], v[174:177], v[206:209], v[40:43]
	v_mfma_f32_16x16x32_bf16 v[28:31], v[166:169], v[214:217], v[28:31]
	v_mfma_f32_16x16x32_bf16 v[24:27], v[174:177], v[214:217], v[24:27]
	v_mfma_f32_16x16x32_bf16 v[12:15], v[166:169], v[222:225], v[12:15]
	v_mfma_f32_16x16x32_bf16 v[8:11], v[174:177], v[222:225], v[8:11]
	v_mfma_f32_16x16x32_bf16 v[60:63], v[170:173], v[202:205], v[60:63]
	v_mfma_f32_16x16x32_bf16 v[56:59], v[178:181], v[202:205], v[56:59]
	v_mfma_f32_16x16x32_bf16 v[44:47], v[170:173], v[210:213], v[44:47]
	v_mfma_f32_16x16x32_bf16 v[40:43], v[178:181], v[210:213], v[40:43]
	v_mfma_f32_16x16x32_bf16 v[28:31], v[170:173], v[218:221], v[28:31]
	v_mfma_f32_16x16x32_bf16 v[24:27], v[178:181], v[218:221], v[24:27]
	v_mfma_f32_16x16x32_bf16 v[12:15], v[170:173], v[228:231], v[12:15]
	v_mfma_f32_16x16x32_bf16 v[8:11], v[178:181], v[228:231], v[8:11]
	v_mfma_f32_16x16x32_bf16 v[52:55], v[182:185], v[198:201], v[52:55]
	v_mfma_f32_16x16x32_bf16 v[48:51], v[190:193], v[198:201], v[48:51]
	v_mfma_f32_16x16x32_bf16 v[36:39], v[182:185], v[206:209], v[36:39]
	v_mfma_f32_16x16x32_bf16 v[32:35], v[190:193], v[206:209], v[32:35]
	v_mfma_f32_16x16x32_bf16 v[20:23], v[182:185], v[214:217], v[20:23]
	v_mfma_f32_16x16x32_bf16 v[16:19], v[190:193], v[214:217], v[16:19]
	v_mfma_f32_16x16x32_bf16 v[4:7], v[182:185], v[222:225], v[4:7]
	v_mfma_f32_16x16x32_bf16 v[0:3], v[190:193], v[222:225], v[0:3]
	v_mfma_f32_16x16x32_bf16 v[52:55], v[186:189], v[202:205], v[52:55]
	v_mfma_f32_16x16x32_bf16 v[48:51], v[194:197], v[202:205], v[48:51]
	v_mfma_f32_16x16x32_bf16 v[36:39], v[186:189], v[210:213], v[36:39]
	v_mfma_f32_16x16x32_bf16 v[32:35], v[194:197], v[210:213], v[32:35]
	v_mfma_f32_16x16x32_bf16 v[20:23], v[186:189], v[218:221], v[20:23]
	v_mfma_f32_16x16x32_bf16 v[16:19], v[194:197], v[218:221], v[16:19]
	v_mfma_f32_16x16x32_bf16 v[4:7], v[186:189], v[228:231], v[4:7]
	v_mfma_f32_16x16x32_bf16 v[0:3], v[194:197], v[228:231], v[0:3]
	s_barrier
; #define PG8_STAGE(bufoff, gbase, voff) do { _Pragma("unroll") for (int _i = 0; _i < 2; ++_i) \
;         __builtin_amdgcn_global_load_lds((const unsigned*)((const char*)(gbase) + (voff)[_i]), (PG8_LAS unsigned*)(lds + (bufoff) + ldsw + _i * 8192), 16, 0, 0); } while (0)
; #define PG8_LDA(dst, b, h) do { _Pragma("unroll") for (int m = 0; m < 4; ++m) _Pragma("unroll") for (int k = 0; k < 2; ++k) dst[m][k] = *(const PG8_LAS bf16x8*)(lds + PG8_SA(b, h) + aoff + m * 2048 + k * 1024); } while (0)
; #define PG8_LDB(dst, b, h) do { _Pragma("unroll") for (int n = 0; n < 2; ++n) _Pragma("unroll") for (int k = 0; k < 2; ++k) dst[n][k] = *(const PG8_LAS bf16x8*)(lds + PG8_SB(b, h) + boff + n * 2048 + k * 1024); } while (0)
; #define PG8_MMA(ai, bj, At, Bt) do { __builtin_amdgcn_s_setprio(1); _Pragma("unroll") for (int m = 0; m < 4; ++m) _Pragma("unroll") for (int n = 0; n < 2; ++n) _Pragma("unroll") for (int k = 0; k < 2; ++k) \
;         acc[ai][bj][m][n] = mma16<F16>(Bt[n][k], At[m][k], acc[ai][bj][m][n]); __builtin_amdgcn_s_setprio(0); } while (0)
; #define PG8_WAIT_V(n) asm volatile("s_waitcnt vmcnt(" #n ")" ::: "memory")
; #define PG8_WAIT_L(n) asm volatile("s_waitcnt lgkmcnt(" #n ")" ::: "memory")
; #define PG8_BAR __builtin_amdgcn_s_barrier()
; #define PG8_SCHED __builtin_amdgcn_sched_barrier(0)
; template <class Epi, class Sched, bool ALIGN_EPI = false, bool SP2 = false, bool F16 = false, bool TOKPERM = false>
; __device__ __forceinline__ void gemm_phase(PG8_LAS unsigned char* lds, const Gemm g, const Sched& S, const Epi& E, int wv) {
;     ...
;             PG8_LDB(B0, 1, 0); PG8_LDB(B1, 1, 1); PG8_SCHED; PG8_LDA(At, 1, 0); PG8_STAGE(PG8_SA(0, 1), a2 + hstep, voffA);
;             PG8_WAIT_V(8); PG8_WAIT_L(0); PG8_BAR; PG8_MMA(0, 0, At, B0); PG8_MMA(0, 1, At, B1); PG8_BAR; PG8_SCHED;
;             PG8_LDA(At, 1, 1); PG8_STAGE(PG8_SB(1, 0), b3, voffB); PG8_STAGE(PG8_SB(1, 1), b3 + hstep, voffB); PG8_STAGE(PG8_SA(1, 0), a3, voffA);
;             PG8_WAIT_V(8); PG8_WAIT_L(0); PG8_BAR; PG8_MMA(1, 0, At, B0); PG8_MMA(1, 1, At, B1); PG8_BAR; PG8_SCHED;
	ds_read_b128 v[166:169], v157
	ds_read_b128 v[170:173], v158
	ds_read_b128 v[174:177], v159
	ds_read_b128 v[178:181], v160
	ds_read_b128 v[182:185], v161
	ds_read_b128 v[186:189], v162
	ds_read_b128 v[190:193], v163
	ds_read_b128 v[194:197], v164
	s_add_u32 s56, s56, 0x40000
	s_addc_u32 s57, s57, 0
	s_mov_b32 m0, s23
	v_lshl_add_u64 v[240:241], s[56:57], 0, v[128:129]
	ds_read_b128 v[198:201], v147 offset:32768
	ds_read_b128 v[202:205], v147 offset:33792
	ds_read_b128 v[206:209], v147 offset:34816
	ds_read_b128 v[210:213], v147 offset:35840
	ds_read_b128 v[214:217], v147 offset:36864
	ds_read_b128 v[218:221], v147 offset:37888
	ds_read_b128 v[222:225], v147 offset:38912
	ds_read_b128 v[228:231], v147 offset:39936
	global_load_lds_dwordx4 v[240:241], off
	v_lshl_add_u64 v[240:241], s[56:57], 0, v[132:133]
	s_mov_b32 m0, s33
	s_nop 0
	global_load_lds_dwordx4 v[240:241], off
	s_waitcnt vmcnt(8)
	s_waitcnt lgkmcnt(0)
	s_barrier
	s_waitcnt lgkmcnt(0)
	v_mfma_f32_16x16x32_bf16 v[124:127], v[166:169], v[198:201], v[124:127]
	v_mfma_f32_16x16x32_bf16 v[120:123], v[174:177], v[198:201], v[120:123]
	v_mfma_f32_16x16x32_bf16 v[108:111], v[166:169], v[206:209], v[108:111]
	v_mfma_f32_16x16x32_bf16 v[104:107], v[174:177], v[206:209], v[104:107]
	v_mfma_f32_16x16x32_bf16 v[92:95], v[166:169], v[214:217], v[92:95]
	v_mfma_f32_16x16x32_bf16 v[88:91], v[174:177], v[214:217], v[88:91]
	v_mfma_f32_16x16x32_bf16 v[76:79], v[166:169], v[222:225], v[76:79]
	v_mfma_f32_16x16x32_bf16 v[72:75], v[174:177], v[222:225], v[72:75]
	v_mfma_f32_16x16x32_bf16 v[124:127], v[170:173], v[202:205], v[124:127]
	v_mfma_f32_16x16x32_bf16 v[120:123], v[178:181], v[202:205], v[120:123]
	v_mfma_f32_16x16x32_bf16 v[108:111], v[170:173], v[210:213], v[108:111]
	v_mfma_f32_16x16x32_bf16 v[104:107], v[178:181], v[210:213], v[104:107]
	v_mfma_f32_16x16x32_bf16 v[92:95], v[170:173], v[218:221], v[92:95]
	v_mfma_f32_16x16x32_bf16 v[88:91], v[178:181], v[218:221], v[88:91]
	v_mfma_f32_16x16x32_bf16 v[76:79], v[170:173], v[228:231], v[76:79]
	v_mfma_f32_16x16x32_bf16 v[72:75], v[178:181], v[228:231], v[72:75]
	v_mfma_f32_16x16x32_bf16 v[116:119], v[182:185], v[198:201], v[116:119]
	v_mfma_f32_16x16x32_bf16 v[112:115], v[190:193], v[198:201], v[112:115]
	v_mfma_f32_16x16x32_bf16 v[100:103], v[182:185], v[206:209], v[100:103]
	v_mfma_f32_16x16x32_bf16 v[96:99], v[190:193], v[206:209], v[96:99]
	v_mfma_f32_16x16x32_bf16 v[84:87], v[182:185], v[214:217], v[84:87]
	v_mfma_f32_16x16x32_bf16 v[80:83], v[190:193], v[214:217], v[80:83]
	v_mfma_f32_16x16x32_bf16 v[68:71], v[182:185], v[222:225], v[68:71]
	v_mfma_f32_16x16x32_bf16 v[64:67], v[190:193], v[222:225], v[64:67]
	v_mfma_f32_16x16x32_bf16 v[116:119], v[186:189], v[202:205], v[116:119]
	v_mfma_f32_16x16x32_bf16 v[112:115], v[194:197], v[202:205], v[112:115]
	v_mfma_f32_16x16x32_bf16 v[100:103], v[186:189], v[210:213], v[100:103]
	v_mfma_f32_16x16x32_bf16 v[96:99], v[194:197], v[210:213], v[96:99]
	v_mfma_f32_16x16x32_bf16 v[84:87], v[186:189], v[218:221], v[84:87]
	v_mfma_f32_16x16x32_bf16 v[80:83], v[194:197], v[218:221], v[80:83]
	v_mfma_f32_16x16x32_bf16 v[68:71], v[186:189], v[228:231], v[68:71]
	v_mfma_f32_16x16x32_bf16 v[64:67], v[194:197], v[228:231], v[64:67]
	s_barrier
	s_mov_b32 m0, s37
	v_lshl_add_u64 v[232:233], v[232:233], 0, s[8:9]
	s_add_u32 s54, s54, 0x40080
	ds_read_b128 v[198:201], v147 offset:49152
	ds_read_b128 v[202:205], v147 offset:50176
	ds_read_b128 v[206:209], v147 offset:51200
	ds_read_b128 v[210:213], v147 offset:52224
	ds_read_b128 v[214:217], v147 offset:53248
	ds_read_b128 v[218:221], v147 offset:54272
	ds_read_b128 v[222:225], v147 offset:55296
	ds_read_b128 v[228:231], v147 offset:56320
	global_load_lds_dwordx4 v[232:233], off
	v_lshl_add_u64 v[232:233], v[234:235], 0, s[8:9]
	s_mov_b32 m0, s44
	s_addc_u32 s55, s55, 0
	global_load_lds_dwordx4 v[232:233], off
	v_lshl_add_u64 v[232:233], s[54:55], 0, v[130:131]
	s_mov_b32 m0, s58
	s_nop 0
	global_load_lds_dwordx4 v[232:233], off
	v_lshl_add_u64 v[232:233], s[54:55], 0, v[134:135]
	s_mov_b32 m0, s59
	s_nop 0
	global_load_lds_dwordx4 v[232:233], off
	v_lshl_add_u64 v[232:233], v[236:237], 0, s[8:9]
	s_mov_b32 m0, s45
	s_nop 0
	global_load_lds_dwordx4 v[232:233], off
	v_lshl_add_u64 v[232:233], v[238:239], 0, s[8:9]
	s_mov_b32 m0, s51
	s_nop 0
	global_load_lds_dwordx4 v[232:233], off
	s_waitcnt vmcnt(8)
	s_waitcnt lgkmcnt(0)
	s_barrier
	s_waitcnt lgkmcnt(0)
	v_mfma_f32_16x16x32_bf16 v[60:63], v[166:169], v[198:201], v[60:63]
	v_mfma_f32_16x16x32_bf16 v[56:59], v[174:177], v[198:201], v[56:59]
	v_mfma_f32_16x16x32_bf16 v[44:47], v[166:169], v[206:209], v[44:47]
	v_mfma_f32_16x16x32_bf16 v[40:43], v[174:177], v[206:209], v[40:43]
	v_mfma_f32_16x16x32_bf16 v[28:31], v[166:169], v[214:217], v[28:31]
	v_mfma_f32_16x16x32_bf16 v[24:27], v[174:177], v[214:217], v[24:27]
	v_mfma_f32_16x16x32_bf16 v[12:15], v[166:169], v[222:225], v[12:15]
	v_mfma_f32_16x16x32_bf16 v[8:11], v[174:177], v[222:225], v[8:11]
	v_mfma_f32_16x16x32_bf16 v[60:63], v[170:173], v[202:205], v[60:63]
	v_mfma_f32_16x16x32_bf16 v[56:59], v[178:181], v[202:205], v[56:59]
	v_mfma_f32_16x16x32_bf16 v[44:47], v[170:173], v[210:213], v[44:47]
	v_mfma_f32_16x16x32_bf16 v[40:43], v[178:181], v[210:213], v[40:43]
	v_mfma_f32_16x16x32_bf16 v[28:31], v[170:173], v[218:221], v[28:31]
	v_mfma_f32_16x16x32_bf16 v[24:27], v[178:181], v[218:221], v[24:27]
	v_mfma_f32_16x16x32_bf16 v[12:15], v[170:173], v[228:231], v[12:15]
	v_mfma_f32_16x16x32_bf16 v[8:11], v[178:181], v[228:231], v[8:11]
	v_mfma_f32_16x16x32_bf16 v[52:55], v[182:185], v[198:201], v[52:55]
	v_mfma_f32_16x16x32_bf16 v[48:51], v[190:193], v[198:201], v[48:51]
	v_mfma_f32_16x16x32_bf16 v[36:39], v[182:185], v[206:209], v[36:39]
	v_mfma_f32_16x16x32_bf16 v[32:35], v[190:193], v[206:209], v[32:35]
	v_mfma_f32_16x16x32_bf16 v[20:23], v[182:185], v[214:217], v[20:23]
	v_mfma_f32_16x16x32_bf16 v[16:19], v[190:193], v[214:217], v[16:19]
	v_mfma_f32_16x16x32_bf16 v[4:7], v[182:185], v[222:225], v[4:7]
	v_mfma_f32_16x16x32_bf16 v[0:3], v[190:193], v[222:225], v[0:3]
	v_mfma_f32_16x16x32_bf16 v[52:55], v[186:189], v[202:205], v[52:55]
	v_mfma_f32_16x16x32_bf16 v[48:51], v[194:197], v[202:205], v[48:51]
	v_mfma_f32_16x16x32_bf16 v[36:39], v[186:189], v[210:213], v[36:39]
	v_mfma_f32_16x16x32_bf16 v[32:35], v[194:197], v[210:213], v[32:35]
	v_mfma_f32_16x16x32_bf16 v[20:23], v[186:189], v[218:221], v[20:23]
	v_mfma_f32_16x16x32_bf16 v[16:19], v[194:197], v[218:221], v[16:19]
	v_mfma_f32_16x16x32_bf16 v[4:7], v[186:189], v[228:231], v[4:7]
	v_mfma_f32_16x16x32_bf16 v[0:3], v[194:197], v[228:231], v[0:3]
	s_barrier
;   __device__ __forceinline__ void operator()(const pg8::f32x4 (&acc)[2][2][4][2], const pg8::Unit& u, int wr, int wc, int fr, int fq) const {
;     int z; asm volatile("v_mov_b32 %0, 0" : "=v"(z));
;     const int row0 = u.pm * 256 + wr * 64 + fr + z, colb = u.pn * 256 + wc * 32 + 8 * fq + z;
; #pragma unroll
;     for (int ai = 0; ai < 2; ++ai)
; #pragma unroll
;       for (int m = 0; m < 4; ++m) {
;         const int tok = row0 + ai * 128 + m * 16; float ss = 0.f;
; #pragma unroll
;         for (int bj = 0; bj < 2; ++bj) {
;           const unsigned off = (unsigned)tok * DM + colb + 128 * bj;
;           f8_t n = __builtin_convertvector(*(const h8_t*)(x16 + off), f8_t);
; #pragma unroll
;           for (int c = 0; c < 4; ++c) { n[c] += sc * acc[ai][bj][m][0][c]; n[4 + c] += sc * acc[ai][bj][m][1][c]; }
;           if (aux) {
;             *(h8_t*)(x16 + off) = __builtin_convertvector(n, h8_t);
;             ss += ((n[0] * n[0] + n[1] * n[1]) + (n[2] * n[2] + n[3] * n[3])) + ((n[4] * n[4] + n[5] * n[5]) + (n[6] * n[6] + n[7] * n[7]));
;           } else {
;             *(f32x4*)(xout + off) = (f32x4){n[0], n[1], n[2], n[3]}; *(f32x4*)(xout + off + 4) = (f32x4){n[4], n[5], n[6], n[7]};
;           }
;         }
;         if (aux) { ss += __shfl_xor(ss, 16); ss += __shfl_xor(ss, 32); if (fq == 0) ssq[(unsigned)tok * 16 + u.pn * 4 + wc] = ss; }
;         if (m & 1) asm volatile("" ::: "memory");
;       }
	s_add_i32 s69, s69, 2
	s_add_u32 s52, s52, 0x100
	s_addc_u32 s53, s53, 0
	s_add_u32 s67, s67, 0x100
	s_addc_u32 s68, s68, 0
	s_cmp_gt_u32 s69, 13
	s_cbranch_scc0 .LBB0_685
	s_lshl_b32 s11, s50, 8
	v_lshl_or_b32 v166, s48, 8, v148
	v_mov_b32 v136, 0
	v_xor_b32_e32 v169, 32, v165
	v_add3_u32 v167, s11, v146, v136
	v_add_u32_e32 v168, v166, v136
	v_lshl_add_u32 v136, v167, 10, v168
	v_lshl_add_u64 v[178:179], v[136:137], 1, s[40:41]
	v_add_u32_e32 v136, 0x80, v136
	global_load_dwordx4 v[170:173], v[178:179], off
	v_lshl_add_u64 v[180:181], v[136:137], 1, s[40:41]
	global_load_dwordx4 v[174:177], v[180:181], off
	v_add_u32_e32 v136, 16, v167
	v_lshl_add_u32 v136, v136, 10, v168
	v_lshl_add_u64 v[224:225], v[136:137], 1, s[40:41]
	v_add_u32_e32 v136, 0x80, v136
	global_load_dwordx4 v[192:195], v[224:225], off
	v_lshl_add_u64 v[248:249], v[136:137], 1, s[40:41]
	global_load_dwordx4 v[196:199], v[248:249], off
	v_add_u32_e32 v136, 32, v167
	v_lshl_add_u32 v136, v136, 10, v168
	v_lshl_add_u64 v[224:225], v[136:137], 1, s[40:41]
	v_add_u32_e32 v136, 0x80, v136
	global_load_dwordx4 v[200:203], v[224:225], off
	v_lshl_add_u64 v[248:249], v[136:137], 1, s[40:41]
	global_load_dwordx4 v[204:207], v[248:249], off
	v_add_u32_e32 v136, 48, v167
	v_lshl_add_u32 v136, v136, 10, v168
	v_lshl_add_u64 v[224:225], v[136:137], 1, s[40:41]
	v_add_u32_e32 v136, 0x80, v136
	global_load_dwordx4 v[208:211], v[224:225], off
	v_lshl_add_u64 v[248:249], v[136:137], 1, s[40:41]
	global_load_dwordx4 v[212:215], v[248:249], off
	v_add_u32_e32 v136, 0x80, v167
	v_lshl_add_u32 v136, v136, 10, v168
	v_lshl_add_u64 v[224:225], v[136:137], 1, s[40:41]
	v_add_u32_e32 v136, 0x80, v136
	global_load_dwordx4 v[216:219], v[224:225], off
	v_lshl_add_u64 v[248:249], v[136:137], 1, s[40:41]
	global_load_dwordx4 v[220:223], v[248:249], off
	v_add_u32_e32 v136, 0x90, v167
	v_lshl_add_u32 v136, v136, 10, v168
	v_lshl_add_u64 v[224:225], v[136:137], 1, s[40:41]
	v_add_u32_e32 v136, 0x80, v136
	global_load_dwordx4 v[228:231], v[224:225], off
	v_lshl_add_u64 v[248:249], v[136:137], 1, s[40:41]
	global_load_dwordx4 v[244:247], v[248:249], off
	v_and_b32_e32 v166, 64, v165
	v_xor_b32_e32 v136, 16, v165
	v_add_u32_e32 v166, 64, v166
	v_cmp_lt_i32_e32 vcc, v136, v166
	s_lshl_b32 s11, s48, 2
	s_or_b32 s11, s11, s36
	v_cndmask_b32_e32 v136, v165, v136, vcc
	v_cmp_lt_i32_e32 vcc, v169, v166
	v_lshlrev_b32_e32 v166, 2, v136
	s_waitcnt vmcnt(10)
	v_cvt_f32_f16_e32 v182, v173
	v_cvt_f32_f16_sdwa v183, v173 dst_sel:DWORD dst_unused:UNUSED_PAD src0_sel:WORD_1
	v_cvt_f32_f16_e32 v184, v171
	v_cvt_f32_f16_sdwa v185, v171 dst_sel:DWORD dst_unused:UNUSED_PAD src0_sel:WORD_1
	v_cvt_f32_f16_e32 v186, v172
	v_cvt_f32_f16_sdwa v187, v172 dst_sel:DWORD dst_unused:UNUSED_PAD src0_sel:WORD_1
	v_cvt_f32_f16_e32 v172, v170
	v_cvt_f32_f16_sdwa v173, v170 dst_sel:DWORD dst_unused:UNUSED_PAD src0_sel:WORD_1
	v_cvt_f32_f16_e32 v170, v177
	v_cvt_f32_f16_sdwa v171, v177 dst_sel:DWORD dst_unused:UNUSED_PAD src0_sel:WORD_1
	v_cvt_f32_f16_e32 v188, v175
	v_cvt_f32_f16_sdwa v189, v175 dst_sel:DWORD dst_unused:UNUSED_PAD src0_sel:WORD_1
	v_cvt_f32_f16_e32 v190, v176
	v_cvt_f32_f16_sdwa v191, v176 dst_sel:DWORD dst_unused:UNUSED_PAD src0_sel:WORD_1
	v_cvt_f32_f16_e32 v176, v174
	v_cvt_f32_f16_sdwa v177, v174 dst_sel:DWORD dst_unused:UNUSED_PAD src0_sel:WORD_1
	v_pk_add_f32 v[124:125], v[124:125], v[172:173]
	v_pk_add_f32 v[172:173], v[120:121], v[186:187]
	v_pk_add_f32 v[126:127], v[126:127], v[184:185]
	v_pk_add_f32 v[122:123], v[122:123], v[182:183]
	v_cvt_pk_f16_f32 v120, v172, v173
	v_cvt_pk_f16_f32 v121, v122, v123
	v_pk_mul_f32 v[174:175], v[124:125], v[124:125]
	v_pk_mul_f32 v[182:183], v[126:127], v[126:127]
	v_pk_fma_f32 v[174:175], v[172:173], v[172:173], v[174:175]
	v_pk_fma_f32 v[182:183], v[122:123], v[122:123], v[182:183]
	v_pk_add_f32 v[176:177], v[116:117], v[176:177]
	v_pk_add_f32 v[116:117], v[112:113], v[190:191]
	v_pk_add_f32 v[184:185], v[118:119], v[188:189]
	v_pk_add_f32 v[112:113], v[114:115], v[170:171]
	v_pk_fma_f32 v[174:175], v[176:177], v[176:177], v[174:175]
	v_pk_fma_f32 v[182:183], v[184:185], v[184:185], v[182:183]
	v_pk_fma_f32 v[174:175], v[116:117], v[116:117], v[174:175]
	v_pk_fma_f32 v[182:183], v[112:113], v[112:113], v[182:183]
	v_pk_add_f32 v[174:175], v[174:175], v[182:183]
	v_add_f32_e32 v114, v174, v175
	v_mov_b32_e32 v115, v114
	s_nop 1
	v_permlane16_swap_b32_e32 v114, v115
	v_cndmask_b32_e32 v169, v165, v169, vcc
	v_cvt_pk_f16_f32 v119, v126, v127
	v_cvt_pk_f16_f32 v118, v124, v125
	global_store_dwordx4 v[178:179], v[118:121], off
	s_nop 1
	v_cvt_pk_f16_f32 v119, v112, v113
	s_waitcnt lgkmcnt(0)
	v_add_f32_e32 v113, v114, v115
	v_lshlrev_b32_e32 v112, 2, v169
	v_mov_b32_e32 v114, v113
	s_nop 1
	v_permlane32_swap_b32_e32 v113, v114
	v_cvt_pk_f16_f32 v118, v116, v117
	v_cvt_pk_f16_f32 v117, v184, v185
	v_cvt_pk_f16_f32 v116, v176, v177
	global_store_dwordx4 v[180:181], v[116:119], off
	s_and_saveexec_b64 s[48:49], s[4:5]
	s_cbranch_execz .LBB0_688
	v_lshl_add_u32 v136, v167, 4, s11
	s_waitcnt lgkmcnt(0)
	v_add_f32_e32 v113, v113, v114
	v_lshl_add_u64 v[114:115], v[136:137], 2, s[42:43]
	global_store_dword v[114:115], v113, off

; #define PG8_STAGE(bufoff, gbase, voff) do { _Pragma("unroll") for (int _i = 0; _i < 2; ++_i) \
;         __builtin_amdgcn_global_load_lds((const unsigned*)((const char*)(gbase) + (voff)[_i]), (PG8_LAS unsigned*)(lds + (bufoff) + ldsw + _i * 8192), 16, 0, 0); } while (0)
; #define PG8_LDA(dst, b, h) do { _Pragma("unroll") for (int m = 0; m < 4; ++m) _Pragma("unroll") for (int k = 0; k < 2; ++k) dst[m][k] = *(const PG8_LAS bf16x8*)(lds + PG8_SA(b, h) + aoff + m * 2048 + k * 1024); } while (0)
; #define PG8_LDB(dst, b, h) do { _Pragma("unroll") for (int n = 0; n < 2; ++n) _Pragma("unroll") for (int k = 0; k < 2; ++k) dst[n][k] = *(const PG8_LAS bf16x8*)(lds + PG8_SB(b, h) + boff + n * 2048 + k * 1024); } while (0)
; #define PG8_WAIT_V(n) asm volatile("s_waitcnt vmcnt(" #n ")" ::: "memory")
; #define PG8_WAIT_L(n) asm volatile("s_waitcnt lgkmcnt(" #n ")" ::: "memory")
; #define PG8_BAR __builtin_amdgcn_s_barrier()
; #define PG8_SCHED __builtin_amdgcn_sched_barrier(0)
; template <class Epi, class Sched, bool ALIGN_EPI = false, bool SP2 = false, bool F16 = false, bool TOKPERM = false>
; __device__ __forceinline__ void gemm_phase(PG8_LAS unsigned char* lds, const Gemm g, const Sched& S, const Epi& E, int wv) {
;     ...
;         const bool has_next = S.next(ui + 1, nxt);
;         const char* nA = has_next ? (const char*)g.A + (size_t)nxt.pm * tstep : cA; const char* nB = has_next ? (const char*)g.Bt + (size_t)nxt.pn * tstep : cB;
;         for (int t = 0; t < nt; t += 2) {
;             const bool last = (t == nt - 2);
;             const char* a1 = cA + (size_t)(t + 1) * kstep;
;             const char* a2 = last ? nA : cA + (size_t)(t + 2) * kstep; const char* b2 = last ? nB : cB + (size_t)(t + 2) * kstep;
;             const char* a3 = a2 + kstep; const char* b3 = b2 + kstep;
;             if (last && has_next) S.a_ready(nxt);
;             if constexpr (SP2) {
;             PG8_LDB(B0, 0, 0); PG8_LDB(B1, 0, 1); PG8_SCHED; PG8_LDA(At, 0, 0); PG8_STAGE(PG8_SA(1, 1), a1 + hstep, voffA);
;             PG8_WAIT_V(8); PG8_WAIT_L(0); PG8_BAR; PG8_MMA(0, 0, At, B0); PG8_MMA(0, 1, At, B1); PG8_BAR; PG8_SCHED;
;             PG8_LDA(At, 0, 1); PG8_STAGE(PG8_SB(0, 0), b2, voffB); PG8_STAGE(PG8_SB(0, 1), b2 + hstep, voffB); PG8_STAGE(PG8_SA(0, 0), a2, voffA);
;             PG8_WAIT_V(8); PG8_WAIT_L(0); PG8_BAR; PG8_MMA(1, 0, At, B0); PG8_MMA(1, 1, At, B1); PG8_BAR; PG8_SCHED;
.LBB0_767:
	s_ashr_i32 s53, s52, 31
	s_lshl_b64 s[54:55], s[52:53], 19
	s_add_u32 s54, s40, s54
	s_addc_u32 s55, s41, s55
	s_and_b64 s[56:57], s[6:7], exec
	s_cselect_b32 s53, s55, s11
	s_cselect_b32 s70, s54, s10
	s_ashr_i32 s51, s50, 31
	s_lshl_b64 s[56:57], s[50:51], 19
	s_add_u32 s56, s0, s56
	s_addc_u32 s57, s1, s57
	s_and_b64 s[58:59], s[6:7], exec
	s_cselect_b32 s51, s57, s13
	s_cselect_b32 s71, s56, s12
	s_add_u32 s10, s10, 0x40080
	s_addc_u32 s11, s11, 0
	s_add_u32 s72, s12, 0x100
	s_addc_u32 s73, s13, 0
	s_mov_b32 s74, -2
	ds_read_b128 v[172:175], v155
	ds_read_b128 v[176:179], v156
	ds_read_b128 v[180:183], v157
	ds_read_b128 v[184:187], v158
	ds_read_b128 v[188:191], v159
	ds_read_b128 v[192:195], v160
	ds_read_b128 v[196:199], v161
	ds_read_b128 v[200:203], v162
	s_add_u32 s12, s10, 0xfffc0080
	s_addc_u32 s13, s11, -1
	s_cmp_eq_u32 s74, 12
	s_cselect_b32 s59, s53, s13
	s_cselect_b32 s58, s70, s12
	s_cselect_b32 s13, s51, s73
	s_cselect_b32 s12, s71, s72
	s_mov_b32 m0, s66
	v_lshl_add_u64 v[148:149], s[10:11], 0, v[140:141]
	ds_read_b128 v[204:207], v153
	ds_read_b128 v[208:211], v153 offset:1024
	ds_read_b128 v[212:215], v153 offset:2048
	ds_read_b128 v[216:219], v153 offset:3072
	ds_read_b128 v[220:223], v153 offset:4096
	ds_read_b128 v[228:231], v153 offset:5120
	ds_read_b128 v[232:235], v153 offset:6144
	ds_read_b128 v[236:239], v153 offset:7168
	global_load_lds_dwordx4 v[148:149], off
	v_lshl_add_u64 v[148:149], s[10:11], 0, v[142:143]
	s_mov_b32 m0, s67
	s_nop 0
	global_load_lds_dwordx4 v[148:149], off
	s_waitcnt vmcnt(8)
	s_waitcnt lgkmcnt(0)
	s_barrier
	s_waitcnt lgkmcnt(0)
	v_mfma_f32_16x16x32_f16 v[124:127], v[172:175], v[204:207], 0
	v_mfma_f32_16x16x32_f16 v[116:119], v[180:183], v[204:207], 0
	v_mfma_f32_16x16x32_f16 v[108:111], v[172:175], v[212:215], 0
	v_mfma_f32_16x16x32_f16 v[104:107], v[180:183], v[212:215], 0
	v_mfma_f32_16x16x32_f16 v[92:95], v[172:175], v[220:223], 0
	v_mfma_f32_16x16x32_f16 v[88:91], v[180:183], v[220:223], 0
	v_mfma_f32_16x16x32_f16 v[76:79], v[172:175], v[232:235], 0
	v_mfma_f32_16x16x32_f16 v[72:75], v[180:183], v[232:235], 0
	v_mfma_f32_16x16x32_f16 v[124:127], v[176:179], v[208:211], v[124:127]
	v_mfma_f32_16x16x32_f16 v[116:119], v[184:187], v[208:211], v[116:119]
	v_mfma_f32_16x16x32_f16 v[108:111], v[176:179], v[216:219], v[108:111]
	v_mfma_f32_16x16x32_f16 v[104:107], v[184:187], v[216:219], v[104:107]
	v_mfma_f32_16x16x32_f16 v[92:95], v[176:179], v[228:231], v[92:95]
	v_mfma_f32_16x16x32_f16 v[88:91], v[184:187], v[228:231], v[88:91]
	v_mfma_f32_16x16x32_f16 v[76:79], v[176:179], v[236:239], v[76:79]
	v_mfma_f32_16x16x32_f16 v[72:75], v[184:187], v[236:239], v[72:75]
	v_mfma_f32_16x16x32_f16 v[120:123], v[188:191], v[204:207], 0
	v_mfma_f32_16x16x32_f16 v[112:115], v[196:199], v[204:207], 0
	v_mfma_f32_16x16x32_f16 v[100:103], v[188:191], v[212:215], 0
	v_mfma_f32_16x16x32_f16 v[96:99], v[196:199], v[212:215], 0
	v_mfma_f32_16x16x32_f16 v[84:87], v[188:191], v[220:223], 0
	v_mfma_f32_16x16x32_f16 v[80:83], v[196:199], v[220:223], 0
	v_mfma_f32_16x16x32_f16 v[68:71], v[188:191], v[232:235], 0
	v_mfma_f32_16x16x32_f16 v[64:67], v[196:199], v[232:235], 0
	v_mfma_f32_16x16x32_f16 v[120:123], v[192:195], v[208:211], v[120:123]
	v_mfma_f32_16x16x32_f16 v[112:115], v[200:203], v[208:211], v[112:115]
	v_mfma_f32_16x16x32_f16 v[100:103], v[192:195], v[216:219], v[100:103]
	v_mfma_f32_16x16x32_f16 v[96:99], v[200:203], v[216:219], v[96:99]
	v_mfma_f32_16x16x32_f16 v[84:87], v[192:195], v[228:231], v[84:87]
	v_mfma_f32_16x16x32_f16 v[80:83], v[200:203], v[228:231], v[80:83]
	v_mfma_f32_16x16x32_f16 v[68:71], v[192:195], v[236:239], v[68:71]
	v_mfma_f32_16x16x32_f16 v[64:67], v[200:203], v[236:239], v[64:67]
	s_barrier
	s_mov_b32 m0, s5
	v_lshl_add_u64 v[148:149], s[12:13], 0, v[132:133]
	s_add_u32 s76, s12, 0x40000
	ds_read_b128 v[204:207], v153 offset:16384
	ds_read_b128 v[208:211], v153 offset:17408
	ds_read_b128 v[212:215], v153 offset:18432
	ds_read_b128 v[216:219], v153 offset:19456
	ds_read_b128 v[220:223], v153 offset:20480
	ds_read_b128 v[228:231], v153 offset:21504
	ds_read_b128 v[232:235], v153 offset:22528
	ds_read_b128 v[236:239], v153 offset:23552
	global_load_lds_dwordx4 v[148:149], off
	v_lshl_add_u64 v[224:225], s[12:13], 0, v[128:129]
	s_mov_b32 m0, s21
	s_addc_u32 s77, s13, 0
	global_load_lds_dwordx4 v[224:225], off
	v_lshl_add_u64 v[240:241], s[76:77], 0, v[132:133]
	s_mov_b32 m0, s22
	v_lshl_add_u64 v[242:243], s[58:59], 0, v[130:131]
	global_load_lds_dwordx4 v[240:241], off
	v_lshl_add_u64 v[240:241], s[76:77], 0, v[128:129]
	s_mov_b32 m0, s23
	s_nop 0
	global_load_lds_dwordx4 v[240:241], off
	v_lshl_add_u64 v[240:241], s[58:59], 0, v[134:135]
	s_mov_b32 m0, s2
	s_nop 0
	global_load_lds_dwordx4 v[240:241], off
	s_mov_b32 m0, s33
	s_nop 0
	global_load_lds_dwordx4 v[242:243], off
	s_waitcnt vmcnt(8)
	s_waitcnt lgkmcnt(0)
	s_barrier
; #define PG8_STAGE(bufoff, gbase, voff) do { _Pragma("unroll") for (int _i = 0; _i < 2; ++_i) \
;         __builtin_amdgcn_global_load_lds((const unsigned*)((const char*)(gbase) + (voff)[_i]), (PG8_LAS unsigned*)(lds + (bufoff) + ldsw + _i * 8192), 16, 0, 0); } while (0)
; #define PG8_LDA(dst, b, h) do { _Pragma("unroll") for (int m = 0; m < 4; ++m) _Pragma("unroll") for (int k = 0; k < 2; ++k) dst[m][k] = *(const PG8_LAS bf16x8*)(lds + PG8_SA(b, h) + aoff + m * 2048 + k * 1024); } while (0)
; #define PG8_LDB(dst, b, h) do { _Pragma("unroll") for (int n = 0; n < 2; ++n) _Pragma("unroll") for (int k = 0; k < 2; ++k) dst[n][k] = *(const PG8_LAS bf16x8*)(lds + PG8_SB(b, h) + boff + n * 2048 + k * 1024); } while (0)
; #define PG8_MMA(ai, bj, At, Bt) do { __builtin_amdgcn_s_setprio(1); _Pragma("unroll") for (int m = 0; m < 4; ++m) _Pragma("unroll") for (int n = 0; n < 2; ++n) _Pragma("unroll") for (int k = 0; k < 2; ++k) \
;         acc[ai][bj][m][n] = mma16<F16>(Bt[n][k], At[m][k], acc[ai][bj][m][n]); __builtin_amdgcn_s_setprio(0); } while (0)
; #define PG8_WAIT_V(n) asm volatile("s_waitcnt vmcnt(" #n ")" ::: "memory")
; #define PG8_WAIT_L(n) asm volatile("s_waitcnt lgkmcnt(" #n ")" ::: "memory")
; template <class Epi, class Sched, bool ALIGN_EPI = false, bool SP2 = false, bool F16 = false, bool TOKPERM = false>
; __device__ __forceinline__ void gemm_phase(PG8_LAS unsigned char* lds, const Gemm g, const Sched& S, const Epi& E, int wv) {
;     ...
;             PG8_WAIT_V(8); PG8_WAIT_L(0); PG8_BAR; PG8_MMA(0, 0, At, B0); PG8_MMA(0, 1, At, B1); PG8_BAR; PG8_SCHED;
;             PG8_LDA(At, 0, 1); PG8_STAGE(PG8_SB(0, 0), b2, voffB); PG8_STAGE(PG8_SB(0, 1), b2 + hstep, voffB); PG8_STAGE(PG8_SA(0, 0), a2, voffA);
;             PG8_WAIT_V(8); PG8_WAIT_L(0); PG8_BAR; PG8_MMA(1, 0, At, B0); PG8_MMA(1, 1, At, B1); PG8_BAR; PG8_SCHED;
;             PG8_LDB(B0, 1, 0); PG8_LDB(B1, 1, 1); PG8_SCHED; PG8_LDA(At, 1, 0); PG8_STAGE(PG8_SA(0, 1), a2 + hstep, voffA);
;             PG8_WAIT_V(8); PG8_WAIT_L(0); PG8_BAR; PG8_MMA(0, 0, At, B0); PG8_MMA(0, 1, At, B1); PG8_BAR; PG8_SCHED;
;             PG8_LDA(At, 1, 1); PG8_STAGE(PG8_SB(1, 0), b3, voffB); PG8_STAGE(PG8_SB(1, 1), b3 + hstep, voffB); PG8_STAGE(PG8_SA(1, 0), a3, voffA);
;             PG8_WAIT_V(8); PG8_WAIT_L(0); PG8_BAR; PG8_MMA(1, 0, At, B0); PG8_MMA(1, 1, At, B1); PG8_BAR; PG8_SCHED;
	s_waitcnt lgkmcnt(0)
	v_mfma_f32_16x16x32_f16 v[60:63], v[172:175], v[204:207], 0
	v_mfma_f32_16x16x32_f16 v[56:59], v[180:183], v[204:207], 0
	v_mfma_f32_16x16x32_f16 v[44:47], v[172:175], v[212:215], 0
	v_mfma_f32_16x16x32_f16 v[40:43], v[180:183], v[212:215], 0
	v_mfma_f32_16x16x32_f16 v[28:31], v[172:175], v[220:223], 0
	v_mfma_f32_16x16x32_f16 v[24:27], v[180:183], v[220:223], 0
	v_mfma_f32_16x16x32_f16 v[12:15], v[172:175], v[232:235], 0
	v_mfma_f32_16x16x32_f16 v[8:11], v[180:183], v[232:235], 0
	v_mfma_f32_16x16x32_f16 v[60:63], v[176:179], v[208:211], v[60:63]
	v_mfma_f32_16x16x32_f16 v[56:59], v[184:187], v[208:211], v[56:59]
	v_mfma_f32_16x16x32_f16 v[44:47], v[176:179], v[216:219], v[44:47]
	v_mfma_f32_16x16x32_f16 v[40:43], v[184:187], v[216:219], v[40:43]
	v_mfma_f32_16x16x32_f16 v[28:31], v[176:179], v[228:231], v[28:31]
	v_mfma_f32_16x16x32_f16 v[24:27], v[184:187], v[228:231], v[24:27]
	v_mfma_f32_16x16x32_f16 v[12:15], v[176:179], v[236:239], v[12:15]
	v_mfma_f32_16x16x32_f16 v[8:11], v[184:187], v[236:239], v[8:11]
	v_mfma_f32_16x16x32_f16 v[52:55], v[188:191], v[204:207], 0
	v_mfma_f32_16x16x32_f16 v[48:51], v[196:199], v[204:207], 0
	v_mfma_f32_16x16x32_f16 v[36:39], v[188:191], v[212:215], 0
	v_mfma_f32_16x16x32_f16 v[32:35], v[196:199], v[212:215], 0
	v_mfma_f32_16x16x32_f16 v[20:23], v[188:191], v[220:223], 0
	v_mfma_f32_16x16x32_f16 v[16:19], v[196:199], v[220:223], 0
	v_mfma_f32_16x16x32_f16 v[4:7], v[188:191], v[232:235], 0
	v_mfma_f32_16x16x32_f16 v[0:3], v[196:199], v[232:235], 0
	v_mfma_f32_16x16x32_f16 v[52:55], v[192:195], v[208:211], v[52:55]
	v_mfma_f32_16x16x32_f16 v[48:51], v[200:203], v[208:211], v[48:51]
	v_mfma_f32_16x16x32_f16 v[36:39], v[192:195], v[216:219], v[36:39]
	v_mfma_f32_16x16x32_f16 v[32:35], v[200:203], v[216:219], v[32:35]
	v_mfma_f32_16x16x32_f16 v[20:23], v[192:195], v[228:231], v[20:23]
	v_mfma_f32_16x16x32_f16 v[16:19], v[200:203], v[228:231], v[16:19]
	v_mfma_f32_16x16x32_f16 v[4:7], v[192:195], v[236:239], v[4:7]
	v_mfma_f32_16x16x32_f16 v[0:3], v[200:203], v[236:239], v[0:3]
	s_barrier
	ds_read_b128 v[172:175], v163
	ds_read_b128 v[176:179], v164
	ds_read_b128 v[180:183], v165
	ds_read_b128 v[184:187], v166
	ds_read_b128 v[188:191], v167
	ds_read_b128 v[192:195], v168
	ds_read_b128 v[196:199], v169
	ds_read_b128 v[200:203], v170
	s_add_u32 s58, s58, 0x40000
	s_addc_u32 s59, s59, 0
	s_mov_b32 m0, s36
	v_lshl_add_u64 v[244:245], s[58:59], 0, v[134:135]
	ds_read_b128 v[204:207], v153 offset:32768
	ds_read_b128 v[208:211], v153 offset:33792
	ds_read_b128 v[212:215], v153 offset:34816
	ds_read_b128 v[216:219], v153 offset:35840
	ds_read_b128 v[220:223], v153 offset:36864
	ds_read_b128 v[228:231], v153 offset:37888
	ds_read_b128 v[232:235], v153 offset:38912
	ds_read_b128 v[236:239], v153 offset:39936
	global_load_lds_dwordx4 v[244:245], off
	v_lshl_add_u64 v[244:245], s[58:59], 0, v[130:131]
	s_mov_b32 m0, s37
	s_nop 0
	global_load_lds_dwordx4 v[244:245], off
	s_waitcnt vmcnt(8)
	s_waitcnt lgkmcnt(0)
	s_barrier
	s_waitcnt lgkmcnt(0)
	v_mfma_f32_16x16x32_f16 v[124:127], v[172:175], v[204:207], v[124:127]
	v_mfma_f32_16x16x32_f16 v[116:119], v[180:183], v[204:207], v[116:119]
	v_mfma_f32_16x16x32_f16 v[108:111], v[172:175], v[212:215], v[108:111]
	v_mfma_f32_16x16x32_f16 v[104:107], v[180:183], v[212:215], v[104:107]
	v_mfma_f32_16x16x32_f16 v[92:95], v[172:175], v[220:223], v[92:95]
	v_mfma_f32_16x16x32_f16 v[88:91], v[180:183], v[220:223], v[88:91]
	v_mfma_f32_16x16x32_f16 v[76:79], v[172:175], v[232:235], v[76:79]
	v_mfma_f32_16x16x32_f16 v[72:75], v[180:183], v[232:235], v[72:75]
	v_mfma_f32_16x16x32_f16 v[124:127], v[176:179], v[208:211], v[124:127]
	v_mfma_f32_16x16x32_f16 v[116:119], v[184:187], v[208:211], v[116:119]
	v_mfma_f32_16x16x32_f16 v[108:111], v[176:179], v[216:219], v[108:111]
	v_mfma_f32_16x16x32_f16 v[104:107], v[184:187], v[216:219], v[104:107]
	v_mfma_f32_16x16x32_f16 v[92:95], v[176:179], v[228:231], v[92:95]
	v_mfma_f32_16x16x32_f16 v[88:91], v[184:187], v[228:231], v[88:91]
	v_mfma_f32_16x16x32_f16 v[76:79], v[176:179], v[236:239], v[76:79]
	v_mfma_f32_16x16x32_f16 v[72:75], v[184:187], v[236:239], v[72:75]
	v_mfma_f32_16x16x32_f16 v[120:123], v[188:191], v[204:207], v[120:123]
	v_mfma_f32_16x16x32_f16 v[112:115], v[196:199], v[204:207], v[112:115]
	v_mfma_f32_16x16x32_f16 v[100:103], v[188:191], v[212:215], v[100:103]
	v_mfma_f32_16x16x32_f16 v[96:99], v[196:199], v[212:215], v[96:99]
	v_mfma_f32_16x16x32_f16 v[84:87], v[188:191], v[220:223], v[84:87]
	v_mfma_f32_16x16x32_f16 v[80:83], v[196:199], v[220:223], v[80:83]
	v_mfma_f32_16x16x32_f16 v[68:71], v[188:191], v[232:235], v[68:71]
	v_mfma_f32_16x16x32_f16 v[64:67], v[196:199], v[232:235], v[64:67]
	v_mfma_f32_16x16x32_f16 v[120:123], v[192:195], v[208:211], v[120:123]
	v_mfma_f32_16x16x32_f16 v[112:115], v[200:203], v[208:211], v[112:115]
	v_mfma_f32_16x16x32_f16 v[100:103], v[192:195], v[216:219], v[100:103]
	v_mfma_f32_16x16x32_f16 v[96:99], v[200:203], v[216:219], v[96:99]
	v_mfma_f32_16x16x32_f16 v[84:87], v[192:195], v[228:231], v[84:87]
	v_mfma_f32_16x16x32_f16 v[80:83], v[200:203], v[228:231], v[80:83]
	v_mfma_f32_16x16x32_f16 v[68:71], v[192:195], v[236:239], v[68:71]
	v_mfma_f32_16x16x32_f16 v[64:67], v[200:203], v[236:239], v[64:67]
	s_barrier
; #define PG8_STAGE(bufoff, gbase, voff) do { _Pragma("unroll") for (int _i = 0; _i < 2; ++_i) \
;         __builtin_amdgcn_global_load_lds((const unsigned*)((const char*)(gbase) + (voff)[_i]), (PG8_LAS unsigned*)(lds + (bufoff) + ldsw + _i * 8192), 16, 0, 0); } while (0)
; #define PG8_LDA(dst, b, h) do { _Pragma("unroll") for (int m = 0; m < 4; ++m) _Pragma("unroll") for (int k = 0; k < 2; ++k) dst[m][k] = *(const PG8_LAS bf16x8*)(lds + PG8_SA(b, h) + aoff + m * 2048 + k * 1024); } while (0)
; #define PG8_LDB(dst, b, h) do { _Pragma("unroll") for (int n = 0; n < 2; ++n) _Pragma("unroll") for (int k = 0; k < 2; ++k) dst[n][k] = *(const PG8_LAS bf16x8*)(lds + PG8_SB(b, h) + boff + n * 2048 + k * 1024); } while (0)
; #define PG8_MMA(ai, bj, At, Bt) do { __builtin_amdgcn_s_setprio(1); _Pragma("unroll") for (int m = 0; m < 4; ++m) _Pragma("unroll") for (int n = 0; n < 2; ++n) _Pragma("unroll") for (int k = 0; k < 2; ++k) \
;         acc[ai][bj][m][n] = mma16<F16>(Bt[n][k], At[m][k], acc[ai][bj][m][n]); __builtin_amdgcn_s_setprio(0); } while (0)
; #define PG8_BAR __builtin_amdgcn_s_barrier()
; template <class Epi, class Sched, bool ALIGN_EPI = false, bool SP2 = false, bool F16 = false, bool TOKPERM = false>
; __device__ __forceinline__ void gemm_phase(PG8_LAS unsigned char* lds, const Gemm g, const Sched& S, const Epi& E, int wv) {
;     ...
;             PG8_LDB(B0, 0, 0); PG8_LDB(B1, 0, 1); PG8_SCHED; PG8_LDA(At, 0, 0); PG8_STAGE(PG8_SA(1, 1), a1 + hstep, voffA);
;             PG8_WAIT_V(8); PG8_WAIT_L(0); PG8_BAR; PG8_MMA(0, 0, At, B0); PG8_MMA(0, 1, At, B1); PG8_BAR; PG8_SCHED;
;             PG8_LDA(At, 0, 1); PG8_STAGE(PG8_SB(0, 0), b2, voffB); PG8_STAGE(PG8_SB(0, 1), b2 + hstep, voffB); PG8_STAGE(PG8_SA(0, 0), a2, voffA);
;             PG8_WAIT_V(8); PG8_WAIT_L(0); PG8_BAR; PG8_MMA(1, 0, At, B0); PG8_MMA(1, 1, At, B1); PG8_BAR; PG8_SCHED;
;             PG8_LDB(B0, 1, 0); PG8_LDB(B1, 1, 1); PG8_SCHED; PG8_LDA(At, 1, 0); PG8_STAGE(PG8_SA(0, 1), a2 + hstep, voffA);
;             PG8_WAIT_V(8); PG8_WAIT_L(0); PG8_BAR; PG8_MMA(0, 0, At, B0); PG8_MMA(0, 1, At, B1); PG8_BAR; PG8_SCHED;
;             PG8_LDA(At, 1, 1); PG8_STAGE(PG8_SB(1, 0), b3, voffB); PG8_STAGE(PG8_SB(1, 1), b3 + hstep, voffB); PG8_STAGE(PG8_SA(1, 0), a3, voffA);
;             PG8_WAIT_V(8); PG8_WAIT_L(0); PG8_BAR; PG8_MMA(1, 0, At, B0); PG8_MMA(1, 1, At, B1); PG8_BAR; PG8_SCHED;
	s_mov_b32 m0, s45
	v_lshl_add_u64 v[148:149], v[148:149], 0, s[16:17]
	s_add_u32 s12, s12, 0x40080
	ds_read_b128 v[204:207], v153 offset:49152
	ds_read_b128 v[208:211], v153 offset:50176
	ds_read_b128 v[212:215], v153 offset:51200
	ds_read_b128 v[216:219], v153 offset:52224
	ds_read_b128 v[220:223], v153 offset:53248
	ds_read_b128 v[228:231], v153 offset:54272
	ds_read_b128 v[232:235], v153 offset:55296
	ds_read_b128 v[236:239], v153 offset:56320
	global_load_lds_dwordx4 v[148:149], off
	v_lshl_add_u64 v[148:149], v[224:225], 0, s[16:17]
	s_mov_b32 m0, s49
	s_addc_u32 s13, s13, 0
	global_load_lds_dwordx4 v[148:149], off
	v_lshl_add_u64 v[148:149], s[12:13], 0, v[132:133]
	s_mov_b32 m0, s62
	s_nop 0
	global_load_lds_dwordx4 v[148:149], off
	v_lshl_add_u64 v[148:149], s[12:13], 0, v[128:129]
	s_mov_b32 m0, s63
	s_nop 0
	global_load_lds_dwordx4 v[148:149], off
	v_lshl_add_u64 v[148:149], v[240:241], 0, s[16:17]
	s_mov_b32 m0, s60
	s_nop 0
	global_load_lds_dwordx4 v[148:149], off
	v_lshl_add_u64 v[148:149], v[242:243], 0, s[16:17]
	s_mov_b32 m0, s61
	s_nop 0
	global_load_lds_dwordx4 v[148:149], off
	s_waitcnt vmcnt(8)
	s_waitcnt lgkmcnt(0)
	s_barrier
	s_waitcnt lgkmcnt(0)
	v_mfma_f32_16x16x32_f16 v[60:63], v[172:175], v[204:207], v[60:63]
	v_mfma_f32_16x16x32_f16 v[56:59], v[180:183], v[204:207], v[56:59]
	v_mfma_f32_16x16x32_f16 v[44:47], v[172:175], v[212:215], v[44:47]
	v_mfma_f32_16x16x32_f16 v[40:43], v[180:183], v[212:215], v[40:43]
	v_mfma_f32_16x16x32_f16 v[28:31], v[172:175], v[220:223], v[28:31]
	v_mfma_f32_16x16x32_f16 v[24:27], v[180:183], v[220:223], v[24:27]
	v_mfma_f32_16x16x32_f16 v[12:15], v[172:175], v[232:235], v[12:15]
	v_mfma_f32_16x16x32_f16 v[8:11], v[180:183], v[232:235], v[8:11]
	v_mfma_f32_16x16x32_f16 v[60:63], v[176:179], v[208:211], v[60:63]
	v_mfma_f32_16x16x32_f16 v[56:59], v[184:187], v[208:211], v[56:59]
	v_mfma_f32_16x16x32_f16 v[44:47], v[176:179], v[216:219], v[44:47]
	v_mfma_f32_16x16x32_f16 v[40:43], v[184:187], v[216:219], v[40:43]
	v_mfma_f32_16x16x32_f16 v[28:31], v[176:179], v[228:231], v[28:31]
	v_mfma_f32_16x16x32_f16 v[24:27], v[184:187], v[228:231], v[24:27]
	v_mfma_f32_16x16x32_f16 v[12:15], v[176:179], v[236:239], v[12:15]
	v_mfma_f32_16x16x32_f16 v[8:11], v[184:187], v[236:239], v[8:11]
	v_mfma_f32_16x16x32_f16 v[52:55], v[188:191], v[204:207], v[52:55]
	v_mfma_f32_16x16x32_f16 v[48:51], v[196:199], v[204:207], v[48:51]
	v_mfma_f32_16x16x32_f16 v[36:39], v[188:191], v[212:215], v[36:39]
	v_mfma_f32_16x16x32_f16 v[32:35], v[196:199], v[212:215], v[32:35]
	v_mfma_f32_16x16x32_f16 v[20:23], v[188:191], v[220:223], v[20:23]
	v_mfma_f32_16x16x32_f16 v[16:19], v[196:199], v[220:223], v[16:19]
	v_mfma_f32_16x16x32_f16 v[4:7], v[188:191], v[232:235], v[4:7]
	v_mfma_f32_16x16x32_f16 v[0:3], v[196:199], v[232:235], v[0:3]
	v_mfma_f32_16x16x32_f16 v[52:55], v[192:195], v[208:211], v[52:55]
	v_mfma_f32_16x16x32_f16 v[48:51], v[200:203], v[208:211], v[48:51]
	v_mfma_f32_16x16x32_f16 v[36:39], v[192:195], v[216:219], v[36:39]
	v_mfma_f32_16x16x32_f16 v[32:35], v[200:203], v[216:219], v[32:35]
	v_mfma_f32_16x16x32_f16 v[20:23], v[192:195], v[228:231], v[20:23]
	v_mfma_f32_16x16x32_f16 v[16:19], v[200:203], v[228:231], v[16:19]
	v_mfma_f32_16x16x32_f16 v[4:7], v[192:195], v[236:239], v[4:7]
	v_mfma_f32_16x16x32_f16 v[0:3], v[200:203], v[236:239], v[0:3]
	s_barrier
	s_add_i32 s74, s74, 2
	s_add_u32 s10, s10, 0x100
	s_addc_u32 s11, s11, 0
	s_add_u32 s72, s72, 0x100
	s_addc_u32 s73, s73, 0
	s_cmp_gt_u32 s74, 13
.LBB0_768:
	ds_read_b128 v[172:175], v155
	ds_read_b128 v[176:179], v156
	ds_read_b128 v[180:183], v157
	ds_read_b128 v[184:187], v158
	ds_read_b128 v[188:191], v159
	ds_read_b128 v[192:195], v160
	ds_read_b128 v[196:199], v161
	ds_read_b128 v[200:203], v162
	s_add_u32 s12, s10, 0xfffc0080
	s_addc_u32 s13, s11, -1
	s_cmp_eq_u32 s74, 12
	s_cselect_b32 s59, s53, s13
	s_cselect_b32 s58, s70, s12
	s_cselect_b32 s13, s51, s73
	s_cselect_b32 s12, s71, s72
	s_mov_b32 m0, s66
	v_lshl_add_u64 v[148:149], s[10:11], 0, v[140:141]
	ds_read_b128 v[204:207], v153
	ds_read_b128 v[208:211], v153 offset:1024
	ds_read_b128 v[212:215], v153 offset:2048
	ds_read_b128 v[216:219], v153 offset:3072
	ds_read_b128 v[220:223], v153 offset:4096
	ds_read_b128 v[228:231], v153 offset:5120
	ds_read_b128 v[232:235], v153 offset:6144
	ds_read_b128 v[236:239], v153 offset:7168
	global_load_lds_dwordx4 v[148:149], off
	v_lshl_add_u64 v[148:149], s[10:11], 0, v[142:143]
	s_mov_b32 m0, s67
	s_nop 0
	global_load_lds_dwordx4 v[148:149], off
	s_waitcnt vmcnt(8)
	s_waitcnt lgkmcnt(0)
	s_barrier
; #define PG8_STAGE(bufoff, gbase, voff) do { _Pragma("unroll") for (int _i = 0; _i < 2; ++_i) \
;         __builtin_amdgcn_global_load_lds((const unsigned*)((const char*)(gbase) + (voff)[_i]), (PG8_LAS unsigned*)(lds + (bufoff) + ldsw + _i * 8192), 16, 0, 0); } while (0)
; #define PG8_LDA(dst, b, h) do { _Pragma("unroll") for (int m = 0; m < 4; ++m) _Pragma("unroll") for (int k = 0; k < 2; ++k) dst[m][k] = *(const PG8_LAS bf16x8*)(lds + PG8_SA(b, h) + aoff + m * 2048 + k * 1024); } while (0)
; #define PG8_LDB(dst, b, h) do { _Pragma("unroll") for (int n = 0; n < 2; ++n) _Pragma("unroll") for (int k = 0; k < 2; ++k) dst[n][k] = *(const PG8_LAS bf16x8*)(lds + PG8_SB(b, h) + boff + n * 2048 + k * 1024); } while (0)
; #define PG8_MMA(ai, bj, At, Bt) do { __builtin_amdgcn_s_setprio(1); _Pragma("unroll") for (int m = 0; m < 4; ++m) _Pragma("unroll") for (int n = 0; n < 2; ++n) _Pragma("unroll") for (int k = 0; k < 2; ++k) \
;         acc[ai][bj][m][n] = mma16<F16>(Bt[n][k], At[m][k], acc[ai][bj][m][n]); __builtin_amdgcn_s_setprio(0); } while (0)
; #define PG8_WAIT_V(n) asm volatile("s_waitcnt vmcnt(" #n ")" ::: "memory")
; #define PG8_WAIT_L(n) asm volatile("s_waitcnt lgkmcnt(" #n ")" ::: "memory")
; #define PG8_BAR __builtin_amdgcn_s_barrier()
; #define PG8_SCHED __builtin_amdgcn_sched_barrier(0)
; template <class Epi, class Sched, bool ALIGN_EPI = false, bool SP2 = false, bool F16 = false, bool TOKPERM = false>
; __device__ __forceinline__ void gemm_phase(PG8_LAS unsigned char* lds, const Gemm g, const Sched& S, const Epi& E, int wv) {
;     ...
;             PG8_LDB(B0, 0, 0); PG8_LDB(B1, 0, 1); PG8_SCHED; PG8_LDA(At, 0, 0); PG8_STAGE(PG8_SA(1, 1), a1 + hstep, voffA);
;             PG8_WAIT_V(8); PG8_WAIT_L(0); PG8_BAR; PG8_MMA(0, 0, At, B0); PG8_MMA(0, 1, At, B1); PG8_BAR; PG8_SCHED;
;             PG8_LDA(At, 0, 1); PG8_STAGE(PG8_SB(0, 0), b2, voffB); PG8_STAGE(PG8_SB(0, 1), b2 + hstep, voffB); PG8_STAGE(PG8_SA(0, 0), a2, voffA);
;             PG8_WAIT_V(8); PG8_WAIT_L(0); PG8_BAR; PG8_MMA(1, 0, At, B0); PG8_MMA(1, 1, At, B1); PG8_BAR; PG8_SCHED;
	s_waitcnt lgkmcnt(0)
	v_mfma_f32_16x16x32_f16 v[124:127], v[172:175], v[204:207], v[124:127]
	v_mfma_f32_16x16x32_f16 v[116:119], v[180:183], v[204:207], v[116:119]
	v_mfma_f32_16x16x32_f16 v[108:111], v[172:175], v[212:215], v[108:111]
	v_mfma_f32_16x16x32_f16 v[104:107], v[180:183], v[212:215], v[104:107]
	v_mfma_f32_16x16x32_f16 v[92:95], v[172:175], v[220:223], v[92:95]
	v_mfma_f32_16x16x32_f16 v[88:91], v[180:183], v[220:223], v[88:91]
	v_mfma_f32_16x16x32_f16 v[76:79], v[172:175], v[232:235], v[76:79]
	v_mfma_f32_16x16x32_f16 v[72:75], v[180:183], v[232:235], v[72:75]
	v_mfma_f32_16x16x32_f16 v[124:127], v[176:179], v[208:211], v[124:127]
	v_mfma_f32_16x16x32_f16 v[116:119], v[184:187], v[208:211], v[116:119]
	v_mfma_f32_16x16x32_f16 v[108:111], v[176:179], v[216:219], v[108:111]
	v_mfma_f32_16x16x32_f16 v[104:107], v[184:187], v[216:219], v[104:107]
	v_mfma_f32_16x16x32_f16 v[92:95], v[176:179], v[228:231], v[92:95]
	v_mfma_f32_16x16x32_f16 v[88:91], v[184:187], v[228:231], v[88:91]
	v_mfma_f32_16x16x32_f16 v[76:79], v[176:179], v[236:239], v[76:79]
	v_mfma_f32_16x16x32_f16 v[72:75], v[184:187], v[236:239], v[72:75]
	v_mfma_f32_16x16x32_f16 v[120:123], v[188:191], v[204:207], v[120:123]
	v_mfma_f32_16x16x32_f16 v[112:115], v[196:199], v[204:207], v[112:115]
	v_mfma_f32_16x16x32_f16 v[100:103], v[188:191], v[212:215], v[100:103]
	v_mfma_f32_16x16x32_f16 v[96:99], v[196:199], v[212:215], v[96:99]
	v_mfma_f32_16x16x32_f16 v[84:87], v[188:191], v[220:223], v[84:87]
	v_mfma_f32_16x16x32_f16 v[80:83], v[196:199], v[220:223], v[80:83]
	v_mfma_f32_16x16x32_f16 v[68:71], v[188:191], v[232:235], v[68:71]
	v_mfma_f32_16x16x32_f16 v[64:67], v[196:199], v[232:235], v[64:67]
	v_mfma_f32_16x16x32_f16 v[120:123], v[192:195], v[208:211], v[120:123]
	v_mfma_f32_16x16x32_f16 v[112:115], v[200:203], v[208:211], v[112:115]
	v_mfma_f32_16x16x32_f16 v[100:103], v[192:195], v[216:219], v[100:103]
	v_mfma_f32_16x16x32_f16 v[96:99], v[200:203], v[216:219], v[96:99]
	v_mfma_f32_16x16x32_f16 v[84:87], v[192:195], v[228:231], v[84:87]
	v_mfma_f32_16x16x32_f16 v[80:83], v[200:203], v[228:231], v[80:83]
	v_mfma_f32_16x16x32_f16 v[68:71], v[192:195], v[236:239], v[68:71]
	v_mfma_f32_16x16x32_f16 v[64:67], v[200:203], v[236:239], v[64:67]
	s_barrier
	s_mov_b32 m0, s5
	v_lshl_add_u64 v[148:149], s[12:13], 0, v[132:133]
	s_add_u32 s76, s12, 0x40000
	ds_read_b128 v[204:207], v153 offset:16384
	ds_read_b128 v[208:211], v153 offset:17408
	ds_read_b128 v[212:215], v153 offset:18432
	ds_read_b128 v[216:219], v153 offset:19456
	ds_read_b128 v[220:223], v153 offset:20480
	ds_read_b128 v[228:231], v153 offset:21504
	ds_read_b128 v[232:235], v153 offset:22528
	ds_read_b128 v[236:239], v153 offset:23552
	global_load_lds_dwordx4 v[148:149], off
	v_lshl_add_u64 v[224:225], s[12:13], 0, v[128:129]
	s_mov_b32 m0, s21
	s_addc_u32 s77, s13, 0
	global_load_lds_dwordx4 v[224:225], off
	v_lshl_add_u64 v[240:241], s[76:77], 0, v[132:133]
	s_mov_b32 m0, s22
	v_lshl_add_u64 v[242:243], s[58:59], 0, v[130:131]
	global_load_lds_dwordx4 v[240:241], off
	v_lshl_add_u64 v[240:241], s[76:77], 0, v[128:129]
	s_mov_b32 m0, s23
	s_nop 0
	global_load_lds_dwordx4 v[240:241], off
	v_lshl_add_u64 v[240:241], s[58:59], 0, v[134:135]
	s_mov_b32 m0, s2
	s_nop 0
	global_load_lds_dwordx4 v[240:241], off
	s_mov_b32 m0, s33
	s_nop 0
	global_load_lds_dwordx4 v[242:243], off
	s_waitcnt vmcnt(8)
	s_waitcnt lgkmcnt(0)
	s_barrier
	s_waitcnt lgkmcnt(0)
	v_mfma_f32_16x16x32_f16 v[60:63], v[172:175], v[204:207], v[60:63]
	v_mfma_f32_16x16x32_f16 v[56:59], v[180:183], v[204:207], v[56:59]
	v_mfma_f32_16x16x32_f16 v[44:47], v[172:175], v[212:215], v[44:47]
	v_mfma_f32_16x16x32_f16 v[40:43], v[180:183], v[212:215], v[40:43]
	v_mfma_f32_16x16x32_f16 v[28:31], v[172:175], v[220:223], v[28:31]
	v_mfma_f32_16x16x32_f16 v[24:27], v[180:183], v[220:223], v[24:27]
	v_mfma_f32_16x16x32_f16 v[12:15], v[172:175], v[232:235], v[12:15]
	v_mfma_f32_16x16x32_f16 v[8:11], v[180:183], v[232:235], v[8:11]
	v_mfma_f32_16x16x32_f16 v[60:63], v[176:179], v[208:211], v[60:63]
	v_mfma_f32_16x16x32_f16 v[56:59], v[184:187], v[208:211], v[56:59]
	v_mfma_f32_16x16x32_f16 v[44:47], v[176:179], v[216:219], v[44:47]
	v_mfma_f32_16x16x32_f16 v[40:43], v[184:187], v[216:219], v[40:43]
	v_mfma_f32_16x16x32_f16 v[28:31], v[176:179], v[228:231], v[28:31]
	v_mfma_f32_16x16x32_f16 v[24:27], v[184:187], v[228:231], v[24:27]
	v_mfma_f32_16x16x32_f16 v[12:15], v[176:179], v[236:239], v[12:15]
	v_mfma_f32_16x16x32_f16 v[8:11], v[184:187], v[236:239], v[8:11]
	v_mfma_f32_16x16x32_f16 v[52:55], v[188:191], v[204:207], v[52:55]
	v_mfma_f32_16x16x32_f16 v[48:51], v[196:199], v[204:207], v[48:51]
	v_mfma_f32_16x16x32_f16 v[36:39], v[188:191], v[212:215], v[36:39]
	v_mfma_f32_16x16x32_f16 v[32:35], v[196:199], v[212:215], v[32:35]
	v_mfma_f32_16x16x32_f16 v[20:23], v[188:191], v[220:223], v[20:23]
	v_mfma_f32_16x16x32_f16 v[16:19], v[196:199], v[220:223], v[16:19]
	v_mfma_f32_16x16x32_f16 v[4:7], v[188:191], v[232:235], v[4:7]
	v_mfma_f32_16x16x32_f16 v[0:3], v[196:199], v[232:235], v[0:3]
	v_mfma_f32_16x16x32_f16 v[52:55], v[192:195], v[208:211], v[52:55]
	v_mfma_f32_16x16x32_f16 v[48:51], v[200:203], v[208:211], v[48:51]
	v_mfma_f32_16x16x32_f16 v[36:39], v[192:195], v[216:219], v[36:39]
	v_mfma_f32_16x16x32_f16 v[32:35], v[200:203], v[216:219], v[32:35]
	v_mfma_f32_16x16x32_f16 v[20:23], v[192:195], v[228:231], v[20:23]
	v_mfma_f32_16x16x32_f16 v[16:19], v[200:203], v[228:231], v[16:19]
	v_mfma_f32_16x16x32_f16 v[4:7], v[192:195], v[236:239], v[4:7]
	v_mfma_f32_16x16x32_f16 v[0:3], v[200:203], v[236:239], v[0:3]
	s_barrier
; #define PG8_STAGE(bufoff, gbase, voff) do { _Pragma("unroll") for (int _i = 0; _i < 2; ++_i) \
;         __builtin_amdgcn_global_load_lds((const unsigned*)((const char*)(gbase) + (voff)[_i]), (PG8_LAS unsigned*)(lds + (bufoff) + ldsw + _i * 8192), 16, 0, 0); } while (0)
; #define PG8_LDA(dst, b, h) do { _Pragma("unroll") for (int m = 0; m < 4; ++m) _Pragma("unroll") for (int k = 0; k < 2; ++k) dst[m][k] = *(const PG8_LAS bf16x8*)(lds + PG8_SA(b, h) + aoff + m * 2048 + k * 1024); } while (0)
; #define PG8_LDB(dst, b, h) do { _Pragma("unroll") for (int n = 0; n < 2; ++n) _Pragma("unroll") for (int k = 0; k < 2; ++k) dst[n][k] = *(const PG8_LAS bf16x8*)(lds + PG8_SB(b, h) + boff + n * 2048 + k * 1024); } while (0)
; #define PG8_MMA(ai, bj, At, Bt) do { __builtin_amdgcn_s_setprio(1); _Pragma("unroll") for (int m = 0; m < 4; ++m) _Pragma("unroll") for (int n = 0; n < 2; ++n) _Pragma("unroll") for (int k = 0; k < 2; ++k) \
;         acc[ai][bj][m][n] = mma16<F16>(Bt[n][k], At[m][k], acc[ai][bj][m][n]); __builtin_amdgcn_s_setprio(0); } while (0)
; #define PG8_WAIT_V(n) asm volatile("s_waitcnt vmcnt(" #n ")" ::: "memory")
; #define PG8_WAIT_L(n) asm volatile("s_waitcnt lgkmcnt(" #n ")" ::: "memory")
; #define PG8_BAR __builtin_amdgcn_s_barrier()
; #define PG8_SCHED __builtin_amdgcn_sched_barrier(0)
; template <class Epi, class Sched, bool ALIGN_EPI = false, bool SP2 = false, bool F16 = false, bool TOKPERM = false>
; __device__ __forceinline__ void gemm_phase(PG8_LAS unsigned char* lds, const Gemm g, const Sched& S, const Epi& E, int wv) {
;     ...
;             PG8_LDB(B0, 1, 0); PG8_LDB(B1, 1, 1); PG8_SCHED; PG8_LDA(At, 1, 0); PG8_STAGE(PG8_SA(0, 1), a2 + hstep, voffA);
;             PG8_WAIT_V(8); PG8_WAIT_L(0); PG8_BAR; PG8_MMA(0, 0, At, B0); PG8_MMA(0, 1, At, B1); PG8_BAR; PG8_SCHED;
;             PG8_LDA(At, 1, 1); PG8_STAGE(PG8_SB(1, 0), b3, voffB); PG8_STAGE(PG8_SB(1, 1), b3 + hstep, voffB); PG8_STAGE(PG8_SA(1, 0), a3, voffA);
;             PG8_WAIT_V(8); PG8_WAIT_L(0); PG8_BAR; PG8_MMA(1, 0, At, B0); PG8_MMA(1, 1, At, B1); PG8_BAR; PG8_SCHED;
;     ...
;         if constexpr (ALIGN_EPI) { if (wr == 0) PG8_BAR; }
	ds_read_b128 v[172:175], v163
	ds_read_b128 v[176:179], v164
	ds_read_b128 v[180:183], v165
	ds_read_b128 v[184:187], v166
	ds_read_b128 v[188:191], v167
	ds_read_b128 v[192:195], v168
	ds_read_b128 v[196:199], v169
	ds_read_b128 v[200:203], v170
	s_add_u32 s58, s58, 0x40000
	s_addc_u32 s59, s59, 0
	s_mov_b32 m0, s36
	v_lshl_add_u64 v[244:245], s[58:59], 0, v[134:135]
	ds_read_b128 v[204:207], v153 offset:32768
	ds_read_b128 v[208:211], v153 offset:33792
	ds_read_b128 v[212:215], v153 offset:34816
	ds_read_b128 v[216:219], v153 offset:35840
	ds_read_b128 v[220:223], v153 offset:36864
	ds_read_b128 v[228:231], v153 offset:37888
	ds_read_b128 v[232:235], v153 offset:38912
	ds_read_b128 v[236:239], v153 offset:39936
	global_load_lds_dwordx4 v[244:245], off
	v_lshl_add_u64 v[244:245], s[58:59], 0, v[130:131]
	s_mov_b32 m0, s37
	s_nop 0
	global_load_lds_dwordx4 v[244:245], off
	s_waitcnt vmcnt(8)
	s_waitcnt lgkmcnt(0)
	s_barrier
	s_waitcnt lgkmcnt(0)
	v_mfma_f32_16x16x32_f16 v[124:127], v[172:175], v[204:207], v[124:127]
	v_mfma_f32_16x16x32_f16 v[116:119], v[180:183], v[204:207], v[116:119]
	v_mfma_f32_16x16x32_f16 v[108:111], v[172:175], v[212:215], v[108:111]
	v_mfma_f32_16x16x32_f16 v[104:107], v[180:183], v[212:215], v[104:107]
	v_mfma_f32_16x16x32_f16 v[92:95], v[172:175], v[220:223], v[92:95]
	v_mfma_f32_16x16x32_f16 v[88:91], v[180:183], v[220:223], v[88:91]
	v_mfma_f32_16x16x32_f16 v[76:79], v[172:175], v[232:235], v[76:79]
	v_mfma_f32_16x16x32_f16 v[72:75], v[180:183], v[232:235], v[72:75]
	v_mfma_f32_16x16x32_f16 v[124:127], v[176:179], v[208:211], v[124:127]
	v_mfma_f32_16x16x32_f16 v[116:119], v[184:187], v[208:211], v[116:119]
	v_mfma_f32_16x16x32_f16 v[108:111], v[176:179], v[216:219], v[108:111]
	v_mfma_f32_16x16x32_f16 v[104:107], v[184:187], v[216:219], v[104:107]
	v_mfma_f32_16x16x32_f16 v[92:95], v[176:179], v[228:231], v[92:95]
	v_mfma_f32_16x16x32_f16 v[88:91], v[184:187], v[228:231], v[88:91]
	v_mfma_f32_16x16x32_f16 v[76:79], v[176:179], v[236:239], v[76:79]
	v_mfma_f32_16x16x32_f16 v[72:75], v[184:187], v[236:239], v[72:75]
	v_mfma_f32_16x16x32_f16 v[120:123], v[188:191], v[204:207], v[120:123]
	v_mfma_f32_16x16x32_f16 v[112:115], v[196:199], v[204:207], v[112:115]
	v_mfma_f32_16x16x32_f16 v[100:103], v[188:191], v[212:215], v[100:103]
	v_mfma_f32_16x16x32_f16 v[96:99], v[196:199], v[212:215], v[96:99]
	v_mfma_f32_16x16x32_f16 v[84:87], v[188:191], v[220:223], v[84:87]
	v_mfma_f32_16x16x32_f16 v[80:83], v[196:199], v[220:223], v[80:83]
	v_mfma_f32_16x16x32_f16 v[68:71], v[188:191], v[232:235], v[68:71]
	v_mfma_f32_16x16x32_f16 v[64:67], v[196:199], v[232:235], v[64:67]
	v_mfma_f32_16x16x32_f16 v[120:123], v[192:195], v[208:211], v[120:123]
	v_mfma_f32_16x16x32_f16 v[112:115], v[200:203], v[208:211], v[112:115]
	v_mfma_f32_16x16x32_f16 v[100:103], v[192:195], v[216:219], v[100:103]
	v_mfma_f32_16x16x32_f16 v[96:99], v[200:203], v[216:219], v[96:99]
	v_mfma_f32_16x16x32_f16 v[84:87], v[192:195], v[228:231], v[84:87]
	v_mfma_f32_16x16x32_f16 v[80:83], v[200:203], v[228:231], v[80:83]
	v_mfma_f32_16x16x32_f16 v[68:71], v[192:195], v[236:239], v[68:71]
	v_mfma_f32_16x16x32_f16 v[64:67], v[200:203], v[236:239], v[64:67]
	s_barrier
	s_mov_b32 m0, s45
	v_lshl_add_u64 v[148:149], v[148:149], 0, s[16:17]
	s_add_u32 s12, s12, 0x40080
	ds_read_b128 v[204:207], v153 offset:49152
	ds_read_b128 v[208:211], v153 offset:50176
	ds_read_b128 v[212:215], v153 offset:51200
	ds_read_b128 v[216:219], v153 offset:52224
	ds_read_b128 v[220:223], v153 offset:53248
	ds_read_b128 v[228:231], v153 offset:54272
	ds_read_b128 v[232:235], v153 offset:55296
	ds_read_b128 v[236:239], v153 offset:56320
	global_load_lds_dwordx4 v[148:149], off
	v_lshl_add_u64 v[148:149], v[224:225], 0, s[16:17]
	s_mov_b32 m0, s49
	s_addc_u32 s13, s13, 0
	global_load_lds_dwordx4 v[148:149], off
	v_lshl_add_u64 v[148:149], s[12:13], 0, v[132:133]
	s_mov_b32 m0, s62
	s_nop 0
	global_load_lds_dwordx4 v[148:149], off
	v_lshl_add_u64 v[148:149], s[12:13], 0, v[128:129]
	s_mov_b32 m0, s63
	s_nop 0
	global_load_lds_dwordx4 v[148:149], off
	v_lshl_add_u64 v[148:149], v[240:241], 0, s[16:17]
	s_mov_b32 m0, s60
	s_nop 0
	global_load_lds_dwordx4 v[148:149], off
	v_lshl_add_u64 v[148:149], v[242:243], 0, s[16:17]
	s_mov_b32 m0, s61
	s_nop 0
	global_load_lds_dwordx4 v[148:149], off
	s_waitcnt vmcnt(8)
	s_waitcnt lgkmcnt(0)
	s_barrier
	s_waitcnt lgkmcnt(0)
	v_mfma_f32_16x16x32_f16 v[60:63], v[172:175], v[204:207], v[60:63]
	v_mfma_f32_16x16x32_f16 v[56:59], v[180:183], v[204:207], v[56:59]
	v_mfma_f32_16x16x32_f16 v[44:47], v[172:175], v[212:215], v[44:47]
	v_mfma_f32_16x16x32_f16 v[40:43], v[180:183], v[212:215], v[40:43]
	v_mfma_f32_16x16x32_f16 v[28:31], v[172:175], v[220:223], v[28:31]
	v_mfma_f32_16x16x32_f16 v[24:27], v[180:183], v[220:223], v[24:27]
	v_mfma_f32_16x16x32_f16 v[12:15], v[172:175], v[232:235], v[12:15]
	v_mfma_f32_16x16x32_f16 v[8:11], v[180:183], v[232:235], v[8:11]
	v_mfma_f32_16x16x32_f16 v[60:63], v[176:179], v[208:211], v[60:63]
	v_mfma_f32_16x16x32_f16 v[56:59], v[184:187], v[208:211], v[56:59]
	v_mfma_f32_16x16x32_f16 v[44:47], v[176:179], v[216:219], v[44:47]
	v_mfma_f32_16x16x32_f16 v[40:43], v[184:187], v[216:219], v[40:43]
	v_mfma_f32_16x16x32_f16 v[28:31], v[176:179], v[228:231], v[28:31]
	v_mfma_f32_16x16x32_f16 v[24:27], v[184:187], v[228:231], v[24:27]
	v_mfma_f32_16x16x32_f16 v[12:15], v[176:179], v[236:239], v[12:15]
	v_mfma_f32_16x16x32_f16 v[8:11], v[184:187], v[236:239], v[8:11]
	v_mfma_f32_16x16x32_f16 v[52:55], v[188:191], v[204:207], v[52:55]
	v_mfma_f32_16x16x32_f16 v[48:51], v[196:199], v[204:207], v[48:51]
	v_mfma_f32_16x16x32_f16 v[36:39], v[188:191], v[212:215], v[36:39]
	v_mfma_f32_16x16x32_f16 v[32:35], v[196:199], v[212:215], v[32:35]
	v_mfma_f32_16x16x32_f16 v[20:23], v[188:191], v[220:223], v[20:23]
	v_mfma_f32_16x16x32_f16 v[16:19], v[196:199], v[220:223], v[16:19]
	v_mfma_f32_16x16x32_f16 v[4:7], v[188:191], v[232:235], v[4:7]
	v_mfma_f32_16x16x32_f16 v[0:3], v[196:199], v[232:235], v[0:3]
	v_mfma_f32_16x16x32_f16 v[52:55], v[192:195], v[208:211], v[52:55]
	v_mfma_f32_16x16x32_f16 v[48:51], v[200:203], v[208:211], v[48:51]
	v_mfma_f32_16x16x32_f16 v[36:39], v[192:195], v[216:219], v[36:39]
	v_mfma_f32_16x16x32_f16 v[32:35], v[200:203], v[216:219], v[32:35]
	v_mfma_f32_16x16x32_f16 v[20:23], v[192:195], v[228:231], v[20:23]
	v_mfma_f32_16x16x32_f16 v[16:19], v[200:203], v[228:231], v[16:19]
	v_mfma_f32_16x16x32_f16 v[4:7], v[192:195], v[236:239], v[4:7]
	v_mfma_f32_16x16x32_f16 v[0:3], v[200:203], v[236:239], v[0:3]
	s_barrier
	s_add_i32 s74, s74, 2
	s_add_u32 s10, s10, 0x100
	s_addc_u32 s11, s11, 0
	s_add_u32 s72, s72, 0x100
	s_addc_u32 s73, s73, 0
	s_cmp_gt_u32 s74, 13
	s_cbranch_scc0 .LBB0_768
	s_and_b64 vcc, exec, s[18:19]
	s_cbranch_vccz .LBB0_771
	s_barrier

; #define PG8_STAGE(bufoff, gbase, voff) do { _Pragma("unroll") for (int _i = 0; _i < 2; ++_i) \
;         __builtin_amdgcn_global_load_lds((const unsigned*)((const char*)(gbase) + (voff)[_i]), (PG8_LAS unsigned*)(lds + (bufoff) + ldsw + _i * 8192), 16, 0, 0); } while (0)
; #define PG8_LDA(dst, b, h) do { _Pragma("unroll") for (int m = 0; m < 4; ++m) _Pragma("unroll") for (int k = 0; k < 2; ++k) dst[m][k] = *(const PG8_LAS bf16x8*)(lds + PG8_SA(b, h) + aoff + m * 2048 + k * 1024); } while (0)
; #define PG8_LDB(dst, b, h) do { _Pragma("unroll") for (int n = 0; n < 2; ++n) _Pragma("unroll") for (int k = 0; k < 2; ++k) dst[n][k] = *(const PG8_LAS bf16x8*)(lds + PG8_SB(b, h) + boff + n * 2048 + k * 1024); } while (0)
; #define PG8_MMA(ai, bj, At, Bt) do { __builtin_amdgcn_s_setprio(1); _Pragma("unroll") for (int m = 0; m < 4; ++m) _Pragma("unroll") for (int n = 0; n < 2; ++n) _Pragma("unroll") for (int k = 0; k < 2; ++k) \
;         acc[ai][bj][m][n] = mma16<F16>(Bt[n][k], At[m][k], acc[ai][bj][m][n]); __builtin_amdgcn_s_setprio(0); } while (0)
; #define PG8_WAIT_V(n) asm volatile("s_waitcnt vmcnt(" #n ")" ::: "memory")
; #define PG8_BAR __builtin_amdgcn_s_barrier()
; template <class Epi, class Sched, bool ALIGN_EPI = false, bool SP2 = false, bool F16 = false, bool TOKPERM = false>
; __device__ __forceinline__ void gemm_phase(PG8_LAS unsigned char* lds, const Gemm g, const Sched& S, const Epi& E, int wv) {
;     ...
;         for (int t = 0; t < nt; t += 2) {
;             const bool last = (t == nt - 2);
;             const char* a1 = cA + (size_t)(t + 1) * kstep;
;             const char* a2 = last ? nA : cA + (size_t)(t + 2) * kstep; const char* b2 = last ? nB : cB + (size_t)(t + 2) * kstep;
;             const char* a3 = a2 + kstep; const char* b3 = b2 + kstep;
;             if (last && has_next) S.a_ready(nxt);
;             if constexpr (SP2) {
;             PG8_LDB(B0, 0, 0); PG8_LDB(B1, 0, 1); PG8_SCHED; PG8_LDA(At, 0, 0); PG8_STAGE(PG8_SA(1, 1), a1 + hstep, voffA);
;             PG8_WAIT_V(8); PG8_WAIT_L(0); PG8_BAR; PG8_MMA(0, 0, At, B0); PG8_MMA(0, 1, At, B1); PG8_BAR; PG8_SCHED;
;             PG8_LDA(At, 0, 1); PG8_STAGE(PG8_SB(0, 0), b2, voffB); PG8_STAGE(PG8_SB(0, 1), b2 + hstep, voffB); PG8_STAGE(PG8_SA(0, 0), a2, voffA);
;             PG8_WAIT_V(8); PG8_WAIT_L(0); PG8_BAR; PG8_MMA(1, 0, At, B0); PG8_MMA(1, 1, At, B1); PG8_BAR; PG8_SCHED;
.LBB0_867:
	ds_read_b128 v[166:169], v149
	ds_read_b128 v[170:173], v150
	ds_read_b128 v[174:177], v151
	ds_read_b128 v[178:181], v152
	ds_read_b128 v[182:185], v153
	ds_read_b128 v[186:189], v154
	ds_read_b128 v[190:193], v155
	ds_read_b128 v[194:197], v156
	s_add_u32 s18, s16, 0x100
	s_addc_u32 s19, s17, 0
	s_cmp_eq_u32 s67, 40
	s_cselect_b32 s23, s11, s19
	s_cselect_b32 s22, s10, s18
	s_cselect_b32 s21, s13, s66
	s_cselect_b32 s20, s12, s65
	s_mov_b32 m0, s59
	v_lshl_add_u64 v[232:233], s[16:17], 0, v[138:139]
	ds_read_b128 v[198:201], v147
	ds_read_b128 v[202:205], v147 offset:1024
	ds_read_b128 v[206:209], v147 offset:2048
	ds_read_b128 v[210:213], v147 offset:3072
	ds_read_b128 v[214:217], v147 offset:4096
	ds_read_b128 v[218:221], v147 offset:5120
	ds_read_b128 v[222:225], v147 offset:6144
	ds_read_b128 v[228:231], v147 offset:7168
	global_load_lds_dwordx4 v[232:233], off
	v_lshl_add_u64 v[232:233], s[16:17], 0, v[140:141]
	s_mov_b32 m0, s60
	s_nop 0
	global_load_lds_dwordx4 v[232:233], off
	s_waitcnt vmcnt(8)
	s_waitcnt lgkmcnt(0)
	s_barrier
	s_waitcnt lgkmcnt(0)
	v_mfma_f32_16x16x32_bf16 v[124:127], v[166:169], v[198:201], v[124:127]
	v_mfma_f32_16x16x32_bf16 v[120:123], v[174:177], v[198:201], v[120:123]
	v_mfma_f32_16x16x32_bf16 v[108:111], v[166:169], v[206:209], v[108:111]
	v_mfma_f32_16x16x32_bf16 v[104:107], v[174:177], v[206:209], v[104:107]
	v_mfma_f32_16x16x32_bf16 v[92:95], v[166:169], v[214:217], v[92:95]
	v_mfma_f32_16x16x32_bf16 v[88:91], v[174:177], v[214:217], v[88:91]
	v_mfma_f32_16x16x32_bf16 v[76:79], v[166:169], v[222:225], v[76:79]
	v_mfma_f32_16x16x32_bf16 v[72:75], v[174:177], v[222:225], v[72:75]
	v_mfma_f32_16x16x32_bf16 v[124:127], v[170:173], v[202:205], v[124:127]
	v_mfma_f32_16x16x32_bf16 v[120:123], v[178:181], v[202:205], v[120:123]
	v_mfma_f32_16x16x32_bf16 v[108:111], v[170:173], v[210:213], v[108:111]
	v_mfma_f32_16x16x32_bf16 v[104:107], v[178:181], v[210:213], v[104:107]
	v_mfma_f32_16x16x32_bf16 v[92:95], v[170:173], v[218:221], v[92:95]
	v_mfma_f32_16x16x32_bf16 v[88:91], v[178:181], v[218:221], v[88:91]
	v_mfma_f32_16x16x32_bf16 v[76:79], v[170:173], v[228:231], v[76:79]
	v_mfma_f32_16x16x32_bf16 v[72:75], v[178:181], v[228:231], v[72:75]
	v_mfma_f32_16x16x32_bf16 v[116:119], v[182:185], v[198:201], v[116:119]
	v_mfma_f32_16x16x32_bf16 v[112:115], v[190:193], v[198:201], v[112:115]
	v_mfma_f32_16x16x32_bf16 v[100:103], v[182:185], v[206:209], v[100:103]
	v_mfma_f32_16x16x32_bf16 v[96:99], v[190:193], v[206:209], v[96:99]
	v_mfma_f32_16x16x32_bf16 v[84:87], v[182:185], v[214:217], v[84:87]
	v_mfma_f32_16x16x32_bf16 v[80:83], v[190:193], v[214:217], v[80:83]
	v_mfma_f32_16x16x32_bf16 v[68:71], v[182:185], v[222:225], v[68:71]
	v_mfma_f32_16x16x32_bf16 v[64:67], v[190:193], v[222:225], v[64:67]
	v_mfma_f32_16x16x32_bf16 v[116:119], v[186:189], v[202:205], v[116:119]
	v_mfma_f32_16x16x32_bf16 v[112:115], v[194:197], v[202:205], v[112:115]
	v_mfma_f32_16x16x32_bf16 v[100:103], v[186:189], v[210:213], v[100:103]
	v_mfma_f32_16x16x32_bf16 v[96:99], v[194:197], v[210:213], v[96:99]
	v_mfma_f32_16x16x32_bf16 v[84:87], v[186:189], v[218:221], v[84:87]
	v_mfma_f32_16x16x32_bf16 v[80:83], v[194:197], v[218:221], v[80:83]
	v_mfma_f32_16x16x32_bf16 v[68:71], v[186:189], v[228:231], v[68:71]
	v_mfma_f32_16x16x32_bf16 v[64:67], v[194:197], v[228:231], v[64:67]
	s_barrier
	s_mov_b32 m0, s4
	v_lshl_add_u64 v[232:233], s[20:21], 0, v[130:131]
	s_add_u32 s16, s20, 0xb0000
	ds_read_b128 v[198:201], v147 offset:16384
	ds_read_b128 v[202:205], v147 offset:17408
	ds_read_b128 v[206:209], v147 offset:18432
	ds_read_b128 v[210:213], v147 offset:19456
	ds_read_b128 v[214:217], v147 offset:20480
	ds_read_b128 v[218:221], v147 offset:21504
	ds_read_b128 v[222:225], v147 offset:22528
	ds_read_b128 v[228:231], v147 offset:23552
	global_load_lds_dwordx4 v[232:233], off
	v_lshl_add_u64 v[234:235], s[20:21], 0, v[134:135]
	s_mov_b32 m0, s5
	s_addc_u32 s17, s21, 0
	global_load_lds_dwordx4 v[234:235], off
	v_lshl_add_u64 v[236:237], s[16:17], 0, v[130:131]
	s_mov_b32 m0, s33
	v_lshl_add_u64 v[238:239], s[22:23], 0, v[132:133]
	global_load_lds_dwordx4 v[236:237], off
	v_lshl_add_u64 v[236:237], s[16:17], 0, v[134:135]
	s_mov_b32 m0, s36
	s_nop 0
	global_load_lds_dwordx4 v[236:237], off
	v_lshl_add_u64 v[236:237], s[22:23], 0, v[128:129]
	s_mov_b32 m0, s3
	s_nop 0
	global_load_lds_dwordx4 v[236:237], off
	s_mov_b32 m0, s37
	s_nop 0
	global_load_lds_dwordx4 v[238:239], off
	s_waitcnt vmcnt(8)
	s_waitcnt lgkmcnt(0)
	s_barrier
	s_waitcnt lgkmcnt(0)
	v_mfma_f32_16x16x32_bf16 v[60:63], v[166:169], v[198:201], v[60:63]
	v_mfma_f32_16x16x32_bf16 v[56:59], v[174:177], v[198:201], v[56:59]
	v_mfma_f32_16x16x32_bf16 v[44:47], v[166:169], v[206:209], v[44:47]
	v_mfma_f32_16x16x32_bf16 v[40:43], v[174:177], v[206:209], v[40:43]
	v_mfma_f32_16x16x32_bf16 v[28:31], v[166:169], v[214:217], v[28:31]
	v_mfma_f32_16x16x32_bf16 v[24:27], v[174:177], v[214:217], v[24:27]
	v_mfma_f32_16x16x32_bf16 v[12:15], v[166:169], v[222:225], v[12:15]
	v_mfma_f32_16x16x32_bf16 v[8:11], v[174:177], v[222:225], v[8:11]
	v_mfma_f32_16x16x32_bf16 v[60:63], v[170:173], v[202:205], v[60:63]
	v_mfma_f32_16x16x32_bf16 v[56:59], v[178:181], v[202:205], v[56:59]
	v_mfma_f32_16x16x32_bf16 v[44:47], v[170:173], v[210:213], v[44:47]
	v_mfma_f32_16x16x32_bf16 v[40:43], v[178:181], v[210:213], v[40:43]
	v_mfma_f32_16x16x32_bf16 v[28:31], v[170:173], v[218:221], v[28:31]
	v_mfma_f32_16x16x32_bf16 v[24:27], v[178:181], v[218:221], v[24:27]
	v_mfma_f32_16x16x32_bf16 v[12:15], v[170:173], v[228:231], v[12:15]
	v_mfma_f32_16x16x32_bf16 v[8:11], v[178:181], v[228:231], v[8:11]
	v_mfma_f32_16x16x32_bf16 v[52:55], v[182:185], v[198:201], v[52:55]
	v_mfma_f32_16x16x32_bf16 v[48:51], v[190:193], v[198:201], v[48:51]
	v_mfma_f32_16x16x32_bf16 v[36:39], v[182:185], v[206:209], v[36:39]
	v_mfma_f32_16x16x32_bf16 v[32:35], v[190:193], v[206:209], v[32:35]
	v_mfma_f32_16x16x32_bf16 v[20:23], v[182:185], v[214:217], v[20:23]
	v_mfma_f32_16x16x32_bf16 v[16:19], v[190:193], v[214:217], v[16:19]
	v_mfma_f32_16x16x32_bf16 v[4:7], v[182:185], v[222:225], v[4:7]
	v_mfma_f32_16x16x32_bf16 v[0:3], v[190:193], v[222:225], v[0:3]
	v_mfma_f32_16x16x32_bf16 v[52:55], v[186:189], v[202:205], v[52:55]
	v_mfma_f32_16x16x32_bf16 v[48:51], v[194:197], v[202:205], v[48:51]
	v_mfma_f32_16x16x32_bf16 v[36:39], v[186:189], v[210:213], v[36:39]
	v_mfma_f32_16x16x32_bf16 v[32:35], v[194:197], v[210:213], v[32:35]
	v_mfma_f32_16x16x32_bf16 v[20:23], v[186:189], v[218:221], v[20:23]
	v_mfma_f32_16x16x32_bf16 v[16:19], v[194:197], v[218:221], v[16:19]
	v_mfma_f32_16x16x32_bf16 v[4:7], v[186:189], v[228:231], v[4:7]
	v_mfma_f32_16x16x32_bf16 v[0:3], v[194:197], v[228:231], v[0:3]
	s_barrier
; #define PG8_STAGE(bufoff, gbase, voff) do { _Pragma("unroll") for (int _i = 0; _i < 2; ++_i) \
;         __builtin_amdgcn_global_load_lds((const unsigned*)((const char*)(gbase) + (voff)[_i]), (PG8_LAS unsigned*)(lds + (bufoff) + ldsw + _i * 8192), 16, 0, 0); } while (0)
; #define PG8_LDA(dst, b, h) do { _Pragma("unroll") for (int m = 0; m < 4; ++m) _Pragma("unroll") for (int k = 0; k < 2; ++k) dst[m][k] = *(const PG8_LAS bf16x8*)(lds + PG8_SA(b, h) + aoff + m * 2048 + k * 1024); } while (0)
; #define PG8_LDB(dst, b, h) do { _Pragma("unroll") for (int n = 0; n < 2; ++n) _Pragma("unroll") for (int k = 0; k < 2; ++k) dst[n][k] = *(const PG8_LAS bf16x8*)(lds + PG8_SB(b, h) + boff + n * 2048 + k * 1024); } while (0)
; #define PG8_MMA(ai, bj, At, Bt) do { __builtin_amdgcn_s_setprio(1); _Pragma("unroll") for (int m = 0; m < 4; ++m) _Pragma("unroll") for (int n = 0; n < 2; ++n) _Pragma("unroll") for (int k = 0; k < 2; ++k) \
;         acc[ai][bj][m][n] = mma16<F16>(Bt[n][k], At[m][k], acc[ai][bj][m][n]); __builtin_amdgcn_s_setprio(0); } while (0)
; #define PG8_WAIT_V(n) asm volatile("s_waitcnt vmcnt(" #n ")" ::: "memory")
; #define PG8_WAIT_L(n) asm volatile("s_waitcnt lgkmcnt(" #n ")" ::: "memory")
; #define PG8_BAR __builtin_amdgcn_s_barrier()
; #define PG8_SCHED __builtin_amdgcn_sched_barrier(0)
; template <class Epi, class Sched, bool ALIGN_EPI = false, bool SP2 = false, bool F16 = false, bool TOKPERM = false>
; __device__ __forceinline__ void gemm_phase(PG8_LAS unsigned char* lds, const Gemm g, const Sched& S, const Epi& E, int wv) {
;     ...
;             PG8_LDB(B0, 1, 0); PG8_LDB(B1, 1, 1); PG8_SCHED; PG8_LDA(At, 1, 0); PG8_STAGE(PG8_SA(0, 1), a2 + hstep, voffA);
;             PG8_WAIT_V(8); PG8_WAIT_L(0); PG8_BAR; PG8_MMA(0, 0, At, B0); PG8_MMA(0, 1, At, B1); PG8_BAR; PG8_SCHED;
;             PG8_LDA(At, 1, 1); PG8_STAGE(PG8_SB(1, 0), b3, voffB); PG8_STAGE(PG8_SB(1, 1), b3 + hstep, voffB); PG8_STAGE(PG8_SA(1, 0), a3, voffA);
;             PG8_WAIT_V(8); PG8_WAIT_L(0); PG8_BAR; PG8_MMA(1, 0, At, B0); PG8_MMA(1, 1, At, B1); PG8_BAR; PG8_SCHED;
	ds_read_b128 v[166:169], v157
	ds_read_b128 v[170:173], v158
	ds_read_b128 v[174:177], v159
	ds_read_b128 v[178:181], v160
	ds_read_b128 v[182:185], v161
	ds_read_b128 v[186:189], v162
	ds_read_b128 v[190:193], v163
	ds_read_b128 v[194:197], v164
	s_add_u32 s16, s22, 0xb0000
	s_addc_u32 s17, s23, 0
	s_mov_b32 m0, s44
	v_lshl_add_u64 v[240:241], s[16:17], 0, v[128:129]
	ds_read_b128 v[198:201], v147 offset:32768
	ds_read_b128 v[202:205], v147 offset:33792
	ds_read_b128 v[206:209], v147 offset:34816
	ds_read_b128 v[210:213], v147 offset:35840
	ds_read_b128 v[214:217], v147 offset:36864
	ds_read_b128 v[218:221], v147 offset:37888
	ds_read_b128 v[222:225], v147 offset:38912
	ds_read_b128 v[228:231], v147 offset:39936
	global_load_lds_dwordx4 v[240:241], off
	v_lshl_add_u64 v[240:241], s[16:17], 0, v[132:133]
	s_mov_b32 m0, s45
	s_nop 0
	global_load_lds_dwordx4 v[240:241], off
	s_waitcnt vmcnt(8)
	s_waitcnt lgkmcnt(0)
	s_barrier
	s_waitcnt lgkmcnt(0)
	v_mfma_f32_16x16x32_bf16 v[124:127], v[166:169], v[198:201], v[124:127]
	v_mfma_f32_16x16x32_bf16 v[120:123], v[174:177], v[198:201], v[120:123]
	v_mfma_f32_16x16x32_bf16 v[108:111], v[166:169], v[206:209], v[108:111]
	v_mfma_f32_16x16x32_bf16 v[104:107], v[174:177], v[206:209], v[104:107]
	v_mfma_f32_16x16x32_bf16 v[92:95], v[166:169], v[214:217], v[92:95]
	v_mfma_f32_16x16x32_bf16 v[88:91], v[174:177], v[214:217], v[88:91]
	v_mfma_f32_16x16x32_bf16 v[76:79], v[166:169], v[222:225], v[76:79]
	v_mfma_f32_16x16x32_bf16 v[72:75], v[174:177], v[222:225], v[72:75]
	v_mfma_f32_16x16x32_bf16 v[124:127], v[170:173], v[202:205], v[124:127]
	v_mfma_f32_16x16x32_bf16 v[120:123], v[178:181], v[202:205], v[120:123]
	v_mfma_f32_16x16x32_bf16 v[108:111], v[170:173], v[210:213], v[108:111]
	v_mfma_f32_16x16x32_bf16 v[104:107], v[178:181], v[210:213], v[104:107]
	v_mfma_f32_16x16x32_bf16 v[92:95], v[170:173], v[218:221], v[92:95]
	v_mfma_f32_16x16x32_bf16 v[88:91], v[178:181], v[218:221], v[88:91]
	v_mfma_f32_16x16x32_bf16 v[76:79], v[170:173], v[228:231], v[76:79]
	v_mfma_f32_16x16x32_bf16 v[72:75], v[178:181], v[228:231], v[72:75]
	v_mfma_f32_16x16x32_bf16 v[116:119], v[182:185], v[198:201], v[116:119]
	v_mfma_f32_16x16x32_bf16 v[112:115], v[190:193], v[198:201], v[112:115]
	v_mfma_f32_16x16x32_bf16 v[100:103], v[182:185], v[206:209], v[100:103]
	v_mfma_f32_16x16x32_bf16 v[96:99], v[190:193], v[206:209], v[96:99]
	v_mfma_f32_16x16x32_bf16 v[84:87], v[182:185], v[214:217], v[84:87]
	v_mfma_f32_16x16x32_bf16 v[80:83], v[190:193], v[214:217], v[80:83]
	v_mfma_f32_16x16x32_bf16 v[68:71], v[182:185], v[222:225], v[68:71]
	v_mfma_f32_16x16x32_bf16 v[64:67], v[190:193], v[222:225], v[64:67]
	v_mfma_f32_16x16x32_bf16 v[116:119], v[186:189], v[202:205], v[116:119]
	v_mfma_f32_16x16x32_bf16 v[112:115], v[194:197], v[202:205], v[112:115]
	v_mfma_f32_16x16x32_bf16 v[100:103], v[186:189], v[210:213], v[100:103]
	v_mfma_f32_16x16x32_bf16 v[96:99], v[194:197], v[210:213], v[96:99]
	v_mfma_f32_16x16x32_bf16 v[84:87], v[186:189], v[218:221], v[84:87]
	v_mfma_f32_16x16x32_bf16 v[80:83], v[194:197], v[218:221], v[80:83]
	v_mfma_f32_16x16x32_bf16 v[68:71], v[186:189], v[228:231], v[68:71]
	v_mfma_f32_16x16x32_bf16 v[64:67], v[194:197], v[228:231], v[64:67]
	s_barrier
	s_mov_b32 m0, s49
	v_lshl_add_u64 v[232:233], v[232:233], 0, s[14:15]
	s_add_u32 s16, s20, 0xb0080
	ds_read_b128 v[198:201], v147 offset:49152
	ds_read_b128 v[202:205], v147 offset:50176
	ds_read_b128 v[206:209], v147 offset:51200
	ds_read_b128 v[210:213], v147 offset:52224
	ds_read_b128 v[214:217], v147 offset:53248
	ds_read_b128 v[218:221], v147 offset:54272
	ds_read_b128 v[222:225], v147 offset:55296
	ds_read_b128 v[228:231], v147 offset:56320
	global_load_lds_dwordx4 v[232:233], off
	v_lshl_add_u64 v[232:233], v[234:235], 0, s[14:15]
	s_mov_b32 m0, s50
	s_addc_u32 s17, s21, 0
	global_load_lds_dwordx4 v[232:233], off
	v_lshl_add_u64 v[232:233], s[16:17], 0, v[130:131]
	s_mov_b32 m0, s53
	s_nop 0
	global_load_lds_dwordx4 v[232:233], off
	v_lshl_add_u64 v[232:233], s[16:17], 0, v[134:135]
	s_mov_b32 m0, s54
	s_nop 0
	global_load_lds_dwordx4 v[232:233], off
	v_lshl_add_u64 v[232:233], v[236:237], 0, s[14:15]
	s_mov_b32 m0, s51
	s_nop 0
	global_load_lds_dwordx4 v[232:233], off
	v_lshl_add_u64 v[232:233], v[238:239], 0, s[14:15]
	s_mov_b32 m0, s52
	s_nop 0
	global_load_lds_dwordx4 v[232:233], off
	s_waitcnt vmcnt(8)
	s_waitcnt lgkmcnt(0)
	s_barrier
	s_waitcnt lgkmcnt(0)
	v_mfma_f32_16x16x32_bf16 v[60:63], v[166:169], v[198:201], v[60:63]
	v_mfma_f32_16x16x32_bf16 v[56:59], v[174:177], v[198:201], v[56:59]
	v_mfma_f32_16x16x32_bf16 v[44:47], v[166:169], v[206:209], v[44:47]
	v_mfma_f32_16x16x32_bf16 v[40:43], v[174:177], v[206:209], v[40:43]
	v_mfma_f32_16x16x32_bf16 v[28:31], v[166:169], v[214:217], v[28:31]
	v_mfma_f32_16x16x32_bf16 v[24:27], v[174:177], v[214:217], v[24:27]
	v_mfma_f32_16x16x32_bf16 v[12:15], v[166:169], v[222:225], v[12:15]
	v_mfma_f32_16x16x32_bf16 v[8:11], v[174:177], v[222:225], v[8:11]
	v_mfma_f32_16x16x32_bf16 v[60:63], v[170:173], v[202:205], v[60:63]
	v_mfma_f32_16x16x32_bf16 v[56:59], v[178:181], v[202:205], v[56:59]
	v_mfma_f32_16x16x32_bf16 v[44:47], v[170:173], v[210:213], v[44:47]
	v_mfma_f32_16x16x32_bf16 v[40:43], v[178:181], v[210:213], v[40:43]
	v_mfma_f32_16x16x32_bf16 v[28:31], v[170:173], v[218:221], v[28:31]
	v_mfma_f32_16x16x32_bf16 v[24:27], v[178:181], v[218:221], v[24:27]
	v_mfma_f32_16x16x32_bf16 v[12:15], v[170:173], v[228:231], v[12:15]
	v_mfma_f32_16x16x32_bf16 v[8:11], v[178:181], v[228:231], v[8:11]
	v_mfma_f32_16x16x32_bf16 v[52:55], v[182:185], v[198:201], v[52:55]
	v_mfma_f32_16x16x32_bf16 v[48:51], v[190:193], v[198:201], v[48:51]
	v_mfma_f32_16x16x32_bf16 v[36:39], v[182:185], v[206:209], v[36:39]
	v_mfma_f32_16x16x32_bf16 v[32:35], v[190:193], v[206:209], v[32:35]
	v_mfma_f32_16x16x32_bf16 v[20:23], v[182:185], v[214:217], v[20:23]
	v_mfma_f32_16x16x32_bf16 v[16:19], v[190:193], v[214:217], v[16:19]
	v_mfma_f32_16x16x32_bf16 v[4:7], v[182:185], v[222:225], v[4:7]
	v_mfma_f32_16x16x32_bf16 v[0:3], v[190:193], v[222:225], v[0:3]
	v_mfma_f32_16x16x32_bf16 v[52:55], v[186:189], v[202:205], v[52:55]
	v_mfma_f32_16x16x32_bf16 v[48:51], v[194:197], v[202:205], v[48:51]
	v_mfma_f32_16x16x32_bf16 v[36:39], v[186:189], v[210:213], v[36:39]
	v_mfma_f32_16x16x32_bf16 v[32:35], v[194:197], v[210:213], v[32:35]
	v_mfma_f32_16x16x32_bf16 v[20:23], v[186:189], v[218:221], v[20:23]
	v_mfma_f32_16x16x32_bf16 v[16:19], v[194:197], v[218:221], v[16:19]
	v_mfma_f32_16x16x32_bf16 v[4:7], v[186:189], v[228:231], v[4:7]
	v_mfma_f32_16x16x32_bf16 v[0:3], v[194:197], v[228:231], v[0:3]
	s_barrier
;   __device__ __forceinline__ void operator()(const pg8::f32x4 (&acc)[2][2][4][2], const pg8::Unit& u, int wr, int wc, int fr, int fq) const {
;     int z; asm volatile("v_mov_b32 %0, 0" : "=v"(z));
;     const int row0 = u.pm * 256 + wr * 64 + fr + z, colb = u.pn * 256 + wc * 32 + 8 * fq + z;
; #pragma unroll
;     for (int ai = 0; ai < 2; ++ai)
; #pragma unroll
;       for (int m = 0; m < 4; ++m) {
;         const int tok = row0 + ai * 128 + m * 16; float ss = 0.f;
; #pragma unroll
;         for (int bj = 0; bj < 2; ++bj) {
;           const unsigned off = (unsigned)tok * DM + colb + 128 * bj;
;           f8_t n = __builtin_convertvector(*(const h8_t*)(x16 + off), f8_t);
; #pragma unroll
;           for (int c = 0; c < 4; ++c) { n[c] += sc * acc[ai][bj][m][0][c]; n[4 + c] += sc * acc[ai][bj][m][1][c]; }
;           if (aux) {
;             *(h8_t*)(x16 + off) = __builtin_convertvector(n, h8_t);
;             ss += ((n[0] * n[0] + n[1] * n[1]) + (n[2] * n[2] + n[3] * n[3])) + ((n[4] * n[4] + n[5] * n[5]) + (n[6] * n[6] + n[7] * n[7]));
;           } else {
;             *(f32x4*)(xout + off) = (f32x4){n[0], n[1], n[2], n[3]}; *(f32x4*)(xout + off + 4) = (f32x4){n[4], n[5], n[6], n[7]};
;           }
;         }
;         if (aux) { ss += __shfl_xor(ss, 16); ss += __shfl_xor(ss, 32); if (fq == 0) ssq[(unsigned)tok * 16 + u.pn * 4 + wc] = ss; }
;         if (m & 1) asm volatile("" ::: "memory");
;       }
	s_add_i32 s67, s67, 2
	s_add_u32 s65, s65, 0x100
	s_addc_u32 s66, s66, 0
	s_cmp_gt_u32 s67, 41
	s_mov_b64 s[16:17], s[18:19]
	s_cbranch_scc0 .LBB0_867
	s_lshl_b32 s16, s64, 8
	v_lshl_or_b32 v166, s63, 8, v148
	v_mov_b32 v136, 0
	v_xor_b32_e32 v169, 32, v165
	v_add3_u32 v167, s16, v146, v136
	v_add_u32_e32 v168, v166, v136
	v_lshl_add_u32 v136, v167, 10, v168
	v_lshl_add_u64 v[178:179], v[136:137], 1, s[40:41]
	v_add_u32_e32 v136, 0x80, v136
	global_load_dwordx4 v[170:173], v[178:179], off
	v_lshl_add_u64 v[180:181], v[136:137], 1, s[40:41]
	global_load_dwordx4 v[174:177], v[180:181], off
	v_add_u32_e32 v136, 16, v167
	v_lshl_add_u32 v136, v136, 10, v168
	v_lshl_add_u64 v[224:225], v[136:137], 1, s[40:41]
	v_add_u32_e32 v136, 0x80, v136
	global_load_dwordx4 v[192:195], v[224:225], off
	v_lshl_add_u64 v[248:249], v[136:137], 1, s[40:41]
	global_load_dwordx4 v[196:199], v[248:249], off
	v_add_u32_e32 v136, 32, v167
	v_lshl_add_u32 v136, v136, 10, v168
	v_lshl_add_u64 v[224:225], v[136:137], 1, s[40:41]
	v_add_u32_e32 v136, 0x80, v136
	global_load_dwordx4 v[200:203], v[224:225], off
	v_lshl_add_u64 v[248:249], v[136:137], 1, s[40:41]
	global_load_dwordx4 v[204:207], v[248:249], off
	v_add_u32_e32 v136, 48, v167
	v_lshl_add_u32 v136, v136, 10, v168
	v_lshl_add_u64 v[224:225], v[136:137], 1, s[40:41]
	v_add_u32_e32 v136, 0x80, v136
	global_load_dwordx4 v[208:211], v[224:225], off
	v_lshl_add_u64 v[248:249], v[136:137], 1, s[40:41]
	global_load_dwordx4 v[212:215], v[248:249], off
	v_add_u32_e32 v136, 0x80, v167
	v_lshl_add_u32 v136, v136, 10, v168
	v_lshl_add_u64 v[224:225], v[136:137], 1, s[40:41]
	v_add_u32_e32 v136, 0x80, v136
	global_load_dwordx4 v[216:219], v[224:225], off
	v_lshl_add_u64 v[248:249], v[136:137], 1, s[40:41]
	global_load_dwordx4 v[220:223], v[248:249], off
	v_add_u32_e32 v136, 0x90, v167
	v_lshl_add_u32 v136, v136, 10, v168
	v_lshl_add_u64 v[224:225], v[136:137], 1, s[40:41]
	v_add_u32_e32 v136, 0x80, v136
	global_load_dwordx4 v[228:231], v[224:225], off
	v_lshl_add_u64 v[248:249], v[136:137], 1, s[40:41]
	global_load_dwordx4 v[244:247], v[248:249], off
	v_and_b32_e32 v166, 64, v165
	v_xor_b32_e32 v136, 16, v165
	v_add_u32_e32 v166, 64, v166
	v_cmp_lt_i32_e32 vcc, v136, v166
	s_lshl_b32 s16, s63, 2
	s_or_b32 s18, s16, s48
	v_cndmask_b32_e32 v136, v165, v136, vcc
	v_cmp_lt_i32_e32 vcc, v169, v166
	v_lshlrev_b32_e32 v166, 2, v136
	s_waitcnt vmcnt(10)
	v_cvt_f32_f16_e32 v182, v173
	v_cvt_f32_f16_sdwa v183, v173 dst_sel:DWORD dst_unused:UNUSED_PAD src0_sel:WORD_1
	v_cvt_f32_f16_e32 v184, v171
	v_cvt_f32_f16_sdwa v185, v171 dst_sel:DWORD dst_unused:UNUSED_PAD src0_sel:WORD_1
	v_cvt_f32_f16_e32 v186, v172
	v_cvt_f32_f16_sdwa v187, v172 dst_sel:DWORD dst_unused:UNUSED_PAD src0_sel:WORD_1
	v_cvt_f32_f16_e32 v172, v170
	v_cvt_f32_f16_sdwa v173, v170 dst_sel:DWORD dst_unused:UNUSED_PAD src0_sel:WORD_1
	v_cvt_f32_f16_e32 v170, v177
	v_cvt_f32_f16_sdwa v171, v177 dst_sel:DWORD dst_unused:UNUSED_PAD src0_sel:WORD_1
	v_cvt_f32_f16_e32 v188, v175
	v_cvt_f32_f16_sdwa v189, v175 dst_sel:DWORD dst_unused:UNUSED_PAD src0_sel:WORD_1
	v_cvt_f32_f16_e32 v190, v176
	v_cvt_f32_f16_sdwa v191, v176 dst_sel:DWORD dst_unused:UNUSED_PAD src0_sel:WORD_1
	v_cvt_f32_f16_e32 v176, v174
	v_cvt_f32_f16_sdwa v177, v174 dst_sel:DWORD dst_unused:UNUSED_PAD src0_sel:WORD_1
	v_pk_fma_f32 v[124:125], v[124:125], 0.5, v[172:173] op_sel_hi:[1,0,1]
	v_pk_fma_f32 v[172:173], v[120:121], 0.5, v[186:187] op_sel_hi:[1,0,1]
	v_pk_fma_f32 v[126:127], v[126:127], 0.5, v[184:185] op_sel_hi:[1,0,1]
	v_pk_fma_f32 v[122:123], v[122:123], 0.5, v[182:183] op_sel_hi:[1,0,1]
	v_cvt_pk_f16_f32 v120, v172, v173
	v_cvt_pk_f16_f32 v121, v122, v123
	v_pk_mul_f32 v[174:175], v[124:125], v[124:125]
	v_pk_mul_f32 v[182:183], v[126:127], v[126:127]
	v_pk_fma_f32 v[174:175], v[172:173], v[172:173], v[174:175]
	v_pk_fma_f32 v[182:183], v[122:123], v[122:123], v[182:183]
	v_pk_fma_f32 v[176:177], v[116:117], 0.5, v[176:177] op_sel_hi:[1,0,1]
	v_pk_fma_f32 v[116:117], v[112:113], 0.5, v[190:191] op_sel_hi:[1,0,1]
	v_pk_fma_f32 v[184:185], v[118:119], 0.5, v[188:189] op_sel_hi:[1,0,1]
	v_pk_fma_f32 v[112:113], v[114:115], 0.5, v[170:171] op_sel_hi:[1,0,1]
	v_pk_fma_f32 v[174:175], v[176:177], v[176:177], v[174:175]
	v_pk_fma_f32 v[182:183], v[184:185], v[184:185], v[182:183]
	v_pk_fma_f32 v[174:175], v[116:117], v[116:117], v[174:175]
	v_pk_fma_f32 v[182:183], v[112:113], v[112:113], v[182:183]
	v_pk_add_f32 v[174:175], v[174:175], v[182:183]
	v_add_f32_e32 v114, v174, v175
	v_mov_b32_e32 v115, v114
	s_nop 1
	v_permlane16_swap_b32_e32 v114, v115
	v_cndmask_b32_e32 v169, v165, v169, vcc
	v_cvt_pk_f16_f32 v119, v126, v127
	v_cvt_pk_f16_f32 v118, v124, v125
	global_store_dwordx4 v[178:179], v[118:121], off
	s_nop 1
	v_cvt_pk_f16_f32 v119, v112, v113
	s_waitcnt lgkmcnt(0)
	v_add_f32_e32 v113, v114, v115
	v_lshlrev_b32_e32 v112, 2, v169
	v_mov_b32_e32 v114, v113
	s_nop 1
	v_permlane32_swap_b32_e32 v113, v114
	v_cvt_pk_f16_f32 v118, v116, v117
	v_cvt_pk_f16_f32 v117, v184, v185
	v_cvt_pk_f16_f32 v116, v176, v177
	global_store_dwordx4 v[180:181], v[116:119], off
	s_and_saveexec_b64 s[16:17], s[6:7]
	s_cbranch_execz .LBB0_870
	v_lshl_add_u32 v136, v167, 4, s18
	s_waitcnt lgkmcnt(0)
	v_add_f32_e32 v113, v113, v114
	v_lshl_add_u64 v[114:115], v[136:137], 2, s[42:43]
	global_store_dword v[114:115], v113, off

; #define PG8_STAGE(bufoff, gbase, voff) do { _Pragma("unroll") for (int _i = 0; _i < 2; ++_i) \
;         __builtin_amdgcn_global_load_lds((const unsigned*)((const char*)(gbase) + (voff)[_i]), (PG8_LAS unsigned*)(lds + (bufoff) + ldsw + _i * 8192), 16, 0, 0); } while (0)
; #define PG8_LDA(dst, b, h) do { _Pragma("unroll") for (int m = 0; m < 4; ++m) _Pragma("unroll") for (int k = 0; k < 2; ++k) dst[m][k] = *(const PG8_LAS bf16x8*)(lds + PG8_SA(b, h) + aoff + m * 2048 + k * 1024); } while (0)
; #define PG8_LDB(dst, b, h) do { _Pragma("unroll") for (int n = 0; n < 2; ++n) _Pragma("unroll") for (int k = 0; k < 2; ++k) dst[n][k] = *(const PG8_LAS bf16x8*)(lds + PG8_SB(b, h) + boff + n * 2048 + k * 1024); } while (0)
; #define PG8_WAIT_V(n) asm volatile("s_waitcnt vmcnt(" #n ")" ::: "memory")
; #define PG8_WAIT_L(n) asm volatile("s_waitcnt lgkmcnt(" #n ")" ::: "memory")
; #define PG8_BAR __builtin_amdgcn_s_barrier()
; #define PG8_SCHED __builtin_amdgcn_sched_barrier(0)
; template <class Epi, class Sched, bool ALIGN_EPI = false, bool SP2 = false, bool F16 = false, bool TOKPERM = false>
; __device__ __forceinline__ void gemm_phase(PG8_LAS unsigned char* lds, const Gemm g, const Sched& S, const Epi& E, int wv) {
;     ...
;         const bool has_next = S.next(ui + 1, nxt);
;         const char* nA = has_next ? (const char*)g.A + (size_t)nxt.pm * tstep : cA; const char* nB = has_next ? (const char*)g.Bt + (size_t)nxt.pn * tstep : cB;
;         for (int t = 0; t < nt; t += 2) {
;             const bool last = (t == nt - 2);
;             const char* a1 = cA + (size_t)(t + 1) * kstep;
;             const char* a2 = last ? nA : cA + (size_t)(t + 2) * kstep; const char* b2 = last ? nB : cB + (size_t)(t + 2) * kstep;
;             const char* a3 = a2 + kstep; const char* b3 = b2 + kstep;
;             if (last && has_next) S.a_ready(nxt);
;             if constexpr (SP2) {
;             PG8_LDB(B0, 0, 0); PG8_LDB(B1, 0, 1); PG8_SCHED; PG8_LDA(At, 0, 0); PG8_STAGE(PG8_SA(1, 1), a1 + hstep, voffA);
;             PG8_WAIT_V(8); PG8_WAIT_L(0); PG8_BAR; PG8_MMA(0, 0, At, B0); PG8_MMA(0, 1, At, B1); PG8_BAR; PG8_SCHED;
;             PG8_LDA(At, 0, 1); PG8_STAGE(PG8_SB(0, 0), b2, voffB); PG8_STAGE(PG8_SB(0, 1), b2 + hstep, voffB); PG8_STAGE(PG8_SA(0, 0), a2, voffA);
;             PG8_WAIT_V(8); PG8_WAIT_L(0); PG8_BAR; PG8_MMA(1, 0, At, B0); PG8_MMA(1, 1, At, B1); PG8_BAR; PG8_SCHED;
.LBB0_949:
	s_ashr_i32 s51, s50, 31
	s_lshl_b64 s[52:53], s[50:51], 19
	s_add_u32 s52, s40, s52
	s_addc_u32 s53, s41, s53
	s_and_b64 s[54:55], s[6:7], exec
	s_cselect_b32 s51, s53, s11
	s_cselect_b32 s70, s52, s10
	s_ashr_i32 s49, s48, 31
	s_lshl_b64 s[54:55], s[48:49], 19
	s_add_u32 s54, s0, s54
	s_addc_u32 s55, s1, s55
	s_and_b64 s[56:57], s[6:7], exec
	s_cselect_b32 s49, s55, s13
	s_cselect_b32 s71, s54, s12
	s_add_u32 s10, s10, 0x40080
	s_addc_u32 s11, s11, 0
	s_add_u32 s72, s12, 0x100
	s_addc_u32 s73, s13, 0
	s_mov_b32 s74, -2
	ds_read_b128 v[172:175], v155
	ds_read_b128 v[176:179], v156
	ds_read_b128 v[180:183], v157
	ds_read_b128 v[184:187], v158
	ds_read_b128 v[188:191], v159
	ds_read_b128 v[192:195], v160
	ds_read_b128 v[196:199], v161
	ds_read_b128 v[200:203], v162
	s_add_u32 s12, s10, 0xfffc0080
	s_addc_u32 s13, s11, -1
	s_cmp_eq_u32 s74, 12
	s_cselect_b32 s57, s51, s13
	s_cselect_b32 s56, s70, s12
	s_cselect_b32 s13, s49, s73
	s_cselect_b32 s12, s71, s72
	s_mov_b32 m0, s66
	v_lshl_add_u64 v[148:149], s[10:11], 0, v[140:141]
	ds_read_b128 v[204:207], v153
	ds_read_b128 v[208:211], v153 offset:1024
	ds_read_b128 v[212:215], v153 offset:2048
	ds_read_b128 v[216:219], v153 offset:3072
	ds_read_b128 v[220:223], v153 offset:4096
	ds_read_b128 v[228:231], v153 offset:5120
	ds_read_b128 v[232:235], v153 offset:6144
	ds_read_b128 v[236:239], v153 offset:7168
	global_load_lds_dwordx4 v[148:149], off
	v_lshl_add_u64 v[148:149], s[10:11], 0, v[142:143]
	s_mov_b32 m0, s67
	s_nop 0
	global_load_lds_dwordx4 v[148:149], off
	s_waitcnt vmcnt(8)
	s_waitcnt lgkmcnt(0)
	s_barrier
	s_waitcnt lgkmcnt(0)
	v_mfma_f32_16x16x32_f16 v[124:127], v[172:175], v[204:207], 0
	v_mfma_f32_16x16x32_f16 v[116:119], v[180:183], v[204:207], 0
	v_mfma_f32_16x16x32_f16 v[108:111], v[172:175], v[212:215], 0
	v_mfma_f32_16x16x32_f16 v[104:107], v[180:183], v[212:215], 0
	v_mfma_f32_16x16x32_f16 v[92:95], v[172:175], v[220:223], 0
	v_mfma_f32_16x16x32_f16 v[88:91], v[180:183], v[220:223], 0
	v_mfma_f32_16x16x32_f16 v[76:79], v[172:175], v[232:235], 0
	v_mfma_f32_16x16x32_f16 v[72:75], v[180:183], v[232:235], 0
	v_mfma_f32_16x16x32_f16 v[124:127], v[176:179], v[208:211], v[124:127]
	v_mfma_f32_16x16x32_f16 v[116:119], v[184:187], v[208:211], v[116:119]
	v_mfma_f32_16x16x32_f16 v[108:111], v[176:179], v[216:219], v[108:111]
	v_mfma_f32_16x16x32_f16 v[104:107], v[184:187], v[216:219], v[104:107]
	v_mfma_f32_16x16x32_f16 v[92:95], v[176:179], v[228:231], v[92:95]
	v_mfma_f32_16x16x32_f16 v[88:91], v[184:187], v[228:231], v[88:91]
	v_mfma_f32_16x16x32_f16 v[76:79], v[176:179], v[236:239], v[76:79]
	v_mfma_f32_16x16x32_f16 v[72:75], v[184:187], v[236:239], v[72:75]
	v_mfma_f32_16x16x32_f16 v[120:123], v[188:191], v[204:207], 0
	v_mfma_f32_16x16x32_f16 v[112:115], v[196:199], v[204:207], 0
	v_mfma_f32_16x16x32_f16 v[100:103], v[188:191], v[212:215], 0
	v_mfma_f32_16x16x32_f16 v[96:99], v[196:199], v[212:215], 0
	v_mfma_f32_16x16x32_f16 v[84:87], v[188:191], v[220:223], 0
	v_mfma_f32_16x16x32_f16 v[80:83], v[196:199], v[220:223], 0
	v_mfma_f32_16x16x32_f16 v[68:71], v[188:191], v[232:235], 0
	v_mfma_f32_16x16x32_f16 v[64:67], v[196:199], v[232:235], 0
	v_mfma_f32_16x16x32_f16 v[120:123], v[192:195], v[208:211], v[120:123]
	v_mfma_f32_16x16x32_f16 v[112:115], v[200:203], v[208:211], v[112:115]
	v_mfma_f32_16x16x32_f16 v[100:103], v[192:195], v[216:219], v[100:103]
	v_mfma_f32_16x16x32_f16 v[96:99], v[200:203], v[216:219], v[96:99]
	v_mfma_f32_16x16x32_f16 v[84:87], v[192:195], v[228:231], v[84:87]
	v_mfma_f32_16x16x32_f16 v[80:83], v[200:203], v[228:231], v[80:83]
	v_mfma_f32_16x16x32_f16 v[68:71], v[192:195], v[236:239], v[68:71]
	v_mfma_f32_16x16x32_f16 v[64:67], v[200:203], v[236:239], v[64:67]
	s_barrier
	s_mov_b32 m0, s5
	v_lshl_add_u64 v[148:149], s[12:13], 0, v[132:133]
	s_add_u32 s76, s12, 0x40000
	ds_read_b128 v[204:207], v153 offset:16384
	ds_read_b128 v[208:211], v153 offset:17408
	ds_read_b128 v[212:215], v153 offset:18432
	ds_read_b128 v[216:219], v153 offset:19456
	ds_read_b128 v[220:223], v153 offset:20480
	ds_read_b128 v[228:231], v153 offset:21504
	ds_read_b128 v[232:235], v153 offset:22528
	ds_read_b128 v[236:239], v153 offset:23552
	global_load_lds_dwordx4 v[148:149], off
	v_lshl_add_u64 v[224:225], s[12:13], 0, v[128:129]
	s_mov_b32 m0, s21
	s_addc_u32 s77, s13, 0
	global_load_lds_dwordx4 v[224:225], off
	v_lshl_add_u64 v[240:241], s[76:77], 0, v[132:133]
	s_mov_b32 m0, s23
	v_lshl_add_u64 v[242:243], s[56:57], 0, v[130:131]
	global_load_lds_dwordx4 v[240:241], off
	v_lshl_add_u64 v[240:241], s[76:77], 0, v[128:129]
	s_mov_b32 m0, s33
	s_nop 0
	global_load_lds_dwordx4 v[240:241], off
	v_lshl_add_u64 v[240:241], s[56:57], 0, v[134:135]
	s_mov_b32 m0, s2
	s_nop 0
	global_load_lds_dwordx4 v[240:241], off
	s_mov_b32 m0, s36
	s_nop 0
	global_load_lds_dwordx4 v[242:243], off
	s_waitcnt vmcnt(8)
	s_waitcnt lgkmcnt(0)
	s_barrier
; #define PG8_STAGE(bufoff, gbase, voff) do { _Pragma("unroll") for (int _i = 0; _i < 2; ++_i) \
;         __builtin_amdgcn_global_load_lds((const unsigned*)((const char*)(gbase) + (voff)[_i]), (PG8_LAS unsigned*)(lds + (bufoff) + ldsw + _i * 8192), 16, 0, 0); } while (0)
; #define PG8_LDA(dst, b, h) do { _Pragma("unroll") for (int m = 0; m < 4; ++m) _Pragma("unroll") for (int k = 0; k < 2; ++k) dst[m][k] = *(const PG8_LAS bf16x8*)(lds + PG8_SA(b, h) + aoff + m * 2048 + k * 1024); } while (0)
; #define PG8_LDB(dst, b, h) do { _Pragma("unroll") for (int n = 0; n < 2; ++n) _Pragma("unroll") for (int k = 0; k < 2; ++k) dst[n][k] = *(const PG8_LAS bf16x8*)(lds + PG8_SB(b, h) + boff + n * 2048 + k * 1024); } while (0)
; #define PG8_MMA(ai, bj, At, Bt) do { __builtin_amdgcn_s_setprio(1); _Pragma("unroll") for (int m = 0; m < 4; ++m) _Pragma("unroll") for (int n = 0; n < 2; ++n) _Pragma("unroll") for (int k = 0; k < 2; ++k) \
;         acc[ai][bj][m][n] = mma16<F16>(Bt[n][k], At[m][k], acc[ai][bj][m][n]); __builtin_amdgcn_s_setprio(0); } while (0)
; #define PG8_WAIT_V(n) asm volatile("s_waitcnt vmcnt(" #n ")" ::: "memory")
; #define PG8_WAIT_L(n) asm volatile("s_waitcnt lgkmcnt(" #n ")" ::: "memory")
; template <class Epi, class Sched, bool ALIGN_EPI = false, bool SP2 = false, bool F16 = false, bool TOKPERM = false>
; __device__ __forceinline__ void gemm_phase(PG8_LAS unsigned char* lds, const Gemm g, const Sched& S, const Epi& E, int wv) {
;     ...
;             PG8_WAIT_V(8); PG8_WAIT_L(0); PG8_BAR; PG8_MMA(0, 0, At, B0); PG8_MMA(0, 1, At, B1); PG8_BAR; PG8_SCHED;
;             PG8_LDA(At, 0, 1); PG8_STAGE(PG8_SB(0, 0), b2, voffB); PG8_STAGE(PG8_SB(0, 1), b2 + hstep, voffB); PG8_STAGE(PG8_SA(0, 0), a2, voffA);
;             PG8_WAIT_V(8); PG8_WAIT_L(0); PG8_BAR; PG8_MMA(1, 0, At, B0); PG8_MMA(1, 1, At, B1); PG8_BAR; PG8_SCHED;
;             PG8_LDB(B0, 1, 0); PG8_LDB(B1, 1, 1); PG8_SCHED; PG8_LDA(At, 1, 0); PG8_STAGE(PG8_SA(0, 1), a2 + hstep, voffA);
;             PG8_WAIT_V(8); PG8_WAIT_L(0); PG8_BAR; PG8_MMA(0, 0, At, B0); PG8_MMA(0, 1, At, B1); PG8_BAR; PG8_SCHED;
;             PG8_LDA(At, 1, 1); PG8_STAGE(PG8_SB(1, 0), b3, voffB); PG8_STAGE(PG8_SB(1, 1), b3 + hstep, voffB); PG8_STAGE(PG8_SA(1, 0), a3, voffA);
;             PG8_WAIT_V(8); PG8_WAIT_L(0); PG8_BAR; PG8_MMA(1, 0, At, B0); PG8_MMA(1, 1, At, B1); PG8_BAR; PG8_SCHED;
	s_waitcnt lgkmcnt(0)
	v_mfma_f32_16x16x32_f16 v[60:63], v[172:175], v[204:207], 0
	v_mfma_f32_16x16x32_f16 v[56:59], v[180:183], v[204:207], 0
	v_mfma_f32_16x16x32_f16 v[44:47], v[172:175], v[212:215], 0
	v_mfma_f32_16x16x32_f16 v[40:43], v[180:183], v[212:215], 0
	v_mfma_f32_16x16x32_f16 v[28:31], v[172:175], v[220:223], 0
	v_mfma_f32_16x16x32_f16 v[24:27], v[180:183], v[220:223], 0
	v_mfma_f32_16x16x32_f16 v[12:15], v[172:175], v[232:235], 0
	v_mfma_f32_16x16x32_f16 v[8:11], v[180:183], v[232:235], 0
	v_mfma_f32_16x16x32_f16 v[60:63], v[176:179], v[208:211], v[60:63]
	v_mfma_f32_16x16x32_f16 v[56:59], v[184:187], v[208:211], v[56:59]
	v_mfma_f32_16x16x32_f16 v[44:47], v[176:179], v[216:219], v[44:47]
	v_mfma_f32_16x16x32_f16 v[40:43], v[184:187], v[216:219], v[40:43]
	v_mfma_f32_16x16x32_f16 v[28:31], v[176:179], v[228:231], v[28:31]
	v_mfma_f32_16x16x32_f16 v[24:27], v[184:187], v[228:231], v[24:27]
	v_mfma_f32_16x16x32_f16 v[12:15], v[176:179], v[236:239], v[12:15]
	v_mfma_f32_16x16x32_f16 v[8:11], v[184:187], v[236:239], v[8:11]
	v_mfma_f32_16x16x32_f16 v[52:55], v[188:191], v[204:207], 0
	v_mfma_f32_16x16x32_f16 v[48:51], v[196:199], v[204:207], 0
	v_mfma_f32_16x16x32_f16 v[36:39], v[188:191], v[212:215], 0
	v_mfma_f32_16x16x32_f16 v[32:35], v[196:199], v[212:215], 0
	v_mfma_f32_16x16x32_f16 v[20:23], v[188:191], v[220:223], 0
	v_mfma_f32_16x16x32_f16 v[16:19], v[196:199], v[220:223], 0
	v_mfma_f32_16x16x32_f16 v[4:7], v[188:191], v[232:235], 0
	v_mfma_f32_16x16x32_f16 v[0:3], v[196:199], v[232:235], 0
	v_mfma_f32_16x16x32_f16 v[52:55], v[192:195], v[208:211], v[52:55]
	v_mfma_f32_16x16x32_f16 v[48:51], v[200:203], v[208:211], v[48:51]
	v_mfma_f32_16x16x32_f16 v[36:39], v[192:195], v[216:219], v[36:39]
	v_mfma_f32_16x16x32_f16 v[32:35], v[200:203], v[216:219], v[32:35]
	v_mfma_f32_16x16x32_f16 v[20:23], v[192:195], v[228:231], v[20:23]
	v_mfma_f32_16x16x32_f16 v[16:19], v[200:203], v[228:231], v[16:19]
	v_mfma_f32_16x16x32_f16 v[4:7], v[192:195], v[236:239], v[4:7]
	v_mfma_f32_16x16x32_f16 v[0:3], v[200:203], v[236:239], v[0:3]
	s_barrier
	ds_read_b128 v[172:175], v163
	ds_read_b128 v[176:179], v164
	ds_read_b128 v[180:183], v165
	ds_read_b128 v[184:187], v166
	ds_read_b128 v[188:191], v167
	ds_read_b128 v[192:195], v168
	ds_read_b128 v[196:199], v169
	ds_read_b128 v[200:203], v170
	s_add_u32 s56, s56, 0x40000
	s_addc_u32 s57, s57, 0
	s_mov_b32 m0, s37
	v_lshl_add_u64 v[244:245], s[56:57], 0, v[134:135]
	ds_read_b128 v[204:207], v153 offset:32768
	ds_read_b128 v[208:211], v153 offset:33792
	ds_read_b128 v[212:215], v153 offset:34816
	ds_read_b128 v[216:219], v153 offset:35840
	ds_read_b128 v[220:223], v153 offset:36864
	ds_read_b128 v[228:231], v153 offset:37888
	ds_read_b128 v[232:235], v153 offset:38912
	ds_read_b128 v[236:239], v153 offset:39936
	global_load_lds_dwordx4 v[244:245], off
	v_lshl_add_u64 v[244:245], s[56:57], 0, v[130:131]
	s_mov_b32 m0, s44
	s_nop 0
	global_load_lds_dwordx4 v[244:245], off
	s_waitcnt vmcnt(8)
	s_waitcnt lgkmcnt(0)
	s_barrier
	s_waitcnt lgkmcnt(0)
	v_mfma_f32_16x16x32_f16 v[124:127], v[172:175], v[204:207], v[124:127]
	v_mfma_f32_16x16x32_f16 v[116:119], v[180:183], v[204:207], v[116:119]
	v_mfma_f32_16x16x32_f16 v[108:111], v[172:175], v[212:215], v[108:111]
	v_mfma_f32_16x16x32_f16 v[104:107], v[180:183], v[212:215], v[104:107]
	v_mfma_f32_16x16x32_f16 v[92:95], v[172:175], v[220:223], v[92:95]
	v_mfma_f32_16x16x32_f16 v[88:91], v[180:183], v[220:223], v[88:91]
	v_mfma_f32_16x16x32_f16 v[76:79], v[172:175], v[232:235], v[76:79]
	v_mfma_f32_16x16x32_f16 v[72:75], v[180:183], v[232:235], v[72:75]
	v_mfma_f32_16x16x32_f16 v[124:127], v[176:179], v[208:211], v[124:127]
	v_mfma_f32_16x16x32_f16 v[116:119], v[184:187], v[208:211], v[116:119]
	v_mfma_f32_16x16x32_f16 v[108:111], v[176:179], v[216:219], v[108:111]
	v_mfma_f32_16x16x32_f16 v[104:107], v[184:187], v[216:219], v[104:107]
	v_mfma_f32_16x16x32_f16 v[92:95], v[176:179], v[228:231], v[92:95]
	v_mfma_f32_16x16x32_f16 v[88:91], v[184:187], v[228:231], v[88:91]
	v_mfma_f32_16x16x32_f16 v[76:79], v[176:179], v[236:239], v[76:79]
	v_mfma_f32_16x16x32_f16 v[72:75], v[184:187], v[236:239], v[72:75]
	v_mfma_f32_16x16x32_f16 v[120:123], v[188:191], v[204:207], v[120:123]
	v_mfma_f32_16x16x32_f16 v[112:115], v[196:199], v[204:207], v[112:115]
	v_mfma_f32_16x16x32_f16 v[100:103], v[188:191], v[212:215], v[100:103]
	v_mfma_f32_16x16x32_f16 v[96:99], v[196:199], v[212:215], v[96:99]
	v_mfma_f32_16x16x32_f16 v[84:87], v[188:191], v[220:223], v[84:87]
	v_mfma_f32_16x16x32_f16 v[80:83], v[196:199], v[220:223], v[80:83]
	v_mfma_f32_16x16x32_f16 v[68:71], v[188:191], v[232:235], v[68:71]
	v_mfma_f32_16x16x32_f16 v[64:67], v[196:199], v[232:235], v[64:67]
	v_mfma_f32_16x16x32_f16 v[120:123], v[192:195], v[208:211], v[120:123]
	v_mfma_f32_16x16x32_f16 v[112:115], v[200:203], v[208:211], v[112:115]
	v_mfma_f32_16x16x32_f16 v[100:103], v[192:195], v[216:219], v[100:103]
	v_mfma_f32_16x16x32_f16 v[96:99], v[200:203], v[216:219], v[96:99]
	v_mfma_f32_16x16x32_f16 v[84:87], v[192:195], v[228:231], v[84:87]
	v_mfma_f32_16x16x32_f16 v[80:83], v[200:203], v[228:231], v[80:83]
	v_mfma_f32_16x16x32_f16 v[68:71], v[192:195], v[236:239], v[68:71]
	v_mfma_f32_16x16x32_f16 v[64:67], v[200:203], v[236:239], v[64:67]
	s_barrier
; #define PG8_STAGE(bufoff, gbase, voff) do { _Pragma("unroll") for (int _i = 0; _i < 2; ++_i) \
;         __builtin_amdgcn_global_load_lds((const unsigned*)((const char*)(gbase) + (voff)[_i]), (PG8_LAS unsigned*)(lds + (bufoff) + ldsw + _i * 8192), 16, 0, 0); } while (0)
; #define PG8_LDA(dst, b, h) do { _Pragma("unroll") for (int m = 0; m < 4; ++m) _Pragma("unroll") for (int k = 0; k < 2; ++k) dst[m][k] = *(const PG8_LAS bf16x8*)(lds + PG8_SA(b, h) + aoff + m * 2048 + k * 1024); } while (0)
; #define PG8_LDB(dst, b, h) do { _Pragma("unroll") for (int n = 0; n < 2; ++n) _Pragma("unroll") for (int k = 0; k < 2; ++k) dst[n][k] = *(const PG8_LAS bf16x8*)(lds + PG8_SB(b, h) + boff + n * 2048 + k * 1024); } while (0)
; #define PG8_MMA(ai, bj, At, Bt) do { __builtin_amdgcn_s_setprio(1); _Pragma("unroll") for (int m = 0; m < 4; ++m) _Pragma("unroll") for (int n = 0; n < 2; ++n) _Pragma("unroll") for (int k = 0; k < 2; ++k) \
;         acc[ai][bj][m][n] = mma16<F16>(Bt[n][k], At[m][k], acc[ai][bj][m][n]); __builtin_amdgcn_s_setprio(0); } while (0)
; #define PG8_BAR __builtin_amdgcn_s_barrier()
; template <class Epi, class Sched, bool ALIGN_EPI = false, bool SP2 = false, bool F16 = false, bool TOKPERM = false>
; __device__ __forceinline__ void gemm_phase(PG8_LAS unsigned char* lds, const Gemm g, const Sched& S, const Epi& E, int wv) {
;     ...
;             PG8_LDB(B0, 0, 0); PG8_LDB(B1, 0, 1); PG8_SCHED; PG8_LDA(At, 0, 0); PG8_STAGE(PG8_SA(1, 1), a1 + hstep, voffA);
;             PG8_WAIT_V(8); PG8_WAIT_L(0); PG8_BAR; PG8_MMA(0, 0, At, B0); PG8_MMA(0, 1, At, B1); PG8_BAR; PG8_SCHED;
;             PG8_LDA(At, 0, 1); PG8_STAGE(PG8_SB(0, 0), b2, voffB); PG8_STAGE(PG8_SB(0, 1), b2 + hstep, voffB); PG8_STAGE(PG8_SA(0, 0), a2, voffA);
;             PG8_WAIT_V(8); PG8_WAIT_L(0); PG8_BAR; PG8_MMA(1, 0, At, B0); PG8_MMA(1, 1, At, B1); PG8_BAR; PG8_SCHED;
;             PG8_LDB(B0, 1, 0); PG8_LDB(B1, 1, 1); PG8_SCHED; PG8_LDA(At, 1, 0); PG8_STAGE(PG8_SA(0, 1), a2 + hstep, voffA);
;             PG8_WAIT_V(8); PG8_WAIT_L(0); PG8_BAR; PG8_MMA(0, 0, At, B0); PG8_MMA(0, 1, At, B1); PG8_BAR; PG8_SCHED;
;             PG8_LDA(At, 1, 1); PG8_STAGE(PG8_SB(1, 0), b3, voffB); PG8_STAGE(PG8_SB(1, 1), b3 + hstep, voffB); PG8_STAGE(PG8_SA(1, 0), a3, voffA);
;             PG8_WAIT_V(8); PG8_WAIT_L(0); PG8_BAR; PG8_MMA(1, 0, At, B0); PG8_MMA(1, 1, At, B1); PG8_BAR; PG8_SCHED;
	s_mov_b32 m0, s58
	v_lshl_add_u64 v[148:149], v[148:149], 0, s[16:17]
	s_add_u32 s12, s12, 0x40080
	ds_read_b128 v[204:207], v153 offset:49152
	ds_read_b128 v[208:211], v153 offset:50176
	ds_read_b128 v[212:215], v153 offset:51200
	ds_read_b128 v[216:219], v153 offset:52224
	ds_read_b128 v[220:223], v153 offset:53248
	ds_read_b128 v[228:231], v153 offset:54272
	ds_read_b128 v[232:235], v153 offset:55296
	ds_read_b128 v[236:239], v153 offset:56320
	global_load_lds_dwordx4 v[148:149], off
	v_lshl_add_u64 v[148:149], v[224:225], 0, s[16:17]
	s_mov_b32 m0, s59
	s_addc_u32 s13, s13, 0
	global_load_lds_dwordx4 v[148:149], off
	v_lshl_add_u64 v[148:149], s[12:13], 0, v[132:133]
	s_mov_b32 m0, s62
	s_nop 0
	global_load_lds_dwordx4 v[148:149], off
	v_lshl_add_u64 v[148:149], s[12:13], 0, v[128:129]
	s_mov_b32 m0, s63
	s_nop 0
	global_load_lds_dwordx4 v[148:149], off
	v_lshl_add_u64 v[148:149], v[240:241], 0, s[16:17]
	s_mov_b32 m0, s60
	s_nop 0
	global_load_lds_dwordx4 v[148:149], off
	v_lshl_add_u64 v[148:149], v[242:243], 0, s[16:17]
	s_mov_b32 m0, s61
	s_nop 0
	global_load_lds_dwordx4 v[148:149], off
	s_waitcnt vmcnt(8)
	s_waitcnt lgkmcnt(0)
	s_barrier
	s_waitcnt lgkmcnt(0)
	v_mfma_f32_16x16x32_f16 v[60:63], v[172:175], v[204:207], v[60:63]
	v_mfma_f32_16x16x32_f16 v[56:59], v[180:183], v[204:207], v[56:59]
	v_mfma_f32_16x16x32_f16 v[44:47], v[172:175], v[212:215], v[44:47]
	v_mfma_f32_16x16x32_f16 v[40:43], v[180:183], v[212:215], v[40:43]
	v_mfma_f32_16x16x32_f16 v[28:31], v[172:175], v[220:223], v[28:31]
	v_mfma_f32_16x16x32_f16 v[24:27], v[180:183], v[220:223], v[24:27]
	v_mfma_f32_16x16x32_f16 v[12:15], v[172:175], v[232:235], v[12:15]
	v_mfma_f32_16x16x32_f16 v[8:11], v[180:183], v[232:235], v[8:11]
	v_mfma_f32_16x16x32_f16 v[60:63], v[176:179], v[208:211], v[60:63]
	v_mfma_f32_16x16x32_f16 v[56:59], v[184:187], v[208:211], v[56:59]
	v_mfma_f32_16x16x32_f16 v[44:47], v[176:179], v[216:219], v[44:47]
	v_mfma_f32_16x16x32_f16 v[40:43], v[184:187], v[216:219], v[40:43]
	v_mfma_f32_16x16x32_f16 v[28:31], v[176:179], v[228:231], v[28:31]
	v_mfma_f32_16x16x32_f16 v[24:27], v[184:187], v[228:231], v[24:27]
	v_mfma_f32_16x16x32_f16 v[12:15], v[176:179], v[236:239], v[12:15]
	v_mfma_f32_16x16x32_f16 v[8:11], v[184:187], v[236:239], v[8:11]
	v_mfma_f32_16x16x32_f16 v[52:55], v[188:191], v[204:207], v[52:55]
	v_mfma_f32_16x16x32_f16 v[48:51], v[196:199], v[204:207], v[48:51]
	v_mfma_f32_16x16x32_f16 v[36:39], v[188:191], v[212:215], v[36:39]
	v_mfma_f32_16x16x32_f16 v[32:35], v[196:199], v[212:215], v[32:35]
	v_mfma_f32_16x16x32_f16 v[20:23], v[188:191], v[220:223], v[20:23]
	v_mfma_f32_16x16x32_f16 v[16:19], v[196:199], v[220:223], v[16:19]
	v_mfma_f32_16x16x32_f16 v[4:7], v[188:191], v[232:235], v[4:7]
	v_mfma_f32_16x16x32_f16 v[0:3], v[196:199], v[232:235], v[0:3]
	v_mfma_f32_16x16x32_f16 v[52:55], v[192:195], v[208:211], v[52:55]
	v_mfma_f32_16x16x32_f16 v[48:51], v[200:203], v[208:211], v[48:51]
	v_mfma_f32_16x16x32_f16 v[36:39], v[192:195], v[216:219], v[36:39]
	v_mfma_f32_16x16x32_f16 v[32:35], v[200:203], v[216:219], v[32:35]
	v_mfma_f32_16x16x32_f16 v[20:23], v[192:195], v[228:231], v[20:23]
	v_mfma_f32_16x16x32_f16 v[16:19], v[200:203], v[228:231], v[16:19]
	v_mfma_f32_16x16x32_f16 v[4:7], v[192:195], v[236:239], v[4:7]
	v_mfma_f32_16x16x32_f16 v[0:3], v[200:203], v[236:239], v[0:3]
	s_barrier
	s_add_i32 s74, s74, 2
	s_add_u32 s10, s10, 0x100
	s_addc_u32 s11, s11, 0
	s_add_u32 s72, s72, 0x100
	s_addc_u32 s73, s73, 0
	s_cmp_gt_u32 s74, 13
.LBB0_950:
	ds_read_b128 v[172:175], v155
	ds_read_b128 v[176:179], v156
	ds_read_b128 v[180:183], v157
	ds_read_b128 v[184:187], v158
	ds_read_b128 v[188:191], v159
	ds_read_b128 v[192:195], v160
	ds_read_b128 v[196:199], v161
	ds_read_b128 v[200:203], v162
	s_add_u32 s12, s10, 0xfffc0080
	s_addc_u32 s13, s11, -1
	s_cmp_eq_u32 s74, 12
	s_cselect_b32 s57, s51, s13
	s_cselect_b32 s56, s70, s12
	s_cselect_b32 s13, s49, s73
	s_cselect_b32 s12, s71, s72
	s_mov_b32 m0, s66
	v_lshl_add_u64 v[148:149], s[10:11], 0, v[140:141]
	ds_read_b128 v[204:207], v153
	ds_read_b128 v[208:211], v153 offset:1024
	ds_read_b128 v[212:215], v153 offset:2048
	ds_read_b128 v[216:219], v153 offset:3072
	ds_read_b128 v[220:223], v153 offset:4096
	ds_read_b128 v[228:231], v153 offset:5120
	ds_read_b128 v[232:235], v153 offset:6144
	ds_read_b128 v[236:239], v153 offset:7168
	global_load_lds_dwordx4 v[148:149], off
	v_lshl_add_u64 v[148:149], s[10:11], 0, v[142:143]
	s_mov_b32 m0, s67
	s_nop 0
	global_load_lds_dwordx4 v[148:149], off
	s_waitcnt vmcnt(8)
	s_waitcnt lgkmcnt(0)
	s_barrier
; #define PG8_STAGE(bufoff, gbase, voff) do { _Pragma("unroll") for (int _i = 0; _i < 2; ++_i) \
;         __builtin_amdgcn_global_load_lds((const unsigned*)((const char*)(gbase) + (voff)[_i]), (PG8_LAS unsigned*)(lds + (bufoff) + ldsw + _i * 8192), 16, 0, 0); } while (0)
; #define PG8_LDA(dst, b, h) do { _Pragma("unroll") for (int m = 0; m < 4; ++m) _Pragma("unroll") for (int k = 0; k < 2; ++k) dst[m][k] = *(const PG8_LAS bf16x8*)(lds + PG8_SA(b, h) + aoff + m * 2048 + k * 1024); } while (0)
; #define PG8_LDB(dst, b, h) do { _Pragma("unroll") for (int n = 0; n < 2; ++n) _Pragma("unroll") for (int k = 0; k < 2; ++k) dst[n][k] = *(const PG8_LAS bf16x8*)(lds + PG8_SB(b, h) + boff + n * 2048 + k * 1024); } while (0)
; #define PG8_MMA(ai, bj, At, Bt) do { __builtin_amdgcn_s_setprio(1); _Pragma("unroll") for (int m = 0; m < 4; ++m) _Pragma("unroll") for (int n = 0; n < 2; ++n) _Pragma("unroll") for (int k = 0; k < 2; ++k) \
;         acc[ai][bj][m][n] = mma16<F16>(Bt[n][k], At[m][k], acc[ai][bj][m][n]); __builtin_amdgcn_s_setprio(0); } while (0)
; #define PG8_WAIT_V(n) asm volatile("s_waitcnt vmcnt(" #n ")" ::: "memory")
; #define PG8_WAIT_L(n) asm volatile("s_waitcnt lgkmcnt(" #n ")" ::: "memory")
; #define PG8_BAR __builtin_amdgcn_s_barrier()
; #define PG8_SCHED __builtin_amdgcn_sched_barrier(0)
; template <class Epi, class Sched, bool ALIGN_EPI = false, bool SP2 = false, bool F16 = false, bool TOKPERM = false>
; __device__ __forceinline__ void gemm_phase(PG8_LAS unsigned char* lds, const Gemm g, const Sched& S, const Epi& E, int wv) {
;     ...
;             PG8_LDB(B0, 0, 0); PG8_LDB(B1, 0, 1); PG8_SCHED; PG8_LDA(At, 0, 0); PG8_STAGE(PG8_SA(1, 1), a1 + hstep, voffA);
;             PG8_WAIT_V(8); PG8_WAIT_L(0); PG8_BAR; PG8_MMA(0, 0, At, B0); PG8_MMA(0, 1, At, B1); PG8_BAR; PG8_SCHED;
;             PG8_LDA(At, 0, 1); PG8_STAGE(PG8_SB(0, 0), b2, voffB); PG8_STAGE(PG8_SB(0, 1), b2 + hstep, voffB); PG8_STAGE(PG8_SA(0, 0), a2, voffA);
;             PG8_WAIT_V(8); PG8_WAIT_L(0); PG8_BAR; PG8_MMA(1, 0, At, B0); PG8_MMA(1, 1, At, B1); PG8_BAR; PG8_SCHED;
	s_waitcnt lgkmcnt(0)
	v_mfma_f32_16x16x32_f16 v[124:127], v[172:175], v[204:207], v[124:127]
	v_mfma_f32_16x16x32_f16 v[116:119], v[180:183], v[204:207], v[116:119]
	v_mfma_f32_16x16x32_f16 v[108:111], v[172:175], v[212:215], v[108:111]
	v_mfma_f32_16x16x32_f16 v[104:107], v[180:183], v[212:215], v[104:107]
	v_mfma_f32_16x16x32_f16 v[92:95], v[172:175], v[220:223], v[92:95]
	v_mfma_f32_16x16x32_f16 v[88:91], v[180:183], v[220:223], v[88:91]
	v_mfma_f32_16x16x32_f16 v[76:79], v[172:175], v[232:235], v[76:79]
	v_mfma_f32_16x16x32_f16 v[72:75], v[180:183], v[232:235], v[72:75]
	v_mfma_f32_16x16x32_f16 v[124:127], v[176:179], v[208:211], v[124:127]
	v_mfma_f32_16x16x32_f16 v[116:119], v[184:187], v[208:211], v[116:119]
	v_mfma_f32_16x16x32_f16 v[108:111], v[176:179], v[216:219], v[108:111]
	v_mfma_f32_16x16x32_f16 v[104:107], v[184:187], v[216:219], v[104:107]
	v_mfma_f32_16x16x32_f16 v[92:95], v[176:179], v[228:231], v[92:95]
	v_mfma_f32_16x16x32_f16 v[88:91], v[184:187], v[228:231], v[88:91]
	v_mfma_f32_16x16x32_f16 v[76:79], v[176:179], v[236:239], v[76:79]
	v_mfma_f32_16x16x32_f16 v[72:75], v[184:187], v[236:239], v[72:75]
	v_mfma_f32_16x16x32_f16 v[120:123], v[188:191], v[204:207], v[120:123]
	v_mfma_f32_16x16x32_f16 v[112:115], v[196:199], v[204:207], v[112:115]
	v_mfma_f32_16x16x32_f16 v[100:103], v[188:191], v[212:215], v[100:103]
	v_mfma_f32_16x16x32_f16 v[96:99], v[196:199], v[212:215], v[96:99]
	v_mfma_f32_16x16x32_f16 v[84:87], v[188:191], v[220:223], v[84:87]
	v_mfma_f32_16x16x32_f16 v[80:83], v[196:199], v[220:223], v[80:83]
	v_mfma_f32_16x16x32_f16 v[68:71], v[188:191], v[232:235], v[68:71]
	v_mfma_f32_16x16x32_f16 v[64:67], v[196:199], v[232:235], v[64:67]
	v_mfma_f32_16x16x32_f16 v[120:123], v[192:195], v[208:211], v[120:123]
	v_mfma_f32_16x16x32_f16 v[112:115], v[200:203], v[208:211], v[112:115]
	v_mfma_f32_16x16x32_f16 v[100:103], v[192:195], v[216:219], v[100:103]
	v_mfma_f32_16x16x32_f16 v[96:99], v[200:203], v[216:219], v[96:99]
	v_mfma_f32_16x16x32_f16 v[84:87], v[192:195], v[228:231], v[84:87]
	v_mfma_f32_16x16x32_f16 v[80:83], v[200:203], v[228:231], v[80:83]
	v_mfma_f32_16x16x32_f16 v[68:71], v[192:195], v[236:239], v[68:71]
	v_mfma_f32_16x16x32_f16 v[64:67], v[200:203], v[236:239], v[64:67]
	s_barrier
	s_mov_b32 m0, s5
	v_lshl_add_u64 v[148:149], s[12:13], 0, v[132:133]
	s_add_u32 s76, s12, 0x40000
	ds_read_b128 v[204:207], v153 offset:16384
	ds_read_b128 v[208:211], v153 offset:17408
	ds_read_b128 v[212:215], v153 offset:18432
	ds_read_b128 v[216:219], v153 offset:19456
	ds_read_b128 v[220:223], v153 offset:20480
	ds_read_b128 v[228:231], v153 offset:21504
	ds_read_b128 v[232:235], v153 offset:22528
	ds_read_b128 v[236:239], v153 offset:23552
	global_load_lds_dwordx4 v[148:149], off
	v_lshl_add_u64 v[224:225], s[12:13], 0, v[128:129]
	s_mov_b32 m0, s21
	s_addc_u32 s77, s13, 0
	global_load_lds_dwordx4 v[224:225], off
	v_lshl_add_u64 v[240:241], s[76:77], 0, v[132:133]
	s_mov_b32 m0, s23
	v_lshl_add_u64 v[242:243], s[56:57], 0, v[130:131]
	global_load_lds_dwordx4 v[240:241], off
	v_lshl_add_u64 v[240:241], s[76:77], 0, v[128:129]
	s_mov_b32 m0, s33
	s_nop 0
	global_load_lds_dwordx4 v[240:241], off
	v_lshl_add_u64 v[240:241], s[56:57], 0, v[134:135]
	s_mov_b32 m0, s2
	s_nop 0
	global_load_lds_dwordx4 v[240:241], off
	s_mov_b32 m0, s36
	s_nop 0
	global_load_lds_dwordx4 v[242:243], off
	s_waitcnt vmcnt(8)
	s_waitcnt lgkmcnt(0)
	s_barrier
	s_waitcnt lgkmcnt(0)
	v_mfma_f32_16x16x32_f16 v[60:63], v[172:175], v[204:207], v[60:63]
	v_mfma_f32_16x16x32_f16 v[56:59], v[180:183], v[204:207], v[56:59]
	v_mfma_f32_16x16x32_f16 v[44:47], v[172:175], v[212:215], v[44:47]
	v_mfma_f32_16x16x32_f16 v[40:43], v[180:183], v[212:215], v[40:43]
	v_mfma_f32_16x16x32_f16 v[28:31], v[172:175], v[220:223], v[28:31]
	v_mfma_f32_16x16x32_f16 v[24:27], v[180:183], v[220:223], v[24:27]
	v_mfma_f32_16x16x32_f16 v[12:15], v[172:175], v[232:235], v[12:15]
	v_mfma_f32_16x16x32_f16 v[8:11], v[180:183], v[232:235], v[8:11]
	v_mfma_f32_16x16x32_f16 v[60:63], v[176:179], v[208:211], v[60:63]
	v_mfma_f32_16x16x32_f16 v[56:59], v[184:187], v[208:211], v[56:59]
	v_mfma_f32_16x16x32_f16 v[44:47], v[176:179], v[216:219], v[44:47]
	v_mfma_f32_16x16x32_f16 v[40:43], v[184:187], v[216:219], v[40:43]
	v_mfma_f32_16x16x32_f16 v[28:31], v[176:179], v[228:231], v[28:31]
	v_mfma_f32_16x16x32_f16 v[24:27], v[184:187], v[228:231], v[24:27]
	v_mfma_f32_16x16x32_f16 v[12:15], v[176:179], v[236:239], v[12:15]
	v_mfma_f32_16x16x32_f16 v[8:11], v[184:187], v[236:239], v[8:11]
	v_mfma_f32_16x16x32_f16 v[52:55], v[188:191], v[204:207], v[52:55]
	v_mfma_f32_16x16x32_f16 v[48:51], v[196:199], v[204:207], v[48:51]
	v_mfma_f32_16x16x32_f16 v[36:39], v[188:191], v[212:215], v[36:39]
	v_mfma_f32_16x16x32_f16 v[32:35], v[196:199], v[212:215], v[32:35]
	v_mfma_f32_16x16x32_f16 v[20:23], v[188:191], v[220:223], v[20:23]
	v_mfma_f32_16x16x32_f16 v[16:19], v[196:199], v[220:223], v[16:19]
	v_mfma_f32_16x16x32_f16 v[4:7], v[188:191], v[232:235], v[4:7]
	v_mfma_f32_16x16x32_f16 v[0:3], v[196:199], v[232:235], v[0:3]
	v_mfma_f32_16x16x32_f16 v[52:55], v[192:195], v[208:211], v[52:55]
	v_mfma_f32_16x16x32_f16 v[48:51], v[200:203], v[208:211], v[48:51]
	v_mfma_f32_16x16x32_f16 v[36:39], v[192:195], v[216:219], v[36:39]
	v_mfma_f32_16x16x32_f16 v[32:35], v[200:203], v[216:219], v[32:35]
	v_mfma_f32_16x16x32_f16 v[20:23], v[192:195], v[228:231], v[20:23]
	v_mfma_f32_16x16x32_f16 v[16:19], v[200:203], v[228:231], v[16:19]
	v_mfma_f32_16x16x32_f16 v[4:7], v[192:195], v[236:239], v[4:7]
	v_mfma_f32_16x16x32_f16 v[0:3], v[200:203], v[236:239], v[0:3]
	s_barrier
; #define PG8_STAGE(bufoff, gbase, voff) do { _Pragma("unroll") for (int _i = 0; _i < 2; ++_i) \
;         __builtin_amdgcn_global_load_lds((const unsigned*)((const char*)(gbase) + (voff)[_i]), (PG8_LAS unsigned*)(lds + (bufoff) + ldsw + _i * 8192), 16, 0, 0); } while (0)
; #define PG8_LDA(dst, b, h) do { _Pragma("unroll") for (int m = 0; m < 4; ++m) _Pragma("unroll") for (int k = 0; k < 2; ++k) dst[m][k] = *(const PG8_LAS bf16x8*)(lds + PG8_SA(b, h) + aoff + m * 2048 + k * 1024); } while (0)
; #define PG8_LDB(dst, b, h) do { _Pragma("unroll") for (int n = 0; n < 2; ++n) _Pragma("unroll") for (int k = 0; k < 2; ++k) dst[n][k] = *(const PG8_LAS bf16x8*)(lds + PG8_SB(b, h) + boff + n * 2048 + k * 1024); } while (0)
; #define PG8_MMA(ai, bj, At, Bt) do { __builtin_amdgcn_s_setprio(1); _Pragma("unroll") for (int m = 0; m < 4; ++m) _Pragma("unroll") for (int n = 0; n < 2; ++n) _Pragma("unroll") for (int k = 0; k < 2; ++k) \
;         acc[ai][bj][m][n] = mma16<F16>(Bt[n][k], At[m][k], acc[ai][bj][m][n]); __builtin_amdgcn_s_setprio(0); } while (0)
; #define PG8_WAIT_V(n) asm volatile("s_waitcnt vmcnt(" #n ")" ::: "memory")
; #define PG8_WAIT_L(n) asm volatile("s_waitcnt lgkmcnt(" #n ")" ::: "memory")
; #define PG8_BAR __builtin_amdgcn_s_barrier()
; #define PG8_SCHED __builtin_amdgcn_sched_barrier(0)
; template <class Epi, class Sched, bool ALIGN_EPI = false, bool SP2 = false, bool F16 = false, bool TOKPERM = false>
; __device__ __forceinline__ void gemm_phase(PG8_LAS unsigned char* lds, const Gemm g, const Sched& S, const Epi& E, int wv) {
;     ...
;             PG8_LDB(B0, 1, 0); PG8_LDB(B1, 1, 1); PG8_SCHED; PG8_LDA(At, 1, 0); PG8_STAGE(PG8_SA(0, 1), a2 + hstep, voffA);
;             PG8_WAIT_V(8); PG8_WAIT_L(0); PG8_BAR; PG8_MMA(0, 0, At, B0); PG8_MMA(0, 1, At, B1); PG8_BAR; PG8_SCHED;
;             PG8_LDA(At, 1, 1); PG8_STAGE(PG8_SB(1, 0), b3, voffB); PG8_STAGE(PG8_SB(1, 1), b3 + hstep, voffB); PG8_STAGE(PG8_SA(1, 0), a3, voffA);
;             PG8_WAIT_V(8); PG8_WAIT_L(0); PG8_BAR; PG8_MMA(1, 0, At, B0); PG8_MMA(1, 1, At, B1); PG8_BAR; PG8_SCHED;
;     ...
;         if constexpr (ALIGN_EPI) { if (wr == 0) PG8_BAR; }
	ds_read_b128 v[172:175], v163
	ds_read_b128 v[176:179], v164
	ds_read_b128 v[180:183], v165
	ds_read_b128 v[184:187], v166
	ds_read_b128 v[188:191], v167
	ds_read_b128 v[192:195], v168
	ds_read_b128 v[196:199], v169
	ds_read_b128 v[200:203], v170
	s_add_u32 s56, s56, 0x40000
	s_addc_u32 s57, s57, 0
	s_mov_b32 m0, s37
	v_lshl_add_u64 v[244:245], s[56:57], 0, v[134:135]
	ds_read_b128 v[204:207], v153 offset:32768
	ds_read_b128 v[208:211], v153 offset:33792
	ds_read_b128 v[212:215], v153 offset:34816
	ds_read_b128 v[216:219], v153 offset:35840
	ds_read_b128 v[220:223], v153 offset:36864
	ds_read_b128 v[228:231], v153 offset:37888
	ds_read_b128 v[232:235], v153 offset:38912
	ds_read_b128 v[236:239], v153 offset:39936
	global_load_lds_dwordx4 v[244:245], off
	v_lshl_add_u64 v[244:245], s[56:57], 0, v[130:131]
	s_mov_b32 m0, s44
	s_nop 0
	global_load_lds_dwordx4 v[244:245], off
	s_waitcnt vmcnt(8)
	s_waitcnt lgkmcnt(0)
	s_barrier
	s_waitcnt lgkmcnt(0)
	v_mfma_f32_16x16x32_f16 v[124:127], v[172:175], v[204:207], v[124:127]
	v_mfma_f32_16x16x32_f16 v[116:119], v[180:183], v[204:207], v[116:119]
	v_mfma_f32_16x16x32_f16 v[108:111], v[172:175], v[212:215], v[108:111]
	v_mfma_f32_16x16x32_f16 v[104:107], v[180:183], v[212:215], v[104:107]
	v_mfma_f32_16x16x32_f16 v[92:95], v[172:175], v[220:223], v[92:95]
	v_mfma_f32_16x16x32_f16 v[88:91], v[180:183], v[220:223], v[88:91]
	v_mfma_f32_16x16x32_f16 v[76:79], v[172:175], v[232:235], v[76:79]
	v_mfma_f32_16x16x32_f16 v[72:75], v[180:183], v[232:235], v[72:75]
	v_mfma_f32_16x16x32_f16 v[124:127], v[176:179], v[208:211], v[124:127]
	v_mfma_f32_16x16x32_f16 v[116:119], v[184:187], v[208:211], v[116:119]
	v_mfma_f32_16x16x32_f16 v[108:111], v[176:179], v[216:219], v[108:111]
	v_mfma_f32_16x16x32_f16 v[104:107], v[184:187], v[216:219], v[104:107]
	v_mfma_f32_16x16x32_f16 v[92:95], v[176:179], v[228:231], v[92:95]
	v_mfma_f32_16x16x32_f16 v[88:91], v[184:187], v[228:231], v[88:91]
	v_mfma_f32_16x16x32_f16 v[76:79], v[176:179], v[236:239], v[76:79]
	v_mfma_f32_16x16x32_f16 v[72:75], v[184:187], v[236:239], v[72:75]
	v_mfma_f32_16x16x32_f16 v[120:123], v[188:191], v[204:207], v[120:123]
	v_mfma_f32_16x16x32_f16 v[112:115], v[196:199], v[204:207], v[112:115]
	v_mfma_f32_16x16x32_f16 v[100:103], v[188:191], v[212:215], v[100:103]
	v_mfma_f32_16x16x32_f16 v[96:99], v[196:199], v[212:215], v[96:99]
	v_mfma_f32_16x16x32_f16 v[84:87], v[188:191], v[220:223], v[84:87]
	v_mfma_f32_16x16x32_f16 v[80:83], v[196:199], v[220:223], v[80:83]
	v_mfma_f32_16x16x32_f16 v[68:71], v[188:191], v[232:235], v[68:71]
	v_mfma_f32_16x16x32_f16 v[64:67], v[196:199], v[232:235], v[64:67]
	v_mfma_f32_16x16x32_f16 v[120:123], v[192:195], v[208:211], v[120:123]
	v_mfma_f32_16x16x32_f16 v[112:115], v[200:203], v[208:211], v[112:115]
	v_mfma_f32_16x16x32_f16 v[100:103], v[192:195], v[216:219], v[100:103]
	v_mfma_f32_16x16x32_f16 v[96:99], v[200:203], v[216:219], v[96:99]
	v_mfma_f32_16x16x32_f16 v[84:87], v[192:195], v[228:231], v[84:87]
	v_mfma_f32_16x16x32_f16 v[80:83], v[200:203], v[228:231], v[80:83]
	v_mfma_f32_16x16x32_f16 v[68:71], v[192:195], v[236:239], v[68:71]
	v_mfma_f32_16x16x32_f16 v[64:67], v[200:203], v[236:239], v[64:67]
	s_barrier
	s_mov_b32 m0, s58
	v_lshl_add_u64 v[148:149], v[148:149], 0, s[16:17]
	s_add_u32 s12, s12, 0x40080
	ds_read_b128 v[204:207], v153 offset:49152
	ds_read_b128 v[208:211], v153 offset:50176
	ds_read_b128 v[212:215], v153 offset:51200
	ds_read_b128 v[216:219], v153 offset:52224
	ds_read_b128 v[220:223], v153 offset:53248
	ds_read_b128 v[228:231], v153 offset:54272
	ds_read_b128 v[232:235], v153 offset:55296
	ds_read_b128 v[236:239], v153 offset:56320
	global_load_lds_dwordx4 v[148:149], off
	v_lshl_add_u64 v[148:149], v[224:225], 0, s[16:17]
	s_mov_b32 m0, s59
	s_addc_u32 s13, s13, 0
	global_load_lds_dwordx4 v[148:149], off
	v_lshl_add_u64 v[148:149], s[12:13], 0, v[132:133]
	s_mov_b32 m0, s62
	s_nop 0
	global_load_lds_dwordx4 v[148:149], off
	v_lshl_add_u64 v[148:149], s[12:13], 0, v[128:129]
	s_mov_b32 m0, s63
	s_nop 0
	global_load_lds_dwordx4 v[148:149], off
	v_lshl_add_u64 v[148:149], v[240:241], 0, s[16:17]
	s_mov_b32 m0, s60
	s_nop 0
	global_load_lds_dwordx4 v[148:149], off
	v_lshl_add_u64 v[148:149], v[242:243], 0, s[16:17]
	s_mov_b32 m0, s61
	s_nop 0
	global_load_lds_dwordx4 v[148:149], off
	s_waitcnt vmcnt(8)
	s_waitcnt lgkmcnt(0)
	s_barrier
	s_waitcnt lgkmcnt(0)
	v_mfma_f32_16x16x32_f16 v[60:63], v[172:175], v[204:207], v[60:63]
	v_mfma_f32_16x16x32_f16 v[56:59], v[180:183], v[204:207], v[56:59]
	v_mfma_f32_16x16x32_f16 v[44:47], v[172:175], v[212:215], v[44:47]
	v_mfma_f32_16x16x32_f16 v[40:43], v[180:183], v[212:215], v[40:43]
	v_mfma_f32_16x16x32_f16 v[28:31], v[172:175], v[220:223], v[28:31]
	v_mfma_f32_16x16x32_f16 v[24:27], v[180:183], v[220:223], v[24:27]
	v_mfma_f32_16x16x32_f16 v[12:15], v[172:175], v[232:235], v[12:15]
	v_mfma_f32_16x16x32_f16 v[8:11], v[180:183], v[232:235], v[8:11]
	v_mfma_f32_16x16x32_f16 v[60:63], v[176:179], v[208:211], v[60:63]
	v_mfma_f32_16x16x32_f16 v[56:59], v[184:187], v[208:211], v[56:59]
	v_mfma_f32_16x16x32_f16 v[44:47], v[176:179], v[216:219], v[44:47]
	v_mfma_f32_16x16x32_f16 v[40:43], v[184:187], v[216:219], v[40:43]
	v_mfma_f32_16x16x32_f16 v[28:31], v[176:179], v[228:231], v[28:31]
	v_mfma_f32_16x16x32_f16 v[24:27], v[184:187], v[228:231], v[24:27]
	v_mfma_f32_16x16x32_f16 v[12:15], v[176:179], v[236:239], v[12:15]
	v_mfma_f32_16x16x32_f16 v[8:11], v[184:187], v[236:239], v[8:11]
	v_mfma_f32_16x16x32_f16 v[52:55], v[188:191], v[204:207], v[52:55]
	v_mfma_f32_16x16x32_f16 v[48:51], v[196:199], v[204:207], v[48:51]
	v_mfma_f32_16x16x32_f16 v[36:39], v[188:191], v[212:215], v[36:39]
	v_mfma_f32_16x16x32_f16 v[32:35], v[196:199], v[212:215], v[32:35]
	v_mfma_f32_16x16x32_f16 v[20:23], v[188:191], v[220:223], v[20:23]
	v_mfma_f32_16x16x32_f16 v[16:19], v[196:199], v[220:223], v[16:19]
	v_mfma_f32_16x16x32_f16 v[4:7], v[188:191], v[232:235], v[4:7]
	v_mfma_f32_16x16x32_f16 v[0:3], v[196:199], v[232:235], v[0:3]
	v_mfma_f32_16x16x32_f16 v[52:55], v[192:195], v[208:211], v[52:55]
	v_mfma_f32_16x16x32_f16 v[48:51], v[200:203], v[208:211], v[48:51]
	v_mfma_f32_16x16x32_f16 v[36:39], v[192:195], v[216:219], v[36:39]
	v_mfma_f32_16x16x32_f16 v[32:35], v[200:203], v[216:219], v[32:35]
	v_mfma_f32_16x16x32_f16 v[20:23], v[192:195], v[228:231], v[20:23]
	v_mfma_f32_16x16x32_f16 v[16:19], v[200:203], v[228:231], v[16:19]
	v_mfma_f32_16x16x32_f16 v[4:7], v[192:195], v[236:239], v[4:7]
	v_mfma_f32_16x16x32_f16 v[0:3], v[200:203], v[236:239], v[0:3]
	s_barrier
	s_add_i32 s74, s74, 2
	s_add_u32 s10, s10, 0x100
	s_addc_u32 s11, s11, 0
	s_add_u32 s72, s72, 0x100
	s_addc_u32 s73, s73, 0
	s_cmp_gt_u32 s74, 13
	s_cbranch_scc0 .LBB0_950
	s_and_b64 vcc, exec, s[18:19]
	s_cbranch_vccz .LBB0_953
	s_barrier

; #define PG8_STAGE(bufoff, gbase, voff) do { _Pragma("unroll") for (int _i = 0; _i < 2; ++_i) \
;         __builtin_amdgcn_global_load_lds((const unsigned*)((const char*)(gbase) + (voff)[_i]), (PG8_LAS unsigned*)(lds + (bufoff) + ldsw + _i * 8192), 16, 0, 0); } while (0)
; #define PG8_LDA(dst, b, h) do { _Pragma("unroll") for (int m = 0; m < 4; ++m) _Pragma("unroll") for (int k = 0; k < 2; ++k) dst[m][k] = *(const PG8_LAS bf16x8*)(lds + PG8_SA(b, h) + aoff + m * 2048 + k * 1024); } while (0)
; #define PG8_LDB(dst, b, h) do { _Pragma("unroll") for (int n = 0; n < 2; ++n) _Pragma("unroll") for (int k = 0; k < 2; ++k) dst[n][k] = *(const PG8_LAS bf16x8*)(lds + PG8_SB(b, h) + boff + n * 2048 + k * 1024); } while (0)
; #define PG8_WAIT_V(n) asm volatile("s_waitcnt vmcnt(" #n ")" ::: "memory")
; #define PG8_WAIT_L(n) asm volatile("s_waitcnt lgkmcnt(" #n ")" ::: "memory")
; #define PG8_BAR __builtin_amdgcn_s_barrier()
; #define PG8_SCHED __builtin_amdgcn_sched_barrier(0)
; template <class Epi, class Sched, bool ALIGN_EPI = false, bool SP2 = false, bool F16 = false, bool TOKPERM = false>
; __device__ __forceinline__ void gemm_phase(PG8_LAS unsigned char* lds, const Gemm g, const Sched& S, const Epi& E, int wv) {
;     ...
;         const bool has_next = S.next(ui + 1, nxt);
;         const char* nA = has_next ? (const char*)g.A + (size_t)nxt.pm * tstep : cA; const char* nB = has_next ? (const char*)g.Bt + (size_t)nxt.pn * tstep : cB;
;         for (int t = 0; t < nt; t += 2) {
;             const bool last = (t == nt - 2);
;             const char* a1 = cA + (size_t)(t + 1) * kstep;
;             const char* a2 = last ? nA : cA + (size_t)(t + 2) * kstep; const char* b2 = last ? nB : cB + (size_t)(t + 2) * kstep;
;             const char* a3 = a2 + kstep; const char* b3 = b2 + kstep;
;             if (last && has_next) S.a_ready(nxt);
;             if constexpr (SP2) {
;             PG8_LDB(B0, 0, 0); PG8_LDB(B1, 0, 1); PG8_SCHED; PG8_LDA(At, 0, 0); PG8_STAGE(PG8_SA(1, 1), a1 + hstep, voffA);
;             PG8_WAIT_V(8); PG8_WAIT_L(0); PG8_BAR; PG8_MMA(0, 0, At, B0); PG8_MMA(0, 1, At, B1); PG8_BAR; PG8_SCHED;
;             PG8_LDA(At, 0, 1); PG8_STAGE(PG8_SB(0, 0), b2, voffB); PG8_STAGE(PG8_SB(0, 1), b2 + hstep, voffB); PG8_STAGE(PG8_SA(0, 0), a2, voffA);
;             PG8_WAIT_V(8); PG8_WAIT_L(0); PG8_BAR; PG8_MMA(1, 0, At, B0); PG8_MMA(1, 1, At, B1); PG8_BAR; PG8_SCHED;
.LBB0_1117:
	s_ashr_i32 s79, s78, 31
	s_lshl_b64 s[14:15], s[78:79], 19
	s_add_u32 s80, s40, s14
	s_addc_u32 s81, s41, s15
	s_and_b64 s[14:15], s[6:7], exec
	s_cselect_b32 s9, s81, s11
	s_cselect_b32 s18, s80, s10
	s_ashr_i32 s77, s76, 31
	s_lshl_b64 s[14:15], s[76:77], 19
	s_add_u32 s82, s0, s14
	s_addc_u32 s83, s1, s15
	s_and_b64 s[14:15], s[6:7], exec
	s_cselect_b32 s19, s83, s13
	s_cselect_b32 s58, s82, s12
	s_add_u32 s59, s12, 0x100
	s_addc_u32 s62, s13, 0
	s_mov_b32 s63, -2
	s_waitcnt lgkmcnt(0)
	ds_read_b128 v[128:131], v190
	ds_read_b128 v[132:135], v191
	ds_read_b128 v[154:157], v192
	ds_read_b128 v[158:161], v193
	ds_read_b128 v[162:165], v194
	ds_read_b128 v[166:169], v195
	ds_read_b128 v[170:173], v196
	ds_read_b128 v[174:177], v197
	s_add_u32 s12, s10, 0x100
	s_addc_u32 s13, s11, 0
	s_cmp_eq_u32 s63, 12
	s_cselect_b32 s17, s9, s13
	s_cselect_b32 s16, s18, s12
	s_cselect_b32 s15, s19, s62
	s_cselect_b32 s14, s58, s59
	s_mov_b32 m0, s22
	v_lshl_add_u64 v[236:237], s[10:11], 0, v[146:147]
	ds_read_b128 v[178:181], v187
	ds_read_b128 v[182:185], v187 offset:1024
	ds_read_b128 v[210:213], v187 offset:2048
	ds_read_b128 v[214:217], v187 offset:3072
	ds_read_b128 v[218:221], v187 offset:4096
	ds_read_b128 v[222:225], v187 offset:5120
	ds_read_b128 v[228:231], v187 offset:6144
	ds_read_b128 v[232:235], v187 offset:7168
	global_load_lds_dwordx4 v[236:237], off
	v_lshl_add_u64 v[236:237], s[10:11], 0, v[148:149]
	s_mov_b32 m0, s23
	s_nop 0
	global_load_lds_dwordx4 v[236:237], off
	s_waitcnt vmcnt(8)
	s_waitcnt lgkmcnt(0)
	s_barrier
	s_waitcnt lgkmcnt(0)
	v_mfma_f32_16x16x32_f16 v[124:127], v[128:131], v[178:181], 0
	v_mfma_f32_16x16x32_f16 v[108:111], v[154:157], v[178:181], 0
	v_mfma_f32_16x16x32_f16 v[120:123], v[128:131], v[210:213], 0
	v_mfma_f32_16x16x32_f16 v[104:107], v[154:157], v[210:213], 0
	v_mfma_f32_16x16x32_f16 v[116:119], v[128:131], v[218:221], 0
	v_mfma_f32_16x16x32_f16 v[100:103], v[154:157], v[218:221], 0
	v_mfma_f32_16x16x32_f16 v[112:115], v[128:131], v[228:231], 0
	v_mfma_f32_16x16x32_f16 v[96:99], v[154:157], v[228:231], 0
	v_mfma_f32_16x16x32_f16 v[124:127], v[132:135], v[182:185], v[124:127]
	v_mfma_f32_16x16x32_f16 v[108:111], v[158:161], v[182:185], v[108:111]
	v_mfma_f32_16x16x32_f16 v[120:123], v[132:135], v[214:217], v[120:123]
	v_mfma_f32_16x16x32_f16 v[104:107], v[158:161], v[214:217], v[104:107]
	v_mfma_f32_16x16x32_f16 v[116:119], v[132:135], v[222:225], v[116:119]
	v_mfma_f32_16x16x32_f16 v[100:103], v[158:161], v[222:225], v[100:103]
	v_mfma_f32_16x16x32_f16 v[112:115], v[132:135], v[232:235], v[112:115]
	v_mfma_f32_16x16x32_f16 v[96:99], v[158:161], v[232:235], v[96:99]
	v_mfma_f32_16x16x32_f16 v[92:95], v[162:165], v[178:181], 0
	v_mfma_f32_16x16x32_f16 v[76:79], v[170:173], v[178:181], 0
	v_mfma_f32_16x16x32_f16 v[88:91], v[162:165], v[210:213], 0
	v_mfma_f32_16x16x32_f16 v[72:75], v[170:173], v[210:213], 0
	v_mfma_f32_16x16x32_f16 v[84:87], v[162:165], v[218:221], 0
	v_mfma_f32_16x16x32_f16 v[68:71], v[170:173], v[218:221], 0
	v_mfma_f32_16x16x32_f16 v[80:83], v[162:165], v[228:231], 0
	v_mfma_f32_16x16x32_f16 v[64:67], v[170:173], v[228:231], 0
	v_mfma_f32_16x16x32_f16 v[92:95], v[166:169], v[182:185], v[92:95]
	v_mfma_f32_16x16x32_f16 v[76:79], v[174:177], v[182:185], v[76:79]
	v_mfma_f32_16x16x32_f16 v[88:91], v[166:169], v[214:217], v[88:91]
	v_mfma_f32_16x16x32_f16 v[72:75], v[174:177], v[214:217], v[72:75]
	v_mfma_f32_16x16x32_f16 v[84:87], v[166:169], v[222:225], v[84:87]
	v_mfma_f32_16x16x32_f16 v[68:71], v[174:177], v[222:225], v[68:71]
	v_mfma_f32_16x16x32_f16 v[80:83], v[166:169], v[232:235], v[80:83]
	v_mfma_f32_16x16x32_f16 v[64:67], v[174:177], v[232:235], v[64:67]
	s_barrier
	s_mov_b32 m0, s3
	v_lshl_add_u64 v[236:237], s[14:15], 0, v[138:139]
	s_add_u32 s10, s14, 0x40000
	ds_read_b128 v[178:181], v187 offset:16384
	ds_read_b128 v[182:185], v187 offset:17408
	ds_read_b128 v[210:213], v187 offset:18432
	ds_read_b128 v[214:217], v187 offset:19456
	ds_read_b128 v[218:221], v187 offset:20480
	ds_read_b128 v[222:225], v187 offset:21504
	ds_read_b128 v[228:231], v187 offset:22528
	ds_read_b128 v[232:235], v187 offset:23552
	global_load_lds_dwordx4 v[236:237], off
	v_lshl_add_u64 v[238:239], s[14:15], 0, v[142:143]
	s_mov_b32 m0, s33
	s_addc_u32 s11, s15, 0
	global_load_lds_dwordx4 v[238:239], off
	v_lshl_add_u64 v[240:241], s[10:11], 0, v[138:139]
	s_mov_b32 m0, s36
	v_lshl_add_u64 v[242:243], s[16:17], 0, v[140:141]
	global_load_lds_dwordx4 v[240:241], off
	v_lshl_add_u64 v[240:241], s[10:11], 0, v[142:143]
	s_mov_b32 m0, s37
	s_nop 0
	global_load_lds_dwordx4 v[240:241], off
	v_lshl_add_u64 v[240:241], s[16:17], 0, v[136:137]
	s_mov_b32 m0, s2
	s_nop 0
	global_load_lds_dwordx4 v[240:241], off
	s_mov_b32 m0, s44
	s_nop 0
	global_load_lds_dwordx4 v[242:243], off
	s_waitcnt vmcnt(8)
	s_waitcnt lgkmcnt(0)
	s_barrier
; #define PG8_STAGE(bufoff, gbase, voff) do { _Pragma("unroll") for (int _i = 0; _i < 2; ++_i) \
;         __builtin_amdgcn_global_load_lds((const unsigned*)((const char*)(gbase) + (voff)[_i]), (PG8_LAS unsigned*)(lds + (bufoff) + ldsw + _i * 8192), 16, 0, 0); } while (0)
; #define PG8_LDA(dst, b, h) do { _Pragma("unroll") for (int m = 0; m < 4; ++m) _Pragma("unroll") for (int k = 0; k < 2; ++k) dst[m][k] = *(const PG8_LAS bf16x8*)(lds + PG8_SA(b, h) + aoff + m * 2048 + k * 1024); } while (0)
; #define PG8_LDB(dst, b, h) do { _Pragma("unroll") for (int n = 0; n < 2; ++n) _Pragma("unroll") for (int k = 0; k < 2; ++k) dst[n][k] = *(const PG8_LAS bf16x8*)(lds + PG8_SB(b, h) + boff + n * 2048 + k * 1024); } while (0)
; #define PG8_MMA(ai, bj, At, Bt) do { __builtin_amdgcn_s_setprio(1); _Pragma("unroll") for (int m = 0; m < 4; ++m) _Pragma("unroll") for (int n = 0; n < 2; ++n) _Pragma("unroll") for (int k = 0; k < 2; ++k) \
;         acc[ai][bj][m][n] = mma16<F16>(Bt[n][k], At[m][k], acc[ai][bj][m][n]); __builtin_amdgcn_s_setprio(0); } while (0)
; #define PG8_WAIT_V(n) asm volatile("s_waitcnt vmcnt(" #n ")" ::: "memory")
; #define PG8_WAIT_L(n) asm volatile("s_waitcnt lgkmcnt(" #n ")" ::: "memory")
; template <class Epi, class Sched, bool ALIGN_EPI = false, bool SP2 = false, bool F16 = false, bool TOKPERM = false>
; __device__ __forceinline__ void gemm_phase(PG8_LAS unsigned char* lds, const Gemm g, const Sched& S, const Epi& E, int wv) {
;     ...
;             PG8_WAIT_V(8); PG8_WAIT_L(0); PG8_BAR; PG8_MMA(0, 0, At, B0); PG8_MMA(0, 1, At, B1); PG8_BAR; PG8_SCHED;
;             PG8_LDA(At, 0, 1); PG8_STAGE(PG8_SB(0, 0), b2, voffB); PG8_STAGE(PG8_SB(0, 1), b2 + hstep, voffB); PG8_STAGE(PG8_SA(0, 0), a2, voffA);
;             PG8_WAIT_V(8); PG8_WAIT_L(0); PG8_BAR; PG8_MMA(1, 0, At, B0); PG8_MMA(1, 1, At, B1); PG8_BAR; PG8_SCHED;
;             PG8_LDB(B0, 1, 0); PG8_LDB(B1, 1, 1); PG8_SCHED; PG8_LDA(At, 1, 0); PG8_STAGE(PG8_SA(0, 1), a2 + hstep, voffA);
;             PG8_WAIT_V(8); PG8_WAIT_L(0); PG8_BAR; PG8_MMA(0, 0, At, B0); PG8_MMA(0, 1, At, B1); PG8_BAR; PG8_SCHED;
;             PG8_LDA(At, 1, 1); PG8_STAGE(PG8_SB(1, 0), b3, voffB); PG8_STAGE(PG8_SB(1, 1), b3 + hstep, voffB); PG8_STAGE(PG8_SA(1, 0), a3, voffA);
;             PG8_WAIT_V(8); PG8_WAIT_L(0); PG8_BAR; PG8_MMA(1, 0, At, B0); PG8_MMA(1, 1, At, B1); PG8_BAR; PG8_SCHED;
	s_waitcnt lgkmcnt(0)
	v_mfma_f32_16x16x32_f16 v[60:63], v[128:131], v[178:181], 0
	v_mfma_f32_16x16x32_f16 v[44:47], v[154:157], v[178:181], 0
	v_mfma_f32_16x16x32_f16 v[56:59], v[128:131], v[210:213], 0
	v_mfma_f32_16x16x32_f16 v[40:43], v[154:157], v[210:213], 0
	v_mfma_f32_16x16x32_f16 v[52:55], v[128:131], v[218:221], 0
	v_mfma_f32_16x16x32_f16 v[36:39], v[154:157], v[218:221], 0
	v_mfma_f32_16x16x32_f16 v[48:51], v[128:131], v[228:231], 0
	v_mfma_f32_16x16x32_f16 v[32:35], v[154:157], v[228:231], 0
	v_mfma_f32_16x16x32_f16 v[60:63], v[132:135], v[182:185], v[60:63]
	v_mfma_f32_16x16x32_f16 v[44:47], v[158:161], v[182:185], v[44:47]
	v_mfma_f32_16x16x32_f16 v[56:59], v[132:135], v[214:217], v[56:59]
	v_mfma_f32_16x16x32_f16 v[40:43], v[158:161], v[214:217], v[40:43]
	v_mfma_f32_16x16x32_f16 v[52:55], v[132:135], v[222:225], v[52:55]
	v_mfma_f32_16x16x32_f16 v[36:39], v[158:161], v[222:225], v[36:39]
	v_mfma_f32_16x16x32_f16 v[48:51], v[132:135], v[232:235], v[48:51]
	v_mfma_f32_16x16x32_f16 v[32:35], v[158:161], v[232:235], v[32:35]
	v_mfma_f32_16x16x32_f16 v[28:31], v[162:165], v[178:181], 0
	v_mfma_f32_16x16x32_f16 v[12:15], v[170:173], v[178:181], 0
	v_mfma_f32_16x16x32_f16 v[24:27], v[162:165], v[210:213], 0
	v_mfma_f32_16x16x32_f16 v[8:11], v[170:173], v[210:213], 0
	v_mfma_f32_16x16x32_f16 v[20:23], v[162:165], v[218:221], 0
	v_mfma_f32_16x16x32_f16 v[4:7], v[170:173], v[218:221], 0
	v_mfma_f32_16x16x32_f16 v[16:19], v[162:165], v[228:231], 0
	v_mfma_f32_16x16x32_f16 v[0:3], v[170:173], v[228:231], 0
	v_mfma_f32_16x16x32_f16 v[28:31], v[166:169], v[182:185], v[28:31]
	v_mfma_f32_16x16x32_f16 v[12:15], v[174:177], v[182:185], v[12:15]
	v_mfma_f32_16x16x32_f16 v[24:27], v[166:169], v[214:217], v[24:27]
	v_mfma_f32_16x16x32_f16 v[8:11], v[174:177], v[214:217], v[8:11]
	v_mfma_f32_16x16x32_f16 v[20:23], v[166:169], v[222:225], v[20:23]
	v_mfma_f32_16x16x32_f16 v[4:7], v[174:177], v[222:225], v[4:7]
	v_mfma_f32_16x16x32_f16 v[16:19], v[166:169], v[232:235], v[16:19]
	v_mfma_f32_16x16x32_f16 v[0:3], v[174:177], v[232:235], v[0:3]
	s_barrier
	ds_read_b128 v[128:131], v198
	ds_read_b128 v[132:135], v199
	ds_read_b128 v[154:157], v200
	ds_read_b128 v[158:161], v201
	ds_read_b128 v[162:165], v202
	ds_read_b128 v[166:169], v203
	ds_read_b128 v[170:173], v204
	ds_read_b128 v[174:177], v205
	s_add_u32 s10, s16, 0x40000
	s_addc_u32 s11, s17, 0
	s_mov_b32 m0, s45
	v_lshl_add_u64 v[244:245], s[10:11], 0, v[136:137]
	ds_read_b128 v[178:181], v187 offset:32768
	ds_read_b128 v[182:185], v187 offset:33792
	ds_read_b128 v[210:213], v187 offset:34816
	ds_read_b128 v[214:217], v187 offset:35840
	ds_read_b128 v[218:221], v187 offset:36864
	ds_read_b128 v[222:225], v187 offset:37888
	ds_read_b128 v[228:231], v187 offset:38912
	ds_read_b128 v[232:235], v187 offset:39936
	global_load_lds_dwordx4 v[244:245], off
	v_lshl_add_u64 v[244:245], s[10:11], 0, v[140:141]
	s_mov_b32 m0, s61
	s_nop 0
	global_load_lds_dwordx4 v[244:245], off
	s_waitcnt vmcnt(8)
	s_waitcnt lgkmcnt(0)
	s_barrier
	s_waitcnt lgkmcnt(0)
	v_mfma_f32_16x16x32_f16 v[124:127], v[128:131], v[178:181], v[124:127]
	v_mfma_f32_16x16x32_f16 v[108:111], v[154:157], v[178:181], v[108:111]
	v_mfma_f32_16x16x32_f16 v[120:123], v[128:131], v[210:213], v[120:123]
	v_mfma_f32_16x16x32_f16 v[104:107], v[154:157], v[210:213], v[104:107]
	v_mfma_f32_16x16x32_f16 v[116:119], v[128:131], v[218:221], v[116:119]
	v_mfma_f32_16x16x32_f16 v[100:103], v[154:157], v[218:221], v[100:103]
	v_mfma_f32_16x16x32_f16 v[112:115], v[128:131], v[228:231], v[112:115]
	v_mfma_f32_16x16x32_f16 v[96:99], v[154:157], v[228:231], v[96:99]
	v_mfma_f32_16x16x32_f16 v[124:127], v[132:135], v[182:185], v[124:127]
	v_mfma_f32_16x16x32_f16 v[108:111], v[158:161], v[182:185], v[108:111]
	v_mfma_f32_16x16x32_f16 v[120:123], v[132:135], v[214:217], v[120:123]
	v_mfma_f32_16x16x32_f16 v[104:107], v[158:161], v[214:217], v[104:107]
	v_mfma_f32_16x16x32_f16 v[116:119], v[132:135], v[222:225], v[116:119]
	v_mfma_f32_16x16x32_f16 v[100:103], v[158:161], v[222:225], v[100:103]
	v_mfma_f32_16x16x32_f16 v[112:115], v[132:135], v[232:235], v[112:115]
	v_mfma_f32_16x16x32_f16 v[96:99], v[158:161], v[232:235], v[96:99]
	v_mfma_f32_16x16x32_f16 v[92:95], v[162:165], v[178:181], v[92:95]
	v_mfma_f32_16x16x32_f16 v[76:79], v[170:173], v[178:181], v[76:79]
	v_mfma_f32_16x16x32_f16 v[88:91], v[162:165], v[210:213], v[88:91]
	v_mfma_f32_16x16x32_f16 v[72:75], v[170:173], v[210:213], v[72:75]
	v_mfma_f32_16x16x32_f16 v[84:87], v[162:165], v[218:221], v[84:87]
	v_mfma_f32_16x16x32_f16 v[68:71], v[170:173], v[218:221], v[68:71]
	v_mfma_f32_16x16x32_f16 v[80:83], v[162:165], v[228:231], v[80:83]
	v_mfma_f32_16x16x32_f16 v[64:67], v[170:173], v[228:231], v[64:67]
	v_mfma_f32_16x16x32_f16 v[92:95], v[166:169], v[182:185], v[92:95]
	v_mfma_f32_16x16x32_f16 v[76:79], v[174:177], v[182:185], v[76:79]
	v_mfma_f32_16x16x32_f16 v[88:91], v[166:169], v[214:217], v[88:91]
	v_mfma_f32_16x16x32_f16 v[72:75], v[174:177], v[214:217], v[72:75]
	v_mfma_f32_16x16x32_f16 v[84:87], v[166:169], v[222:225], v[84:87]
	v_mfma_f32_16x16x32_f16 v[68:71], v[174:177], v[222:225], v[68:71]
	v_mfma_f32_16x16x32_f16 v[80:83], v[166:169], v[232:235], v[80:83]
	v_mfma_f32_16x16x32_f16 v[64:67], v[174:177], v[232:235], v[64:67]
	s_barrier
; #define PG8_STAGE(bufoff, gbase, voff) do { _Pragma("unroll") for (int _i = 0; _i < 2; ++_i) \
;         __builtin_amdgcn_global_load_lds((const unsigned*)((const char*)(gbase) + (voff)[_i]), (PG8_LAS unsigned*)(lds + (bufoff) + ldsw + _i * 8192), 16, 0, 0); } while (0)
; #define PG8_LDA(dst, b, h) do { _Pragma("unroll") for (int m = 0; m < 4; ++m) _Pragma("unroll") for (int k = 0; k < 2; ++k) dst[m][k] = *(const PG8_LAS bf16x8*)(lds + PG8_SA(b, h) + aoff + m * 2048 + k * 1024); } while (0)
; #define PG8_LDB(dst, b, h) do { _Pragma("unroll") for (int n = 0; n < 2; ++n) _Pragma("unroll") for (int k = 0; k < 2; ++k) dst[n][k] = *(const PG8_LAS bf16x8*)(lds + PG8_SB(b, h) + boff + n * 2048 + k * 1024); } while (0)
; #define PG8_MMA(ai, bj, At, Bt) do { __builtin_amdgcn_s_setprio(1); _Pragma("unroll") for (int m = 0; m < 4; ++m) _Pragma("unroll") for (int n = 0; n < 2; ++n) _Pragma("unroll") for (int k = 0; k < 2; ++k) \
;         acc[ai][bj][m][n] = mma16<F16>(Bt[n][k], At[m][k], acc[ai][bj][m][n]); __builtin_amdgcn_s_setprio(0); } while (0)
; #define PG8_BAR __builtin_amdgcn_s_barrier()
; template <class Epi, class Sched, bool ALIGN_EPI = false, bool SP2 = false, bool F16 = false, bool TOKPERM = false>
; __device__ __forceinline__ void gemm_phase(PG8_LAS unsigned char* lds, const Gemm g, const Sched& S, const Epi& E, int wv) {
;     ...
;             PG8_LDB(B0, 0, 0); PG8_LDB(B1, 0, 1); PG8_SCHED; PG8_LDA(At, 0, 0); PG8_STAGE(PG8_SA(1, 1), a1 + hstep, voffA);
;             PG8_WAIT_V(8); PG8_WAIT_L(0); PG8_BAR; PG8_MMA(0, 0, At, B0); PG8_MMA(0, 1, At, B1); PG8_BAR; PG8_SCHED;
;             PG8_LDA(At, 0, 1); PG8_STAGE(PG8_SB(0, 0), b2, voffB); PG8_STAGE(PG8_SB(0, 1), b2 + hstep, voffB); PG8_STAGE(PG8_SA(0, 0), a2, voffA);
;             PG8_WAIT_V(8); PG8_WAIT_L(0); PG8_BAR; PG8_MMA(1, 0, At, B0); PG8_MMA(1, 1, At, B1); PG8_BAR; PG8_SCHED;
;             PG8_LDB(B0, 1, 0); PG8_LDB(B1, 1, 1); PG8_SCHED; PG8_LDA(At, 1, 0); PG8_STAGE(PG8_SA(0, 1), a2 + hstep, voffA);
;             PG8_WAIT_V(8); PG8_WAIT_L(0); PG8_BAR; PG8_MMA(0, 0, At, B0); PG8_MMA(0, 1, At, B1); PG8_BAR; PG8_SCHED;
;             PG8_LDA(At, 1, 1); PG8_STAGE(PG8_SB(1, 0), b3, voffB); PG8_STAGE(PG8_SB(1, 1), b3 + hstep, voffB); PG8_STAGE(PG8_SA(1, 0), a3, voffA);
;             PG8_WAIT_V(8); PG8_WAIT_L(0); PG8_BAR; PG8_MMA(1, 0, At, B0); PG8_MMA(1, 1, At, B1); PG8_BAR; PG8_SCHED;
	s_mov_b32 m0, s94
	v_lshl_add_u64 v[236:237], v[236:237], 0, s[64:65]
	s_add_u32 s10, s14, 0x40080
	ds_read_b128 v[178:181], v187 offset:49152
	ds_read_b128 v[182:185], v187 offset:50176
	ds_read_b128 v[210:213], v187 offset:51200
	ds_read_b128 v[214:217], v187 offset:52224
	ds_read_b128 v[218:221], v187 offset:53248
	ds_read_b128 v[222:225], v187 offset:54272
	ds_read_b128 v[228:231], v187 offset:55296
	ds_read_b128 v[232:235], v187 offset:56320
	global_load_lds_dwordx4 v[236:237], off
	v_lshl_add_u64 v[236:237], v[238:239], 0, s[64:65]
	s_mov_b32 m0, s97
	s_addc_u32 s11, s15, 0
	global_load_lds_dwordx4 v[236:237], off
	v_lshl_add_u64 v[236:237], s[10:11], 0, v[138:139]
	s_mov_b32 m0, s73
	s_nop 0
	global_load_lds_dwordx4 v[236:237], off
	v_lshl_add_u64 v[236:237], s[10:11], 0, v[142:143]
	s_mov_b32 m0, s75
	s_nop 0
	global_load_lds_dwordx4 v[236:237], off
	v_lshl_add_u64 v[236:237], v[240:241], 0, s[64:65]
	s_mov_b32 m0, s4
	s_nop 0
	global_load_lds_dwordx4 v[236:237], off
	v_lshl_add_u64 v[236:237], v[242:243], 0, s[64:65]
	s_mov_b32 m0, s71
	s_nop 0
	global_load_lds_dwordx4 v[236:237], off
	s_waitcnt vmcnt(8)
	s_waitcnt lgkmcnt(0)
	s_barrier
	s_waitcnt lgkmcnt(0)
	v_mfma_f32_16x16x32_f16 v[60:63], v[128:131], v[178:181], v[60:63]
	v_mfma_f32_16x16x32_f16 v[44:47], v[154:157], v[178:181], v[44:47]
	v_mfma_f32_16x16x32_f16 v[56:59], v[128:131], v[210:213], v[56:59]
	v_mfma_f32_16x16x32_f16 v[40:43], v[154:157], v[210:213], v[40:43]
	v_mfma_f32_16x16x32_f16 v[52:55], v[128:131], v[218:221], v[52:55]
	v_mfma_f32_16x16x32_f16 v[36:39], v[154:157], v[218:221], v[36:39]
	v_mfma_f32_16x16x32_f16 v[48:51], v[128:131], v[228:231], v[48:51]
	v_mfma_f32_16x16x32_f16 v[32:35], v[154:157], v[228:231], v[32:35]
	v_mfma_f32_16x16x32_f16 v[60:63], v[132:135], v[182:185], v[60:63]
	v_mfma_f32_16x16x32_f16 v[44:47], v[158:161], v[182:185], v[44:47]
	v_mfma_f32_16x16x32_f16 v[56:59], v[132:135], v[214:217], v[56:59]
	v_mfma_f32_16x16x32_f16 v[40:43], v[158:161], v[214:217], v[40:43]
	v_mfma_f32_16x16x32_f16 v[52:55], v[132:135], v[222:225], v[52:55]
	v_mfma_f32_16x16x32_f16 v[36:39], v[158:161], v[222:225], v[36:39]
	v_mfma_f32_16x16x32_f16 v[48:51], v[132:135], v[232:235], v[48:51]
	v_mfma_f32_16x16x32_f16 v[32:35], v[158:161], v[232:235], v[32:35]
	v_mfma_f32_16x16x32_f16 v[28:31], v[162:165], v[178:181], v[28:31]
	v_mfma_f32_16x16x32_f16 v[12:15], v[170:173], v[178:181], v[12:15]
	v_mfma_f32_16x16x32_f16 v[24:27], v[162:165], v[210:213], v[24:27]
	v_mfma_f32_16x16x32_f16 v[8:11], v[170:173], v[210:213], v[8:11]
	v_mfma_f32_16x16x32_f16 v[20:23], v[162:165], v[218:221], v[20:23]
	v_mfma_f32_16x16x32_f16 v[4:7], v[170:173], v[218:221], v[4:7]
	v_mfma_f32_16x16x32_f16 v[16:19], v[162:165], v[228:231], v[16:19]
	v_mfma_f32_16x16x32_f16 v[0:3], v[170:173], v[228:231], v[0:3]
	v_mfma_f32_16x16x32_f16 v[28:31], v[166:169], v[182:185], v[28:31]
	v_mfma_f32_16x16x32_f16 v[12:15], v[174:177], v[182:185], v[12:15]
	v_mfma_f32_16x16x32_f16 v[24:27], v[166:169], v[214:217], v[24:27]
	v_mfma_f32_16x16x32_f16 v[8:11], v[174:177], v[214:217], v[8:11]
	v_mfma_f32_16x16x32_f16 v[20:23], v[166:169], v[222:225], v[20:23]
	v_mfma_f32_16x16x32_f16 v[4:7], v[174:177], v[222:225], v[4:7]
	v_mfma_f32_16x16x32_f16 v[16:19], v[166:169], v[232:235], v[16:19]
	v_mfma_f32_16x16x32_f16 v[0:3], v[174:177], v[232:235], v[0:3]
	s_barrier
	s_add_i32 s63, s63, 2
	s_add_u32 s59, s59, 0x100
	s_addc_u32 s62, s62, 0
	s_cmp_gt_u32 s63, 13
	s_mov_b64 s[10:11], s[12:13]
.LBB0_1118:
	ds_read_b128 v[128:131], v190
	ds_read_b128 v[132:135], v191
	ds_read_b128 v[154:157], v192
	ds_read_b128 v[158:161], v193
	ds_read_b128 v[162:165], v194
	ds_read_b128 v[166:169], v195
	ds_read_b128 v[170:173], v196
	ds_read_b128 v[174:177], v197
	s_add_u32 s12, s10, 0x100
	s_addc_u32 s13, s11, 0
	s_cmp_eq_u32 s63, 12
	s_cselect_b32 s17, s9, s13
	s_cselect_b32 s16, s18, s12
	s_cselect_b32 s15, s19, s62
	s_cselect_b32 s14, s58, s59
	s_mov_b32 m0, s22
	v_lshl_add_u64 v[236:237], s[10:11], 0, v[146:147]
	ds_read_b128 v[178:181], v187
	ds_read_b128 v[182:185], v187 offset:1024
	ds_read_b128 v[210:213], v187 offset:2048
	ds_read_b128 v[214:217], v187 offset:3072
	ds_read_b128 v[218:221], v187 offset:4096
	ds_read_b128 v[222:225], v187 offset:5120
	ds_read_b128 v[228:231], v187 offset:6144
	ds_read_b128 v[232:235], v187 offset:7168
	global_load_lds_dwordx4 v[236:237], off
	v_lshl_add_u64 v[236:237], s[10:11], 0, v[148:149]
	s_mov_b32 m0, s23
	s_nop 0
	global_load_lds_dwordx4 v[236:237], off
	s_waitcnt vmcnt(8)
	s_waitcnt lgkmcnt(0)
	s_barrier
; #define PG8_STAGE(bufoff, gbase, voff) do { _Pragma("unroll") for (int _i = 0; _i < 2; ++_i) \
;         __builtin_amdgcn_global_load_lds((const unsigned*)((const char*)(gbase) + (voff)[_i]), (PG8_LAS unsigned*)(lds + (bufoff) + ldsw + _i * 8192), 16, 0, 0); } while (0)
; #define PG8_LDA(dst, b, h) do { _Pragma("unroll") for (int m = 0; m < 4; ++m) _Pragma("unroll") for (int k = 0; k < 2; ++k) dst[m][k] = *(const PG8_LAS bf16x8*)(lds + PG8_SA(b, h) + aoff + m * 2048 + k * 1024); } while (0)
; #define PG8_LDB(dst, b, h) do { _Pragma("unroll") for (int n = 0; n < 2; ++n) _Pragma("unroll") for (int k = 0; k < 2; ++k) dst[n][k] = *(const PG8_LAS bf16x8*)(lds + PG8_SB(b, h) + boff + n * 2048 + k * 1024); } while (0)
; #define PG8_MMA(ai, bj, At, Bt) do { __builtin_amdgcn_s_setprio(1); _Pragma("unroll") for (int m = 0; m < 4; ++m) _Pragma("unroll") for (int n = 0; n < 2; ++n) _Pragma("unroll") for (int k = 0; k < 2; ++k) \
;         acc[ai][bj][m][n] = mma16<F16>(Bt[n][k], At[m][k], acc[ai][bj][m][n]); __builtin_amdgcn_s_setprio(0); } while (0)
; #define PG8_WAIT_V(n) asm volatile("s_waitcnt vmcnt(" #n ")" ::: "memory")
; #define PG8_WAIT_L(n) asm volatile("s_waitcnt lgkmcnt(" #n ")" ::: "memory")
; #define PG8_BAR __builtin_amdgcn_s_barrier()
; #define PG8_SCHED __builtin_amdgcn_sched_barrier(0)
; template <class Epi, class Sched, bool ALIGN_EPI = false, bool SP2 = false, bool F16 = false, bool TOKPERM = false>
; __device__ __forceinline__ void gemm_phase(PG8_LAS unsigned char* lds, const Gemm g, const Sched& S, const Epi& E, int wv) {
;     ...
;             PG8_LDB(B0, 0, 0); PG8_LDB(B1, 0, 1); PG8_SCHED; PG8_LDA(At, 0, 0); PG8_STAGE(PG8_SA(1, 1), a1 + hstep, voffA);
;             PG8_WAIT_V(8); PG8_WAIT_L(0); PG8_BAR; PG8_MMA(0, 0, At, B0); PG8_MMA(0, 1, At, B1); PG8_BAR; PG8_SCHED;
;             PG8_LDA(At, 0, 1); PG8_STAGE(PG8_SB(0, 0), b2, voffB); PG8_STAGE(PG8_SB(0, 1), b2 + hstep, voffB); PG8_STAGE(PG8_SA(0, 0), a2, voffA);
;             PG8_WAIT_V(8); PG8_WAIT_L(0); PG8_BAR; PG8_MMA(1, 0, At, B0); PG8_MMA(1, 1, At, B1); PG8_BAR; PG8_SCHED;
	s_waitcnt lgkmcnt(0)
	v_mfma_f32_16x16x32_f16 v[124:127], v[128:131], v[178:181], v[124:127]
	v_mfma_f32_16x16x32_f16 v[108:111], v[154:157], v[178:181], v[108:111]
	v_mfma_f32_16x16x32_f16 v[120:123], v[128:131], v[210:213], v[120:123]
	v_mfma_f32_16x16x32_f16 v[104:107], v[154:157], v[210:213], v[104:107]
	v_mfma_f32_16x16x32_f16 v[116:119], v[128:131], v[218:221], v[116:119]
	v_mfma_f32_16x16x32_f16 v[100:103], v[154:157], v[218:221], v[100:103]
	v_mfma_f32_16x16x32_f16 v[112:115], v[128:131], v[228:231], v[112:115]
	v_mfma_f32_16x16x32_f16 v[96:99], v[154:157], v[228:231], v[96:99]
	v_mfma_f32_16x16x32_f16 v[124:127], v[132:135], v[182:185], v[124:127]
	v_mfma_f32_16x16x32_f16 v[108:111], v[158:161], v[182:185], v[108:111]
	v_mfma_f32_16x16x32_f16 v[120:123], v[132:135], v[214:217], v[120:123]
	v_mfma_f32_16x16x32_f16 v[104:107], v[158:161], v[214:217], v[104:107]
	v_mfma_f32_16x16x32_f16 v[116:119], v[132:135], v[222:225], v[116:119]
	v_mfma_f32_16x16x32_f16 v[100:103], v[158:161], v[222:225], v[100:103]
	v_mfma_f32_16x16x32_f16 v[112:115], v[132:135], v[232:235], v[112:115]
	v_mfma_f32_16x16x32_f16 v[96:99], v[158:161], v[232:235], v[96:99]
	v_mfma_f32_16x16x32_f16 v[92:95], v[162:165], v[178:181], v[92:95]
	v_mfma_f32_16x16x32_f16 v[76:79], v[170:173], v[178:181], v[76:79]
	v_mfma_f32_16x16x32_f16 v[88:91], v[162:165], v[210:213], v[88:91]
	v_mfma_f32_16x16x32_f16 v[72:75], v[170:173], v[210:213], v[72:75]
	v_mfma_f32_16x16x32_f16 v[84:87], v[162:165], v[218:221], v[84:87]
	v_mfma_f32_16x16x32_f16 v[68:71], v[170:173], v[218:221], v[68:71]
	v_mfma_f32_16x16x32_f16 v[80:83], v[162:165], v[228:231], v[80:83]
	v_mfma_f32_16x16x32_f16 v[64:67], v[170:173], v[228:231], v[64:67]
	v_mfma_f32_16x16x32_f16 v[92:95], v[166:169], v[182:185], v[92:95]
	v_mfma_f32_16x16x32_f16 v[76:79], v[174:177], v[182:185], v[76:79]
	v_mfma_f32_16x16x32_f16 v[88:91], v[166:169], v[214:217], v[88:91]
	v_mfma_f32_16x16x32_f16 v[72:75], v[174:177], v[214:217], v[72:75]
	v_mfma_f32_16x16x32_f16 v[84:87], v[166:169], v[222:225], v[84:87]
	v_mfma_f32_16x16x32_f16 v[68:71], v[174:177], v[222:225], v[68:71]
	v_mfma_f32_16x16x32_f16 v[80:83], v[166:169], v[232:235], v[80:83]
	v_mfma_f32_16x16x32_f16 v[64:67], v[174:177], v[232:235], v[64:67]
	s_barrier
	s_mov_b32 m0, s3
	v_lshl_add_u64 v[236:237], s[14:15], 0, v[138:139]
	s_add_u32 s10, s14, 0x40000
	ds_read_b128 v[178:181], v187 offset:16384
	ds_read_b128 v[182:185], v187 offset:17408
	ds_read_b128 v[210:213], v187 offset:18432
	ds_read_b128 v[214:217], v187 offset:19456
	ds_read_b128 v[218:221], v187 offset:20480
	ds_read_b128 v[222:225], v187 offset:21504
	ds_read_b128 v[228:231], v187 offset:22528
	ds_read_b128 v[232:235], v187 offset:23552
	global_load_lds_dwordx4 v[236:237], off
	v_lshl_add_u64 v[238:239], s[14:15], 0, v[142:143]
	s_mov_b32 m0, s33
	s_addc_u32 s11, s15, 0
	global_load_lds_dwordx4 v[238:239], off
	v_lshl_add_u64 v[240:241], s[10:11], 0, v[138:139]
	s_mov_b32 m0, s36
	v_lshl_add_u64 v[242:243], s[16:17], 0, v[140:141]
	global_load_lds_dwordx4 v[240:241], off
	v_lshl_add_u64 v[240:241], s[10:11], 0, v[142:143]
	s_mov_b32 m0, s37
	s_nop 0
	global_load_lds_dwordx4 v[240:241], off
	v_lshl_add_u64 v[240:241], s[16:17], 0, v[136:137]
	s_mov_b32 m0, s2
	s_nop 0
	global_load_lds_dwordx4 v[240:241], off
	s_mov_b32 m0, s44
	s_nop 0
	global_load_lds_dwordx4 v[242:243], off
	s_waitcnt vmcnt(8)
	s_waitcnt lgkmcnt(0)
	s_barrier
	s_waitcnt lgkmcnt(0)
	v_mfma_f32_16x16x32_f16 v[60:63], v[128:131], v[178:181], v[60:63]
	v_mfma_f32_16x16x32_f16 v[44:47], v[154:157], v[178:181], v[44:47]
	v_mfma_f32_16x16x32_f16 v[56:59], v[128:131], v[210:213], v[56:59]
	v_mfma_f32_16x16x32_f16 v[40:43], v[154:157], v[210:213], v[40:43]
	v_mfma_f32_16x16x32_f16 v[52:55], v[128:131], v[218:221], v[52:55]
	v_mfma_f32_16x16x32_f16 v[36:39], v[154:157], v[218:221], v[36:39]
	v_mfma_f32_16x16x32_f16 v[48:51], v[128:131], v[228:231], v[48:51]
	v_mfma_f32_16x16x32_f16 v[32:35], v[154:157], v[228:231], v[32:35]
	v_mfma_f32_16x16x32_f16 v[60:63], v[132:135], v[182:185], v[60:63]
	v_mfma_f32_16x16x32_f16 v[44:47], v[158:161], v[182:185], v[44:47]
	v_mfma_f32_16x16x32_f16 v[56:59], v[132:135], v[214:217], v[56:59]
	v_mfma_f32_16x16x32_f16 v[40:43], v[158:161], v[214:217], v[40:43]
	v_mfma_f32_16x16x32_f16 v[52:55], v[132:135], v[222:225], v[52:55]
	v_mfma_f32_16x16x32_f16 v[36:39], v[158:161], v[222:225], v[36:39]
	v_mfma_f32_16x16x32_f16 v[48:51], v[132:135], v[232:235], v[48:51]
	v_mfma_f32_16x16x32_f16 v[32:35], v[158:161], v[232:235], v[32:35]
	v_mfma_f32_16x16x32_f16 v[28:31], v[162:165], v[178:181], v[28:31]
	v_mfma_f32_16x16x32_f16 v[12:15], v[170:173], v[178:181], v[12:15]
	v_mfma_f32_16x16x32_f16 v[24:27], v[162:165], v[210:213], v[24:27]
	v_mfma_f32_16x16x32_f16 v[8:11], v[170:173], v[210:213], v[8:11]
	v_mfma_f32_16x16x32_f16 v[20:23], v[162:165], v[218:221], v[20:23]
	v_mfma_f32_16x16x32_f16 v[4:7], v[170:173], v[218:221], v[4:7]
	v_mfma_f32_16x16x32_f16 v[16:19], v[162:165], v[228:231], v[16:19]
	v_mfma_f32_16x16x32_f16 v[0:3], v[170:173], v[228:231], v[0:3]
	v_mfma_f32_16x16x32_f16 v[28:31], v[166:169], v[182:185], v[28:31]
	v_mfma_f32_16x16x32_f16 v[12:15], v[174:177], v[182:185], v[12:15]
	v_mfma_f32_16x16x32_f16 v[24:27], v[166:169], v[214:217], v[24:27]
	v_mfma_f32_16x16x32_f16 v[8:11], v[174:177], v[214:217], v[8:11]
	v_mfma_f32_16x16x32_f16 v[20:23], v[166:169], v[222:225], v[20:23]
	v_mfma_f32_16x16x32_f16 v[4:7], v[174:177], v[222:225], v[4:7]
	v_mfma_f32_16x16x32_f16 v[16:19], v[166:169], v[232:235], v[16:19]
	v_mfma_f32_16x16x32_f16 v[0:3], v[174:177], v[232:235], v[0:3]
	s_barrier
; #define PG8_STAGE(bufoff, gbase, voff) do { _Pragma("unroll") for (int _i = 0; _i < 2; ++_i) \
;         __builtin_amdgcn_global_load_lds((const unsigned*)((const char*)(gbase) + (voff)[_i]), (PG8_LAS unsigned*)(lds + (bufoff) + ldsw + _i * 8192), 16, 0, 0); } while (0)
; #define PG8_LDA(dst, b, h) do { _Pragma("unroll") for (int m = 0; m < 4; ++m) _Pragma("unroll") for (int k = 0; k < 2; ++k) dst[m][k] = *(const PG8_LAS bf16x8*)(lds + PG8_SA(b, h) + aoff + m * 2048 + k * 1024); } while (0)
; #define PG8_LDB(dst, b, h) do { _Pragma("unroll") for (int n = 0; n < 2; ++n) _Pragma("unroll") for (int k = 0; k < 2; ++k) dst[n][k] = *(const PG8_LAS bf16x8*)(lds + PG8_SB(b, h) + boff + n * 2048 + k * 1024); } while (0)
; #define PG8_MMA(ai, bj, At, Bt) do { __builtin_amdgcn_s_setprio(1); _Pragma("unroll") for (int m = 0; m < 4; ++m) _Pragma("unroll") for (int n = 0; n < 2; ++n) _Pragma("unroll") for (int k = 0; k < 2; ++k) \
;         acc[ai][bj][m][n] = mma16<F16>(Bt[n][k], At[m][k], acc[ai][bj][m][n]); __builtin_amdgcn_s_setprio(0); } while (0)
; #define PG8_WAIT_V(n) asm volatile("s_waitcnt vmcnt(" #n ")" ::: "memory")
; #define PG8_WAIT_L(n) asm volatile("s_waitcnt lgkmcnt(" #n ")" ::: "memory")
; #define PG8_BAR __builtin_amdgcn_s_barrier()
; #define PG8_SCHED __builtin_amdgcn_sched_barrier(0)
; template <class Epi, class Sched, bool ALIGN_EPI = false, bool SP2 = false, bool F16 = false, bool TOKPERM = false>
; __device__ __forceinline__ void gemm_phase(PG8_LAS unsigned char* lds, const Gemm g, const Sched& S, const Epi& E, int wv) {
;     ...
;             PG8_LDB(B0, 1, 0); PG8_LDB(B1, 1, 1); PG8_SCHED; PG8_LDA(At, 1, 0); PG8_STAGE(PG8_SA(0, 1), a2 + hstep, voffA);
;             PG8_WAIT_V(8); PG8_WAIT_L(0); PG8_BAR; PG8_MMA(0, 0, At, B0); PG8_MMA(0, 1, At, B1); PG8_BAR; PG8_SCHED;
;             PG8_LDA(At, 1, 1); PG8_STAGE(PG8_SB(1, 0), b3, voffB); PG8_STAGE(PG8_SB(1, 1), b3 + hstep, voffB); PG8_STAGE(PG8_SA(1, 0), a3, voffA);
;             PG8_WAIT_V(8); PG8_WAIT_L(0); PG8_BAR; PG8_MMA(1, 0, At, B0); PG8_MMA(1, 1, At, B1); PG8_BAR; PG8_SCHED;
	ds_read_b128 v[128:131], v198
	ds_read_b128 v[132:135], v199
	ds_read_b128 v[154:157], v200
	ds_read_b128 v[158:161], v201
	ds_read_b128 v[162:165], v202
	ds_read_b128 v[166:169], v203
	ds_read_b128 v[170:173], v204
	ds_read_b128 v[174:177], v205
	s_add_u32 s10, s16, 0x40000
	s_addc_u32 s11, s17, 0
	s_mov_b32 m0, s45
	v_lshl_add_u64 v[244:245], s[10:11], 0, v[136:137]
	ds_read_b128 v[178:181], v187 offset:32768
	ds_read_b128 v[182:185], v187 offset:33792
	ds_read_b128 v[210:213], v187 offset:34816
	ds_read_b128 v[214:217], v187 offset:35840
	ds_read_b128 v[218:221], v187 offset:36864
	ds_read_b128 v[222:225], v187 offset:37888
	ds_read_b128 v[228:231], v187 offset:38912
	ds_read_b128 v[232:235], v187 offset:39936
	global_load_lds_dwordx4 v[244:245], off
	v_lshl_add_u64 v[244:245], s[10:11], 0, v[140:141]
	s_mov_b32 m0, s61
	s_nop 0
	global_load_lds_dwordx4 v[244:245], off
	s_waitcnt vmcnt(8)
	s_waitcnt lgkmcnt(0)
	s_barrier
	s_waitcnt lgkmcnt(0)
	v_mfma_f32_16x16x32_f16 v[124:127], v[128:131], v[178:181], v[124:127]
	v_mfma_f32_16x16x32_f16 v[108:111], v[154:157], v[178:181], v[108:111]
	v_mfma_f32_16x16x32_f16 v[120:123], v[128:131], v[210:213], v[120:123]
	v_mfma_f32_16x16x32_f16 v[104:107], v[154:157], v[210:213], v[104:107]
	v_mfma_f32_16x16x32_f16 v[116:119], v[128:131], v[218:221], v[116:119]
	v_mfma_f32_16x16x32_f16 v[100:103], v[154:157], v[218:221], v[100:103]
	v_mfma_f32_16x16x32_f16 v[112:115], v[128:131], v[228:231], v[112:115]
	v_mfma_f32_16x16x32_f16 v[96:99], v[154:157], v[228:231], v[96:99]
	v_mfma_f32_16x16x32_f16 v[124:127], v[132:135], v[182:185], v[124:127]
	v_mfma_f32_16x16x32_f16 v[108:111], v[158:161], v[182:185], v[108:111]
	v_mfma_f32_16x16x32_f16 v[120:123], v[132:135], v[214:217], v[120:123]
	v_mfma_f32_16x16x32_f16 v[104:107], v[158:161], v[214:217], v[104:107]
	v_mfma_f32_16x16x32_f16 v[116:119], v[132:135], v[222:225], v[116:119]
	v_mfma_f32_16x16x32_f16 v[100:103], v[158:161], v[222:225], v[100:103]
	v_mfma_f32_16x16x32_f16 v[112:115], v[132:135], v[232:235], v[112:115]
	v_mfma_f32_16x16x32_f16 v[96:99], v[158:161], v[232:235], v[96:99]
	v_mfma_f32_16x16x32_f16 v[92:95], v[162:165], v[178:181], v[92:95]
	v_mfma_f32_16x16x32_f16 v[76:79], v[170:173], v[178:181], v[76:79]
	v_mfma_f32_16x16x32_f16 v[88:91], v[162:165], v[210:213], v[88:91]
	v_mfma_f32_16x16x32_f16 v[72:75], v[170:173], v[210:213], v[72:75]
	v_mfma_f32_16x16x32_f16 v[84:87], v[162:165], v[218:221], v[84:87]
	v_mfma_f32_16x16x32_f16 v[68:71], v[170:173], v[218:221], v[68:71]
	v_mfma_f32_16x16x32_f16 v[80:83], v[162:165], v[228:231], v[80:83]
	v_mfma_f32_16x16x32_f16 v[64:67], v[170:173], v[228:231], v[64:67]
	v_mfma_f32_16x16x32_f16 v[92:95], v[166:169], v[182:185], v[92:95]
	v_mfma_f32_16x16x32_f16 v[76:79], v[174:177], v[182:185], v[76:79]
	v_mfma_f32_16x16x32_f16 v[88:91], v[166:169], v[214:217], v[88:91]
	v_mfma_f32_16x16x32_f16 v[72:75], v[174:177], v[214:217], v[72:75]
	v_mfma_f32_16x16x32_f16 v[84:87], v[166:169], v[222:225], v[84:87]
	v_mfma_f32_16x16x32_f16 v[68:71], v[174:177], v[222:225], v[68:71]
	v_mfma_f32_16x16x32_f16 v[80:83], v[166:169], v[232:235], v[80:83]
	v_mfma_f32_16x16x32_f16 v[64:67], v[174:177], v[232:235], v[64:67]
	s_barrier
	s_mov_b32 m0, s94
	v_lshl_add_u64 v[236:237], v[236:237], 0, s[64:65]
	s_add_u32 s10, s14, 0x40080
	ds_read_b128 v[178:181], v187 offset:49152
	ds_read_b128 v[182:185], v187 offset:50176
	ds_read_b128 v[210:213], v187 offset:51200
	ds_read_b128 v[214:217], v187 offset:52224
	ds_read_b128 v[218:221], v187 offset:53248
	ds_read_b128 v[222:225], v187 offset:54272
	ds_read_b128 v[228:231], v187 offset:55296
	ds_read_b128 v[232:235], v187 offset:56320
	global_load_lds_dwordx4 v[236:237], off
	v_lshl_add_u64 v[236:237], v[238:239], 0, s[64:65]
	s_mov_b32 m0, s97
	s_addc_u32 s11, s15, 0
	global_load_lds_dwordx4 v[236:237], off
	v_lshl_add_u64 v[236:237], s[10:11], 0, v[138:139]
	s_mov_b32 m0, s73
	s_nop 0
	global_load_lds_dwordx4 v[236:237], off
	v_lshl_add_u64 v[236:237], s[10:11], 0, v[142:143]
	s_mov_b32 m0, s75
	s_nop 0
	global_load_lds_dwordx4 v[236:237], off
	v_lshl_add_u64 v[236:237], v[240:241], 0, s[64:65]
	s_mov_b32 m0, s4
	s_nop 0
	global_load_lds_dwordx4 v[236:237], off
	v_lshl_add_u64 v[236:237], v[242:243], 0, s[64:65]
	s_mov_b32 m0, s71
	s_nop 0
	global_load_lds_dwordx4 v[236:237], off
	s_waitcnt vmcnt(8)
	s_waitcnt lgkmcnt(0)
	s_barrier
	s_waitcnt lgkmcnt(0)
	v_mfma_f32_16x16x32_f16 v[60:63], v[128:131], v[178:181], v[60:63]
	v_mfma_f32_16x16x32_f16 v[44:47], v[154:157], v[178:181], v[44:47]
	v_mfma_f32_16x16x32_f16 v[56:59], v[128:131], v[210:213], v[56:59]
	v_mfma_f32_16x16x32_f16 v[40:43], v[154:157], v[210:213], v[40:43]
	v_mfma_f32_16x16x32_f16 v[52:55], v[128:131], v[218:221], v[52:55]
	v_mfma_f32_16x16x32_f16 v[36:39], v[154:157], v[218:221], v[36:39]
	v_mfma_f32_16x16x32_f16 v[48:51], v[128:131], v[228:231], v[48:51]
	v_mfma_f32_16x16x32_f16 v[32:35], v[154:157], v[228:231], v[32:35]
	v_mfma_f32_16x16x32_f16 v[60:63], v[132:135], v[182:185], v[60:63]
	v_mfma_f32_16x16x32_f16 v[44:47], v[158:161], v[182:185], v[44:47]
	v_mfma_f32_16x16x32_f16 v[56:59], v[132:135], v[214:217], v[56:59]
	v_mfma_f32_16x16x32_f16 v[40:43], v[158:161], v[214:217], v[40:43]
	v_mfma_f32_16x16x32_f16 v[52:55], v[132:135], v[222:225], v[52:55]
	v_mfma_f32_16x16x32_f16 v[36:39], v[158:161], v[222:225], v[36:39]
	v_mfma_f32_16x16x32_f16 v[48:51], v[132:135], v[232:235], v[48:51]
	v_mfma_f32_16x16x32_f16 v[32:35], v[158:161], v[232:235], v[32:35]
	v_mfma_f32_16x16x32_f16 v[28:31], v[162:165], v[178:181], v[28:31]
	v_mfma_f32_16x16x32_f16 v[12:15], v[170:173], v[178:181], v[12:15]
	v_mfma_f32_16x16x32_f16 v[24:27], v[162:165], v[210:213], v[24:27]
	v_mfma_f32_16x16x32_f16 v[8:11], v[170:173], v[210:213], v[8:11]
	v_mfma_f32_16x16x32_f16 v[20:23], v[162:165], v[218:221], v[20:23]
	v_mfma_f32_16x16x32_f16 v[4:7], v[170:173], v[218:221], v[4:7]
	v_mfma_f32_16x16x32_f16 v[16:19], v[162:165], v[228:231], v[16:19]
	v_mfma_f32_16x16x32_f16 v[0:3], v[170:173], v[228:231], v[0:3]
	v_mfma_f32_16x16x32_f16 v[28:31], v[166:169], v[182:185], v[28:31]
	v_mfma_f32_16x16x32_f16 v[12:15], v[174:177], v[182:185], v[12:15]
	v_mfma_f32_16x16x32_f16 v[24:27], v[166:169], v[214:217], v[24:27]
	v_mfma_f32_16x16x32_f16 v[8:11], v[174:177], v[214:217], v[8:11]
	v_mfma_f32_16x16x32_f16 v[20:23], v[166:169], v[222:225], v[20:23]
	v_mfma_f32_16x16x32_f16 v[4:7], v[174:177], v[222:225], v[4:7]
	v_mfma_f32_16x16x32_f16 v[16:19], v[166:169], v[232:235], v[16:19]
	v_mfma_f32_16x16x32_f16 v[0:3], v[174:177], v[232:235], v[0:3]
	s_barrier
	s_add_i32 s63, s63, 2
	s_add_u32 s59, s59, 0x100
	s_addc_u32 s62, s62, 0
	s_cmp_gt_u32 s63, 13
	s_mov_b64 s[10:11], s[12:13]
	s_cbranch_scc0 .LBB0_1118
	s_and_b64 vcc, exec, s[66:67]
	s_cbranch_vccz .LBB0_1121
	s_barrier

; #define PG8_STAGE(bufoff, gbase, voff) do { _Pragma("unroll") for (int _i = 0; _i < 2; ++_i) \
;         __builtin_amdgcn_global_load_lds((const unsigned*)((const char*)(gbase) + (voff)[_i]), (PG8_LAS unsigned*)(lds + (bufoff) + ldsw + _i * 8192), 16, 0, 0); } while (0)
; #define PG8_LDA(dst, b, h) do { _Pragma("unroll") for (int m = 0; m < 4; ++m) _Pragma("unroll") for (int k = 0; k < 2; ++k) dst[m][k] = *(const PG8_LAS bf16x8*)(lds + PG8_SA(b, h) + aoff + m * 2048 + k * 1024); } while (0)
; #define PG8_LDB(dst, b, h) do { _Pragma("unroll") for (int n = 0; n < 2; ++n) _Pragma("unroll") for (int k = 0; k < 2; ++k) dst[n][k] = *(const PG8_LAS bf16x8*)(lds + PG8_SB(b, h) + boff + n * 2048 + k * 1024); } while (0)
; #define PG8_MMA(ai, bj, At, Bt) do { __builtin_amdgcn_s_setprio(1); _Pragma("unroll") for (int m = 0; m < 4; ++m) _Pragma("unroll") for (int n = 0; n < 2; ++n) _Pragma("unroll") for (int k = 0; k < 2; ++k) \
;         acc[ai][bj][m][n] = mma16<F16>(Bt[n][k], At[m][k], acc[ai][bj][m][n]); __builtin_amdgcn_s_setprio(0); } while (0)
; #define PG8_WAIT_V(n) asm volatile("s_waitcnt vmcnt(" #n ")" ::: "memory")
; #define PG8_WAIT_L(n) asm volatile("s_waitcnt lgkmcnt(" #n ")" ::: "memory")
; #define PG8_BAR __builtin_amdgcn_s_barrier()
; template <class Epi, class Sched, bool ALIGN_EPI = false, bool SP2 = false, bool F16 = false, bool TOKPERM = false>
; __device__ __forceinline__ void gemm_phase(PG8_LAS unsigned char* lds, const Gemm g, const Sched& S, const Epi& E, int wv) {
;     ...
;             const char* a1 = cA + (size_t)(t + 1) * kstep;
;             const char* a2 = last ? nA : cA + (size_t)(t + 2) * kstep; const char* b2 = last ? nB : cB + (size_t)(t + 2) * kstep;
;             const char* a3 = a2 + kstep; const char* b3 = b2 + kstep;
;             if (last && has_next) S.a_ready(nxt);
;             if constexpr (SP2) {
;             PG8_LDB(B0, 0, 0); PG8_LDB(B1, 0, 1); PG8_SCHED; PG8_LDA(At, 0, 0); PG8_STAGE(PG8_SA(1, 1), a1 + hstep, voffA);
;             PG8_WAIT_V(8); PG8_WAIT_L(0); PG8_BAR; PG8_MMA(0, 0, At, B0); PG8_MMA(0, 1, At, B1); PG8_BAR; PG8_SCHED;
;             PG8_LDA(At, 0, 1); PG8_STAGE(PG8_SB(0, 0), b2, voffB); PG8_STAGE(PG8_SB(0, 1), b2 + hstep, voffB); PG8_STAGE(PG8_SA(0, 0), a2, voffA);
;             PG8_WAIT_V(8); PG8_WAIT_L(0); PG8_BAR; PG8_MMA(1, 0, At, B0); PG8_MMA(1, 1, At, B1); PG8_BAR; PG8_SCHED;
.LBB0_1524:
	ds_read_b128 v[166:169], v149
	ds_read_b128 v[170:173], v150
	ds_read_b128 v[174:177], v151
	ds_read_b128 v[178:181], v152
	ds_read_b128 v[182:185], v153
	ds_read_b128 v[186:189], v154
	ds_read_b128 v[190:193], v155
	ds_read_b128 v[194:197], v156
	s_add_u32 s44, s24, 0xfffc0080
	s_addc_u32 s45, s25, -1
	s_cmp_eq_u32 s65, 12
	s_cselect_b32 s47, s15, s45
	s_cselect_b32 s46, s21, s44
	s_cselect_b32 s45, s13, s64
	s_cselect_b32 s44, s62, s63
	s_mov_b32 m0, s60
	v_lshl_add_u64 v[232:233], s[24:25], 0, v[138:139]
	ds_read_b128 v[198:201], v147
	ds_read_b128 v[202:205], v147 offset:1024
	ds_read_b128 v[206:209], v147 offset:2048
	ds_read_b128 v[210:213], v147 offset:3072
	ds_read_b128 v[214:217], v147 offset:4096
	ds_read_b128 v[218:221], v147 offset:5120
	ds_read_b128 v[222:225], v147 offset:6144
	ds_read_b128 v[228:231], v147 offset:7168
	global_load_lds_dwordx4 v[232:233], off
	v_lshl_add_u64 v[232:233], s[24:25], 0, v[140:141]
	s_mov_b32 m0, s61
	s_nop 0
	global_load_lds_dwordx4 v[232:233], off
	s_waitcnt vmcnt(8)
	s_waitcnt lgkmcnt(0)
	s_barrier
	s_waitcnt lgkmcnt(0)
	v_mfma_f32_16x16x32_bf16 v[124:127], v[166:169], v[198:201], v[124:127]
	v_mfma_f32_16x16x32_bf16 v[120:123], v[174:177], v[198:201], v[120:123]
	v_mfma_f32_16x16x32_bf16 v[108:111], v[166:169], v[206:209], v[108:111]
	v_mfma_f32_16x16x32_bf16 v[104:107], v[174:177], v[206:209], v[104:107]
	v_mfma_f32_16x16x32_bf16 v[92:95], v[166:169], v[214:217], v[92:95]
	v_mfma_f32_16x16x32_bf16 v[88:91], v[174:177], v[214:217], v[88:91]
	v_mfma_f32_16x16x32_bf16 v[76:79], v[166:169], v[222:225], v[76:79]
	v_mfma_f32_16x16x32_bf16 v[72:75], v[174:177], v[222:225], v[72:75]
	v_mfma_f32_16x16x32_bf16 v[124:127], v[170:173], v[202:205], v[124:127]
	v_mfma_f32_16x16x32_bf16 v[120:123], v[178:181], v[202:205], v[120:123]
	v_mfma_f32_16x16x32_bf16 v[108:111], v[170:173], v[210:213], v[108:111]
	v_mfma_f32_16x16x32_bf16 v[104:107], v[178:181], v[210:213], v[104:107]
	v_mfma_f32_16x16x32_bf16 v[92:95], v[170:173], v[218:221], v[92:95]
	v_mfma_f32_16x16x32_bf16 v[88:91], v[178:181], v[218:221], v[88:91]
	v_mfma_f32_16x16x32_bf16 v[76:79], v[170:173], v[228:231], v[76:79]
	v_mfma_f32_16x16x32_bf16 v[72:75], v[178:181], v[228:231], v[72:75]
	v_mfma_f32_16x16x32_bf16 v[116:119], v[182:185], v[198:201], v[116:119]
	v_mfma_f32_16x16x32_bf16 v[112:115], v[190:193], v[198:201], v[112:115]
	v_mfma_f32_16x16x32_bf16 v[100:103], v[182:185], v[206:209], v[100:103]
	v_mfma_f32_16x16x32_bf16 v[96:99], v[190:193], v[206:209], v[96:99]
	v_mfma_f32_16x16x32_bf16 v[84:87], v[182:185], v[214:217], v[84:87]
	v_mfma_f32_16x16x32_bf16 v[80:83], v[190:193], v[214:217], v[80:83]
	v_mfma_f32_16x16x32_bf16 v[68:71], v[182:185], v[222:225], v[68:71]
	v_mfma_f32_16x16x32_bf16 v[64:67], v[190:193], v[222:225], v[64:67]
	v_mfma_f32_16x16x32_bf16 v[116:119], v[186:189], v[202:205], v[116:119]
	v_mfma_f32_16x16x32_bf16 v[112:115], v[194:197], v[202:205], v[112:115]
	v_mfma_f32_16x16x32_bf16 v[100:103], v[186:189], v[210:213], v[100:103]
	v_mfma_f32_16x16x32_bf16 v[96:99], v[194:197], v[210:213], v[96:99]
	v_mfma_f32_16x16x32_bf16 v[84:87], v[186:189], v[218:221], v[84:87]
	v_mfma_f32_16x16x32_bf16 v[80:83], v[194:197], v[218:221], v[80:83]
	v_mfma_f32_16x16x32_bf16 v[68:71], v[186:189], v[228:231], v[68:71]
	v_mfma_f32_16x16x32_bf16 v[64:67], v[194:197], v[228:231], v[64:67]
	s_barrier
	s_mov_b32 m0, s4
	v_lshl_add_u64 v[232:233], s[44:45], 0, v[130:131]
	s_add_u32 s66, s44, 0x40000
	ds_read_b128 v[198:201], v147 offset:16384
	ds_read_b128 v[202:205], v147 offset:17408
	ds_read_b128 v[206:209], v147 offset:18432
	ds_read_b128 v[210:213], v147 offset:19456
	ds_read_b128 v[214:217], v147 offset:20480
	ds_read_b128 v[218:221], v147 offset:21504
	ds_read_b128 v[222:225], v147 offset:22528
	ds_read_b128 v[228:231], v147 offset:23552
	global_load_lds_dwordx4 v[232:233], off
	v_lshl_add_u64 v[234:235], s[44:45], 0, v[134:135]
	s_mov_b32 m0, s5
	s_addc_u32 s67, s45, 0
	global_load_lds_dwordx4 v[234:235], off
	v_lshl_add_u64 v[236:237], s[66:67], 0, v[130:131]
	s_mov_b32 m0, s23
	v_lshl_add_u64 v[238:239], s[46:47], 0, v[132:133]
	global_load_lds_dwordx4 v[236:237], off
	v_lshl_add_u64 v[236:237], s[66:67], 0, v[134:135]
	s_mov_b32 m0, s33
	s_nop 0
	global_load_lds_dwordx4 v[236:237], off
	v_lshl_add_u64 v[236:237], s[46:47], 0, v[128:129]
	s_mov_b32 m0, s3
	s_nop 0
	global_load_lds_dwordx4 v[236:237], off
	s_mov_b32 m0, s36
	s_nop 0
	global_load_lds_dwordx4 v[238:239], off
	s_waitcnt vmcnt(8)
	s_waitcnt lgkmcnt(0)
	s_barrier
	s_waitcnt lgkmcnt(0)
	v_mfma_f32_16x16x32_bf16 v[60:63], v[166:169], v[198:201], v[60:63]
	v_mfma_f32_16x16x32_bf16 v[56:59], v[174:177], v[198:201], v[56:59]
	v_mfma_f32_16x16x32_bf16 v[44:47], v[166:169], v[206:209], v[44:47]
	v_mfma_f32_16x16x32_bf16 v[40:43], v[174:177], v[206:209], v[40:43]
	v_mfma_f32_16x16x32_bf16 v[28:31], v[166:169], v[214:217], v[28:31]
	v_mfma_f32_16x16x32_bf16 v[24:27], v[174:177], v[214:217], v[24:27]
	v_mfma_f32_16x16x32_bf16 v[12:15], v[166:169], v[222:225], v[12:15]
	v_mfma_f32_16x16x32_bf16 v[8:11], v[174:177], v[222:225], v[8:11]
	v_mfma_f32_16x16x32_bf16 v[60:63], v[170:173], v[202:205], v[60:63]
	v_mfma_f32_16x16x32_bf16 v[56:59], v[178:181], v[202:205], v[56:59]
	v_mfma_f32_16x16x32_bf16 v[44:47], v[170:173], v[210:213], v[44:47]
	v_mfma_f32_16x16x32_bf16 v[40:43], v[178:181], v[210:213], v[40:43]
	v_mfma_f32_16x16x32_bf16 v[28:31], v[170:173], v[218:221], v[28:31]
	v_mfma_f32_16x16x32_bf16 v[24:27], v[178:181], v[218:221], v[24:27]
	v_mfma_f32_16x16x32_bf16 v[12:15], v[170:173], v[228:231], v[12:15]
	v_mfma_f32_16x16x32_bf16 v[8:11], v[178:181], v[228:231], v[8:11]
	v_mfma_f32_16x16x32_bf16 v[52:55], v[182:185], v[198:201], v[52:55]
	v_mfma_f32_16x16x32_bf16 v[48:51], v[190:193], v[198:201], v[48:51]
	v_mfma_f32_16x16x32_bf16 v[36:39], v[182:185], v[206:209], v[36:39]
	v_mfma_f32_16x16x32_bf16 v[32:35], v[190:193], v[206:209], v[32:35]
	v_mfma_f32_16x16x32_bf16 v[20:23], v[182:185], v[214:217], v[20:23]
	v_mfma_f32_16x16x32_bf16 v[16:19], v[190:193], v[214:217], v[16:19]
	v_mfma_f32_16x16x32_bf16 v[4:7], v[182:185], v[222:225], v[4:7]
	v_mfma_f32_16x16x32_bf16 v[0:3], v[190:193], v[222:225], v[0:3]
	v_mfma_f32_16x16x32_bf16 v[52:55], v[186:189], v[202:205], v[52:55]
	v_mfma_f32_16x16x32_bf16 v[48:51], v[194:197], v[202:205], v[48:51]
	v_mfma_f32_16x16x32_bf16 v[36:39], v[186:189], v[210:213], v[36:39]
	v_mfma_f32_16x16x32_bf16 v[32:35], v[194:197], v[210:213], v[32:35]
	v_mfma_f32_16x16x32_bf16 v[20:23], v[186:189], v[218:221], v[20:23]
	v_mfma_f32_16x16x32_bf16 v[16:19], v[194:197], v[218:221], v[16:19]
	v_mfma_f32_16x16x32_bf16 v[4:7], v[186:189], v[228:231], v[4:7]
	v_mfma_f32_16x16x32_bf16 v[0:3], v[194:197], v[228:231], v[0:3]
	s_barrier
; #define PG8_STAGE(bufoff, gbase, voff) do { _Pragma("unroll") for (int _i = 0; _i < 2; ++_i) \
;         __builtin_amdgcn_global_load_lds((const unsigned*)((const char*)(gbase) + (voff)[_i]), (PG8_LAS unsigned*)(lds + (bufoff) + ldsw + _i * 8192), 16, 0, 0); } while (0)
; #define PG8_LDA(dst, b, h) do { _Pragma("unroll") for (int m = 0; m < 4; ++m) _Pragma("unroll") for (int k = 0; k < 2; ++k) dst[m][k] = *(const PG8_LAS bf16x8*)(lds + PG8_SA(b, h) + aoff + m * 2048 + k * 1024); } while (0)
; #define PG8_LDB(dst, b, h) do { _Pragma("unroll") for (int n = 0; n < 2; ++n) _Pragma("unroll") for (int k = 0; k < 2; ++k) dst[n][k] = *(const PG8_LAS bf16x8*)(lds + PG8_SB(b, h) + boff + n * 2048 + k * 1024); } while (0)
; #define PG8_MMA(ai, bj, At, Bt) do { __builtin_amdgcn_s_setprio(1); _Pragma("unroll") for (int m = 0; m < 4; ++m) _Pragma("unroll") for (int n = 0; n < 2; ++n) _Pragma("unroll") for (int k = 0; k < 2; ++k) \
;         acc[ai][bj][m][n] = mma16<F16>(Bt[n][k], At[m][k], acc[ai][bj][m][n]); __builtin_amdgcn_s_setprio(0); } while (0)
; #define PG8_WAIT_V(n) asm volatile("s_waitcnt vmcnt(" #n ")" ::: "memory")
; #define PG8_WAIT_L(n) asm volatile("s_waitcnt lgkmcnt(" #n ")" ::: "memory")
; #define PG8_BAR __builtin_amdgcn_s_barrier()
; #define PG8_SCHED __builtin_amdgcn_sched_barrier(0)
; template <class Epi, class Sched, bool ALIGN_EPI = false, bool SP2 = false, bool F16 = false, bool TOKPERM = false>
; __device__ __forceinline__ void gemm_phase(PG8_LAS unsigned char* lds, const Gemm g, const Sched& S, const Epi& E, int wv) {
;     ...
;             PG8_LDB(B0, 1, 0); PG8_LDB(B1, 1, 1); PG8_SCHED; PG8_LDA(At, 1, 0); PG8_STAGE(PG8_SA(0, 1), a2 + hstep, voffA);
;             PG8_WAIT_V(8); PG8_WAIT_L(0); PG8_BAR; PG8_MMA(0, 0, At, B0); PG8_MMA(0, 1, At, B1); PG8_BAR; PG8_SCHED;
;             PG8_LDA(At, 1, 1); PG8_STAGE(PG8_SB(1, 0), b3, voffB); PG8_STAGE(PG8_SB(1, 1), b3 + hstep, voffB); PG8_STAGE(PG8_SA(1, 0), a3, voffA);
;             PG8_WAIT_V(8); PG8_WAIT_L(0); PG8_BAR; PG8_MMA(1, 0, At, B0); PG8_MMA(1, 1, At, B1); PG8_BAR; PG8_SCHED;
	ds_read_b128 v[166:169], v157
	ds_read_b128 v[170:173], v158
	ds_read_b128 v[174:177], v159
	ds_read_b128 v[178:181], v160
	ds_read_b128 v[182:185], v161
	ds_read_b128 v[186:189], v162
	ds_read_b128 v[190:193], v163
	ds_read_b128 v[194:197], v164
	s_add_u32 s46, s46, 0x40000
	s_addc_u32 s47, s47, 0
	s_mov_b32 m0, s37
	v_lshl_add_u64 v[240:241], s[46:47], 0, v[128:129]
	ds_read_b128 v[198:201], v147 offset:32768
	ds_read_b128 v[202:205], v147 offset:33792
	ds_read_b128 v[206:209], v147 offset:34816
	ds_read_b128 v[210:213], v147 offset:35840
	ds_read_b128 v[214:217], v147 offset:36864
	ds_read_b128 v[218:221], v147 offset:37888
	ds_read_b128 v[222:225], v147 offset:38912
	ds_read_b128 v[228:231], v147 offset:39936
	global_load_lds_dwordx4 v[240:241], off
	v_lshl_add_u64 v[240:241], s[46:47], 0, v[132:133]
	s_mov_b32 m0, s48
	s_nop 0
	global_load_lds_dwordx4 v[240:241], off
	s_waitcnt vmcnt(8)
	s_waitcnt lgkmcnt(0)
	s_barrier
	s_waitcnt lgkmcnt(0)
	v_mfma_f32_16x16x32_bf16 v[124:127], v[166:169], v[198:201], v[124:127]
	v_mfma_f32_16x16x32_bf16 v[120:123], v[174:177], v[198:201], v[120:123]
	v_mfma_f32_16x16x32_bf16 v[108:111], v[166:169], v[206:209], v[108:111]
	v_mfma_f32_16x16x32_bf16 v[104:107], v[174:177], v[206:209], v[104:107]
	v_mfma_f32_16x16x32_bf16 v[92:95], v[166:169], v[214:217], v[92:95]
	v_mfma_f32_16x16x32_bf16 v[88:91], v[174:177], v[214:217], v[88:91]
	v_mfma_f32_16x16x32_bf16 v[76:79], v[166:169], v[222:225], v[76:79]
	v_mfma_f32_16x16x32_bf16 v[72:75], v[174:177], v[222:225], v[72:75]
	v_mfma_f32_16x16x32_bf16 v[124:127], v[170:173], v[202:205], v[124:127]
	v_mfma_f32_16x16x32_bf16 v[120:123], v[178:181], v[202:205], v[120:123]
	v_mfma_f32_16x16x32_bf16 v[108:111], v[170:173], v[210:213], v[108:111]
	v_mfma_f32_16x16x32_bf16 v[104:107], v[178:181], v[210:213], v[104:107]
	v_mfma_f32_16x16x32_bf16 v[92:95], v[170:173], v[218:221], v[92:95]
	v_mfma_f32_16x16x32_bf16 v[88:91], v[178:181], v[218:221], v[88:91]
	v_mfma_f32_16x16x32_bf16 v[76:79], v[170:173], v[228:231], v[76:79]
	v_mfma_f32_16x16x32_bf16 v[72:75], v[178:181], v[228:231], v[72:75]
	v_mfma_f32_16x16x32_bf16 v[116:119], v[182:185], v[198:201], v[116:119]
	v_mfma_f32_16x16x32_bf16 v[112:115], v[190:193], v[198:201], v[112:115]
	v_mfma_f32_16x16x32_bf16 v[100:103], v[182:185], v[206:209], v[100:103]
	v_mfma_f32_16x16x32_bf16 v[96:99], v[190:193], v[206:209], v[96:99]
	v_mfma_f32_16x16x32_bf16 v[84:87], v[182:185], v[214:217], v[84:87]
	v_mfma_f32_16x16x32_bf16 v[80:83], v[190:193], v[214:217], v[80:83]
	v_mfma_f32_16x16x32_bf16 v[68:71], v[182:185], v[222:225], v[68:71]
	v_mfma_f32_16x16x32_bf16 v[64:67], v[190:193], v[222:225], v[64:67]
	v_mfma_f32_16x16x32_bf16 v[116:119], v[186:189], v[202:205], v[116:119]
	v_mfma_f32_16x16x32_bf16 v[112:115], v[194:197], v[202:205], v[112:115]
	v_mfma_f32_16x16x32_bf16 v[100:103], v[186:189], v[210:213], v[100:103]
	v_mfma_f32_16x16x32_bf16 v[96:99], v[194:197], v[210:213], v[96:99]
	v_mfma_f32_16x16x32_bf16 v[84:87], v[186:189], v[218:221], v[84:87]
	v_mfma_f32_16x16x32_bf16 v[80:83], v[194:197], v[218:221], v[80:83]
	v_mfma_f32_16x16x32_bf16 v[68:71], v[186:189], v[228:231], v[68:71]
	v_mfma_f32_16x16x32_bf16 v[64:67], v[194:197], v[228:231], v[64:67]
	s_barrier
	s_mov_b32 m0, s50
	v_lshl_add_u64 v[232:233], v[232:233], 0, s[10:11]
	s_add_u32 s44, s44, 0x40080
	ds_read_b128 v[198:201], v147 offset:49152
	ds_read_b128 v[202:205], v147 offset:50176
	ds_read_b128 v[206:209], v147 offset:51200
	ds_read_b128 v[210:213], v147 offset:52224
	ds_read_b128 v[214:217], v147 offset:53248
	ds_read_b128 v[218:221], v147 offset:54272
	ds_read_b128 v[222:225], v147 offset:55296
	ds_read_b128 v[228:231], v147 offset:56320
	global_load_lds_dwordx4 v[232:233], off
	v_lshl_add_u64 v[232:233], v[234:235], 0, s[10:11]
	s_mov_b32 m0, s51
	s_addc_u32 s45, s45, 0
	global_load_lds_dwordx4 v[232:233], off
	v_lshl_add_u64 v[232:233], s[44:45], 0, v[130:131]
	s_mov_b32 m0, s54
	s_nop 0
	global_load_lds_dwordx4 v[232:233], off
	v_lshl_add_u64 v[232:233], s[44:45], 0, v[134:135]
	s_mov_b32 m0, s55
	s_nop 0
	global_load_lds_dwordx4 v[232:233], off
	v_lshl_add_u64 v[232:233], v[236:237], 0, s[10:11]
	s_mov_b32 m0, s52
	s_nop 0
	global_load_lds_dwordx4 v[232:233], off
	v_lshl_add_u64 v[232:233], v[238:239], 0, s[10:11]
	s_mov_b32 m0, s53
	s_nop 0
	global_load_lds_dwordx4 v[232:233], off
	s_waitcnt vmcnt(8)
	s_waitcnt lgkmcnt(0)
	s_barrier
	s_waitcnt lgkmcnt(0)
	v_mfma_f32_16x16x32_bf16 v[60:63], v[166:169], v[198:201], v[60:63]
	v_mfma_f32_16x16x32_bf16 v[56:59], v[174:177], v[198:201], v[56:59]
	v_mfma_f32_16x16x32_bf16 v[44:47], v[166:169], v[206:209], v[44:47]
	v_mfma_f32_16x16x32_bf16 v[40:43], v[174:177], v[206:209], v[40:43]
	v_mfma_f32_16x16x32_bf16 v[28:31], v[166:169], v[214:217], v[28:31]
	v_mfma_f32_16x16x32_bf16 v[24:27], v[174:177], v[214:217], v[24:27]
	v_mfma_f32_16x16x32_bf16 v[12:15], v[166:169], v[222:225], v[12:15]
	v_mfma_f32_16x16x32_bf16 v[8:11], v[174:177], v[222:225], v[8:11]
	v_mfma_f32_16x16x32_bf16 v[60:63], v[170:173], v[202:205], v[60:63]
	v_mfma_f32_16x16x32_bf16 v[56:59], v[178:181], v[202:205], v[56:59]
	v_mfma_f32_16x16x32_bf16 v[44:47], v[170:173], v[210:213], v[44:47]
	v_mfma_f32_16x16x32_bf16 v[40:43], v[178:181], v[210:213], v[40:43]
	v_mfma_f32_16x16x32_bf16 v[28:31], v[170:173], v[218:221], v[28:31]
	v_mfma_f32_16x16x32_bf16 v[24:27], v[178:181], v[218:221], v[24:27]
	v_mfma_f32_16x16x32_bf16 v[12:15], v[170:173], v[228:231], v[12:15]
	v_mfma_f32_16x16x32_bf16 v[8:11], v[178:181], v[228:231], v[8:11]
	v_mfma_f32_16x16x32_bf16 v[52:55], v[182:185], v[198:201], v[52:55]
	v_mfma_f32_16x16x32_bf16 v[48:51], v[190:193], v[198:201], v[48:51]
	v_mfma_f32_16x16x32_bf16 v[36:39], v[182:185], v[206:209], v[36:39]
	v_mfma_f32_16x16x32_bf16 v[32:35], v[190:193], v[206:209], v[32:35]
	v_mfma_f32_16x16x32_bf16 v[20:23], v[182:185], v[214:217], v[20:23]
	v_mfma_f32_16x16x32_bf16 v[16:19], v[190:193], v[214:217], v[16:19]
	v_mfma_f32_16x16x32_bf16 v[4:7], v[182:185], v[222:225], v[4:7]
	v_mfma_f32_16x16x32_bf16 v[0:3], v[190:193], v[222:225], v[0:3]
	v_mfma_f32_16x16x32_bf16 v[52:55], v[186:189], v[202:205], v[52:55]
	v_mfma_f32_16x16x32_bf16 v[48:51], v[194:197], v[202:205], v[48:51]
	v_mfma_f32_16x16x32_bf16 v[36:39], v[186:189], v[210:213], v[36:39]
	v_mfma_f32_16x16x32_bf16 v[32:35], v[194:197], v[210:213], v[32:35]
	v_mfma_f32_16x16x32_bf16 v[20:23], v[186:189], v[218:221], v[20:23]
	v_mfma_f32_16x16x32_bf16 v[16:19], v[194:197], v[218:221], v[16:19]
	v_mfma_f32_16x16x32_bf16 v[4:7], v[186:189], v[228:231], v[4:7]
	v_mfma_f32_16x16x32_bf16 v[0:3], v[194:197], v[228:231], v[0:3]
	s_barrier
;   __device__ __forceinline__ void operator()(const pg8::f32x4 (&acc)[2][2][4][2], const pg8::Unit& u, int wr, int wc, int fr, int fq) const {
;     ...
;     const int row0 = u.pm * 256 + wr * 64 + fr + z, colb = u.pn * 256 + wc * 32 + 8 * fq + z;
; #pragma unroll
;     for (int ai = 0; ai < 2; ++ai)
; #pragma unroll
;       for (int m = 0; m < 4; ++m) {
;         const int tok = row0 + ai * 128 + m * 16; float ss = 0.f;
; #pragma unroll
;         for (int bj = 0; bj < 2; ++bj) {
;           const unsigned off = (unsigned)tok * DM + colb + 128 * bj;
;           f8_t n = __builtin_convertvector(*(const h8_t*)(x16 + off), f8_t);
; #pragma unroll
;           for (int c = 0; c < 4; ++c) { n[c] += sc * acc[ai][bj][m][0][c]; n[4 + c] += sc * acc[ai][bj][m][1][c]; }
;           if (aux) {
;             *(h8_t*)(x16 + off) = __builtin_convertvector(n, h8_t);
;             ss += ((n[0] * n[0] + n[1] * n[1]) + (n[2] * n[2] + n[3] * n[3])) + ((n[4] * n[4] + n[5] * n[5]) + (n[6] * n[6] + n[7] * n[7]));
;           } else {
;             *(f32x4*)(xout + off) = (f32x4){n[0], n[1], n[2], n[3]}; *(f32x4*)(xout + off + 4) = (f32x4){n[4], n[5], n[6], n[7]};
;           }
;         }
;         if (aux) { ss += __shfl_xor(ss, 16); ss += __shfl_xor(ss, 32); if (fq == 0) ssq[(unsigned)tok * 16 + u.pn * 4 + wc] = ss; }
	s_add_i32 s65, s65, 2
	s_add_u32 s24, s24, 0x100
	s_addc_u32 s25, s25, 0
	s_add_u32 s63, s63, 0x100
	s_addc_u32 s64, s64, 0
	s_cmp_gt_u32 s65, 13
	s_cbranch_scc0 .LBB0_1524
	s_lshl_b32 s13, s22, 8
	v_lshl_or_b32 v166, s20, 8, v148
	v_mov_b32 v136, 0
	v_xor_b32_e32 v169, 32, v165
	v_add3_u32 v167, s13, v146, v136
	v_add_u32_e32 v168, v166, v136
	v_lshl_add_u32 v136, v167, 10, v168
	v_lshl_add_u64 v[178:179], v[136:137], 1, s[40:41]
	v_add_u32_e32 v136, 0x80, v136
	global_load_dwordx4 v[170:173], v[178:179], off
	v_lshl_add_u64 v[180:181], v[136:137], 1, s[40:41]
	global_load_dwordx4 v[174:177], v[180:181], off
	v_add_u32_e32 v136, 16, v167
	v_lshl_add_u32 v136, v136, 10, v168
	v_lshl_add_u64 v[224:225], v[136:137], 1, s[40:41]
	v_add_u32_e32 v136, 0x80, v136
	global_load_dwordx4 v[192:195], v[224:225], off
	v_lshl_add_u64 v[248:249], v[136:137], 1, s[40:41]
	global_load_dwordx4 v[196:199], v[248:249], off
	v_add_u32_e32 v136, 32, v167
	v_lshl_add_u32 v136, v136, 10, v168
	v_lshl_add_u64 v[224:225], v[136:137], 1, s[40:41]
	v_add_u32_e32 v136, 0x80, v136
	global_load_dwordx4 v[200:203], v[224:225], off
	v_lshl_add_u64 v[248:249], v[136:137], 1, s[40:41]
	global_load_dwordx4 v[204:207], v[248:249], off
	v_add_u32_e32 v136, 48, v167
	v_lshl_add_u32 v136, v136, 10, v168
	v_lshl_add_u64 v[224:225], v[136:137], 1, s[40:41]
	v_add_u32_e32 v136, 0x80, v136
	global_load_dwordx4 v[208:211], v[224:225], off
	v_lshl_add_u64 v[248:249], v[136:137], 1, s[40:41]
	global_load_dwordx4 v[212:215], v[248:249], off
	v_add_u32_e32 v136, 0x80, v167
	v_lshl_add_u32 v136, v136, 10, v168
	v_lshl_add_u64 v[224:225], v[136:137], 1, s[40:41]
	v_add_u32_e32 v136, 0x80, v136
	global_load_dwordx4 v[216:219], v[224:225], off
	v_lshl_add_u64 v[248:249], v[136:137], 1, s[40:41]
	global_load_dwordx4 v[220:223], v[248:249], off
	v_add_u32_e32 v136, 0x90, v167
	v_lshl_add_u32 v136, v136, 10, v168
	v_lshl_add_u64 v[224:225], v[136:137], 1, s[40:41]
	v_add_u32_e32 v136, 0x80, v136
	global_load_dwordx4 v[228:231], v[224:225], off
	v_lshl_add_u64 v[248:249], v[136:137], 1, s[40:41]
	global_load_dwordx4 v[244:247], v[248:249], off
	v_and_b32_e32 v166, 64, v165
	v_xor_b32_e32 v136, 16, v165
	v_add_u32_e32 v166, 64, v166
	v_cmp_lt_i32_e32 vcc, v136, v166
	s_lshl_b32 s13, s20, 2
	s_or_b32 s13, s13, s49
	v_cndmask_b32_e32 v136, v165, v136, vcc
	v_cmp_lt_i32_e32 vcc, v169, v166
	v_lshlrev_b32_e32 v166, 2, v136
	s_waitcnt vmcnt(10)
	v_cvt_f32_f16_e32 v182, v173
	v_cvt_f32_f16_sdwa v183, v173 dst_sel:DWORD dst_unused:UNUSED_PAD src0_sel:WORD_1
	v_cvt_f32_f16_e32 v184, v171
	v_cvt_f32_f16_sdwa v185, v171 dst_sel:DWORD dst_unused:UNUSED_PAD src0_sel:WORD_1
	v_cvt_f32_f16_e32 v186, v172
	v_cvt_f32_f16_sdwa v187, v172 dst_sel:DWORD dst_unused:UNUSED_PAD src0_sel:WORD_1
	v_cvt_f32_f16_e32 v172, v170
	v_cvt_f32_f16_sdwa v173, v170 dst_sel:DWORD dst_unused:UNUSED_PAD src0_sel:WORD_1
	v_cvt_f32_f16_e32 v170, v177
	v_cvt_f32_f16_sdwa v171, v177 dst_sel:DWORD dst_unused:UNUSED_PAD src0_sel:WORD_1
	v_cvt_f32_f16_e32 v188, v175
	v_cvt_f32_f16_sdwa v189, v175 dst_sel:DWORD dst_unused:UNUSED_PAD src0_sel:WORD_1
	v_cvt_f32_f16_e32 v190, v176
	v_cvt_f32_f16_sdwa v191, v176 dst_sel:DWORD dst_unused:UNUSED_PAD src0_sel:WORD_1
	v_cvt_f32_f16_e32 v176, v174
	v_cvt_f32_f16_sdwa v177, v174 dst_sel:DWORD dst_unused:UNUSED_PAD src0_sel:WORD_1
	v_pk_add_f32 v[124:125], v[124:125], v[172:173]
	v_pk_add_f32 v[172:173], v[120:121], v[186:187]
	v_pk_add_f32 v[126:127], v[126:127], v[184:185]
	v_pk_add_f32 v[122:123], v[122:123], v[182:183]
	v_cvt_pk_f16_f32 v120, v172, v173
	v_cvt_pk_f16_f32 v121, v122, v123
	v_pk_mul_f32 v[174:175], v[124:125], v[124:125]
	v_pk_mul_f32 v[182:183], v[126:127], v[126:127]
	v_pk_fma_f32 v[174:175], v[172:173], v[172:173], v[174:175]
	v_pk_fma_f32 v[182:183], v[122:123], v[122:123], v[182:183]
	v_pk_add_f32 v[176:177], v[116:117], v[176:177]
	v_pk_add_f32 v[116:117], v[112:113], v[190:191]
	v_pk_add_f32 v[184:185], v[118:119], v[188:189]
	v_pk_add_f32 v[112:113], v[114:115], v[170:171]
	v_pk_fma_f32 v[174:175], v[176:177], v[176:177], v[174:175]
	v_pk_fma_f32 v[182:183], v[184:185], v[184:185], v[182:183]
	v_pk_fma_f32 v[174:175], v[116:117], v[116:117], v[174:175]
	v_pk_fma_f32 v[182:183], v[112:113], v[112:113], v[182:183]
	v_pk_add_f32 v[174:175], v[174:175], v[182:183]
	v_add_f32_e32 v114, v174, v175
	v_mov_b32_e32 v115, v114
	s_nop 1
	v_permlane16_swap_b32_e32 v114, v115
	v_cndmask_b32_e32 v169, v165, v169, vcc
	v_cvt_pk_f16_f32 v119, v126, v127
	v_cvt_pk_f16_f32 v118, v124, v125
	global_store_dwordx4 v[178:179], v[118:121], off
	s_nop 1
	v_cvt_pk_f16_f32 v119, v112, v113
	s_waitcnt lgkmcnt(0)
	v_add_f32_e32 v113, v114, v115
	v_lshlrev_b32_e32 v112, 2, v169
	v_mov_b32_e32 v114, v113
	s_nop 1
	v_permlane32_swap_b32_e32 v113, v114
	v_cvt_pk_f16_f32 v118, v116, v117
	v_cvt_pk_f16_f32 v117, v184, v185
	v_cvt_pk_f16_f32 v116, v176, v177
	global_store_dwordx4 v[180:181], v[116:119], off
	s_and_saveexec_b64 s[20:21], s[6:7]
	s_cbranch_execz .LBB0_1527
	v_lshl_add_u32 v136, v167, 4, s13
	s_waitcnt lgkmcnt(0)
	v_add_f32_e32 v113, v113, v114
	v_lshl_add_u64 v[114:115], v[136:137], 2, s[42:43]
	global_store_dword v[114:115], v113, off

; #define PG8_STAGE(bufoff, gbase, voff) do { _Pragma("unroll") for (int _i = 0; _i < 2; ++_i) \
;         __builtin_amdgcn_global_load_lds((const unsigned*)((const char*)(gbase) + (voff)[_i]), (PG8_LAS unsigned*)(lds + (bufoff) + ldsw + _i * 8192), 16, 0, 0); } while (0)
; #define PG8_LDA(dst, b, h) do { _Pragma("unroll") for (int m = 0; m < 4; ++m) _Pragma("unroll") for (int k = 0; k < 2; ++k) dst[m][k] = *(const PG8_LAS bf16x8*)(lds + PG8_SA(b, h) + aoff + m * 2048 + k * 1024); } while (0)
; #define PG8_LDB(dst, b, h) do { _Pragma("unroll") for (int n = 0; n < 2; ++n) _Pragma("unroll") for (int k = 0; k < 2; ++k) dst[n][k] = *(const PG8_LAS bf16x8*)(lds + PG8_SB(b, h) + boff + n * 2048 + k * 1024); } while (0)
; #define PG8_WAIT_V(n) asm volatile("s_waitcnt vmcnt(" #n ")" ::: "memory")
; #define PG8_WAIT_L(n) asm volatile("s_waitcnt lgkmcnt(" #n ")" ::: "memory")
; #define PG8_BAR __builtin_amdgcn_s_barrier()
; #define PG8_SCHED __builtin_amdgcn_sched_barrier(0)
; template <class Epi, class Sched, bool ALIGN_EPI = false, bool SP2 = false, bool F16 = false, bool TOKPERM = false>
; __device__ __forceinline__ void gemm_phase(PG8_LAS unsigned char* lds, const Gemm g, const Sched& S, const Epi& E, int wv) {
;     ...
;         const bool has_next = S.next(ui + 1, nxt);
;         const char* nA = has_next ? (const char*)g.A + (size_t)nxt.pm * tstep : cA; const char* nB = has_next ? (const char*)g.Bt + (size_t)nxt.pn * tstep : cB;
;         for (int t = 0; t < nt; t += 2) {
;             const bool last = (t == nt - 2);
;             const char* a1 = cA + (size_t)(t + 1) * kstep;
;             const char* a2 = last ? nA : cA + (size_t)(t + 2) * kstep; const char* b2 = last ? nB : cB + (size_t)(t + 2) * kstep;
;             const char* a3 = a2 + kstep; const char* b3 = b2 + kstep;
;             if (last && has_next) S.a_ready(nxt);
;             if constexpr (SP2) {
;             PG8_LDB(B0, 0, 0); PG8_LDB(B1, 0, 1); PG8_SCHED; PG8_LDA(At, 0, 0); PG8_STAGE(PG8_SA(1, 1), a1 + hstep, voffA);
;             PG8_WAIT_V(8); PG8_WAIT_L(0); PG8_BAR; PG8_MMA(0, 0, At, B0); PG8_MMA(0, 1, At, B1); PG8_BAR; PG8_SCHED;
;             PG8_LDA(At, 0, 1); PG8_STAGE(PG8_SB(0, 0), b2, voffB); PG8_STAGE(PG8_SB(0, 1), b2 + hstep, voffB); PG8_STAGE(PG8_SA(0, 0), a2, voffA);
;             PG8_WAIT_V(8); PG8_WAIT_L(0); PG8_BAR; PG8_MMA(1, 0, At, B0); PG8_MMA(1, 1, At, B1); PG8_BAR; PG8_SCHED;
.LBB0_1606:
	s_ashr_i32 s25, s24, 31
	s_lshl_b64 s[36:37], s[24:25], 19
	s_add_u32 s36, s40, s36
	s_addc_u32 s37, s41, s37
	s_and_b64 s[42:43], s[4:5], exec
	s_cselect_b32 s25, s37, s9
	s_cselect_b32 s64, s36, s8
	s_ashr_i32 s23, s22, 31
	s_lshl_b64 s[42:43], s[22:23], 19
	s_add_u32 s42, s0, s42
	s_addc_u32 s43, s1, s43
	s_and_b64 s[44:45], s[4:5], exec
	s_cselect_b32 s23, s43, s11
	s_cselect_b32 s65, s42, s10
	s_add_u32 s8, s8, 0x40080
	s_addc_u32 s9, s9, 0
	s_add_u32 s66, s10, 0x100
	s_addc_u32 s67, s11, 0
	s_mov_b32 s68, -2
	ds_read_b128 v[172:175], v155
	ds_read_b128 v[176:179], v156
	ds_read_b128 v[180:183], v157
	ds_read_b128 v[184:187], v158
	ds_read_b128 v[188:191], v159
	ds_read_b128 v[192:195], v160
	ds_read_b128 v[196:199], v161
	ds_read_b128 v[200:203], v162
	s_add_u32 s10, s8, 0xfffc0080
	s_addc_u32 s11, s9, -1
	s_cmp_eq_u32 s68, 12
	s_cselect_b32 s45, s25, s11
	s_cselect_b32 s44, s64, s10
	s_cselect_b32 s11, s23, s67
	s_cselect_b32 s10, s65, s66
	s_mov_b32 m0, s60
	v_lshl_add_u64 v[148:149], s[8:9], 0, v[140:141]
	ds_read_b128 v[204:207], v153
	ds_read_b128 v[208:211], v153 offset:1024
	ds_read_b128 v[212:215], v153 offset:2048
	ds_read_b128 v[216:219], v153 offset:3072
	ds_read_b128 v[220:223], v153 offset:4096
	ds_read_b128 v[224:227], v153 offset:5120
	ds_read_b128 v[228:231], v153 offset:6144
	ds_read_b128 v[232:235], v153 offset:7168
	global_load_lds_dwordx4 v[148:149], off
	v_lshl_add_u64 v[148:149], s[8:9], 0, v[142:143]
	s_mov_b32 m0, s61
	s_nop 0
	global_load_lds_dwordx4 v[148:149], off
	s_waitcnt vmcnt(8)
	s_waitcnt lgkmcnt(0)
	s_barrier
	s_waitcnt lgkmcnt(0)
	v_mfma_f32_16x16x32_f16 v[124:127], v[172:175], v[204:207], 0
	v_mfma_f32_16x16x32_f16 v[116:119], v[180:183], v[204:207], 0
	v_mfma_f32_16x16x32_f16 v[108:111], v[172:175], v[212:215], 0
	v_mfma_f32_16x16x32_f16 v[104:107], v[180:183], v[212:215], 0
	v_mfma_f32_16x16x32_f16 v[92:95], v[172:175], v[220:223], 0
	v_mfma_f32_16x16x32_f16 v[88:91], v[180:183], v[220:223], 0
	v_mfma_f32_16x16x32_f16 v[76:79], v[172:175], v[228:231], 0
	v_mfma_f32_16x16x32_f16 v[72:75], v[180:183], v[228:231], 0
	v_mfma_f32_16x16x32_f16 v[124:127], v[176:179], v[208:211], v[124:127]
	v_mfma_f32_16x16x32_f16 v[116:119], v[184:187], v[208:211], v[116:119]
	v_mfma_f32_16x16x32_f16 v[108:111], v[176:179], v[216:219], v[108:111]
	v_mfma_f32_16x16x32_f16 v[104:107], v[184:187], v[216:219], v[104:107]
	v_mfma_f32_16x16x32_f16 v[92:95], v[176:179], v[224:227], v[92:95]
	v_mfma_f32_16x16x32_f16 v[88:91], v[184:187], v[224:227], v[88:91]
	v_mfma_f32_16x16x32_f16 v[76:79], v[176:179], v[232:235], v[76:79]
	v_mfma_f32_16x16x32_f16 v[72:75], v[184:187], v[232:235], v[72:75]
	v_mfma_f32_16x16x32_f16 v[120:123], v[188:191], v[204:207], 0
	v_mfma_f32_16x16x32_f16 v[112:115], v[196:199], v[204:207], 0
	v_mfma_f32_16x16x32_f16 v[100:103], v[188:191], v[212:215], 0
	v_mfma_f32_16x16x32_f16 v[96:99], v[196:199], v[212:215], 0
	v_mfma_f32_16x16x32_f16 v[84:87], v[188:191], v[220:223], 0
	v_mfma_f32_16x16x32_f16 v[80:83], v[196:199], v[220:223], 0
	v_mfma_f32_16x16x32_f16 v[68:71], v[188:191], v[228:231], 0
	v_mfma_f32_16x16x32_f16 v[64:67], v[196:199], v[228:231], 0
	v_mfma_f32_16x16x32_f16 v[120:123], v[192:195], v[208:211], v[120:123]
	v_mfma_f32_16x16x32_f16 v[112:115], v[200:203], v[208:211], v[112:115]
	v_mfma_f32_16x16x32_f16 v[100:103], v[192:195], v[216:219], v[100:103]
	v_mfma_f32_16x16x32_f16 v[96:99], v[200:203], v[216:219], v[96:99]
	v_mfma_f32_16x16x32_f16 v[84:87], v[192:195], v[224:227], v[84:87]
	v_mfma_f32_16x16x32_f16 v[80:83], v[200:203], v[224:227], v[80:83]
	v_mfma_f32_16x16x32_f16 v[68:71], v[192:195], v[232:235], v[68:71]
	v_mfma_f32_16x16x32_f16 v[64:67], v[200:203], v[232:235], v[64:67]
	s_barrier
	s_mov_b32 m0, s21
	v_lshl_add_u64 v[148:149], s[10:11], 0, v[132:133]
	s_add_u32 s70, s10, 0x40000
	ds_read_b128 v[204:207], v153 offset:16384
	ds_read_b128 v[208:211], v153 offset:17408
	ds_read_b128 v[212:215], v153 offset:18432
	ds_read_b128 v[216:219], v153 offset:19456
	ds_read_b128 v[220:223], v153 offset:20480
	ds_read_b128 v[224:227], v153 offset:21504
	ds_read_b128 v[228:231], v153 offset:22528
	ds_read_b128 v[232:235], v153 offset:23552
	global_load_lds_dwordx4 v[148:149], off
	v_lshl_add_u64 v[236:237], s[10:11], 0, v[128:129]
	s_mov_b32 m0, s33
	s_addc_u32 s71, s11, 0
	global_load_lds_dwordx4 v[236:237], off
	v_lshl_add_u64 v[238:239], s[70:71], 0, v[132:133]
	s_mov_b32 m0, s46
	v_lshl_add_u64 v[240:241], s[44:45], 0, v[130:131]
	global_load_lds_dwordx4 v[238:239], off
	v_lshl_add_u64 v[238:239], s[70:71], 0, v[128:129]
	s_mov_b32 m0, s47
	s_nop 0
	global_load_lds_dwordx4 v[238:239], off
	v_lshl_add_u64 v[238:239], s[44:45], 0, v[134:135]
	s_mov_b32 m0, s2
	s_nop 0
	global_load_lds_dwordx4 v[238:239], off
	s_mov_b32 m0, s48
	s_nop 0
	global_load_lds_dwordx4 v[240:241], off
	s_waitcnt vmcnt(8)
	s_waitcnt lgkmcnt(0)
	s_barrier
; #define PG8_STAGE(bufoff, gbase, voff) do { _Pragma("unroll") for (int _i = 0; _i < 2; ++_i) \
;         __builtin_amdgcn_global_load_lds((const unsigned*)((const char*)(gbase) + (voff)[_i]), (PG8_LAS unsigned*)(lds + (bufoff) + ldsw + _i * 8192), 16, 0, 0); } while (0)
; #define PG8_LDA(dst, b, h) do { _Pragma("unroll") for (int m = 0; m < 4; ++m) _Pragma("unroll") for (int k = 0; k < 2; ++k) dst[m][k] = *(const PG8_LAS bf16x8*)(lds + PG8_SA(b, h) + aoff + m * 2048 + k * 1024); } while (0)
; #define PG8_LDB(dst, b, h) do { _Pragma("unroll") for (int n = 0; n < 2; ++n) _Pragma("unroll") for (int k = 0; k < 2; ++k) dst[n][k] = *(const PG8_LAS bf16x8*)(lds + PG8_SB(b, h) + boff + n * 2048 + k * 1024); } while (0)
; #define PG8_MMA(ai, bj, At, Bt) do { __builtin_amdgcn_s_setprio(1); _Pragma("unroll") for (int m = 0; m < 4; ++m) _Pragma("unroll") for (int n = 0; n < 2; ++n) _Pragma("unroll") for (int k = 0; k < 2; ++k) \
;         acc[ai][bj][m][n] = mma16<F16>(Bt[n][k], At[m][k], acc[ai][bj][m][n]); __builtin_amdgcn_s_setprio(0); } while (0)
; #define PG8_WAIT_V(n) asm volatile("s_waitcnt vmcnt(" #n ")" ::: "memory")
; #define PG8_WAIT_L(n) asm volatile("s_waitcnt lgkmcnt(" #n ")" ::: "memory")
; #define PG8_BAR __builtin_amdgcn_s_barrier()
; #define PG8_SCHED __builtin_amdgcn_sched_barrier(0)
; template <class Epi, class Sched, bool ALIGN_EPI = false, bool SP2 = false, bool F16 = false, bool TOKPERM = false>
; __device__ __forceinline__ void gemm_phase(PG8_LAS unsigned char* lds, const Gemm g, const Sched& S, const Epi& E, int wv) {
;     ...
;             PG8_WAIT_V(8); PG8_WAIT_L(0); PG8_BAR; PG8_MMA(1, 0, At, B0); PG8_MMA(1, 1, At, B1); PG8_BAR; PG8_SCHED;
;             PG8_LDB(B0, 1, 0); PG8_LDB(B1, 1, 1); PG8_SCHED; PG8_LDA(At, 1, 0); PG8_STAGE(PG8_SA(0, 1), a2 + hstep, voffA);
;             PG8_WAIT_V(8); PG8_WAIT_L(0); PG8_BAR; PG8_MMA(0, 0, At, B0); PG8_MMA(0, 1, At, B1); PG8_BAR; PG8_SCHED;
;             PG8_LDA(At, 1, 1); PG8_STAGE(PG8_SB(1, 0), b3, voffB); PG8_STAGE(PG8_SB(1, 1), b3 + hstep, voffB); PG8_STAGE(PG8_SA(1, 0), a3, voffA);
;             PG8_WAIT_V(8); PG8_WAIT_L(0); PG8_BAR; PG8_MMA(1, 0, At, B0); PG8_MMA(1, 1, At, B1); PG8_BAR; PG8_SCHED;
	s_waitcnt lgkmcnt(0)
	v_mfma_f32_16x16x32_f16 v[60:63], v[172:175], v[204:207], 0
	v_mfma_f32_16x16x32_f16 v[56:59], v[180:183], v[204:207], 0
	v_mfma_f32_16x16x32_f16 v[44:47], v[172:175], v[212:215], 0
	v_mfma_f32_16x16x32_f16 v[40:43], v[180:183], v[212:215], 0
	v_mfma_f32_16x16x32_f16 v[28:31], v[172:175], v[220:223], 0
	v_mfma_f32_16x16x32_f16 v[24:27], v[180:183], v[220:223], 0
	v_mfma_f32_16x16x32_f16 v[12:15], v[172:175], v[228:231], 0
	v_mfma_f32_16x16x32_f16 v[8:11], v[180:183], v[228:231], 0
	v_mfma_f32_16x16x32_f16 v[60:63], v[176:179], v[208:211], v[60:63]
	v_mfma_f32_16x16x32_f16 v[56:59], v[184:187], v[208:211], v[56:59]
	v_mfma_f32_16x16x32_f16 v[44:47], v[176:179], v[216:219], v[44:47]
	v_mfma_f32_16x16x32_f16 v[40:43], v[184:187], v[216:219], v[40:43]
	v_mfma_f32_16x16x32_f16 v[28:31], v[176:179], v[224:227], v[28:31]
	v_mfma_f32_16x16x32_f16 v[24:27], v[184:187], v[224:227], v[24:27]
	v_mfma_f32_16x16x32_f16 v[12:15], v[176:179], v[232:235], v[12:15]
	v_mfma_f32_16x16x32_f16 v[8:11], v[184:187], v[232:235], v[8:11]
	v_mfma_f32_16x16x32_f16 v[52:55], v[188:191], v[204:207], 0
	v_mfma_f32_16x16x32_f16 v[48:51], v[196:199], v[204:207], 0
	v_mfma_f32_16x16x32_f16 v[36:39], v[188:191], v[212:215], 0
	v_mfma_f32_16x16x32_f16 v[32:35], v[196:199], v[212:215], 0
	v_mfma_f32_16x16x32_f16 v[20:23], v[188:191], v[220:223], 0
	v_mfma_f32_16x16x32_f16 v[16:19], v[196:199], v[220:223], 0
	v_mfma_f32_16x16x32_f16 v[4:7], v[188:191], v[228:231], 0
	v_mfma_f32_16x16x32_f16 v[0:3], v[196:199], v[228:231], 0
	v_mfma_f32_16x16x32_f16 v[52:55], v[192:195], v[208:211], v[52:55]
	v_mfma_f32_16x16x32_f16 v[48:51], v[200:203], v[208:211], v[48:51]
	v_mfma_f32_16x16x32_f16 v[36:39], v[192:195], v[216:219], v[36:39]
	v_mfma_f32_16x16x32_f16 v[32:35], v[200:203], v[216:219], v[32:35]
	v_mfma_f32_16x16x32_f16 v[20:23], v[192:195], v[224:227], v[20:23]
	v_mfma_f32_16x16x32_f16 v[16:19], v[200:203], v[224:227], v[16:19]
	v_mfma_f32_16x16x32_f16 v[4:7], v[192:195], v[232:235], v[4:7]
	v_mfma_f32_16x16x32_f16 v[0:3], v[200:203], v[232:235], v[0:3]
	s_barrier
	ds_read_b128 v[172:175], v163
	ds_read_b128 v[176:179], v164
	ds_read_b128 v[180:183], v165
	ds_read_b128 v[184:187], v166
	ds_read_b128 v[188:191], v167
	ds_read_b128 v[192:195], v168
	ds_read_b128 v[196:199], v169
	ds_read_b128 v[200:203], v170
	s_add_u32 s44, s44, 0x40000
	s_addc_u32 s45, s45, 0
	s_mov_b32 m0, s49
	v_lshl_add_u64 v[242:243], s[44:45], 0, v[134:135]
	ds_read_b128 v[204:207], v153 offset:32768
	ds_read_b128 v[208:211], v153 offset:33792
	ds_read_b128 v[212:215], v153 offset:34816
	ds_read_b128 v[216:219], v153 offset:35840
	ds_read_b128 v[220:223], v153 offset:36864
	ds_read_b128 v[224:227], v153 offset:37888
	ds_read_b128 v[228:231], v153 offset:38912
	ds_read_b128 v[232:235], v153 offset:39936
	global_load_lds_dwordx4 v[242:243], off
	v_lshl_add_u64 v[242:243], s[44:45], 0, v[130:131]
	s_mov_b32 m0, s50
	s_nop 0
	global_load_lds_dwordx4 v[242:243], off
	s_waitcnt vmcnt(8)
	s_waitcnt lgkmcnt(0)
	s_barrier
	s_waitcnt lgkmcnt(0)
	v_mfma_f32_16x16x32_f16 v[124:127], v[172:175], v[204:207], v[124:127]
	v_mfma_f32_16x16x32_f16 v[116:119], v[180:183], v[204:207], v[116:119]
	v_mfma_f32_16x16x32_f16 v[108:111], v[172:175], v[212:215], v[108:111]
	v_mfma_f32_16x16x32_f16 v[104:107], v[180:183], v[212:215], v[104:107]
	v_mfma_f32_16x16x32_f16 v[92:95], v[172:175], v[220:223], v[92:95]
	v_mfma_f32_16x16x32_f16 v[88:91], v[180:183], v[220:223], v[88:91]
	v_mfma_f32_16x16x32_f16 v[76:79], v[172:175], v[228:231], v[76:79]
	v_mfma_f32_16x16x32_f16 v[72:75], v[180:183], v[228:231], v[72:75]
	v_mfma_f32_16x16x32_f16 v[124:127], v[176:179], v[208:211], v[124:127]
	v_mfma_f32_16x16x32_f16 v[116:119], v[184:187], v[208:211], v[116:119]
	v_mfma_f32_16x16x32_f16 v[108:111], v[176:179], v[216:219], v[108:111]
	v_mfma_f32_16x16x32_f16 v[104:107], v[184:187], v[216:219], v[104:107]
	v_mfma_f32_16x16x32_f16 v[92:95], v[176:179], v[224:227], v[92:95]
	v_mfma_f32_16x16x32_f16 v[88:91], v[184:187], v[224:227], v[88:91]
	v_mfma_f32_16x16x32_f16 v[76:79], v[176:179], v[232:235], v[76:79]
	v_mfma_f32_16x16x32_f16 v[72:75], v[184:187], v[232:235], v[72:75]
	v_mfma_f32_16x16x32_f16 v[120:123], v[188:191], v[204:207], v[120:123]
	v_mfma_f32_16x16x32_f16 v[112:115], v[196:199], v[204:207], v[112:115]
	v_mfma_f32_16x16x32_f16 v[100:103], v[188:191], v[212:215], v[100:103]
	v_mfma_f32_16x16x32_f16 v[96:99], v[196:199], v[212:215], v[96:99]
	v_mfma_f32_16x16x32_f16 v[84:87], v[188:191], v[220:223], v[84:87]
	v_mfma_f32_16x16x32_f16 v[80:83], v[196:199], v[220:223], v[80:83]
	v_mfma_f32_16x16x32_f16 v[68:71], v[188:191], v[228:231], v[68:71]
	v_mfma_f32_16x16x32_f16 v[64:67], v[196:199], v[228:231], v[64:67]
	v_mfma_f32_16x16x32_f16 v[120:123], v[192:195], v[208:211], v[120:123]
	v_mfma_f32_16x16x32_f16 v[112:115], v[200:203], v[208:211], v[112:115]
	v_mfma_f32_16x16x32_f16 v[100:103], v[192:195], v[216:219], v[100:103]
	v_mfma_f32_16x16x32_f16 v[96:99], v[200:203], v[216:219], v[96:99]
	v_mfma_f32_16x16x32_f16 v[84:87], v[192:195], v[224:227], v[84:87]
	v_mfma_f32_16x16x32_f16 v[80:83], v[200:203], v[224:227], v[80:83]
	v_mfma_f32_16x16x32_f16 v[68:71], v[192:195], v[232:235], v[68:71]
	v_mfma_f32_16x16x32_f16 v[64:67], v[200:203], v[232:235], v[64:67]
	s_barrier
; #define PG8_STAGE(bufoff, gbase, voff) do { _Pragma("unroll") for (int _i = 0; _i < 2; ++_i) \
;         __builtin_amdgcn_global_load_lds((const unsigned*)((const char*)(gbase) + (voff)[_i]), (PG8_LAS unsigned*)(lds + (bufoff) + ldsw + _i * 8192), 16, 0, 0); } while (0)
; #define PG8_LDA(dst, b, h) do { _Pragma("unroll") for (int m = 0; m < 4; ++m) _Pragma("unroll") for (int k = 0; k < 2; ++k) dst[m][k] = *(const PG8_LAS bf16x8*)(lds + PG8_SA(b, h) + aoff + m * 2048 + k * 1024); } while (0)
; #define PG8_LDB(dst, b, h) do { _Pragma("unroll") for (int n = 0; n < 2; ++n) _Pragma("unroll") for (int k = 0; k < 2; ++k) dst[n][k] = *(const PG8_LAS bf16x8*)(lds + PG8_SB(b, h) + boff + n * 2048 + k * 1024); } while (0)
; #define PG8_MMA(ai, bj, At, Bt) do { __builtin_amdgcn_s_setprio(1); _Pragma("unroll") for (int m = 0; m < 4; ++m) _Pragma("unroll") for (int n = 0; n < 2; ++n) _Pragma("unroll") for (int k = 0; k < 2; ++k) \
;         acc[ai][bj][m][n] = mma16<F16>(Bt[n][k], At[m][k], acc[ai][bj][m][n]); __builtin_amdgcn_s_setprio(0); } while (0)
; #define PG8_BAR __builtin_amdgcn_s_barrier()
; template <class Epi, class Sched, bool ALIGN_EPI = false, bool SP2 = false, bool F16 = false, bool TOKPERM = false>
; __device__ __forceinline__ void gemm_phase(PG8_LAS unsigned char* lds, const Gemm g, const Sched& S, const Epi& E, int wv) {
;     ...
;             PG8_LDB(B0, 0, 0); PG8_LDB(B1, 0, 1); PG8_SCHED; PG8_LDA(At, 0, 0); PG8_STAGE(PG8_SA(1, 1), a1 + hstep, voffA);
;             PG8_WAIT_V(8); PG8_WAIT_L(0); PG8_BAR; PG8_MMA(0, 0, At, B0); PG8_MMA(0, 1, At, B1); PG8_BAR; PG8_SCHED;
;             PG8_LDA(At, 0, 1); PG8_STAGE(PG8_SB(0, 0), b2, voffB); PG8_STAGE(PG8_SB(0, 1), b2 + hstep, voffB); PG8_STAGE(PG8_SA(0, 0), a2, voffA);
;             PG8_WAIT_V(8); PG8_WAIT_L(0); PG8_BAR; PG8_MMA(1, 0, At, B0); PG8_MMA(1, 1, At, B1); PG8_BAR; PG8_SCHED;
;             PG8_LDB(B0, 1, 0); PG8_LDB(B1, 1, 1); PG8_SCHED; PG8_LDA(At, 1, 0); PG8_STAGE(PG8_SA(0, 1), a2 + hstep, voffA);
;             PG8_WAIT_V(8); PG8_WAIT_L(0); PG8_BAR; PG8_MMA(0, 0, At, B0); PG8_MMA(0, 1, At, B1); PG8_BAR; PG8_SCHED;
;             PG8_LDA(At, 1, 1); PG8_STAGE(PG8_SB(1, 0), b3, voffB); PG8_STAGE(PG8_SB(1, 1), b3 + hstep, voffB); PG8_STAGE(PG8_SA(1, 0), a3, voffA);
;             PG8_WAIT_V(8); PG8_WAIT_L(0); PG8_BAR; PG8_MMA(1, 0, At, B0); PG8_MMA(1, 1, At, B1); PG8_BAR; PG8_SCHED;
	s_mov_b32 m0, s52
	v_lshl_add_u64 v[148:149], v[148:149], 0, s[14:15]
	s_add_u32 s10, s10, 0x40080
	ds_read_b128 v[204:207], v153 offset:49152
	ds_read_b128 v[208:211], v153 offset:50176
	ds_read_b128 v[212:215], v153 offset:51200
	ds_read_b128 v[216:219], v153 offset:52224
	ds_read_b128 v[220:223], v153 offset:53248
	ds_read_b128 v[224:227], v153 offset:54272
	ds_read_b128 v[228:231], v153 offset:55296
	ds_read_b128 v[232:235], v153 offset:56320
	global_load_lds_dwordx4 v[148:149], off
	v_lshl_add_u64 v[148:149], v[236:237], 0, s[14:15]
	s_mov_b32 m0, s53
	s_addc_u32 s11, s11, 0
	global_load_lds_dwordx4 v[148:149], off
	v_lshl_add_u64 v[148:149], s[10:11], 0, v[132:133]
	s_mov_b32 m0, s56
	s_nop 0
	global_load_lds_dwordx4 v[148:149], off
	v_lshl_add_u64 v[148:149], s[10:11], 0, v[128:129]
	s_mov_b32 m0, s57
	s_nop 0
	global_load_lds_dwordx4 v[148:149], off
	v_lshl_add_u64 v[148:149], v[238:239], 0, s[14:15]
	s_mov_b32 m0, s54
	s_nop 0
	global_load_lds_dwordx4 v[148:149], off
	v_lshl_add_u64 v[148:149], v[240:241], 0, s[14:15]
	s_mov_b32 m0, s55
	s_nop 0
	global_load_lds_dwordx4 v[148:149], off
	s_waitcnt vmcnt(8)
	s_waitcnt lgkmcnt(0)
	s_barrier
	s_waitcnt lgkmcnt(0)
	v_mfma_f32_16x16x32_f16 v[60:63], v[172:175], v[204:207], v[60:63]
	v_mfma_f32_16x16x32_f16 v[56:59], v[180:183], v[204:207], v[56:59]
	v_mfma_f32_16x16x32_f16 v[44:47], v[172:175], v[212:215], v[44:47]
	v_mfma_f32_16x16x32_f16 v[40:43], v[180:183], v[212:215], v[40:43]
	v_mfma_f32_16x16x32_f16 v[28:31], v[172:175], v[220:223], v[28:31]
	v_mfma_f32_16x16x32_f16 v[24:27], v[180:183], v[220:223], v[24:27]
	v_mfma_f32_16x16x32_f16 v[12:15], v[172:175], v[228:231], v[12:15]
	v_mfma_f32_16x16x32_f16 v[8:11], v[180:183], v[228:231], v[8:11]
	v_mfma_f32_16x16x32_f16 v[60:63], v[176:179], v[208:211], v[60:63]
	v_mfma_f32_16x16x32_f16 v[56:59], v[184:187], v[208:211], v[56:59]
	v_mfma_f32_16x16x32_f16 v[44:47], v[176:179], v[216:219], v[44:47]
	v_mfma_f32_16x16x32_f16 v[40:43], v[184:187], v[216:219], v[40:43]
	v_mfma_f32_16x16x32_f16 v[28:31], v[176:179], v[224:227], v[28:31]
	v_mfma_f32_16x16x32_f16 v[24:27], v[184:187], v[224:227], v[24:27]
	v_mfma_f32_16x16x32_f16 v[12:15], v[176:179], v[232:235], v[12:15]
	v_mfma_f32_16x16x32_f16 v[8:11], v[184:187], v[232:235], v[8:11]
	v_mfma_f32_16x16x32_f16 v[52:55], v[188:191], v[204:207], v[52:55]
	v_mfma_f32_16x16x32_f16 v[48:51], v[196:199], v[204:207], v[48:51]
	v_mfma_f32_16x16x32_f16 v[36:39], v[188:191], v[212:215], v[36:39]
	v_mfma_f32_16x16x32_f16 v[32:35], v[196:199], v[212:215], v[32:35]
	v_mfma_f32_16x16x32_f16 v[20:23], v[188:191], v[220:223], v[20:23]
	v_mfma_f32_16x16x32_f16 v[16:19], v[196:199], v[220:223], v[16:19]
	v_mfma_f32_16x16x32_f16 v[4:7], v[188:191], v[228:231], v[4:7]
	v_mfma_f32_16x16x32_f16 v[0:3], v[196:199], v[228:231], v[0:3]
	v_mfma_f32_16x16x32_f16 v[52:55], v[192:195], v[208:211], v[52:55]
	v_mfma_f32_16x16x32_f16 v[48:51], v[200:203], v[208:211], v[48:51]
	v_mfma_f32_16x16x32_f16 v[36:39], v[192:195], v[216:219], v[36:39]
	v_mfma_f32_16x16x32_f16 v[32:35], v[200:203], v[216:219], v[32:35]
	v_mfma_f32_16x16x32_f16 v[20:23], v[192:195], v[224:227], v[20:23]
	v_mfma_f32_16x16x32_f16 v[16:19], v[200:203], v[224:227], v[16:19]
	v_mfma_f32_16x16x32_f16 v[4:7], v[192:195], v[232:235], v[4:7]
	v_mfma_f32_16x16x32_f16 v[0:3], v[200:203], v[232:235], v[0:3]
	s_barrier
	s_add_i32 s68, s68, 2
	s_add_u32 s8, s8, 0x100
	s_addc_u32 s9, s9, 0
	s_add_u32 s66, s66, 0x100
	s_addc_u32 s67, s67, 0
	s_cmp_gt_u32 s68, 13
.LBB0_1607:
	ds_read_b128 v[172:175], v155
	ds_read_b128 v[176:179], v156
	ds_read_b128 v[180:183], v157
	ds_read_b128 v[184:187], v158
	ds_read_b128 v[188:191], v159
	ds_read_b128 v[192:195], v160
	ds_read_b128 v[196:199], v161
	ds_read_b128 v[200:203], v162
	s_add_u32 s10, s8, 0xfffc0080
	s_addc_u32 s11, s9, -1
	s_cmp_eq_u32 s68, 12
	s_cselect_b32 s45, s25, s11
	s_cselect_b32 s44, s64, s10
	s_cselect_b32 s11, s23, s67
	s_cselect_b32 s10, s65, s66
	s_mov_b32 m0, s60
	v_lshl_add_u64 v[148:149], s[8:9], 0, v[140:141]
	ds_read_b128 v[204:207], v153
	ds_read_b128 v[208:211], v153 offset:1024
	ds_read_b128 v[212:215], v153 offset:2048
	ds_read_b128 v[216:219], v153 offset:3072
	ds_read_b128 v[220:223], v153 offset:4096
	ds_read_b128 v[224:227], v153 offset:5120
	ds_read_b128 v[228:231], v153 offset:6144
	ds_read_b128 v[232:235], v153 offset:7168
	global_load_lds_dwordx4 v[148:149], off
	v_lshl_add_u64 v[148:149], s[8:9], 0, v[142:143]
	s_mov_b32 m0, s61
	s_nop 0
	global_load_lds_dwordx4 v[148:149], off
	s_waitcnt vmcnt(8)
	s_waitcnt lgkmcnt(0)
	s_barrier
; #define PG8_STAGE(bufoff, gbase, voff) do { _Pragma("unroll") for (int _i = 0; _i < 2; ++_i) \
;         __builtin_amdgcn_global_load_lds((const unsigned*)((const char*)(gbase) + (voff)[_i]), (PG8_LAS unsigned*)(lds + (bufoff) + ldsw + _i * 8192), 16, 0, 0); } while (0)
; #define PG8_LDA(dst, b, h) do { _Pragma("unroll") for (int m = 0; m < 4; ++m) _Pragma("unroll") for (int k = 0; k < 2; ++k) dst[m][k] = *(const PG8_LAS bf16x8*)(lds + PG8_SA(b, h) + aoff + m * 2048 + k * 1024); } while (0)
; #define PG8_LDB(dst, b, h) do { _Pragma("unroll") for (int n = 0; n < 2; ++n) _Pragma("unroll") for (int k = 0; k < 2; ++k) dst[n][k] = *(const PG8_LAS bf16x8*)(lds + PG8_SB(b, h) + boff + n * 2048 + k * 1024); } while (0)
; #define PG8_MMA(ai, bj, At, Bt) do { __builtin_amdgcn_s_setprio(1); _Pragma("unroll") for (int m = 0; m < 4; ++m) _Pragma("unroll") for (int n = 0; n < 2; ++n) _Pragma("unroll") for (int k = 0; k < 2; ++k) \
;         acc[ai][bj][m][n] = mma16<F16>(Bt[n][k], At[m][k], acc[ai][bj][m][n]); __builtin_amdgcn_s_setprio(0); } while (0)
; #define PG8_WAIT_V(n) asm volatile("s_waitcnt vmcnt(" #n ")" ::: "memory")
; #define PG8_WAIT_L(n) asm volatile("s_waitcnt lgkmcnt(" #n ")" ::: "memory")
; #define PG8_BAR __builtin_amdgcn_s_barrier()
; #define PG8_SCHED __builtin_amdgcn_sched_barrier(0)
; template <class Epi, class Sched, bool ALIGN_EPI = false, bool SP2 = false, bool F16 = false, bool TOKPERM = false>
; __device__ __forceinline__ void gemm_phase(PG8_LAS unsigned char* lds, const Gemm g, const Sched& S, const Epi& E, int wv) {
;     ...
;             PG8_WAIT_V(8); PG8_WAIT_L(0); PG8_BAR; PG8_MMA(0, 0, At, B0); PG8_MMA(0, 1, At, B1); PG8_BAR; PG8_SCHED;
;             PG8_LDA(At, 0, 1); PG8_STAGE(PG8_SB(0, 0), b2, voffB); PG8_STAGE(PG8_SB(0, 1), b2 + hstep, voffB); PG8_STAGE(PG8_SA(0, 0), a2, voffA);
;             PG8_WAIT_V(8); PG8_WAIT_L(0); PG8_BAR; PG8_MMA(1, 0, At, B0); PG8_MMA(1, 1, At, B1); PG8_BAR; PG8_SCHED;
;             PG8_LDB(B0, 1, 0); PG8_LDB(B1, 1, 1); PG8_SCHED; PG8_LDA(At, 1, 0); PG8_STAGE(PG8_SA(0, 1), a2 + hstep, voffA);
;             PG8_WAIT_V(8); PG8_WAIT_L(0); PG8_BAR; PG8_MMA(0, 0, At, B0); PG8_MMA(0, 1, At, B1); PG8_BAR; PG8_SCHED;
	s_waitcnt lgkmcnt(0)
	v_mfma_f32_16x16x32_f16 v[124:127], v[172:175], v[204:207], v[124:127]
	v_mfma_f32_16x16x32_f16 v[116:119], v[180:183], v[204:207], v[116:119]
	v_mfma_f32_16x16x32_f16 v[108:111], v[172:175], v[212:215], v[108:111]
	v_mfma_f32_16x16x32_f16 v[104:107], v[180:183], v[212:215], v[104:107]
	v_mfma_f32_16x16x32_f16 v[92:95], v[172:175], v[220:223], v[92:95]
	v_mfma_f32_16x16x32_f16 v[88:91], v[180:183], v[220:223], v[88:91]
	v_mfma_f32_16x16x32_f16 v[76:79], v[172:175], v[228:231], v[76:79]
	v_mfma_f32_16x16x32_f16 v[72:75], v[180:183], v[228:231], v[72:75]
	v_mfma_f32_16x16x32_f16 v[124:127], v[176:179], v[208:211], v[124:127]
	v_mfma_f32_16x16x32_f16 v[116:119], v[184:187], v[208:211], v[116:119]
	v_mfma_f32_16x16x32_f16 v[108:111], v[176:179], v[216:219], v[108:111]
	v_mfma_f32_16x16x32_f16 v[104:107], v[184:187], v[216:219], v[104:107]
	v_mfma_f32_16x16x32_f16 v[92:95], v[176:179], v[224:227], v[92:95]
	v_mfma_f32_16x16x32_f16 v[88:91], v[184:187], v[224:227], v[88:91]
	v_mfma_f32_16x16x32_f16 v[76:79], v[176:179], v[232:235], v[76:79]
	v_mfma_f32_16x16x32_f16 v[72:75], v[184:187], v[232:235], v[72:75]
	v_mfma_f32_16x16x32_f16 v[120:123], v[188:191], v[204:207], v[120:123]
	v_mfma_f32_16x16x32_f16 v[112:115], v[196:199], v[204:207], v[112:115]
	v_mfma_f32_16x16x32_f16 v[100:103], v[188:191], v[212:215], v[100:103]
	v_mfma_f32_16x16x32_f16 v[96:99], v[196:199], v[212:215], v[96:99]
	v_mfma_f32_16x16x32_f16 v[84:87], v[188:191], v[220:223], v[84:87]
	v_mfma_f32_16x16x32_f16 v[80:83], v[196:199], v[220:223], v[80:83]
	v_mfma_f32_16x16x32_f16 v[68:71], v[188:191], v[228:231], v[68:71]
	v_mfma_f32_16x16x32_f16 v[64:67], v[196:199], v[228:231], v[64:67]
	v_mfma_f32_16x16x32_f16 v[120:123], v[192:195], v[208:211], v[120:123]
	v_mfma_f32_16x16x32_f16 v[112:115], v[200:203], v[208:211], v[112:115]
	v_mfma_f32_16x16x32_f16 v[100:103], v[192:195], v[216:219], v[100:103]
	v_mfma_f32_16x16x32_f16 v[96:99], v[200:203], v[216:219], v[96:99]
	v_mfma_f32_16x16x32_f16 v[84:87], v[192:195], v[224:227], v[84:87]
	v_mfma_f32_16x16x32_f16 v[80:83], v[200:203], v[224:227], v[80:83]
	v_mfma_f32_16x16x32_f16 v[68:71], v[192:195], v[232:235], v[68:71]
	v_mfma_f32_16x16x32_f16 v[64:67], v[200:203], v[232:235], v[64:67]
	s_barrier
	s_mov_b32 m0, s21
	v_lshl_add_u64 v[148:149], s[10:11], 0, v[132:133]
	s_add_u32 s70, s10, 0x40000
	ds_read_b128 v[204:207], v153 offset:16384
	ds_read_b128 v[208:211], v153 offset:17408
	ds_read_b128 v[212:215], v153 offset:18432
	ds_read_b128 v[216:219], v153 offset:19456
	ds_read_b128 v[220:223], v153 offset:20480
	ds_read_b128 v[224:227], v153 offset:21504
	ds_read_b128 v[228:231], v153 offset:22528
	ds_read_b128 v[232:235], v153 offset:23552
	global_load_lds_dwordx4 v[148:149], off
	v_lshl_add_u64 v[236:237], s[10:11], 0, v[128:129]
	s_mov_b32 m0, s33
	s_addc_u32 s71, s11, 0
	global_load_lds_dwordx4 v[236:237], off
	v_lshl_add_u64 v[238:239], s[70:71], 0, v[132:133]
	s_mov_b32 m0, s46
	v_lshl_add_u64 v[240:241], s[44:45], 0, v[130:131]
	global_load_lds_dwordx4 v[238:239], off
	v_lshl_add_u64 v[238:239], s[70:71], 0, v[128:129]
	s_mov_b32 m0, s47
	s_nop 0
	global_load_lds_dwordx4 v[238:239], off
	v_lshl_add_u64 v[238:239], s[44:45], 0, v[134:135]
	s_mov_b32 m0, s2
	s_nop 0
	global_load_lds_dwordx4 v[238:239], off
	s_mov_b32 m0, s48
	s_nop 0
	global_load_lds_dwordx4 v[240:241], off
	s_waitcnt vmcnt(8)
	s_waitcnt lgkmcnt(0)
	s_barrier
	s_waitcnt lgkmcnt(0)
	v_mfma_f32_16x16x32_f16 v[60:63], v[172:175], v[204:207], v[60:63]
	v_mfma_f32_16x16x32_f16 v[56:59], v[180:183], v[204:207], v[56:59]
	v_mfma_f32_16x16x32_f16 v[44:47], v[172:175], v[212:215], v[44:47]
	v_mfma_f32_16x16x32_f16 v[40:43], v[180:183], v[212:215], v[40:43]
	v_mfma_f32_16x16x32_f16 v[28:31], v[172:175], v[220:223], v[28:31]
	v_mfma_f32_16x16x32_f16 v[24:27], v[180:183], v[220:223], v[24:27]
	v_mfma_f32_16x16x32_f16 v[12:15], v[172:175], v[228:231], v[12:15]
	v_mfma_f32_16x16x32_f16 v[8:11], v[180:183], v[228:231], v[8:11]
	v_mfma_f32_16x16x32_f16 v[60:63], v[176:179], v[208:211], v[60:63]
	v_mfma_f32_16x16x32_f16 v[56:59], v[184:187], v[208:211], v[56:59]
	v_mfma_f32_16x16x32_f16 v[44:47], v[176:179], v[216:219], v[44:47]
	v_mfma_f32_16x16x32_f16 v[40:43], v[184:187], v[216:219], v[40:43]
	v_mfma_f32_16x16x32_f16 v[28:31], v[176:179], v[224:227], v[28:31]
	v_mfma_f32_16x16x32_f16 v[24:27], v[184:187], v[224:227], v[24:27]
	v_mfma_f32_16x16x32_f16 v[12:15], v[176:179], v[232:235], v[12:15]
	v_mfma_f32_16x16x32_f16 v[8:11], v[184:187], v[232:235], v[8:11]
	v_mfma_f32_16x16x32_f16 v[52:55], v[188:191], v[204:207], v[52:55]
	v_mfma_f32_16x16x32_f16 v[48:51], v[196:199], v[204:207], v[48:51]
	v_mfma_f32_16x16x32_f16 v[36:39], v[188:191], v[212:215], v[36:39]
	v_mfma_f32_16x16x32_f16 v[32:35], v[196:199], v[212:215], v[32:35]
	v_mfma_f32_16x16x32_f16 v[20:23], v[188:191], v[220:223], v[20:23]
	v_mfma_f32_16x16x32_f16 v[16:19], v[196:199], v[220:223], v[16:19]
	v_mfma_f32_16x16x32_f16 v[4:7], v[188:191], v[228:231], v[4:7]
	v_mfma_f32_16x16x32_f16 v[0:3], v[196:199], v[228:231], v[0:3]
	v_mfma_f32_16x16x32_f16 v[52:55], v[192:195], v[208:211], v[52:55]
	v_mfma_f32_16x16x32_f16 v[48:51], v[200:203], v[208:211], v[48:51]
	v_mfma_f32_16x16x32_f16 v[36:39], v[192:195], v[216:219], v[36:39]
	v_mfma_f32_16x16x32_f16 v[32:35], v[200:203], v[216:219], v[32:35]
	v_mfma_f32_16x16x32_f16 v[20:23], v[192:195], v[224:227], v[20:23]
	v_mfma_f32_16x16x32_f16 v[16:19], v[200:203], v[224:227], v[16:19]
	v_mfma_f32_16x16x32_f16 v[4:7], v[192:195], v[232:235], v[4:7]
	v_mfma_f32_16x16x32_f16 v[0:3], v[200:203], v[232:235], v[0:3]
	s_barrier
; #define PG8_STAGE(bufoff, gbase, voff) do { _Pragma("unroll") for (int _i = 0; _i < 2; ++_i) \
;         __builtin_amdgcn_global_load_lds((const unsigned*)((const char*)(gbase) + (voff)[_i]), (PG8_LAS unsigned*)(lds + (bufoff) + ldsw + _i * 8192), 16, 0, 0); } while (0)
; #define PG8_LDA(dst, b, h) do { _Pragma("unroll") for (int m = 0; m < 4; ++m) _Pragma("unroll") for (int k = 0; k < 2; ++k) dst[m][k] = *(const PG8_LAS bf16x8*)(lds + PG8_SA(b, h) + aoff + m * 2048 + k * 1024); } while (0)
; #define PG8_LDB(dst, b, h) do { _Pragma("unroll") for (int n = 0; n < 2; ++n) _Pragma("unroll") for (int k = 0; k < 2; ++k) dst[n][k] = *(const PG8_LAS bf16x8*)(lds + PG8_SB(b, h) + boff + n * 2048 + k * 1024); } while (0)
; #define PG8_MMA(ai, bj, At, Bt) do { __builtin_amdgcn_s_setprio(1); _Pragma("unroll") for (int m = 0; m < 4; ++m) _Pragma("unroll") for (int n = 0; n < 2; ++n) _Pragma("unroll") for (int k = 0; k < 2; ++k) \
;         acc[ai][bj][m][n] = mma16<F16>(Bt[n][k], At[m][k], acc[ai][bj][m][n]); __builtin_amdgcn_s_setprio(0); } while (0)
; #define PG8_WAIT_V(n) asm volatile("s_waitcnt vmcnt(" #n ")" ::: "memory")
; #define PG8_WAIT_L(n) asm volatile("s_waitcnt lgkmcnt(" #n ")" ::: "memory")
; #define PG8_BAR __builtin_amdgcn_s_barrier()
; #define PG8_SCHED __builtin_amdgcn_sched_barrier(0)
; template <class Epi, class Sched, bool ALIGN_EPI = false, bool SP2 = false, bool F16 = false, bool TOKPERM = false>
; __device__ __forceinline__ void gemm_phase(PG8_LAS unsigned char* lds, const Gemm g, const Sched& S, const Epi& E, int wv) {
;     ...
;             PG8_LDB(B0, 1, 0); PG8_LDB(B1, 1, 1); PG8_SCHED; PG8_LDA(At, 1, 0); PG8_STAGE(PG8_SA(0, 1), a2 + hstep, voffA);
;             PG8_WAIT_V(8); PG8_WAIT_L(0); PG8_BAR; PG8_MMA(0, 0, At, B0); PG8_MMA(0, 1, At, B1); PG8_BAR; PG8_SCHED;
;             PG8_LDA(At, 1, 1); PG8_STAGE(PG8_SB(1, 0), b3, voffB); PG8_STAGE(PG8_SB(1, 1), b3 + hstep, voffB); PG8_STAGE(PG8_SA(1, 0), a3, voffA);
;             PG8_WAIT_V(8); PG8_WAIT_L(0); PG8_BAR; PG8_MMA(1, 0, At, B0); PG8_MMA(1, 1, At, B1); PG8_BAR; PG8_SCHED;
	ds_read_b128 v[172:175], v163
	ds_read_b128 v[176:179], v164
	ds_read_b128 v[180:183], v165
	ds_read_b128 v[184:187], v166
	ds_read_b128 v[188:191], v167
	ds_read_b128 v[192:195], v168
	ds_read_b128 v[196:199], v169
	ds_read_b128 v[200:203], v170
	s_add_u32 s44, s44, 0x40000
	s_addc_u32 s45, s45, 0
	s_mov_b32 m0, s49
	v_lshl_add_u64 v[242:243], s[44:45], 0, v[134:135]
	ds_read_b128 v[204:207], v153 offset:32768
	ds_read_b128 v[208:211], v153 offset:33792
	ds_read_b128 v[212:215], v153 offset:34816
	ds_read_b128 v[216:219], v153 offset:35840
	ds_read_b128 v[220:223], v153 offset:36864
	ds_read_b128 v[224:227], v153 offset:37888
	ds_read_b128 v[228:231], v153 offset:38912
	ds_read_b128 v[232:235], v153 offset:39936
	global_load_lds_dwordx4 v[242:243], off
	v_lshl_add_u64 v[242:243], s[44:45], 0, v[130:131]
	s_mov_b32 m0, s50
	s_nop 0
	global_load_lds_dwordx4 v[242:243], off
	s_waitcnt vmcnt(8)
	s_waitcnt lgkmcnt(0)
	s_barrier
	s_waitcnt lgkmcnt(0)
	v_mfma_f32_16x16x32_f16 v[124:127], v[172:175], v[204:207], v[124:127]
	v_mfma_f32_16x16x32_f16 v[116:119], v[180:183], v[204:207], v[116:119]
	v_mfma_f32_16x16x32_f16 v[108:111], v[172:175], v[212:215], v[108:111]
	v_mfma_f32_16x16x32_f16 v[104:107], v[180:183], v[212:215], v[104:107]
	v_mfma_f32_16x16x32_f16 v[92:95], v[172:175], v[220:223], v[92:95]
	v_mfma_f32_16x16x32_f16 v[88:91], v[180:183], v[220:223], v[88:91]
	v_mfma_f32_16x16x32_f16 v[76:79], v[172:175], v[228:231], v[76:79]
	v_mfma_f32_16x16x32_f16 v[72:75], v[180:183], v[228:231], v[72:75]
	v_mfma_f32_16x16x32_f16 v[124:127], v[176:179], v[208:211], v[124:127]
	v_mfma_f32_16x16x32_f16 v[116:119], v[184:187], v[208:211], v[116:119]
	v_mfma_f32_16x16x32_f16 v[108:111], v[176:179], v[216:219], v[108:111]
	v_mfma_f32_16x16x32_f16 v[104:107], v[184:187], v[216:219], v[104:107]
	v_mfma_f32_16x16x32_f16 v[92:95], v[176:179], v[224:227], v[92:95]
	v_mfma_f32_16x16x32_f16 v[88:91], v[184:187], v[224:227], v[88:91]
	v_mfma_f32_16x16x32_f16 v[76:79], v[176:179], v[232:235], v[76:79]
	v_mfma_f32_16x16x32_f16 v[72:75], v[184:187], v[232:235], v[72:75]
	v_mfma_f32_16x16x32_f16 v[120:123], v[188:191], v[204:207], v[120:123]
	v_mfma_f32_16x16x32_f16 v[112:115], v[196:199], v[204:207], v[112:115]
	v_mfma_f32_16x16x32_f16 v[100:103], v[188:191], v[212:215], v[100:103]
	v_mfma_f32_16x16x32_f16 v[96:99], v[196:199], v[212:215], v[96:99]
	v_mfma_f32_16x16x32_f16 v[84:87], v[188:191], v[220:223], v[84:87]
	v_mfma_f32_16x16x32_f16 v[80:83], v[196:199], v[220:223], v[80:83]
	v_mfma_f32_16x16x32_f16 v[68:71], v[188:191], v[228:231], v[68:71]
	v_mfma_f32_16x16x32_f16 v[64:67], v[196:199], v[228:231], v[64:67]
	v_mfma_f32_16x16x32_f16 v[120:123], v[192:195], v[208:211], v[120:123]
	v_mfma_f32_16x16x32_f16 v[112:115], v[200:203], v[208:211], v[112:115]
	v_mfma_f32_16x16x32_f16 v[100:103], v[192:195], v[216:219], v[100:103]
	v_mfma_f32_16x16x32_f16 v[96:99], v[200:203], v[216:219], v[96:99]
	v_mfma_f32_16x16x32_f16 v[84:87], v[192:195], v[224:227], v[84:87]
	v_mfma_f32_16x16x32_f16 v[80:83], v[200:203], v[224:227], v[80:83]
	v_mfma_f32_16x16x32_f16 v[68:71], v[192:195], v[232:235], v[68:71]
	v_mfma_f32_16x16x32_f16 v[64:67], v[200:203], v[232:235], v[64:67]
	s_barrier
	s_mov_b32 m0, s52
	v_lshl_add_u64 v[148:149], v[148:149], 0, s[14:15]
	s_add_u32 s10, s10, 0x40080
	ds_read_b128 v[204:207], v153 offset:49152
	ds_read_b128 v[208:211], v153 offset:50176
	ds_read_b128 v[212:215], v153 offset:51200
	ds_read_b128 v[216:219], v153 offset:52224
	ds_read_b128 v[220:223], v153 offset:53248
	ds_read_b128 v[224:227], v153 offset:54272
	ds_read_b128 v[228:231], v153 offset:55296
	ds_read_b128 v[232:235], v153 offset:56320
	global_load_lds_dwordx4 v[148:149], off
	v_lshl_add_u64 v[148:149], v[236:237], 0, s[14:15]
	s_mov_b32 m0, s53
	s_addc_u32 s11, s11, 0
	global_load_lds_dwordx4 v[148:149], off
	v_lshl_add_u64 v[148:149], s[10:11], 0, v[132:133]
	s_mov_b32 m0, s56
	s_nop 0
	global_load_lds_dwordx4 v[148:149], off
	v_lshl_add_u64 v[148:149], s[10:11], 0, v[128:129]
	s_mov_b32 m0, s57
	s_nop 0
	global_load_lds_dwordx4 v[148:149], off
	v_lshl_add_u64 v[148:149], v[238:239], 0, s[14:15]
	s_mov_b32 m0, s54
	s_nop 0
	global_load_lds_dwordx4 v[148:149], off
	v_lshl_add_u64 v[148:149], v[240:241], 0, s[14:15]
	s_mov_b32 m0, s55
	s_nop 0
	global_load_lds_dwordx4 v[148:149], off
	s_waitcnt vmcnt(8)
	s_waitcnt lgkmcnt(0)
	s_barrier
	s_waitcnt lgkmcnt(0)
	v_mfma_f32_16x16x32_f16 v[60:63], v[172:175], v[204:207], v[60:63]
	v_mfma_f32_16x16x32_f16 v[56:59], v[180:183], v[204:207], v[56:59]
	v_mfma_f32_16x16x32_f16 v[44:47], v[172:175], v[212:215], v[44:47]
	v_mfma_f32_16x16x32_f16 v[40:43], v[180:183], v[212:215], v[40:43]
	v_mfma_f32_16x16x32_f16 v[28:31], v[172:175], v[220:223], v[28:31]
	v_mfma_f32_16x16x32_f16 v[24:27], v[180:183], v[220:223], v[24:27]
	v_mfma_f32_16x16x32_f16 v[12:15], v[172:175], v[228:231], v[12:15]
	v_mfma_f32_16x16x32_f16 v[8:11], v[180:183], v[228:231], v[8:11]
	v_mfma_f32_16x16x32_f16 v[60:63], v[176:179], v[208:211], v[60:63]
	v_mfma_f32_16x16x32_f16 v[56:59], v[184:187], v[208:211], v[56:59]
	v_mfma_f32_16x16x32_f16 v[44:47], v[176:179], v[216:219], v[44:47]
	v_mfma_f32_16x16x32_f16 v[40:43], v[184:187], v[216:219], v[40:43]
	v_mfma_f32_16x16x32_f16 v[28:31], v[176:179], v[224:227], v[28:31]
	v_mfma_f32_16x16x32_f16 v[24:27], v[184:187], v[224:227], v[24:27]
	v_mfma_f32_16x16x32_f16 v[12:15], v[176:179], v[232:235], v[12:15]
	v_mfma_f32_16x16x32_f16 v[8:11], v[184:187], v[232:235], v[8:11]
	v_mfma_f32_16x16x32_f16 v[52:55], v[188:191], v[204:207], v[52:55]
	v_mfma_f32_16x16x32_f16 v[48:51], v[196:199], v[204:207], v[48:51]
	v_mfma_f32_16x16x32_f16 v[36:39], v[188:191], v[212:215], v[36:39]
	v_mfma_f32_16x16x32_f16 v[32:35], v[196:199], v[212:215], v[32:35]
	v_mfma_f32_16x16x32_f16 v[20:23], v[188:191], v[220:223], v[20:23]
	v_mfma_f32_16x16x32_f16 v[16:19], v[196:199], v[220:223], v[16:19]
	v_mfma_f32_16x16x32_f16 v[4:7], v[188:191], v[228:231], v[4:7]
	v_mfma_f32_16x16x32_f16 v[0:3], v[196:199], v[228:231], v[0:3]
	v_mfma_f32_16x16x32_f16 v[52:55], v[192:195], v[208:211], v[52:55]
	v_mfma_f32_16x16x32_f16 v[48:51], v[200:203], v[208:211], v[48:51]
	v_mfma_f32_16x16x32_f16 v[36:39], v[192:195], v[216:219], v[36:39]
	v_mfma_f32_16x16x32_f16 v[32:35], v[200:203], v[216:219], v[32:35]
	v_mfma_f32_16x16x32_f16 v[20:23], v[192:195], v[224:227], v[20:23]
	v_mfma_f32_16x16x32_f16 v[16:19], v[200:203], v[224:227], v[16:19]
	v_mfma_f32_16x16x32_f16 v[4:7], v[192:195], v[232:235], v[4:7]
	v_mfma_f32_16x16x32_f16 v[0:3], v[200:203], v[232:235], v[0:3]
	s_barrier
	s_add_i32 s68, s68, 2
	s_add_u32 s8, s8, 0x100
	s_addc_u32 s9, s9, 0
	s_add_u32 s66, s66, 0x100
	s_addc_u32 s67, s67, 0
	s_cmp_gt_u32 s68, 13
	s_cbranch_scc0 .LBB0_1607
	s_and_b64 vcc, exec, s[16:17]
	s_cbranch_vccz .LBB0_1610
	s_barrier

; #define PG8_STAGE(bufoff, gbase, voff) do { _Pragma("unroll") for (int _i = 0; _i < 2; ++_i) \
;         __builtin_amdgcn_global_load_lds((const unsigned*)((const char*)(gbase) + (voff)[_i]), (PG8_LAS unsigned*)(lds + (bufoff) + ldsw + _i * 8192), 16, 0, 0); } while (0)
; #define PG8_LDA(dst, b, h) do { _Pragma("unroll") for (int m = 0; m < 4; ++m) _Pragma("unroll") for (int k = 0; k < 2; ++k) dst[m][k] = *(const PG8_LAS bf16x8*)(lds + PG8_SA(b, h) + aoff + m * 2048 + k * 1024); } while (0)
; #define PG8_LDB(dst, b, h) do { _Pragma("unroll") for (int n = 0; n < 2; ++n) _Pragma("unroll") for (int k = 0; k < 2; ++k) dst[n][k] = *(const PG8_LAS bf16x8*)(lds + PG8_SB(b, h) + boff + n * 2048 + k * 1024); } while (0)
; #define PG8_MMA(ai, bj, At, Bt) do { __builtin_amdgcn_s_setprio(1); _Pragma("unroll") for (int m = 0; m < 4; ++m) _Pragma("unroll") for (int n = 0; n < 2; ++n) _Pragma("unroll") for (int k = 0; k < 2; ++k) \
;         acc[ai][bj][m][n] = mma16<F16>(Bt[n][k], At[m][k], acc[ai][bj][m][n]); __builtin_amdgcn_s_setprio(0); } while (0)
; #define PG8_WAIT_V(n) asm volatile("s_waitcnt vmcnt(" #n ")" ::: "memory")
; #define PG8_WAIT_L(n) asm volatile("s_waitcnt lgkmcnt(" #n ")" ::: "memory")
; #define PG8_BAR __builtin_amdgcn_s_barrier()
; template <class Epi, class Sched, bool ALIGN_EPI = false, bool SP2 = false, bool F16 = false, bool TOKPERM = false>
; __device__ __forceinline__ void gemm_phase(PG8_LAS unsigned char* lds, const Gemm g, const Sched& S, const Epi& E, int wv) {
;     ...
;             const char* a1 = cA + (size_t)(t + 1) * kstep;
;             const char* a2 = last ? nA : cA + (size_t)(t + 2) * kstep; const char* b2 = last ? nB : cB + (size_t)(t + 2) * kstep;
;             const char* a3 = a2 + kstep; const char* b3 = b2 + kstep;
;             if (last && has_next) S.a_ready(nxt);
;             if constexpr (SP2) {
;             PG8_LDB(B0, 0, 0); PG8_LDB(B1, 0, 1); PG8_SCHED; PG8_LDA(At, 0, 0); PG8_STAGE(PG8_SA(1, 1), a1 + hstep, voffA);
;             PG8_WAIT_V(8); PG8_WAIT_L(0); PG8_BAR; PG8_MMA(0, 0, At, B0); PG8_MMA(0, 1, At, B1); PG8_BAR; PG8_SCHED;
;             PG8_LDA(At, 0, 1); PG8_STAGE(PG8_SB(0, 0), b2, voffB); PG8_STAGE(PG8_SB(0, 1), b2 + hstep, voffB); PG8_STAGE(PG8_SA(0, 0), a2, voffA);
;             PG8_WAIT_V(8); PG8_WAIT_L(0); PG8_BAR; PG8_MMA(1, 0, At, B0); PG8_MMA(1, 1, At, B1); PG8_BAR; PG8_SCHED;
.LBB0_1687:
	ds_read_b128 v[166:169], v149
	ds_read_b128 v[170:173], v150
	ds_read_b128 v[174:177], v151
	ds_read_b128 v[178:181], v152
	ds_read_b128 v[182:185], v153
	ds_read_b128 v[186:189], v154
	ds_read_b128 v[190:193], v155
	ds_read_b128 v[194:197], v156
	s_add_u32 s10, s8, 0x100
	s_addc_u32 s11, s9, 0
	s_cmp_eq_u32 s53, 40
	s_cselect_b32 s15, s3, s11
	s_cselect_b32 s14, s2, s10
	s_cselect_b32 s13, s5, s52
	s_cselect_b32 s12, s4, s51
	s_mov_b32 m0, s45
	v_lshl_add_u64 v[230:231], s[8:9], 0, v[138:139]
	ds_read_b128 v[198:201], v147
	ds_read_b128 v[202:205], v147 offset:1024
	ds_read_b128 v[206:209], v147 offset:2048
	ds_read_b128 v[210:213], v147 offset:3072
	ds_read_b128 v[214:217], v147 offset:4096
	ds_read_b128 v[218:221], v147 offset:5120
	ds_read_b128 v[222:225], v147 offset:6144
	ds_read_b128 v[226:229], v147 offset:7168
	global_load_lds_dwordx4 v[230:231], off
	v_lshl_add_u64 v[230:231], s[8:9], 0, v[140:141]
	s_mov_b32 m0, s46
	s_nop 0
	global_load_lds_dwordx4 v[230:231], off
	s_waitcnt vmcnt(8)
	s_waitcnt lgkmcnt(0)
	s_barrier
	s_waitcnt lgkmcnt(0)
	v_mfma_f32_16x16x32_bf16 v[124:127], v[166:169], v[198:201], v[124:127]
	v_mfma_f32_16x16x32_bf16 v[120:123], v[174:177], v[198:201], v[120:123]
	v_mfma_f32_16x16x32_bf16 v[108:111], v[166:169], v[206:209], v[108:111]
	v_mfma_f32_16x16x32_bf16 v[104:107], v[174:177], v[206:209], v[104:107]
	v_mfma_f32_16x16x32_bf16 v[92:95], v[166:169], v[214:217], v[92:95]
	v_mfma_f32_16x16x32_bf16 v[88:91], v[174:177], v[214:217], v[88:91]
	v_mfma_f32_16x16x32_bf16 v[76:79], v[166:169], v[222:225], v[76:79]
	v_mfma_f32_16x16x32_bf16 v[72:75], v[174:177], v[222:225], v[72:75]
	v_mfma_f32_16x16x32_bf16 v[124:127], v[170:173], v[202:205], v[124:127]
	v_mfma_f32_16x16x32_bf16 v[120:123], v[178:181], v[202:205], v[120:123]
	v_mfma_f32_16x16x32_bf16 v[108:111], v[170:173], v[210:213], v[108:111]
	v_mfma_f32_16x16x32_bf16 v[104:107], v[178:181], v[210:213], v[104:107]
	v_mfma_f32_16x16x32_bf16 v[92:95], v[170:173], v[218:221], v[92:95]
	v_mfma_f32_16x16x32_bf16 v[88:91], v[178:181], v[218:221], v[88:91]
	v_mfma_f32_16x16x32_bf16 v[76:79], v[170:173], v[226:229], v[76:79]
	v_mfma_f32_16x16x32_bf16 v[72:75], v[178:181], v[226:229], v[72:75]
	v_mfma_f32_16x16x32_bf16 v[116:119], v[182:185], v[198:201], v[116:119]
	v_mfma_f32_16x16x32_bf16 v[112:115], v[190:193], v[198:201], v[112:115]
	v_mfma_f32_16x16x32_bf16 v[100:103], v[182:185], v[206:209], v[100:103]
	v_mfma_f32_16x16x32_bf16 v[96:99], v[190:193], v[206:209], v[96:99]
	v_mfma_f32_16x16x32_bf16 v[84:87], v[182:185], v[214:217], v[84:87]
	v_mfma_f32_16x16x32_bf16 v[80:83], v[190:193], v[214:217], v[80:83]
	v_mfma_f32_16x16x32_bf16 v[68:71], v[182:185], v[222:225], v[68:71]
	v_mfma_f32_16x16x32_bf16 v[64:67], v[190:193], v[222:225], v[64:67]
	v_mfma_f32_16x16x32_bf16 v[116:119], v[186:189], v[202:205], v[116:119]
	v_mfma_f32_16x16x32_bf16 v[112:115], v[194:197], v[202:205], v[112:115]
	v_mfma_f32_16x16x32_bf16 v[100:103], v[186:189], v[210:213], v[100:103]
	v_mfma_f32_16x16x32_bf16 v[96:99], v[194:197], v[210:213], v[96:99]
	v_mfma_f32_16x16x32_bf16 v[84:87], v[186:189], v[218:221], v[84:87]
	v_mfma_f32_16x16x32_bf16 v[80:83], v[194:197], v[218:221], v[80:83]
	v_mfma_f32_16x16x32_bf16 v[68:71], v[186:189], v[226:229], v[68:71]
	v_mfma_f32_16x16x32_bf16 v[64:67], v[194:197], v[226:229], v[64:67]
	s_barrier
	s_mov_b32 m0, s21
	v_lshl_add_u64 v[230:231], s[12:13], 0, v[130:131]
	s_add_u32 s8, s12, 0xb0000
	ds_read_b128 v[198:201], v147 offset:16384
	ds_read_b128 v[202:205], v147 offset:17408
	ds_read_b128 v[206:209], v147 offset:18432
	ds_read_b128 v[210:213], v147 offset:19456
	ds_read_b128 v[214:217], v147 offset:20480
	ds_read_b128 v[218:221], v147 offset:21504
	ds_read_b128 v[222:225], v147 offset:22528
	ds_read_b128 v[226:229], v147 offset:23552
	global_load_lds_dwordx4 v[230:231], off
	v_lshl_add_u64 v[232:233], s[12:13], 0, v[134:135]
	s_mov_b32 m0, s22
	s_addc_u32 s9, s13, 0
	global_load_lds_dwordx4 v[232:233], off
	v_lshl_add_u64 v[234:235], s[8:9], 0, v[130:131]
	s_mov_b32 m0, s23
	v_lshl_add_u64 v[236:237], s[14:15], 0, v[132:133]
	global_load_lds_dwordx4 v[234:235], off
	v_lshl_add_u64 v[234:235], s[8:9], 0, v[134:135]
	s_mov_b32 m0, s24
	s_nop 0
	global_load_lds_dwordx4 v[234:235], off
	v_lshl_add_u64 v[234:235], s[14:15], 0, v[128:129]
	s_mov_b32 m0, s20
	s_nop 0
	global_load_lds_dwordx4 v[234:235], off
	s_mov_b32 m0, s25
	s_nop 0
	global_load_lds_dwordx4 v[236:237], off
	s_waitcnt vmcnt(8)
	s_waitcnt lgkmcnt(0)
	s_barrier
	s_waitcnt lgkmcnt(0)
	v_mfma_f32_16x16x32_bf16 v[60:63], v[166:169], v[198:201], v[60:63]
	v_mfma_f32_16x16x32_bf16 v[56:59], v[174:177], v[198:201], v[56:59]
	v_mfma_f32_16x16x32_bf16 v[44:47], v[166:169], v[206:209], v[44:47]
	v_mfma_f32_16x16x32_bf16 v[40:43], v[174:177], v[206:209], v[40:43]
	v_mfma_f32_16x16x32_bf16 v[28:31], v[166:169], v[214:217], v[28:31]
	v_mfma_f32_16x16x32_bf16 v[24:27], v[174:177], v[214:217], v[24:27]
	v_mfma_f32_16x16x32_bf16 v[12:15], v[166:169], v[222:225], v[12:15]
	v_mfma_f32_16x16x32_bf16 v[8:11], v[174:177], v[222:225], v[8:11]
	v_mfma_f32_16x16x32_bf16 v[60:63], v[170:173], v[202:205], v[60:63]
	v_mfma_f32_16x16x32_bf16 v[56:59], v[178:181], v[202:205], v[56:59]
	v_mfma_f32_16x16x32_bf16 v[44:47], v[170:173], v[210:213], v[44:47]
	v_mfma_f32_16x16x32_bf16 v[40:43], v[178:181], v[210:213], v[40:43]
	v_mfma_f32_16x16x32_bf16 v[28:31], v[170:173], v[218:221], v[28:31]
	v_mfma_f32_16x16x32_bf16 v[24:27], v[178:181], v[218:221], v[24:27]
	v_mfma_f32_16x16x32_bf16 v[12:15], v[170:173], v[226:229], v[12:15]
	v_mfma_f32_16x16x32_bf16 v[8:11], v[178:181], v[226:229], v[8:11]
	v_mfma_f32_16x16x32_bf16 v[52:55], v[182:185], v[198:201], v[52:55]
	v_mfma_f32_16x16x32_bf16 v[48:51], v[190:193], v[198:201], v[48:51]
	v_mfma_f32_16x16x32_bf16 v[36:39], v[182:185], v[206:209], v[36:39]
	v_mfma_f32_16x16x32_bf16 v[32:35], v[190:193], v[206:209], v[32:35]
	v_mfma_f32_16x16x32_bf16 v[20:23], v[182:185], v[214:217], v[20:23]
	v_mfma_f32_16x16x32_bf16 v[16:19], v[190:193], v[214:217], v[16:19]
	v_mfma_f32_16x16x32_bf16 v[4:7], v[182:185], v[222:225], v[4:7]
	v_mfma_f32_16x16x32_bf16 v[0:3], v[190:193], v[222:225], v[0:3]
	v_mfma_f32_16x16x32_bf16 v[52:55], v[186:189], v[202:205], v[52:55]
	v_mfma_f32_16x16x32_bf16 v[48:51], v[194:197], v[202:205], v[48:51]
	v_mfma_f32_16x16x32_bf16 v[36:39], v[186:189], v[210:213], v[36:39]
	v_mfma_f32_16x16x32_bf16 v[32:35], v[194:197], v[210:213], v[32:35]
	v_mfma_f32_16x16x32_bf16 v[20:23], v[186:189], v[218:221], v[20:23]
	v_mfma_f32_16x16x32_bf16 v[16:19], v[194:197], v[218:221], v[16:19]
	v_mfma_f32_16x16x32_bf16 v[4:7], v[186:189], v[226:229], v[4:7]
	v_mfma_f32_16x16x32_bf16 v[0:3], v[194:197], v[226:229], v[0:3]
	s_barrier
; #define PG8_STAGE(bufoff, gbase, voff) do { _Pragma("unroll") for (int _i = 0; _i < 2; ++_i) \
;         __builtin_amdgcn_global_load_lds((const unsigned*)((const char*)(gbase) + (voff)[_i]), (PG8_LAS unsigned*)(lds + (bufoff) + ldsw + _i * 8192), 16, 0, 0); } while (0)
; #define PG8_LDA(dst, b, h) do { _Pragma("unroll") for (int m = 0; m < 4; ++m) _Pragma("unroll") for (int k = 0; k < 2; ++k) dst[m][k] = *(const PG8_LAS bf16x8*)(lds + PG8_SA(b, h) + aoff + m * 2048 + k * 1024); } while (0)
; #define PG8_LDB(dst, b, h) do { _Pragma("unroll") for (int n = 0; n < 2; ++n) _Pragma("unroll") for (int k = 0; k < 2; ++k) dst[n][k] = *(const PG8_LAS bf16x8*)(lds + PG8_SB(b, h) + boff + n * 2048 + k * 1024); } while (0)
; #define PG8_MMA(ai, bj, At, Bt) do { __builtin_amdgcn_s_setprio(1); _Pragma("unroll") for (int m = 0; m < 4; ++m) _Pragma("unroll") for (int n = 0; n < 2; ++n) _Pragma("unroll") for (int k = 0; k < 2; ++k) \
;         acc[ai][bj][m][n] = mma16<F16>(Bt[n][k], At[m][k], acc[ai][bj][m][n]); __builtin_amdgcn_s_setprio(0); } while (0)
; #define PG8_WAIT_V(n) asm volatile("s_waitcnt vmcnt(" #n ")" ::: "memory")
; #define PG8_WAIT_L(n) asm volatile("s_waitcnt lgkmcnt(" #n ")" ::: "memory")
; #define PG8_BAR __builtin_amdgcn_s_barrier()
; #define PG8_SCHED __builtin_amdgcn_sched_barrier(0)
; template <class Epi, class Sched, bool ALIGN_EPI = false, bool SP2 = false, bool F16 = false, bool TOKPERM = false>
; __device__ __forceinline__ void gemm_phase(PG8_LAS unsigned char* lds, const Gemm g, const Sched& S, const Epi& E, int wv) {
;     ...
;             PG8_LDB(B0, 1, 0); PG8_LDB(B1, 1, 1); PG8_SCHED; PG8_LDA(At, 1, 0); PG8_STAGE(PG8_SA(0, 1), a2 + hstep, voffA);
;             PG8_WAIT_V(8); PG8_WAIT_L(0); PG8_BAR; PG8_MMA(0, 0, At, B0); PG8_MMA(0, 1, At, B1); PG8_BAR; PG8_SCHED;
;             PG8_LDA(At, 1, 1); PG8_STAGE(PG8_SB(1, 0), b3, voffB); PG8_STAGE(PG8_SB(1, 1), b3 + hstep, voffB); PG8_STAGE(PG8_SA(1, 0), a3, voffA);
;             PG8_WAIT_V(8); PG8_WAIT_L(0); PG8_BAR; PG8_MMA(1, 0, At, B0); PG8_MMA(1, 1, At, B1); PG8_BAR; PG8_SCHED;
	ds_read_b128 v[166:169], v157
	ds_read_b128 v[170:173], v158
	ds_read_b128 v[174:177], v159
	ds_read_b128 v[178:181], v160
	ds_read_b128 v[182:185], v161
	ds_read_b128 v[186:189], v162
	ds_read_b128 v[190:193], v163
	ds_read_b128 v[194:197], v164
	s_add_u32 s8, s14, 0xb0000
	s_addc_u32 s9, s15, 0
	s_mov_b32 m0, s27
	v_lshl_add_u64 v[238:239], s[8:9], 0, v[128:129]
	ds_read_b128 v[198:201], v147 offset:32768
	ds_read_b128 v[202:205], v147 offset:33792
	ds_read_b128 v[206:209], v147 offset:34816
	ds_read_b128 v[210:213], v147 offset:35840
	ds_read_b128 v[214:217], v147 offset:36864
	ds_read_b128 v[218:221], v147 offset:37888
	ds_read_b128 v[222:225], v147 offset:38912
	ds_read_b128 v[226:229], v147 offset:39936
	global_load_lds_dwordx4 v[238:239], off
	v_lshl_add_u64 v[238:239], s[8:9], 0, v[132:133]
	s_mov_b32 m0, s29
	s_nop 0
	global_load_lds_dwordx4 v[238:239], off
	s_waitcnt vmcnt(8)
	s_waitcnt lgkmcnt(0)
	s_barrier
	s_waitcnt lgkmcnt(0)
	v_mfma_f32_16x16x32_bf16 v[124:127], v[166:169], v[198:201], v[124:127]
	v_mfma_f32_16x16x32_bf16 v[120:123], v[174:177], v[198:201], v[120:123]
	v_mfma_f32_16x16x32_bf16 v[108:111], v[166:169], v[206:209], v[108:111]
	v_mfma_f32_16x16x32_bf16 v[104:107], v[174:177], v[206:209], v[104:107]
	v_mfma_f32_16x16x32_bf16 v[92:95], v[166:169], v[214:217], v[92:95]
	v_mfma_f32_16x16x32_bf16 v[88:91], v[174:177], v[214:217], v[88:91]
	v_mfma_f32_16x16x32_bf16 v[76:79], v[166:169], v[222:225], v[76:79]
	v_mfma_f32_16x16x32_bf16 v[72:75], v[174:177], v[222:225], v[72:75]
	v_mfma_f32_16x16x32_bf16 v[124:127], v[170:173], v[202:205], v[124:127]
	v_mfma_f32_16x16x32_bf16 v[120:123], v[178:181], v[202:205], v[120:123]
	v_mfma_f32_16x16x32_bf16 v[108:111], v[170:173], v[210:213], v[108:111]
	v_mfma_f32_16x16x32_bf16 v[104:107], v[178:181], v[210:213], v[104:107]
	v_mfma_f32_16x16x32_bf16 v[92:95], v[170:173], v[218:221], v[92:95]
	v_mfma_f32_16x16x32_bf16 v[88:91], v[178:181], v[218:221], v[88:91]
	v_mfma_f32_16x16x32_bf16 v[76:79], v[170:173], v[226:229], v[76:79]
	v_mfma_f32_16x16x32_bf16 v[72:75], v[178:181], v[226:229], v[72:75]
	v_mfma_f32_16x16x32_bf16 v[116:119], v[182:185], v[198:201], v[116:119]
	v_mfma_f32_16x16x32_bf16 v[112:115], v[190:193], v[198:201], v[112:115]
	v_mfma_f32_16x16x32_bf16 v[100:103], v[182:185], v[206:209], v[100:103]
	v_mfma_f32_16x16x32_bf16 v[96:99], v[190:193], v[206:209], v[96:99]
	v_mfma_f32_16x16x32_bf16 v[84:87], v[182:185], v[214:217], v[84:87]
	v_mfma_f32_16x16x32_bf16 v[80:83], v[190:193], v[214:217], v[80:83]
	v_mfma_f32_16x16x32_bf16 v[68:71], v[182:185], v[222:225], v[68:71]
	v_mfma_f32_16x16x32_bf16 v[64:67], v[190:193], v[222:225], v[64:67]
	v_mfma_f32_16x16x32_bf16 v[116:119], v[186:189], v[202:205], v[116:119]
	v_mfma_f32_16x16x32_bf16 v[112:115], v[194:197], v[202:205], v[112:115]
	v_mfma_f32_16x16x32_bf16 v[100:103], v[186:189], v[210:213], v[100:103]
	v_mfma_f32_16x16x32_bf16 v[96:99], v[194:197], v[210:213], v[96:99]
	v_mfma_f32_16x16x32_bf16 v[84:87], v[186:189], v[218:221], v[84:87]
	v_mfma_f32_16x16x32_bf16 v[80:83], v[194:197], v[218:221], v[80:83]
	v_mfma_f32_16x16x32_bf16 v[68:71], v[186:189], v[226:229], v[68:71]
	v_mfma_f32_16x16x32_bf16 v[64:67], v[194:197], v[226:229], v[64:67]
	s_barrier
	s_mov_b32 m0, s33
	v_lshl_add_u64 v[230:231], v[230:231], 0, s[6:7]
	s_add_u32 s8, s12, 0xb0080
	ds_read_b128 v[198:201], v147 offset:49152
	ds_read_b128 v[202:205], v147 offset:50176
	ds_read_b128 v[206:209], v147 offset:51200
	ds_read_b128 v[210:213], v147 offset:52224
	ds_read_b128 v[214:217], v147 offset:53248
	ds_read_b128 v[218:221], v147 offset:54272
	ds_read_b128 v[222:225], v147 offset:55296
	ds_read_b128 v[226:229], v147 offset:56320
	global_load_lds_dwordx4 v[230:231], off
	v_lshl_add_u64 v[230:231], v[232:233], 0, s[6:7]
	s_mov_b32 m0, s34
	s_addc_u32 s9, s13, 0
	global_load_lds_dwordx4 v[230:231], off
	v_lshl_add_u64 v[230:231], s[8:9], 0, v[130:131]
	s_mov_b32 m0, s37
	s_nop 0
	global_load_lds_dwordx4 v[230:231], off
	v_lshl_add_u64 v[230:231], s[8:9], 0, v[134:135]
	s_mov_b32 m0, s42
	s_nop 0
	global_load_lds_dwordx4 v[230:231], off
	v_lshl_add_u64 v[230:231], v[234:235], 0, s[6:7]
	s_mov_b32 m0, s35
	s_nop 0
	global_load_lds_dwordx4 v[230:231], off
	v_lshl_add_u64 v[230:231], v[236:237], 0, s[6:7]
	s_mov_b32 m0, s36
	s_nop 0
	global_load_lds_dwordx4 v[230:231], off
	s_waitcnt vmcnt(8)
	s_waitcnt lgkmcnt(0)
	s_barrier
	s_waitcnt lgkmcnt(0)
	v_mfma_f32_16x16x32_bf16 v[60:63], v[166:169], v[198:201], v[60:63]
	v_mfma_f32_16x16x32_bf16 v[56:59], v[174:177], v[198:201], v[56:59]
	v_mfma_f32_16x16x32_bf16 v[44:47], v[166:169], v[206:209], v[44:47]
	v_mfma_f32_16x16x32_bf16 v[40:43], v[174:177], v[206:209], v[40:43]
	v_mfma_f32_16x16x32_bf16 v[28:31], v[166:169], v[214:217], v[28:31]
	v_mfma_f32_16x16x32_bf16 v[24:27], v[174:177], v[214:217], v[24:27]
	v_mfma_f32_16x16x32_bf16 v[12:15], v[166:169], v[222:225], v[12:15]
	v_mfma_f32_16x16x32_bf16 v[8:11], v[174:177], v[222:225], v[8:11]
	v_mfma_f32_16x16x32_bf16 v[60:63], v[170:173], v[202:205], v[60:63]
	v_mfma_f32_16x16x32_bf16 v[56:59], v[178:181], v[202:205], v[56:59]
	v_mfma_f32_16x16x32_bf16 v[44:47], v[170:173], v[210:213], v[44:47]
	v_mfma_f32_16x16x32_bf16 v[40:43], v[178:181], v[210:213], v[40:43]
	v_mfma_f32_16x16x32_bf16 v[28:31], v[170:173], v[218:221], v[28:31]
	v_mfma_f32_16x16x32_bf16 v[24:27], v[178:181], v[218:221], v[24:27]
	v_mfma_f32_16x16x32_bf16 v[12:15], v[170:173], v[226:229], v[12:15]
	v_mfma_f32_16x16x32_bf16 v[8:11], v[178:181], v[226:229], v[8:11]
	v_mfma_f32_16x16x32_bf16 v[52:55], v[182:185], v[198:201], v[52:55]
	v_mfma_f32_16x16x32_bf16 v[48:51], v[190:193], v[198:201], v[48:51]
	v_mfma_f32_16x16x32_bf16 v[36:39], v[182:185], v[206:209], v[36:39]
	v_mfma_f32_16x16x32_bf16 v[32:35], v[190:193], v[206:209], v[32:35]
	v_mfma_f32_16x16x32_bf16 v[20:23], v[182:185], v[214:217], v[20:23]
	v_mfma_f32_16x16x32_bf16 v[16:19], v[190:193], v[214:217], v[16:19]
	v_mfma_f32_16x16x32_bf16 v[4:7], v[182:185], v[222:225], v[4:7]
	v_mfma_f32_16x16x32_bf16 v[0:3], v[190:193], v[222:225], v[0:3]
	v_mfma_f32_16x16x32_bf16 v[52:55], v[186:189], v[202:205], v[52:55]
	v_mfma_f32_16x16x32_bf16 v[48:51], v[194:197], v[202:205], v[48:51]
	v_mfma_f32_16x16x32_bf16 v[36:39], v[186:189], v[210:213], v[36:39]
	v_mfma_f32_16x16x32_bf16 v[32:35], v[194:197], v[210:213], v[32:35]
	v_mfma_f32_16x16x32_bf16 v[20:23], v[186:189], v[218:221], v[20:23]
	v_mfma_f32_16x16x32_bf16 v[16:19], v[194:197], v[218:221], v[16:19]
	v_mfma_f32_16x16x32_bf16 v[4:7], v[186:189], v[226:229], v[4:7]
	v_mfma_f32_16x16x32_bf16 v[0:3], v[194:197], v[226:229], v[0:3]
	s_barrier
;   __device__ __forceinline__ void operator()(const pg8::f32x4 (&acc)[2][2][4][2], const pg8::Unit& u, int wr, int wc, int fr, int fq) const {
;     ...
;           const unsigned off = (unsigned)tok * DM + colb + 128 * bj;
;           f8_t n = __builtin_convertvector(*(const h8_t*)(x16 + off), f8_t);
; #pragma unroll
;           for (int c = 0; c < 4; ++c) { n[c] += sc * acc[ai][bj][m][0][c]; n[4 + c] += sc * acc[ai][bj][m][1][c]; }
;           if (aux) {
;             *(h8_t*)(x16 + off) = __builtin_convertvector(n, h8_t);
;             ss += ((n[0] * n[0] + n[1] * n[1]) + (n[2] * n[2] + n[3] * n[3])) + ((n[4] * n[4] + n[5] * n[5]) + (n[6] * n[6] + n[7] * n[7]));
;           } else {
;             *(f32x4*)(xout + off) = (f32x4){n[0], n[1], n[2], n[3]}; *(f32x4*)(xout + off + 4) = (f32x4){n[4], n[5], n[6], n[7]};
;           }
	s_add_i32 s53, s53, 2
	s_add_u32 s51, s51, 0x100
	s_addc_u32 s52, s52, 0
	s_cmp_gt_u32 s53, 41
	s_mov_b64 s[8:9], s[10:11]
	s_cbranch_scc0 .LBB0_1687
	v_mov_b32 v136, 0
	s_lshl_b32 s8, s49, 8
	v_lshl_or_b32 v166, s50, 8, v148
	v_add3_u32 v165, s8, v146, v136
	v_add_u32_e32 v136, v166, v136
	v_lshl_add_u32 v136, v165, 10, v136
	v_lshl_add_u64 v[166:167], v[136:137], 1, s[40:41]
	global_load_dwordx4 v[166:169], v[166:167], off
	v_mov_b32_e32 v171, v137
	v_lshl_add_u64 v[172:173], v[136:137], 2, s[30:31]
	v_add_u32_e32 v170, 0x80, v136
	v_lshl_add_u64 v[174:175], v[170:171], 1, s[40:41]
	s_and_b64 vcc, exec, s[0:1]
	s_mov_b32 s50, s47
	s_mov_b32 s49, s48
	s_mov_b64 s[10:11], s[4:5]
	s_mov_b64 s[8:9], s[2:3]
	s_waitcnt vmcnt(0)
	v_cvt_f32_f16_e32 v178, v167
	v_cvt_f32_f16_e32 v182, v166
	v_cvt_f32_f16_sdwa v183, v166 dst_sel:DWORD dst_unused:UNUSED_PAD src0_sel:WORD_1
	v_cvt_f32_f16_sdwa v179, v167 dst_sel:DWORD dst_unused:UNUSED_PAD src0_sel:WORD_1
	v_cvt_f32_f16_e32 v176, v169
	v_cvt_f32_f16_e32 v180, v168
	v_cvt_f32_f16_sdwa v181, v168 dst_sel:DWORD dst_unused:UNUSED_PAD src0_sel:WORD_1
	v_cvt_f32_f16_sdwa v177, v169 dst_sel:DWORD dst_unused:UNUSED_PAD src0_sel:WORD_1
	v_pk_fma_f32 v[124:125], v[124:125], 0.5, v[182:183] op_sel_hi:[1,0,1]
	v_pk_fma_f32 v[126:127], v[126:127], 0.5, v[178:179] op_sel_hi:[1,0,1]
	v_pk_fma_f32 v[120:121], v[120:121], 0.5, v[180:181] op_sel_hi:[1,0,1]
	v_pk_fma_f32 v[122:123], v[122:123], 0.5, v[176:177] op_sel_hi:[1,0,1]
	global_store_dwordx4 v[172:173], v[124:127], off
	global_store_dwordx4 v[172:173], v[120:123], off offset:16
	global_load_dwordx4 v[120:123], v[174:175], off
	v_lshl_add_u64 v[126:127], v[170:171], 2, s[30:31]
	v_mov_b32_e32 v125, v137
	v_add_u32_e32 v124, 0x4000, v136
	v_lshl_add_u64 v[166:167], v[124:125], 1, s[40:41]
	s_waitcnt vmcnt(0)
	v_cvt_f32_f16_e32 v170, v121
	v_cvt_f32_f16_e32 v174, v120
	v_cvt_f32_f16_sdwa v175, v120 dst_sel:DWORD dst_unused:UNUSED_PAD src0_sel:WORD_1
	v_cvt_f32_f16_sdwa v171, v121 dst_sel:DWORD dst_unused:UNUSED_PAD src0_sel:WORD_1
	v_cvt_f32_f16_e32 v168, v123
	v_cvt_f32_f16_e32 v172, v122
	v_cvt_f32_f16_sdwa v173, v122 dst_sel:DWORD dst_unused:UNUSED_PAD src0_sel:WORD_1
	v_cvt_f32_f16_sdwa v169, v123 dst_sel:DWORD dst_unused:UNUSED_PAD src0_sel:WORD_1
	v_pk_fma_f32 v[116:117], v[116:117], 0.5, v[174:175] op_sel_hi:[1,0,1]
	v_pk_fma_f32 v[118:119], v[118:119], 0.5, v[170:171] op_sel_hi:[1,0,1]
	v_pk_fma_f32 v[112:113], v[112:113], 0.5, v[172:173] op_sel_hi:[1,0,1]
	v_pk_fma_f32 v[114:115], v[114:115], 0.5, v[168:169] op_sel_hi:[1,0,1]
	global_store_dwordx4 v[126:127], v[116:119], off
	global_store_dwordx4 v[126:127], v[112:115], off offset:16
	global_load_dwordx4 v[112:115], v[166:167], off
	v_lshl_add_u64 v[118:119], v[124:125], 2, s[30:31]
	v_mov_b32_e32 v117, v137
	v_add_u32_e32 v116, 0x4080, v136
	v_lshl_add_u64 v[120:121], v[116:117], 1, s[40:41]
	s_waitcnt vmcnt(0)
	v_cvt_f32_f16_e32 v124, v113
	v_cvt_f32_f16_e32 v166, v112
	v_cvt_f32_f16_sdwa v167, v112 dst_sel:DWORD dst_unused:UNUSED_PAD src0_sel:WORD_1
	v_cvt_f32_f16_sdwa v125, v113 dst_sel:DWORD dst_unused:UNUSED_PAD src0_sel:WORD_1
	v_cvt_f32_f16_e32 v122, v115
	v_cvt_f32_f16_e32 v126, v114
	v_cvt_f32_f16_sdwa v127, v114 dst_sel:DWORD dst_unused:UNUSED_PAD src0_sel:WORD_1
	v_cvt_f32_f16_sdwa v123, v115 dst_sel:DWORD dst_unused:UNUSED_PAD src0_sel:WORD_1
	v_pk_fma_f32 v[108:109], v[108:109], 0.5, v[166:167] op_sel_hi:[1,0,1]
	v_pk_fma_f32 v[110:111], v[110:111], 0.5, v[124:125] op_sel_hi:[1,0,1]
	v_pk_fma_f32 v[104:105], v[104:105], 0.5, v[126:127] op_sel_hi:[1,0,1]
	v_pk_fma_f32 v[106:107], v[106:107], 0.5, v[122:123] op_sel_hi:[1,0,1]
	global_store_dwordx4 v[118:119], v[108:111], off
	global_store_dwordx4 v[118:119], v[104:107], off offset:16
	global_load_dwordx4 v[104:107], v[120:121], off
	v_lshl_add_u64 v[110:111], v[116:117], 2, s[30:31]
	v_mov_b32_e32 v109, v137
	v_add_u32_e32 v108, 0x8000, v136
	v_lshl_add_u64 v[112:113], v[108:109], 1, s[40:41]
	s_waitcnt vmcnt(0)
	v_cvt_f32_f16_e32 v116, v105
	v_cvt_f32_f16_e32 v120, v104
	v_cvt_f32_f16_sdwa v121, v104 dst_sel:DWORD dst_unused:UNUSED_PAD src0_sel:WORD_1
	v_cvt_f32_f16_sdwa v117, v105 dst_sel:DWORD dst_unused:UNUSED_PAD src0_sel:WORD_1
	v_cvt_f32_f16_e32 v114, v107
	v_cvt_f32_f16_e32 v118, v106
	v_cvt_f32_f16_sdwa v119, v106 dst_sel:DWORD dst_unused:UNUSED_PAD src0_sel:WORD_1
	v_cvt_f32_f16_sdwa v115, v107 dst_sel:DWORD dst_unused:UNUSED_PAD src0_sel:WORD_1
	v_pk_fma_f32 v[100:101], v[100:101], 0.5, v[120:121] op_sel_hi:[1,0,1]
	v_pk_fma_f32 v[102:103], v[102:103], 0.5, v[116:117] op_sel_hi:[1,0,1]
	v_pk_fma_f32 v[96:97], v[96:97], 0.5, v[118:119] op_sel_hi:[1,0,1]
	v_pk_fma_f32 v[98:99], v[98:99], 0.5, v[114:115] op_sel_hi:[1,0,1]
	global_store_dwordx4 v[110:111], v[100:103], off
	global_store_dwordx4 v[110:111], v[96:99], off offset:16
	global_load_dwordx4 v[96:99], v[112:113], off
	v_lshl_add_u64 v[102:103], v[108:109], 2, s[30:31]
	v_mov_b32_e32 v101, v137
	v_add_u32_e32 v100, 0x8080, v136
	v_lshl_add_u64 v[104:105], v[100:101], 1, s[40:41]
	s_waitcnt vmcnt(0)
	v_cvt_f32_f16_e32 v108, v97
	v_cvt_f32_f16_e32 v112, v96
	v_cvt_f32_f16_sdwa v113, v96 dst_sel:DWORD dst_unused:UNUSED_PAD src0_sel:WORD_1
	v_cvt_f32_f16_sdwa v109, v97 dst_sel:DWORD dst_unused:UNUSED_PAD src0_sel:WORD_1
	v_cvt_f32_f16_e32 v106, v99
	v_cvt_f32_f16_e32 v110, v98
	v_cvt_f32_f16_sdwa v111, v98 dst_sel:DWORD dst_unused:UNUSED_PAD src0_sel:WORD_1
	v_cvt_f32_f16_sdwa v107, v99 dst_sel:DWORD dst_unused:UNUSED_PAD src0_sel:WORD_1
	v_pk_fma_f32 v[92:93], v[92:93], 0.5, v[112:113] op_sel_hi:[1,0,1]
	v_pk_fma_f32 v[94:95], v[94:95], 0.5, v[108:109] op_sel_hi:[1,0,1]
	v_pk_fma_f32 v[88:89], v[88:89], 0.5, v[110:111] op_sel_hi:[1,0,1]
	v_pk_fma_f32 v[90:91], v[90:91], 0.5, v[106:107] op_sel_hi:[1,0,1]
	global_store_dwordx4 v[102:103], v[92:95], off
	global_store_dwordx4 v[102:103], v[88:91], off offset:16
	global_load_dwordx4 v[88:91], v[104:105], off
	v_lshl_add_u64 v[94:95], v[100:101], 2, s[30:31]
	v_mov_b32_e32 v93, v137
	v_add_u32_e32 v92, 0xc000, v136
	v_lshl_add_u64 v[96:97], v[92:93], 1, s[40:41]
	s_waitcnt vmcnt(0)
;   __device__ __forceinline__ void operator()(const pg8::f32x4 (&acc)[2][2][4][2], const pg8::Unit& u, int wr, int wc, int fr, int fq) const {
;     ...
;           const unsigned off = (unsigned)tok * DM + colb + 128 * bj;
;           f8_t n = __builtin_convertvector(*(const h8_t*)(x16 + off), f8_t);
; #pragma unroll
;           for (int c = 0; c < 4; ++c) { n[c] += sc * acc[ai][bj][m][0][c]; n[4 + c] += sc * acc[ai][bj][m][1][c]; }
;           if (aux) {
;             *(h8_t*)(x16 + off) = __builtin_convertvector(n, h8_t);
;             ss += ((n[0] * n[0] + n[1] * n[1]) + (n[2] * n[2] + n[3] * n[3])) + ((n[4] * n[4] + n[5] * n[5]) + (n[6] * n[6] + n[7] * n[7]));
;           } else {
;             *(f32x4*)(xout + off) = (f32x4){n[0], n[1], n[2], n[3]}; *(f32x4*)(xout + off + 4) = (f32x4){n[4], n[5], n[6], n[7]};
;           }
	v_cvt_f32_f16_e32 v100, v89
	v_cvt_f32_f16_e32 v104, v88
	v_cvt_f32_f16_sdwa v105, v88 dst_sel:DWORD dst_unused:UNUSED_PAD src0_sel:WORD_1
	v_cvt_f32_f16_sdwa v101, v89 dst_sel:DWORD dst_unused:UNUSED_PAD src0_sel:WORD_1
	v_cvt_f32_f16_e32 v98, v91
	v_cvt_f32_f16_e32 v102, v90
	v_cvt_f32_f16_sdwa v103, v90 dst_sel:DWORD dst_unused:UNUSED_PAD src0_sel:WORD_1
	v_cvt_f32_f16_sdwa v99, v91 dst_sel:DWORD dst_unused:UNUSED_PAD src0_sel:WORD_1
	v_pk_fma_f32 v[84:85], v[84:85], 0.5, v[104:105] op_sel_hi:[1,0,1]
	v_pk_fma_f32 v[86:87], v[86:87], 0.5, v[100:101] op_sel_hi:[1,0,1]
	v_pk_fma_f32 v[80:81], v[80:81], 0.5, v[102:103] op_sel_hi:[1,0,1]
	v_pk_fma_f32 v[82:83], v[82:83], 0.5, v[98:99] op_sel_hi:[1,0,1]
	global_store_dwordx4 v[94:95], v[84:87], off
	global_store_dwordx4 v[94:95], v[80:83], off offset:16
	global_load_dwordx4 v[80:83], v[96:97], off
	v_lshl_add_u64 v[86:87], v[92:93], 2, s[30:31]
	v_mov_b32_e32 v85, v137
	v_add_u32_e32 v84, 0xc080, v136
	v_lshl_add_u64 v[88:89], v[84:85], 1, s[40:41]
	s_waitcnt vmcnt(0)
	v_cvt_f32_f16_e32 v92, v81
	v_cvt_f32_f16_e32 v96, v80
	v_cvt_f32_f16_sdwa v97, v80 dst_sel:DWORD dst_unused:UNUSED_PAD src0_sel:WORD_1
	v_cvt_f32_f16_sdwa v93, v81 dst_sel:DWORD dst_unused:UNUSED_PAD src0_sel:WORD_1
	v_cvt_f32_f16_e32 v90, v83
	v_cvt_f32_f16_e32 v94, v82
	v_cvt_f32_f16_sdwa v95, v82 dst_sel:DWORD dst_unused:UNUSED_PAD src0_sel:WORD_1
	v_cvt_f32_f16_sdwa v91, v83 dst_sel:DWORD dst_unused:UNUSED_PAD src0_sel:WORD_1
	v_pk_fma_f32 v[76:77], v[76:77], 0.5, v[96:97] op_sel_hi:[1,0,1]
	v_pk_fma_f32 v[78:79], v[78:79], 0.5, v[92:93] op_sel_hi:[1,0,1]
	v_pk_fma_f32 v[72:73], v[72:73], 0.5, v[94:95] op_sel_hi:[1,0,1]
	v_pk_fma_f32 v[74:75], v[74:75], 0.5, v[90:91] op_sel_hi:[1,0,1]
	global_store_dwordx4 v[86:87], v[76:79], off
	global_store_dwordx4 v[86:87], v[72:75], off offset:16
	global_load_dwordx4 v[72:75], v[88:89], off
	v_lshl_add_u64 v[78:79], v[84:85], 2, s[30:31]
	v_mov_b32_e32 v77, v137
	v_add_u32_e32 v76, 0x20000, v136
	v_lshl_add_u64 v[80:81], v[76:77], 1, s[40:41]
	s_waitcnt vmcnt(0)
	v_cvt_f32_f16_e32 v84, v73
	v_cvt_f32_f16_e32 v88, v72
	v_cvt_f32_f16_sdwa v89, v72 dst_sel:DWORD dst_unused:UNUSED_PAD src0_sel:WORD_1
	v_cvt_f32_f16_sdwa v85, v73 dst_sel:DWORD dst_unused:UNUSED_PAD src0_sel:WORD_1
	v_cvt_f32_f16_e32 v82, v75
	v_cvt_f32_f16_e32 v86, v74
	v_cvt_f32_f16_sdwa v87, v74 dst_sel:DWORD dst_unused:UNUSED_PAD src0_sel:WORD_1
	v_cvt_f32_f16_sdwa v83, v75 dst_sel:DWORD dst_unused:UNUSED_PAD src0_sel:WORD_1
	v_pk_fma_f32 v[68:69], v[68:69], 0.5, v[88:89] op_sel_hi:[1,0,1]
	v_pk_fma_f32 v[70:71], v[70:71], 0.5, v[84:85] op_sel_hi:[1,0,1]
	v_pk_fma_f32 v[64:65], v[64:65], 0.5, v[86:87] op_sel_hi:[1,0,1]
	v_pk_fma_f32 v[66:67], v[66:67], 0.5, v[82:83] op_sel_hi:[1,0,1]
	global_store_dwordx4 v[78:79], v[68:71], off
	global_store_dwordx4 v[78:79], v[64:67], off offset:16
	global_load_dwordx4 v[64:67], v[80:81], off
	v_lshl_add_u64 v[70:71], v[76:77], 2, s[30:31]
	v_mov_b32_e32 v69, v137
	v_add_u32_e32 v68, 0x20080, v136
	v_lshl_add_u64 v[72:73], v[68:69], 1, s[40:41]
	s_waitcnt vmcnt(0)
	v_cvt_f32_f16_e32 v76, v65
	v_cvt_f32_f16_e32 v80, v64
	v_cvt_f32_f16_sdwa v81, v64 dst_sel:DWORD dst_unused:UNUSED_PAD src0_sel:WORD_1
	v_cvt_f32_f16_sdwa v77, v65 dst_sel:DWORD dst_unused:UNUSED_PAD src0_sel:WORD_1
	v_cvt_f32_f16_e32 v74, v67
	v_cvt_f32_f16_e32 v78, v66
	v_cvt_f32_f16_sdwa v79, v66 dst_sel:DWORD dst_unused:UNUSED_PAD src0_sel:WORD_1
	v_cvt_f32_f16_sdwa v75, v67 dst_sel:DWORD dst_unused:UNUSED_PAD src0_sel:WORD_1
	v_pk_fma_f32 v[60:61], v[60:61], 0.5, v[80:81] op_sel_hi:[1,0,1]
	v_pk_fma_f32 v[62:63], v[62:63], 0.5, v[76:77] op_sel_hi:[1,0,1]
	v_pk_fma_f32 v[56:57], v[56:57], 0.5, v[78:79] op_sel_hi:[1,0,1]
	v_pk_fma_f32 v[58:59], v[58:59], 0.5, v[74:75] op_sel_hi:[1,0,1]
	global_store_dwordx4 v[70:71], v[60:63], off
	global_store_dwordx4 v[70:71], v[56:59], off offset:16
	global_load_dwordx4 v[56:59], v[72:73], off
	v_lshl_add_u64 v[62:63], v[68:69], 2, s[30:31]
	v_mov_b32_e32 v61, v137
	v_add_u32_e32 v60, 0x24000, v136
	v_lshl_add_u64 v[64:65], v[60:61], 1, s[40:41]
	s_waitcnt vmcnt(0)
	v_cvt_f32_f16_e32 v68, v57
	v_cvt_f32_f16_e32 v72, v56
	v_cvt_f32_f16_sdwa v73, v56 dst_sel:DWORD dst_unused:UNUSED_PAD src0_sel:WORD_1
	v_cvt_f32_f16_sdwa v69, v57 dst_sel:DWORD dst_unused:UNUSED_PAD src0_sel:WORD_1
	v_cvt_f32_f16_e32 v66, v59
	v_cvt_f32_f16_e32 v70, v58
	v_cvt_f32_f16_sdwa v71, v58 dst_sel:DWORD dst_unused:UNUSED_PAD src0_sel:WORD_1
	v_cvt_f32_f16_sdwa v67, v59 dst_sel:DWORD dst_unused:UNUSED_PAD src0_sel:WORD_1
	v_pk_fma_f32 v[52:53], v[52:53], 0.5, v[72:73] op_sel_hi:[1,0,1]
	v_pk_fma_f32 v[54:55], v[54:55], 0.5, v[68:69] op_sel_hi:[1,0,1]
	v_pk_fma_f32 v[48:49], v[48:49], 0.5, v[70:71] op_sel_hi:[1,0,1]
	v_pk_fma_f32 v[50:51], v[50:51], 0.5, v[66:67] op_sel_hi:[1,0,1]
	global_store_dwordx4 v[62:63], v[52:55], off
	global_store_dwordx4 v[62:63], v[48:51], off offset:16
	global_load_dwordx4 v[48:51], v[64:65], off
	v_lshl_add_u64 v[54:55], v[60:61], 2, s[30:31]
	v_mov_b32_e32 v53, v137
	v_add_u32_e32 v52, 0x24080, v136
	v_lshl_add_u64 v[56:57], v[52:53], 1, s[40:41]
	s_waitcnt vmcnt(0)
; #define PG8_WAIT_V(n) asm volatile("s_waitcnt vmcnt(" #n ")" ::: "memory")
; #define PG8_BAR __builtin_amdgcn_s_barrier()
; template <class Epi, class Sched, bool ALIGN_EPI = false, bool SP2 = false, bool F16 = false, bool TOKPERM = false>
; __device__ __forceinline__ void gemm_phase(PG8_LAS unsigned char* lds, const Gemm g, const Sched& S, const Epi& E, int wv) {
;     ...
;     PG8_WAIT_V(0);
;     if constexpr (!ALIGN_EPI) { if (wr == 0) PG8_BAR; }
;     PG8_BAR;
;   __device__ __forceinline__ void operator()(const pg8::f32x4 (&acc)[2][2][4][2], const pg8::Unit& u, int wr, int wc, int fr, int fq) const {
;     ...
;           const unsigned off = (unsigned)tok * DM + colb + 128 * bj;
;           f8_t n = __builtin_convertvector(*(const h8_t*)(x16 + off), f8_t);
; #pragma unroll
;           for (int c = 0; c < 4; ++c) { n[c] += sc * acc[ai][bj][m][0][c]; n[4 + c] += sc * acc[ai][bj][m][1][c]; }
;           if (aux) {
;             *(h8_t*)(x16 + off) = __builtin_convertvector(n, h8_t);
;             ss += ((n[0] * n[0] + n[1] * n[1]) + (n[2] * n[2] + n[3] * n[3])) + ((n[4] * n[4] + n[5] * n[5]) + (n[6] * n[6] + n[7] * n[7]));
;           } else {
;             *(f32x4*)(xout + off) = (f32x4){n[0], n[1], n[2], n[3]}; *(f32x4*)(xout + off + 4) = (f32x4){n[4], n[5], n[6], n[7]};
;           }
	v_cvt_f32_f16_e32 v60, v49
	v_cvt_f32_f16_e32 v64, v48
	v_cvt_f32_f16_sdwa v65, v48 dst_sel:DWORD dst_unused:UNUSED_PAD src0_sel:WORD_1
	v_cvt_f32_f16_sdwa v61, v49 dst_sel:DWORD dst_unused:UNUSED_PAD src0_sel:WORD_1
	v_cvt_f32_f16_e32 v58, v51
	v_cvt_f32_f16_e32 v62, v50
	v_cvt_f32_f16_sdwa v63, v50 dst_sel:DWORD dst_unused:UNUSED_PAD src0_sel:WORD_1
	v_cvt_f32_f16_sdwa v59, v51 dst_sel:DWORD dst_unused:UNUSED_PAD src0_sel:WORD_1
	v_pk_fma_f32 v[44:45], v[44:45], 0.5, v[64:65] op_sel_hi:[1,0,1]
	v_pk_fma_f32 v[46:47], v[46:47], 0.5, v[60:61] op_sel_hi:[1,0,1]
	v_pk_fma_f32 v[40:41], v[40:41], 0.5, v[62:63] op_sel_hi:[1,0,1]
	v_pk_fma_f32 v[42:43], v[42:43], 0.5, v[58:59] op_sel_hi:[1,0,1]
	global_store_dwordx4 v[54:55], v[44:47], off
	global_store_dwordx4 v[54:55], v[40:43], off offset:16
	global_load_dwordx4 v[40:43], v[56:57], off
	v_lshl_add_u64 v[46:47], v[52:53], 2, s[30:31]
	v_mov_b32_e32 v45, v137
	v_add_u32_e32 v44, 0x28000, v136
	v_lshl_add_u64 v[48:49], v[44:45], 1, s[40:41]
	s_waitcnt vmcnt(0)
	v_cvt_f32_f16_e32 v52, v41
	v_cvt_f32_f16_e32 v56, v40
	v_cvt_f32_f16_sdwa v57, v40 dst_sel:DWORD dst_unused:UNUSED_PAD src0_sel:WORD_1
	v_cvt_f32_f16_sdwa v53, v41 dst_sel:DWORD dst_unused:UNUSED_PAD src0_sel:WORD_1
	v_cvt_f32_f16_e32 v50, v43
	v_cvt_f32_f16_e32 v54, v42
	v_cvt_f32_f16_sdwa v55, v42 dst_sel:DWORD dst_unused:UNUSED_PAD src0_sel:WORD_1
	v_cvt_f32_f16_sdwa v51, v43 dst_sel:DWORD dst_unused:UNUSED_PAD src0_sel:WORD_1
	v_pk_fma_f32 v[36:37], v[36:37], 0.5, v[56:57] op_sel_hi:[1,0,1]
	v_pk_fma_f32 v[38:39], v[38:39], 0.5, v[52:53] op_sel_hi:[1,0,1]
	v_pk_fma_f32 v[32:33], v[32:33], 0.5, v[54:55] op_sel_hi:[1,0,1]
	v_pk_fma_f32 v[34:35], v[34:35], 0.5, v[50:51] op_sel_hi:[1,0,1]
	global_store_dwordx4 v[46:47], v[36:39], off
	global_store_dwordx4 v[46:47], v[32:35], off offset:16
	global_load_dwordx4 v[32:35], v[48:49], off
	v_lshl_add_u64 v[38:39], v[44:45], 2, s[30:31]
	v_mov_b32_e32 v37, v137
	v_add_u32_e32 v36, 0x28080, v136
	v_lshl_add_u64 v[40:41], v[36:37], 1, s[40:41]
	s_waitcnt vmcnt(0)
	v_cvt_f32_f16_e32 v44, v33
	v_cvt_f32_f16_e32 v48, v32
	v_cvt_f32_f16_sdwa v49, v32 dst_sel:DWORD dst_unused:UNUSED_PAD src0_sel:WORD_1
	v_cvt_f32_f16_sdwa v45, v33 dst_sel:DWORD dst_unused:UNUSED_PAD src0_sel:WORD_1
	v_cvt_f32_f16_e32 v42, v35
	v_cvt_f32_f16_e32 v46, v34
	v_cvt_f32_f16_sdwa v47, v34 dst_sel:DWORD dst_unused:UNUSED_PAD src0_sel:WORD_1
	v_cvt_f32_f16_sdwa v43, v35 dst_sel:DWORD dst_unused:UNUSED_PAD src0_sel:WORD_1
	v_pk_fma_f32 v[28:29], v[28:29], 0.5, v[48:49] op_sel_hi:[1,0,1]
	v_pk_fma_f32 v[30:31], v[30:31], 0.5, v[44:45] op_sel_hi:[1,0,1]
	v_pk_fma_f32 v[24:25], v[24:25], 0.5, v[46:47] op_sel_hi:[1,0,1]
	v_pk_fma_f32 v[26:27], v[26:27], 0.5, v[42:43] op_sel_hi:[1,0,1]
	global_store_dwordx4 v[38:39], v[28:31], off
	global_store_dwordx4 v[38:39], v[24:27], off offset:16
	global_load_dwordx4 v[24:27], v[40:41], off
	v_lshl_add_u64 v[30:31], v[36:37], 2, s[30:31]
	v_mov_b32_e32 v29, v137
	v_add_u32_e32 v28, 0x2c000, v136
	v_lshl_add_u64 v[32:33], v[28:29], 1, s[40:41]
	v_add_u32_e32 v136, 0x2c080, v136
	s_waitcnt vmcnt(0)
	v_cvt_f32_f16_e32 v36, v25
	v_cvt_f32_f16_e32 v40, v24
	v_cvt_f32_f16_sdwa v41, v24 dst_sel:DWORD dst_unused:UNUSED_PAD src0_sel:WORD_1
	v_cvt_f32_f16_sdwa v37, v25 dst_sel:DWORD dst_unused:UNUSED_PAD src0_sel:WORD_1
	v_cvt_f32_f16_e32 v34, v27
	v_cvt_f32_f16_e32 v38, v26
	v_cvt_f32_f16_sdwa v39, v26 dst_sel:DWORD dst_unused:UNUSED_PAD src0_sel:WORD_1
	v_cvt_f32_f16_sdwa v35, v27 dst_sel:DWORD dst_unused:UNUSED_PAD src0_sel:WORD_1
	v_pk_fma_f32 v[20:21], v[20:21], 0.5, v[40:41] op_sel_hi:[1,0,1]
	v_pk_fma_f32 v[22:23], v[22:23], 0.5, v[36:37] op_sel_hi:[1,0,1]
	v_pk_fma_f32 v[16:17], v[16:17], 0.5, v[38:39] op_sel_hi:[1,0,1]
	v_pk_fma_f32 v[18:19], v[18:19], 0.5, v[34:35] op_sel_hi:[1,0,1]
	global_store_dwordx4 v[30:31], v[20:23], off
	global_store_dwordx4 v[30:31], v[16:19], off offset:16
	global_load_dwordx4 v[16:19], v[32:33], off
	v_lshl_add_u64 v[20:21], v[28:29], 2, s[30:31]
	v_lshl_add_u64 v[22:23], v[136:137], 1, s[40:41]
	s_waitcnt vmcnt(0)
	v_cvt_f32_f16_e32 v26, v17
	v_cvt_f32_f16_e32 v30, v16
	v_cvt_f32_f16_sdwa v31, v16 dst_sel:DWORD dst_unused:UNUSED_PAD src0_sel:WORD_1
	v_cvt_f32_f16_sdwa v27, v17 dst_sel:DWORD dst_unused:UNUSED_PAD src0_sel:WORD_1
	v_cvt_f32_f16_e32 v24, v19
	v_cvt_f32_f16_e32 v28, v18
	v_cvt_f32_f16_sdwa v29, v18 dst_sel:DWORD dst_unused:UNUSED_PAD src0_sel:WORD_1
	v_cvt_f32_f16_sdwa v25, v19 dst_sel:DWORD dst_unused:UNUSED_PAD src0_sel:WORD_1
	v_pk_fma_f32 v[12:13], v[12:13], 0.5, v[30:31] op_sel_hi:[1,0,1]
	v_pk_fma_f32 v[14:15], v[14:15], 0.5, v[26:27] op_sel_hi:[1,0,1]
	v_pk_fma_f32 v[8:9], v[8:9], 0.5, v[28:29] op_sel_hi:[1,0,1]
	v_pk_fma_f32 v[10:11], v[10:11], 0.5, v[24:25] op_sel_hi:[1,0,1]
	global_store_dwordx4 v[20:21], v[12:15], off
	global_store_dwordx4 v[20:21], v[8:11], off offset:16
	global_load_dwordx4 v[8:11], v[22:23], off
	v_lshl_add_u64 v[12:13], v[136:137], 2, s[30:31]
	s_waitcnt vmcnt(0)
	v_cvt_f32_f16_e32 v16, v9
	v_cvt_f32_f16_e32 v20, v8
	v_cvt_f32_f16_sdwa v21, v8 dst_sel:DWORD dst_unused:UNUSED_PAD src0_sel:WORD_1
	v_cvt_f32_f16_sdwa v17, v9 dst_sel:DWORD dst_unused:UNUSED_PAD src0_sel:WORD_1
	v_cvt_f32_f16_e32 v14, v11
	v_cvt_f32_f16_e32 v18, v10
	v_cvt_f32_f16_sdwa v19, v10 dst_sel:DWORD dst_unused:UNUSED_PAD src0_sel:WORD_1
	v_cvt_f32_f16_sdwa v15, v11 dst_sel:DWORD dst_unused:UNUSED_PAD src0_sel:WORD_1
	v_pk_fma_f32 v[4:5], v[4:5], 0.5, v[20:21] op_sel_hi:[1,0,1]
	v_pk_fma_f32 v[6:7], v[6:7], 0.5, v[16:17] op_sel_hi:[1,0,1]
	v_pk_fma_f32 v[0:1], v[0:1], 0.5, v[18:19] op_sel_hi:[1,0,1]
	v_pk_fma_f32 v[2:3], v[2:3], 0.5, v[14:15] op_sel_hi:[1,0,1]
	global_store_dwordx4 v[12:13], v[4:7], off
	global_store_dwordx4 v[12:13], v[0:3], off offset:16
	s_cbranch_vccz .LBB0_1676
	s_waitcnt vmcnt(0)
	s_cmpk_gt_u32 s16, 0xff
	s_cbranch_scc1 .LBB0_1691
	s_barrier
